# GEMM K-loops: one workgroup barrier per super-phase instead of two (separate loop copies for the leading and trailing wave halves, trailing half at priority 2)
# baseline (speedup 1.0000x reference)
; __device__ __forceinline__ int otid() { int t = (int)threadIdx.x; asm volatile("" : "+v"(t)); return t; }
; #define LAS __attribute__((address_space(3)))
; template <class Epi, class Sched, bool ALIGN_EPI = false, bool SP2 = false, bool ABLK = false, bool BBLK = false>
; __device__ __forceinline__ void gemm_phase(PG8_LAS unsigned char* lds, const Gemm g, const Sched& S, const Epi& E) {
;     const int tid = otid(), wid = __builtin_amdgcn_readfirstlane(tid >> 6), lane = tid & 63, wr = wid >> 2, wc = wid & 3, fr = lane & 15, fq = lane >> 4;
; __global__ void __launch_bounds__(NTHREADS, 2) k_mega(KP p) {
;     extern __shared__ __attribute__((aligned(16))) unsigned char smem[];
;     LAS unsigned char* lds = (LAS unsigned char*)smem;
;     volatile LAS unsigned* xbw = (volatile LAS unsigned*)(lds + LDS_BYTES - 16);
;     if (threadIdx.x < 4) xbw[threadIdx.x] = 0u;
;     __syncthreads();
;     const XcdBarrier bar = xcd_barrier_post((unsigned*)(p.ws + WS_CTL) + CW_BAR, xbw);
_Z6k_mega2KP:
	v_readfirstlane_b32 s100, v0
	s_nop 3
	s_lshr_b32 s100, s100, 8
	s_load_dwordx16 s[40:55], s[0:1], 0xc0
	s_mov_b32 s85, s2
	v_cmp_gt_u32_e32 vcc, 4, v0
	s_and_saveexec_b64 s[2:3], vcc
	v_lshl_add_u32 v1, v0, 2, 0
	v_add_u32_e32 v1, 0x23ff0, v1
	v_mov_b32_e32 v2, 0
	ds_write_b32 v1, v2
	s_or_b64 exec, exec, s[2:3]
	s_waitcnt lgkmcnt(0)
	s_add_u32 s2, s54, 0x1000
	s_addc_u32 s3, s55, 0
	v_writelane_b32 v252, s2, 0
	s_barrier
	s_nop 0
	v_writelane_b32 v252, s3, 1
	s_getreg_b32 s2, hwreg(HW_REG_XCC_ID, 0, 4)
	s_and_b32 s2, s2, 15
	v_writelane_b32 v252, s2, 2
	v_cmp_eq_u32_e64 s[4:5], 0, v0
	s_mov_b64 s[2:3], exec
	s_nop 0
	v_writelane_b32 v252, s4, 3
	s_nop 1
	v_writelane_b32 v252, s5, 4
	s_and_b64 s[4:5], s[2:3], s[4:5]
	s_mov_b64 exec, s[4:5]
	s_cbranch_execz .LBB0_5
	s_mov_b64 s[4:5], exec
	v_mbcnt_lo_u32_b32 v1, s4, 0
	v_mbcnt_hi_u32_b32 v1, s5, v1
	v_cmp_eq_u32_e32 vcc, 0, v1
	s_and_b64 s[6:7], exec, vcc
	s_mov_b64 exec, s[6:7]
	s_cbranch_execz .LBB0_5
	v_readlane_b32 s6, v252, 2
	s_bcnt1_i32_b64 s4, s[4:5]
	s_lshl_b32 s6, s6, 8
	v_mov_b32_e32 v2, s4
	v_readlane_b32 s4, v252, 0
	v_mov_b32_e32 v1, s6
	v_readlane_b32 s5, v252, 1
	s_nop 4
	global_atomic_add v1, v2, s[4:5] offset:1024

; __device__ __forceinline__ int otid() { int t = (int)threadIdx.x; asm volatile("" : "+v"(t)); return t; }
; #define PG8_STAGE(bufoff, gbase, voff) do { _Pragma("unroll") for (int _i = 0; _i < 2; ++_i) \
;         __builtin_amdgcn_global_load_lds((const unsigned*)((const char*)(gbase) + (voff)[_i]), (PG8_LAS unsigned*)(lds + (bufoff) + ldsw + _i * 8192), 16, 0, 0); } while (0)
; #define PG8_BAR __builtin_amdgcn_s_barrier()
; template <class Epi, class Sched, bool ALIGN_EPI = false, bool SP2 = false, bool ABLK = false, bool BBLK = false>
; __device__ __forceinline__ void gemm_phase(PG8_LAS unsigned char* lds, const Gemm g, const Sched& S, const Epi& E) {
;     const int tid = otid(), wid = __builtin_amdgcn_readfirstlane(tid >> 6), lane = tid & 63, wr = wid >> 2, wc = wid & 3, fr = lane & 15, fq = lane >> 4;
;     const int K = g.K, nt = K / BK;
;     unsigned voffA[2], voffB[2];
; #pragma unroll
;     for (int i = 0; i < 2; ++i) { int R, C; stage_rc(tid * 16 + i * 8192, R, C); const int Rb = Epi::PERM ? ((R & ~31) + perm32(R & 31)) : R;
;         voffA[i] = ABLK ? (unsigned)(R * BK + C) * 2u : (unsigned)(R * K + C) * 2u; voffB[i] = BBLK ? (unsigned)(Rb * BK + C) * 2u : (unsigned)(Rb * K + C) * 2u; }
;     ...
;     if (!S.next(0, cur)) return;
;     f32x4 acc[2][2][4][2];
; #pragma unroll
;     for (int a = 0; a < 2; ++a)
; #pragma unroll
;         for (int b = 0; b < 2; ++b)
; #pragma unroll
;             for (int m = 0; m < 4; ++m)
; #pragma unroll
;                 for (int n = 0; n < 2; ++n) acc[a][b][m][n] = (f32x4){0.f, 0.f, 0.f, 0.f};
;     bf16x8 At[4][2], B0[2][2], B1[2][2];
;     const char* cA = (const char*)g.A + (size_t)cur.pm * tstep; const char* cB = (const char*)g.Bt + (size_t)cur.pn * tstep;
;     S.a_ready(cur);
;     if constexpr (SP2) {
;         PG8_STAGE(PG8_SB(0, 0), cB, voffB); PG8_STAGE(PG8_SB(0, 1), cB + hstepB, voffB); PG8_STAGE(PG8_SA(0, 0), cA, voffA); PG8_STAGE(PG8_SA(0, 1), cA + hstepA, voffA);
;         if (wr == 1) PG8_BAR;
.LBB0_175:
	s_cmp_lg_u32 s0, 1
	v_writelane_b32 v255, s0, 38
	s_cbranch_scc0 .LBB0_191
	s_cmp_eq_u32 s0, 2
	s_cselect_b64 s[58:59], -1, 0
	s_cmp_lg_u32 s0, 2
	s_cselect_b64 s[0:1], -1, 0
	v_writelane_b32 v255, s0, 39
	s_waitcnt lgkmcnt(0)
	s_mov_b32 s28, s85
	v_mov_b32_e32 v3, v0
	v_writelane_b32 v255, s1, 40
	s_cmpk_lt_i32 s28, 0x1600
	v_readfirstlane_b32 s4, v3
	s_movk_i32 s56, 0x2c1
	s_cbranch_scc0 .LBB0_193
	v_lshlrev_b32_e32 v7, 4, v3
	v_add_u32_e32 v5, 0x2000, v7
	v_ashrrev_i32_e32 v4, 31, v5
	v_lshrrev_b32_e32 v4, 22, v4
	v_add_u32_e32 v4, v5, v4
	v_ashrrev_i32_e32 v4, 10, v4
	v_mul_i32_i24_e32 v6, 0x400, v4
	v_sub_u32_e32 v5, v5, v6
	v_lshrrev_b32_e32 v6, 4, v5
	v_bitop3_b32 v6, v6, v5, 32 bitop3:0x6c
	v_ashrrev_i32_e32 v5, 31, v6
	v_lshrrev_b32_e32 v5, 26, v5
	s_and_b64 s[0:1], s[58:59], exec
	v_add_u32_e32 v8, v6, v5
	v_lshlrev_b32_e32 v9, 3, v4
	s_mov_b32 s0, 0x2d00000
	v_ashrrev_i32_e32 v5, 6, v8
	v_and_b32_e32 v9, -16, v9
	s_cselect_b32 s0, s0, 0x100000
	v_add_u32_e32 v9, v5, v9
	s_add_u32 s29, s54, s0
	v_and_b32_e32 v10, 3, v5
	s_mov_b32 s0, 0x1ffffe0
	v_lshrrev_b32_e32 v11, 2, v9
	v_lshlrev_b32_e32 v12, 1, v9
	v_and_b32_e32 v8, 0xc0, v8
	v_and_or_b32 v10, v9, s0, v10
	v_and_b32_e32 v11, 4, v11
	v_and_b32_e32 v12, 24, v12
	v_sub_u32_e32 v6, v6, v8
	v_or3_b32 v10, v10, v11, v12
	v_lshlrev_b32_e32 v11, 5, v4
	v_ashrrev_i16_sdwa v6, v1, sext(v6) dst_sel:DWORD dst_unused:UNUSED_PAD src0_sel:DWORD src1_sel:BYTE_0
	v_and_b32_e32 v11, 32, v11
	v_bfe_i32 v6, v6, 0, 16
	v_add_lshl_u32 v8, v11, v6, 1
	v_lshl_add_u32 v136, v10, 7, v8
	v_lshl_add_u32 v138, v9, 7, v8
	v_bfe_i32 v8, v3, 27, 1
	v_lshrrev_b32_e32 v8, 22, v8
	v_add_u32_e32 v8, v7, v8
	v_and_b32_e32 v8, 0xfffffc00, v8
	v_sub_u32_e32 v7, v7, v8
	v_lshrrev_b32_e32 v8, 4, v7
	v_bitop3_b32 v9, v8, v7, 32 bitop3:0x6c
	v_ashrrev_i32_e32 v8, 31, v3
	v_lshrrev_b32_e32 v8, 26, v8
	v_ashrrev_i32_e32 v7, 31, v7
	v_add_u32_e32 v8, v3, v8
	v_lshrrev_b32_e32 v7, 26, v7
	v_ashrrev_i32_e32 v8, 6, v8
	v_add_u32_e32 v7, v9, v7
	v_lshlrev_b32_e32 v10, 3, v8
	v_ashrrev_i32_e32 v7, 6, v7
	v_and_b32_e32 v10, -16, v10
	s_addc_u32 s30, s55, 0
	v_add_u32_e32 v10, v7, v10
	v_and_b32_e32 v11, 3, v7
	s_ashr_i32 s34, s28, 31
	v_and_or_b32 v11, v10, s0, v11
	s_lshr_b32 s0, s34, 29
	s_add_i32 s0, s28, s0
	s_ashr_i32 s3, s4, 6
	s_ashr_i32 s1, s0, 3
	s_and_b32 s0, s0, -8
	s_ashr_i32 s5, s4, 8
	s_lshl_b32 s31, s3, 10
	s_sub_i32 s0, s28, s0
	s_cmp_lt_i32 s0, 0
	s_cselect_b32 s2, s56, 0x2c0
	s_mul_i32 s0, s2, s0
	s_add_i32 s0, s0, s1
	s_mul_hi_i32 s1, s0, 0x2e8ba2e9
	s_lshr_b32 s2, s1, 31
	s_ashr_i32 s1, s1, 5
	s_add_i32 s1, s1, s2
	s_lshl_b32 s6, s1, 2
	s_mulk_i32 s1, 0xb0
	s_sub_i32 s0, s0, s1
	s_bfe_u32 s1, s0, 0x2001d
	s_add_i32 s1, s0, s1
	s_sext_i32_i16 s2, s1
	s_and_b32 s1, s1, 0xfffc
	v_lshrrev_b32_e32 v12, 2, v10
	v_lshlrev_b32_e32 v13, 1, v10
	s_sub_i32 s0, s0, s1
	v_and_b32_e32 v12, 4, v12
	v_and_b32_e32 v13, 24, v13
	s_sext_i32_i16 s0, s0
	v_or3_b32 v11, v11, v12, v13
	v_mul_i32_i24_e32 v13, 64, v7
	s_lshr_b32 s2, s2, 2
	s_add_i32 s18, s6, s0
	v_sub_u32_e32 v9, v9, v13
	s_ashr_i32 s19, s18, 31
	s_bfe_i64 s[6:7], s[2:3], 0x100000
	v_lshlrev_b32_e32 v12, 5, v8
	v_ashrrev_i16_sdwa v9, v1, sext(v9) dst_sel:DWORD dst_unused:UNUSED_PAD src0_sel:DWORD src1_sel:BYTE_0
	s_lshl_b64 s[0:1], s[18:19], 20
	s_lshl_b64 s[6:7], s[6:7], 20
	v_and_b32_e32 v12, 32, v12
	v_bfe_i32 v9, v9, 0, 16
	s_add_u32 s22, s29, s6
	v_add_lshl_u32 v12, v12, v9, 1
	s_addc_u32 s23, s30, s7
	s_add_i32 s19, s31, 0
	v_lshl_add_u32 v140, v11, 7, v12
	s_add_i32 m0, s19, 0x10000
	v_lshl_add_u32 v142, v10, 7, v12
	global_load_lds_dwordx4 v140, s[22:23]
	s_add_i32 m0, s19, 0x12000
	s_add_u32 s6, s22, 0x4000
	global_load_lds_dwordx4 v136, s[22:23]
	s_addc_u32 s7, s23, 0
	s_add_i32 m0, s19, 0x14000
	s_nop 0
	global_load_lds_dwordx4 v140, s[6:7]
	s_add_i32 m0, s19, 0x16000
	s_nop 0
	global_load_lds_dwordx4 v136, s[6:7]
	v_readlane_b32 s6, v252, 27
	v_readlane_b32 s7, v252, 28
	s_add_u32 s20, s6, s0
	s_addc_u32 s21, s7, s1
	s_add_i32 s35, s19, 0x2000
	s_mov_b32 m0, s19
	s_add_u32 s0, s20, 0x4000
	global_load_lds_dwordx4 v142, s[20:21]
	s_mov_b32 m0, s35
	s_addc_u32 s1, s21, 0
	s_add_i32 s36, s19, 0x4000
	global_load_lds_dwordx4 v138, s[20:21]
	s_mov_b32 m0, s36
	s_add_i32 s37, s19, 0x6000
	global_load_lds_dwordx4 v142, s[0:1]
	s_mov_b32 m0, s37
	s_cmp_eq_u32 s5, 1
	global_load_lds_dwordx4 v138, s[0:1]
	s_cselect_b64 s[0:1], -1, 0
	s_cmp_lg_u32 s5, 1
	s_cbranch_scc1 .LBB0_179
; __device__ __forceinline__ int otid() { int t = (int)threadIdx.x; asm volatile("" : "+v"(t)); return t; }
; #define PG8_STAGE(bufoff, gbase, voff) do { _Pragma("unroll") for (int _i = 0; _i < 2; ++_i) \
;         __builtin_amdgcn_global_load_lds((const unsigned*)((const char*)(gbase) + (voff)[_i]), (PG8_LAS unsigned*)(lds + (bufoff) + ldsw + _i * 8192), 16, 0, 0); } while (0)
; #define PG8_WAIT_V(n) asm volatile("s_waitcnt vmcnt(" #n ")" ::: "memory")
; #define PG8_BAR __builtin_amdgcn_s_barrier()
; template <class Epi, class Sched, bool ALIGN_EPI = false, bool SP2 = false, bool ABLK = false, bool BBLK = false>
; __device__ __forceinline__ void gemm_phase(PG8_LAS unsigned char* lds, const Gemm g, const Sched& S, const Epi& E) {
;     const int tid = otid(), wid = __builtin_amdgcn_readfirstlane(tid >> 6), lane = tid & 63, wr = wid >> 2, wc = wid & 3, fr = lane & 15, fq = lane >> 4;
;     const int K = g.K, nt = K / BK;
;     unsigned voffA[2], voffB[2];
; #pragma unroll
;     for (int i = 0; i < 2; ++i) { int R, C; stage_rc(tid * 16 + i * 8192, R, C); const int Rb = Epi::PERM ? ((R & ~31) + perm32(R & 31)) : R;
;         voffA[i] = ABLK ? (unsigned)(R * BK + C) * 2u : (unsigned)(R * K + C) * 2u; voffB[i] = BBLK ? (unsigned)(Rb * BK + C) * 2u : (unsigned)(Rb * K + C) * 2u; }
;     const size_t kstepB = BBLK ? (size_t)BM * BK * 2 : (size_t)(BK * 2), kstepA = ABLK ? (size_t)BM * BK * 2 : (size_t)(BK * 2);
;     const size_t hstepB = BBLK ? (size_t)HALF * BK * 2 : (size_t)HALF * K * 2, hstepA = ABLK ? (size_t)HALF * BK * 2 : (size_t)HALF * K * 2;
;     const size_t tstep = (size_t)BM * K * 2;
;     const unsigned ldsw = (unsigned)wid * 1024u;
;     const int aoff = lds_byte(wr * 64 + fr, fq * 8), boff = lds_byte(wc * 32 + fr, fq * 8);
;     ...
;         if (wr == 1) PG8_BAR;
;         PG8_WAIT_V(2); PG8_BAR;
;         PG8_STAGE(PG8_SB(1, 0), cB + kstepB, voffB); PG8_STAGE(PG8_SA(1, 0), cA + kstepA, voffA); PG8_STAGE(PG8_SB(1, 1), cB + hstepB + kstepB, voffB);
;         PG8_WAIT_V(6); PG8_BAR;
.LBB0_179:
	s_and_b32 s7, s3, 3
	s_lshl_b32 s6, s5, 6
	s_lshl_b32 s5, s5, 13
	s_lshl_b32 s7, s7, 12
	s_add_u32 s8, s22, 0x8000
	v_mov_b32_e32 v141, v2
	s_addc_u32 s9, s23, 0
	s_add_i32 m0, s19, 0x18000
	v_lshl_add_u64 v[10:11], s[8:9], 0, v[140:141]
	v_mov_b32_e32 v137, v2
	s_waitcnt vmcnt(2)
	s_barrier
	global_load_lds_dwordx4 v[10:11], off
	s_add_i32 m0, s19, 0x1a000
	v_lshl_add_u64 v[10:11], s[8:9], 0, v[136:137]
	s_add_u32 s8, s20, 0x8000
	v_mov_b32_e32 v143, v2
	s_addc_u32 s9, s21, 0
	s_add_i32 s62, s19, 0x8000
	v_mov_b32_e32 v139, v2
	global_load_lds_dwordx4 v[10:11], off
	v_lshl_add_u64 v[10:11], s[8:9], 0, v[142:143]
	s_mov_b32 m0, s62
	s_add_i32 s63, s19, 0xa000
	global_load_lds_dwordx4 v[10:11], off
	v_lshl_add_u64 v[10:11], s[8:9], 0, v[138:139]
	s_add_u32 s8, s22, 0xc000
	s_mov_b32 m0, s63
	s_addc_u32 s9, s23, 0
	global_load_lds_dwordx4 v[10:11], off
	s_add_i32 m0, s19, 0x1c000
	v_lshl_add_u64 v[10:11], s[8:9], 0, v[140:141]
	global_load_lds_dwordx4 v[10:11], off
	v_lshl_add_u64 v[10:11], s[8:9], 0, v[136:137]
	s_add_i32 m0, s19, 0x1e000
	v_and_b32_e32 v12, 15, v3
	global_load_lds_dwordx4 v[10:11], off
	s_sext_i32_i16 s12, s2
	v_and_b32_e32 v11, 63, v3
	v_and_b32_e32 v10, 48, v3
	v_lshlrev_b32_e32 v3, 2, v12
	s_lshl_b32 s2, s3, 9
	v_lshl_or_b32 v13, v12, 6, v10
	v_and_b32_e32 v14, 32, v3
	s_add_i32 s64, s2, 0
	v_bitop3_b32 v160, v13, s7, v14 bitop3:0xde
	s_add_i32 s64, s64, 0x20000
	s_ashr_i32 s7, s6, 31
	s_cmpk_lt_u32 s4, 0x100
	v_bitop3_b32 v16, v13, s5, v14 bitop3:0xde
	s_cselect_b64 s[4:5], -1, 0
	s_bfe_u32 s82, s3, 0x10001
	v_or_b32_e32 v12, s6, v12
	v_mov_b32_e32 v13, s7
	s_lshl_b64 s[6:7], s[6:7], 2
	v_readlane_b32 s2, v252, 25
	s_add_u32 s6, s2, s6
	v_readlane_b32 s2, v252, 26
	v_lshlrev_b64 v[12:13], 7, v[12:13]
	s_addc_u32 s7, s2, s7
	s_lshl_b32 s2, s3, 6
	v_lshl_add_u64 v[12:13], s[96:97], 0, v[12:13]
	s_and_b32 s2, s2, 64
	s_mov_b32 s3, s83
	v_lshlrev_b32_e32 v14, 2, v11
	v_lshl_add_u64 v[12:13], v[12:13], 0, s[2:3]
	v_mov_b32_e32 v11, v2
	v_lshl_add_u64 v[146:147], v[12:13], 0, v[10:11]
	v_lshlrev_b32_e32 v10, 10, v8
	v_and_b32_e32 v10, 0xfffff800, v10
	v_lshl_add_u32 v7, v7, 7, v10
	v_and_b32_e32 v8, 1, v8
	v_lshl_or_b32 v7, v8, 6, v7
	v_lshl_add_u32 v148, v9, 1, v7
	v_lshlrev_b32_e32 v7, 10, v4
	v_and_b32_e32 v7, 0xfffff800, v7
	s_waitcnt vmcnt(6)
	v_lshl_add_u32 v5, v5, 7, v7
	v_and_b32_e32 v4, 1, v4
	v_mov_b32_e32 v15, v2
	v_lshl_or_b32 v4, v4, 6, v5
	v_lshl_add_u64 v[144:145], s[6:7], 0, v[14:15]
	v_mov_b32_e32 v149, v2
	v_lshl_add_u32 v150, v6, 1, v4
	v_mov_b32_e32 v151, v2
	s_mov_b32 s65, 0
	v_add_u32_e32 v161, 0, v16
	s_barrier
	s_branch .LBB0_182

; #define PG8_LAS __attribute__((address_space(3)))
; #define PG8_STAGE(bufoff, gbase, voff) do { _Pragma("unroll") for (int _i = 0; _i < 2; ++_i) \
;         __builtin_amdgcn_global_load_lds((const unsigned*)((const char*)(gbase) + (voff)[_i]), (PG8_LAS unsigned*)(lds + (bufoff) + ldsw + _i * 8192), 16, 0, 0); } while (0)
; #define PG8_LDA(dst, b, h) do { _Pragma("unroll") for (int m = 0; m < 4; ++m) _Pragma("unroll") for (int k = 0; k < 2; ++k) dst[m][k] = *(const PG8_LAS bf16x8*)(lds + PG8_SA(b, h) + aoff + m * 2048 + k * 1024); } while (0)
; #define PG8_WAIT_V(n) asm volatile("s_waitcnt vmcnt(" #n ")" ::: "memory")
; #define PG8_BAR __builtin_amdgcn_s_barrier()
; template <class Epi, class Sched, bool ALIGN_EPI = false, bool SP2 = false, bool ABLK = false, bool BBLK = false>
; __device__ __forceinline__ void gemm_phase(PG8_LAS unsigned char* lds, const Gemm g, const Sched& S, const Epi& E) {
;     ...
;         const bool has_next = S.next(ui + 1, nxt);
;         PG8_LAS unsigned char* const rs_area = lds + STAGE_BYTES + wid * 512;
;         E.stage(cur, rs_area, wr, lane);
;         const char* nA = has_next ? (const char*)g.A + (size_t)nxt.pm * tstep : cA; const char* nB = has_next ? (const char*)g.Bt + (size_t)nxt.pn * tstep : cB;
;         for (int t = 0; t < nt; t += 2) {
;             const bool last = (t == nt - 2);
;             const char* a1 = cA + (size_t)(t + 1) * kstepA;
;             const char* a2 = last ? nA : cA + (size_t)(t + 2) * kstepA; const char* b2 = last ? nB : cB + (size_t)(t + 2) * kstepB;
;             const char* a3 = a2 + kstepA; const char* b3 = b2 + kstepB;
;             if (last && has_next) S.a_ready(nxt);
;             if constexpr (SP2) {
;             PG8_LDB(B0, 0, 0); PG8_LDB(B1, 0, 1); PG8_SCHED; PG8_LDA(At, 0, 0); PG8_STAGE(PG8_SA(1, 1), a1 + hstepA, voffA);
;             PG8_WAIT_V(8); PG8_WAIT_L(0); PG8_BAR; PG8_MMA(0, 0, At, B0); PG8_MMA(0, 1, At, B1); PG8_BAR; PG8_SCHED;
;             PG8_LDA(At, 0, 1); PG8_STAGE(PG8_SB(0, 0), b2, voffB); PG8_STAGE(PG8_SB(0, 1), b2 + hstepB, voffB); PG8_STAGE(PG8_SA(0, 0), a2, voffA);
;     ...
; #pragma unroll
;         for (int a = 0; a < 2; ++a)
; #pragma unroll
;             for (int b = 0; b < 2; ++b)
; #pragma unroll
;                 for (int m = 0; m < 4; ++m)
; #pragma unroll
;                     for (int n = 0; n < 2; ++n) acc[a][b][m][n] = (f32x4){0.f, 0.f, 0.f, 0.f};
.LBB0_184:
	s_lshl_b32 s10, s18, 8
	s_ashr_i32 s11, s10, 31
	s_mov_b32 m0, s64
	v_lshl_add_u64 v[4:5], s[10:11], 2, v[144:145]
	global_load_lds_dword v[4:5], off
	v_lshl_add_u64 v[4:5], v[4:5], 0, s[90:91]
	s_add_i32 m0, s64, 0x100
	s_ashr_i32 s9, s8, 31
	global_load_lds_dword v[4:5], off
	s_lshl_b64 s[10:11], s[8:9], 20
	v_readlane_b32 s16, v252, 27
	v_readlane_b32 s17, v252, 28
	s_add_u32 s10, s16, s10
	s_addc_u32 s11, s17, s11
	s_and_b64 s[16:17], s[2:3], exec
	s_cselect_b32 s9, s11, s21
	s_cselect_b32 s70, s10, s20
	s_ashr_i32 s7, s6, 31
	s_lshl_b64 s[16:17], s[6:7], 20
	s_add_u32 s16, s29, s16
	s_addc_u32 s17, s30, s17
	s_and_b64 s[24:25], s[2:3], exec
	s_cselect_b32 s7, s17, s23
	s_cselect_b32 s71, s16, s22
	s_add_u32 s20, s20, 0xc000
	s_addc_u32 s21, s21, 0
	s_add_u32 s77, s22, 0x10000
	v_mov_b32_e32 v4, 0
	s_addc_u32 vcc_lo, s23, 0
	s_mov_b32 vcc_hi, -2
	v_mov_b32_e32 v5, v4
	v_mov_b32_e32 v6, v4
	v_mov_b32_e32 v7, v4
	v_mov_b32_e32 v8, v4
	v_mov_b32_e32 v9, v4
	v_mov_b32_e32 v10, v4
	v_mov_b32_e32 v11, v4
	v_mov_b32_e32 v20, v4
	v_mov_b32_e32 v21, v4
	v_mov_b32_e32 v22, v4
	v_mov_b32_e32 v23, v4
	v_mov_b32_e32 v24, v4
	v_mov_b32_e32 v25, v4
	v_mov_b32_e32 v26, v4
	v_mov_b32_e32 v27, v4
	v_mov_b32_e32 v40, v4
	v_mov_b32_e32 v41, v4
	v_mov_b32_e32 v42, v4
	v_mov_b32_e32 v43, v4
	v_mov_b32_e32 v44, v4
	v_mov_b32_e32 v45, v4
	v_mov_b32_e32 v46, v4
	v_mov_b32_e32 v47, v4
	v_mov_b32_e32 v56, v4
	v_mov_b32_e32 v57, v4
	v_mov_b32_e32 v58, v4
	v_mov_b32_e32 v59, v4
	v_mov_b32_e32 v60, v4
	v_mov_b32_e32 v61, v4
	v_mov_b32_e32 v62, v4
	v_mov_b32_e32 v63, v4
	v_mov_b32_e32 v12, v4
	v_mov_b32_e32 v13, v4
	v_mov_b32_e32 v14, v4
	v_mov_b32_e32 v15, v4
	v_mov_b32_e32 v16, v4
	v_mov_b32_e32 v17, v4
	v_mov_b32_e32 v18, v4
	v_mov_b32_e32 v19, v4
	v_mov_b32_e32 v28, v4
	v_mov_b32_e32 v29, v4
	v_mov_b32_e32 v30, v4
	v_mov_b32_e32 v31, v4
	v_mov_b32_e32 v32, v4
	v_mov_b32_e32 v33, v4
	v_mov_b32_e32 v34, v4
	v_mov_b32_e32 v35, v4
	v_mov_b32_e32 v48, v4
	v_mov_b32_e32 v49, v4
	v_mov_b32_e32 v50, v4
	v_mov_b32_e32 v51, v4
	v_mov_b32_e32 v52, v4
	v_mov_b32_e32 v53, v4
	v_mov_b32_e32 v54, v4
	v_mov_b32_e32 v55, v4
	v_mov_b32_e32 v64, v4
	v_mov_b32_e32 v65, v4
	v_mov_b32_e32 v66, v4
	v_mov_b32_e32 v67, v4
	v_mov_b32_e32 v68, v4
	v_mov_b32_e32 v69, v4
	v_mov_b32_e32 v70, v4
	v_mov_b32_e32 v71, v4
	v_mov_b32_e32 v72, v4
	v_mov_b32_e32 v73, v4
	v_mov_b32_e32 v74, v4
	v_mov_b32_e32 v75, v4
	v_mov_b32_e32 v76, v4
	v_mov_b32_e32 v77, v4
	v_mov_b32_e32 v78, v4
	v_mov_b32_e32 v79, v4
	v_mov_b32_e32 v88, v4
	v_mov_b32_e32 v89, v4
	v_mov_b32_e32 v90, v4
	v_mov_b32_e32 v91, v4
	v_mov_b32_e32 v92, v4
	v_mov_b32_e32 v93, v4
	v_mov_b32_e32 v94, v4
	v_mov_b32_e32 v95, v4
	v_mov_b32_e32 v104, v4
	v_mov_b32_e32 v105, v4
	v_mov_b32_e32 v106, v4
	v_mov_b32_e32 v107, v4
	v_mov_b32_e32 v108, v4
	v_mov_b32_e32 v109, v4
	v_mov_b32_e32 v110, v4
	v_mov_b32_e32 v111, v4
	v_mov_b32_e32 v120, v4
	v_mov_b32_e32 v121, v4
	v_mov_b32_e32 v122, v4
	v_mov_b32_e32 v123, v4
	v_mov_b32_e32 v124, v4
	v_mov_b32_e32 v125, v4
	v_mov_b32_e32 v126, v4
	v_mov_b32_e32 v127, v4
	v_mov_b32_e32 v80, v4
	v_mov_b32_e32 v81, v4
	v_mov_b32_e32 v82, v4
	v_mov_b32_e32 v83, v4
	v_mov_b32_e32 v84, v4
	v_mov_b32_e32 v85, v4
	v_mov_b32_e32 v86, v4
	v_mov_b32_e32 v87, v4
	v_mov_b32_e32 v96, v4
	v_mov_b32_e32 v97, v4
	v_mov_b32_e32 v98, v4
	v_mov_b32_e32 v99, v4
	v_mov_b32_e32 v100, v4
	v_mov_b32_e32 v101, v4
	v_mov_b32_e32 v102, v4
	v_mov_b32_e32 v103, v4
	v_mov_b32_e32 v112, v4
	v_mov_b32_e32 v113, v4
	v_mov_b32_e32 v114, v4
	v_mov_b32_e32 v115, v4
	v_mov_b32_e32 v116, v4
	v_mov_b32_e32 v117, v4
	v_mov_b32_e32 v118, v4
	v_mov_b32_e32 v119, v4
	v_mov_b32_e32 v128, v4
	v_mov_b32_e32 v129, v4
	v_mov_b32_e32 v130, v4
	v_mov_b32_e32 v131, v4
	v_mov_b32_e32 v132, v4
	v_mov_b32_e32 v133, v4
	v_mov_b32_e32 v134, v4
	v_mov_b32_e32 v135, v4
	s_cmp_eq_u32 s100, 0
	s_cbranch_scc0 .Lk1_FFN1
.LBB0_185:
	s_add_u32 s13, s20, 0x4000
	s_addc_u32 s22, s21, 0
	s_cmp_eq_u32 vcc_hi, 28
	s_cselect_b32 s26, s70, s13
	s_cselect_b32 s27, s9, s22
	s_cselect_b32 s24, s71, s77
	s_cselect_b32 s25, s7, vcc_lo
	s_add_u32 s22, s26, 0x8000
	s_addc_u32 s23, s27, 0
	s_add_i32 s13, 0, 0x10000
	v_add_u32_e32 v36, s13, v160
	s_add_i32 s88, 0, 0x14000
	ds_read_b128 v[152:155], v36
	ds_read_b128 v[156:159], v36 offset:1024
	ds_read_b128 v[162:165], v36 offset:2048
	ds_read_b128 v[166:169], v36 offset:3072
	v_add_u32_e32 v36, s88, v160
	ds_read_b128 v[170:173], v36
	ds_read_b128 v[174:177], v36 offset:1024
	ds_read_b128 v[178:181], v36 offset:2048
	ds_read_b128 v[182:185], v36 offset:3072
	s_add_i32 m0, s19, 0xc000
	ds_read_b128 v[186:189], v161
	ds_read_b128 v[190:193], v161 offset:1024
	ds_read_b128 v[194:197], v161 offset:2048
	ds_read_b128 v[198:201], v161 offset:3072
	ds_read_b128 v[202:205], v161 offset:4096
	ds_read_b128 v[206:209], v161 offset:5120
	ds_read_b128 v[210:213], v161 offset:6144
	ds_read_b128 v[214:217], v161 offset:7168
	global_load_lds_dwordx4 v148, s[20:21]
	s_add_i32 m0, s19, 0xe000
	s_nop 0
	global_load_lds_dwordx4 v150, s[20:21]
	s_waitcnt vmcnt(8)
	s_waitcnt lgkmcnt(0)
	s_setprio 1
	s_waitcnt lgkmcnt(0)
; #define PG8_STAGE(bufoff, gbase, voff) do { _Pragma("unroll") for (int _i = 0; _i < 2; ++_i) \
;         __builtin_amdgcn_global_load_lds((const unsigned*)((const char*)(gbase) + (voff)[_i]), (PG8_LAS unsigned*)(lds + (bufoff) + ldsw + _i * 8192), 16, 0, 0); } while (0)
; #define PG8_LDA(dst, b, h) do { _Pragma("unroll") for (int m = 0; m < 4; ++m) _Pragma("unroll") for (int k = 0; k < 2; ++k) dst[m][k] = *(const PG8_LAS bf16x8*)(lds + PG8_SA(b, h) + aoff + m * 2048 + k * 1024); } while (0)
; #define PG8_LDB(dst, b, h) do { _Pragma("unroll") for (int n = 0; n < 2; ++n) _Pragma("unroll") for (int k = 0; k < 2; ++k) dst[n][k] = *(const PG8_LAS bf16x8*)(lds + PG8_SB(b, h) + boff + n * 2048 + k * 1024); } while (0)
; #define PG8_MMA(ai, bj, At, Bt) do { __builtin_amdgcn_s_setprio(1); _Pragma("unroll") for (int m = 0; m < 4; ++m) _Pragma("unroll") for (int n = 0; n < 2; ++n) _Pragma("unroll") for (int k = 0; k < 2; ++k) \
;         acc[ai][bj][m][n] = __builtin_amdgcn_mfma_f32_16x16x32_bf16(Bt[n][k], At[m][k], acc[ai][bj][m][n], 0, 0, 0); __builtin_amdgcn_s_setprio(0); } while (0)
; #define PG8_WAIT_V(n) asm volatile("s_waitcnt vmcnt(" #n ")" ::: "memory")
; #define PG8_WAIT_L(n) asm volatile("s_waitcnt lgkmcnt(" #n ")" ::: "memory")
; #define PG8_BAR __builtin_amdgcn_s_barrier()
; #define PG8_SCHED __builtin_amdgcn_sched_barrier(0)
; template <class Epi, class Sched, bool ALIGN_EPI = false, bool SP2 = false, bool ABLK = false, bool BBLK = false>
; __device__ __forceinline__ void gemm_phase(PG8_LAS unsigned char* lds, const Gemm g, const Sched& S, const Epi& E) {
;     ...
;             PG8_LDB(B0, 0, 0); PG8_LDB(B1, 0, 1); PG8_SCHED; PG8_LDA(At, 0, 0); PG8_STAGE(PG8_SA(1, 1), a1 + hstepA, voffA);
;             PG8_WAIT_V(8); PG8_WAIT_L(0); PG8_BAR; PG8_MMA(0, 0, At, B0); PG8_MMA(0, 1, At, B1); PG8_BAR; PG8_SCHED;
;             PG8_LDA(At, 0, 1); PG8_STAGE(PG8_SB(0, 0), b2, voffB); PG8_STAGE(PG8_SB(0, 1), b2 + hstepB, voffB); PG8_STAGE(PG8_SA(0, 0), a2, voffA);
;             PG8_WAIT_V(8); PG8_WAIT_L(0); PG8_BAR; PG8_MMA(1, 0, At, B0); PG8_MMA(1, 1, At, B1); PG8_BAR; PG8_SCHED;
	v_mfma_f32_16x16x32_bf16 v[132:135], v[152:155], v[186:189], v[132:135]
	v_mfma_f32_16x16x32_bf16 v[128:131], v[162:165], v[186:189], v[128:131]
	v_mfma_f32_16x16x32_bf16 v[116:119], v[152:155], v[194:197], v[116:119]
	v_mfma_f32_16x16x32_bf16 v[112:115], v[162:165], v[194:197], v[112:115]
	v_mfma_f32_16x16x32_bf16 v[100:103], v[152:155], v[202:205], v[100:103]
	v_mfma_f32_16x16x32_bf16 v[96:99], v[162:165], v[202:205], v[96:99]
	v_mfma_f32_16x16x32_bf16 v[84:87], v[152:155], v[210:213], v[84:87]
	v_mfma_f32_16x16x32_bf16 v[80:83], v[162:165], v[210:213], v[80:83]
	v_mfma_f32_16x16x32_bf16 v[132:135], v[156:159], v[190:193], v[132:135]
	v_mfma_f32_16x16x32_bf16 v[128:131], v[166:169], v[190:193], v[128:131]
	v_mfma_f32_16x16x32_bf16 v[116:119], v[156:159], v[198:201], v[116:119]
	v_mfma_f32_16x16x32_bf16 v[112:115], v[166:169], v[198:201], v[112:115]
	v_mfma_f32_16x16x32_bf16 v[100:103], v[156:159], v[206:209], v[100:103]
	v_mfma_f32_16x16x32_bf16 v[96:99], v[166:169], v[206:209], v[96:99]
	v_mfma_f32_16x16x32_bf16 v[84:87], v[156:159], v[214:217], v[84:87]
	v_mfma_f32_16x16x32_bf16 v[80:83], v[166:169], v[214:217], v[80:83]
	s_setprio 0
	s_setprio 1
	v_mfma_f32_16x16x32_bf16 v[124:127], v[170:173], v[186:189], v[124:127]
	v_mfma_f32_16x16x32_bf16 v[120:123], v[178:181], v[186:189], v[120:123]
	v_mfma_f32_16x16x32_bf16 v[108:111], v[170:173], v[194:197], v[108:111]
	v_mfma_f32_16x16x32_bf16 v[104:107], v[178:181], v[194:197], v[104:107]
	v_mfma_f32_16x16x32_bf16 v[92:95], v[170:173], v[202:205], v[92:95]
	v_mfma_f32_16x16x32_bf16 v[88:91], v[178:181], v[202:205], v[88:91]
	v_mfma_f32_16x16x32_bf16 v[76:79], v[170:173], v[210:213], v[76:79]
	v_mfma_f32_16x16x32_bf16 v[72:75], v[178:181], v[210:213], v[72:75]
	v_mfma_f32_16x16x32_bf16 v[124:127], v[174:177], v[190:193], v[124:127]
	v_mfma_f32_16x16x32_bf16 v[120:123], v[182:185], v[190:193], v[120:123]
	v_mfma_f32_16x16x32_bf16 v[108:111], v[174:177], v[198:201], v[108:111]
	v_mfma_f32_16x16x32_bf16 v[104:107], v[182:185], v[198:201], v[104:107]
	v_mfma_f32_16x16x32_bf16 v[92:95], v[174:177], v[206:209], v[92:95]
	v_mfma_f32_16x16x32_bf16 v[88:91], v[182:185], v[206:209], v[88:91]
	v_mfma_f32_16x16x32_bf16 v[76:79], v[174:177], v[214:217], v[76:79]
	v_mfma_f32_16x16x32_bf16 v[72:75], v[182:185], v[214:217], v[72:75]
	s_setprio 0
	s_barrier
	s_add_i32 s13, s13, s31
	s_mov_b32 m0, s13
	ds_read_b128 v[186:189], v161 offset:16384
	ds_read_b128 v[190:193], v161 offset:17408
	ds_read_b128 v[194:197], v161 offset:18432
	ds_read_b128 v[198:201], v161 offset:19456
	ds_read_b128 v[202:205], v161 offset:20480
	ds_read_b128 v[206:209], v161 offset:21504
	ds_read_b128 v[210:213], v161 offset:22528
	ds_read_b128 v[214:217], v161 offset:23552
	global_load_lds_dwordx4 v140, s[24:25]
	s_add_i32 m0, s13, 0x2000
	s_add_u32 s68, s24, 0x4000
	s_addc_u32 s69, s25, 0
	s_add_i32 s13, s88, s31
	global_load_lds_dwordx4 v136, s[24:25]
	s_mov_b32 m0, s13
	s_nop 0
	global_load_lds_dwordx4 v140, s[68:69]
	s_add_i32 m0, s13, 0x2000
	s_nop 0
	global_load_lds_dwordx4 v136, s[68:69]
	s_mov_b32 m0, s19
	s_nop 0
	global_load_lds_dwordx4 v142, s[26:27]
	s_mov_b32 m0, s35
	s_nop 0
	global_load_lds_dwordx4 v138, s[26:27]
	s_waitcnt vmcnt(8)
	s_waitcnt lgkmcnt(0)
	s_setprio 1
	s_waitcnt lgkmcnt(0)
	v_mfma_f32_16x16x32_bf16 v[68:71], v[152:155], v[186:189], v[68:71]
	v_mfma_f32_16x16x32_bf16 v[64:67], v[162:165], v[186:189], v[64:67]
	v_mfma_f32_16x16x32_bf16 v[52:55], v[152:155], v[194:197], v[52:55]
	v_mfma_f32_16x16x32_bf16 v[48:51], v[162:165], v[194:197], v[48:51]
	v_mfma_f32_16x16x32_bf16 v[32:35], v[152:155], v[202:205], v[32:35]
	v_mfma_f32_16x16x32_bf16 v[28:31], v[162:165], v[202:205], v[28:31]
	v_mfma_f32_16x16x32_bf16 v[16:19], v[152:155], v[210:213], v[16:19]
	v_mfma_f32_16x16x32_bf16 v[12:15], v[162:165], v[210:213], v[12:15]
	v_mfma_f32_16x16x32_bf16 v[68:71], v[156:159], v[190:193], v[68:71]
	v_mfma_f32_16x16x32_bf16 v[64:67], v[166:169], v[190:193], v[64:67]
	v_mfma_f32_16x16x32_bf16 v[52:55], v[156:159], v[198:201], v[52:55]
	v_mfma_f32_16x16x32_bf16 v[48:51], v[166:169], v[198:201], v[48:51]
	v_mfma_f32_16x16x32_bf16 v[32:35], v[156:159], v[206:209], v[32:35]
	v_mfma_f32_16x16x32_bf16 v[28:31], v[166:169], v[206:209], v[28:31]
	v_mfma_f32_16x16x32_bf16 v[16:19], v[156:159], v[214:217], v[16:19]
	v_mfma_f32_16x16x32_bf16 v[12:15], v[166:169], v[214:217], v[12:15]
	s_setprio 0
	s_setprio 1
	v_mfma_f32_16x16x32_bf16 v[60:63], v[170:173], v[186:189], v[60:63]
	v_mfma_f32_16x16x32_bf16 v[56:59], v[178:181], v[186:189], v[56:59]
	v_mfma_f32_16x16x32_bf16 v[44:47], v[170:173], v[194:197], v[44:47]
	v_mfma_f32_16x16x32_bf16 v[40:43], v[178:181], v[194:197], v[40:43]
	v_mfma_f32_16x16x32_bf16 v[24:27], v[170:173], v[202:205], v[24:27]
	v_mfma_f32_16x16x32_bf16 v[20:23], v[178:181], v[202:205], v[20:23]
	v_mfma_f32_16x16x32_bf16 v[8:11], v[170:173], v[210:213], v[8:11]
	v_mfma_f32_16x16x32_bf16 v[4:7], v[178:181], v[210:213], v[4:7]
	v_mfma_f32_16x16x32_bf16 v[60:63], v[174:177], v[190:193], v[60:63]
	v_mfma_f32_16x16x32_bf16 v[56:59], v[182:185], v[190:193], v[56:59]
	v_mfma_f32_16x16x32_bf16 v[44:47], v[174:177], v[198:201], v[44:47]
	v_mfma_f32_16x16x32_bf16 v[40:43], v[182:185], v[198:201], v[40:43]
	v_mfma_f32_16x16x32_bf16 v[24:27], v[174:177], v[206:209], v[24:27]
	v_mfma_f32_16x16x32_bf16 v[20:23], v[182:185], v[206:209], v[20:23]
	v_mfma_f32_16x16x32_bf16 v[8:11], v[174:177], v[214:217], v[8:11]
	v_mfma_f32_16x16x32_bf16 v[4:7], v[182:185], v[214:217], v[4:7]
	s_setprio 0
	s_barrier
; #define PG8_STAGE(bufoff, gbase, voff) do { _Pragma("unroll") for (int _i = 0; _i < 2; ++_i) \
;         __builtin_amdgcn_global_load_lds((const unsigned*)((const char*)(gbase) + (voff)[_i]), (PG8_LAS unsigned*)(lds + (bufoff) + ldsw + _i * 8192), 16, 0, 0); } while (0)
; #define PG8_LDA(dst, b, h) do { _Pragma("unroll") for (int m = 0; m < 4; ++m) _Pragma("unroll") for (int k = 0; k < 2; ++k) dst[m][k] = *(const PG8_LAS bf16x8*)(lds + PG8_SA(b, h) + aoff + m * 2048 + k * 1024); } while (0)
; #define PG8_LDB(dst, b, h) do { _Pragma("unroll") for (int n = 0; n < 2; ++n) _Pragma("unroll") for (int k = 0; k < 2; ++k) dst[n][k] = *(const PG8_LAS bf16x8*)(lds + PG8_SB(b, h) + boff + n * 2048 + k * 1024); } while (0)
; #define PG8_MMA(ai, bj, At, Bt) do { __builtin_amdgcn_s_setprio(1); _Pragma("unroll") for (int m = 0; m < 4; ++m) _Pragma("unroll") for (int n = 0; n < 2; ++n) _Pragma("unroll") for (int k = 0; k < 2; ++k) \
;         acc[ai][bj][m][n] = __builtin_amdgcn_mfma_f32_16x16x32_bf16(Bt[n][k], At[m][k], acc[ai][bj][m][n], 0, 0, 0); __builtin_amdgcn_s_setprio(0); } while (0)
; #define PG8_WAIT_V(n) asm volatile("s_waitcnt vmcnt(" #n ")" ::: "memory")
; #define PG8_WAIT_L(n) asm volatile("s_waitcnt lgkmcnt(" #n ")" ::: "memory")
; #define PG8_BAR __builtin_amdgcn_s_barrier()
; #define PG8_SCHED __builtin_amdgcn_sched_barrier(0)
; template <class Epi, class Sched, bool ALIGN_EPI = false, bool SP2 = false, bool ABLK = false, bool BBLK = false>
; __device__ __forceinline__ void gemm_phase(PG8_LAS unsigned char* lds, const Gemm g, const Sched& S, const Epi& E) {
;     ...
;             PG8_LDB(B0, 1, 0); PG8_LDB(B1, 1, 1); PG8_SCHED; PG8_LDA(At, 1, 0); PG8_STAGE(PG8_SA(0, 1), a2 + hstepA, voffA);
;             PG8_WAIT_V(8); PG8_WAIT_L(0); PG8_BAR; PG8_MMA(0, 0, At, B0); PG8_MMA(0, 1, At, B1); PG8_BAR; PG8_SCHED;
;             PG8_LDA(At, 1, 1); PG8_STAGE(PG8_SB(1, 0), b3, voffB); PG8_STAGE(PG8_SB(1, 1), b3 + hstepB, voffB); PG8_STAGE(PG8_SA(1, 0), a3, voffA);
;             PG8_WAIT_V(8); PG8_WAIT_L(0); PG8_BAR; PG8_MMA(1, 0, At, B0); PG8_MMA(1, 1, At, B1); PG8_BAR; PG8_SCHED;
	s_add_i32 s13, 0, 0x18000
	v_add_u32_e32 v36, s13, v160
	s_add_i32 s68, 0, 0x1c000
	ds_read_b128 v[152:155], v36
	ds_read_b128 v[156:159], v36 offset:1024
	ds_read_b128 v[162:165], v36 offset:2048
	ds_read_b128 v[166:169], v36 offset:3072
	v_add_u32_e32 v36, s68, v160
	ds_read_b128 v[170:173], v36
	ds_read_b128 v[174:177], v36 offset:1024
	ds_read_b128 v[178:181], v36 offset:2048
	ds_read_b128 v[182:185], v36 offset:3072
	s_add_u32 s26, s26, 0x4000
	s_addc_u32 s27, s27, 0
	s_mov_b32 m0, s36
	ds_read_b128 v[186:189], v161 offset:32768
	ds_read_b128 v[190:193], v161 offset:33792
	ds_read_b128 v[194:197], v161 offset:34816
	ds_read_b128 v[198:201], v161 offset:35840
	ds_read_b128 v[202:205], v161 offset:36864
	ds_read_b128 v[206:209], v161 offset:37888
	ds_read_b128 v[210:213], v161 offset:38912
	ds_read_b128 v[214:217], v161 offset:39936
	global_load_lds_dwordx4 v142, s[26:27]
	s_mov_b32 m0, s37
	s_nop 0
	global_load_lds_dwordx4 v138, s[26:27]
	s_waitcnt vmcnt(8)
	s_waitcnt lgkmcnt(0)
	s_setprio 1
	s_waitcnt lgkmcnt(0)
	v_mfma_f32_16x16x32_bf16 v[132:135], v[152:155], v[186:189], v[132:135]
	v_mfma_f32_16x16x32_bf16 v[128:131], v[162:165], v[186:189], v[128:131]
	v_mfma_f32_16x16x32_bf16 v[116:119], v[152:155], v[194:197], v[116:119]
	v_mfma_f32_16x16x32_bf16 v[112:115], v[162:165], v[194:197], v[112:115]
	v_mfma_f32_16x16x32_bf16 v[100:103], v[152:155], v[202:205], v[100:103]
	v_mfma_f32_16x16x32_bf16 v[96:99], v[162:165], v[202:205], v[96:99]
	v_mfma_f32_16x16x32_bf16 v[84:87], v[152:155], v[210:213], v[84:87]
	v_mfma_f32_16x16x32_bf16 v[80:83], v[162:165], v[210:213], v[80:83]
	v_mfma_f32_16x16x32_bf16 v[132:135], v[156:159], v[190:193], v[132:135]
	v_mfma_f32_16x16x32_bf16 v[128:131], v[166:169], v[190:193], v[128:131]
	v_mfma_f32_16x16x32_bf16 v[116:119], v[156:159], v[198:201], v[116:119]
	v_mfma_f32_16x16x32_bf16 v[112:115], v[166:169], v[198:201], v[112:115]
	v_mfma_f32_16x16x32_bf16 v[100:103], v[156:159], v[206:209], v[100:103]
	v_mfma_f32_16x16x32_bf16 v[96:99], v[166:169], v[206:209], v[96:99]
	v_mfma_f32_16x16x32_bf16 v[84:87], v[156:159], v[214:217], v[84:87]
	v_mfma_f32_16x16x32_bf16 v[80:83], v[166:169], v[214:217], v[80:83]
	s_setprio 0
	s_setprio 1
	v_mfma_f32_16x16x32_bf16 v[124:127], v[170:173], v[186:189], v[124:127]
	v_mfma_f32_16x16x32_bf16 v[120:123], v[178:181], v[186:189], v[120:123]
	v_mfma_f32_16x16x32_bf16 v[108:111], v[170:173], v[194:197], v[108:111]
	v_mfma_f32_16x16x32_bf16 v[104:107], v[178:181], v[194:197], v[104:107]
	v_mfma_f32_16x16x32_bf16 v[92:95], v[170:173], v[202:205], v[92:95]
	v_mfma_f32_16x16x32_bf16 v[88:91], v[178:181], v[202:205], v[88:91]
	v_mfma_f32_16x16x32_bf16 v[76:79], v[170:173], v[210:213], v[76:79]
	v_mfma_f32_16x16x32_bf16 v[72:75], v[178:181], v[210:213], v[72:75]
	v_mfma_f32_16x16x32_bf16 v[124:127], v[174:177], v[190:193], v[124:127]
	v_mfma_f32_16x16x32_bf16 v[120:123], v[182:185], v[190:193], v[120:123]
	v_mfma_f32_16x16x32_bf16 v[108:111], v[174:177], v[198:201], v[108:111]
	v_mfma_f32_16x16x32_bf16 v[104:107], v[182:185], v[198:201], v[104:107]
	v_mfma_f32_16x16x32_bf16 v[92:95], v[174:177], v[206:209], v[92:95]
	v_mfma_f32_16x16x32_bf16 v[88:91], v[182:185], v[206:209], v[88:91]
	v_mfma_f32_16x16x32_bf16 v[76:79], v[174:177], v[214:217], v[76:79]
	v_mfma_f32_16x16x32_bf16 v[72:75], v[182:185], v[214:217], v[72:75]
	s_setprio 0
	s_barrier
	s_add_u32 s26, s24, 0x8000
	s_addc_u32 s27, s25, 0
	s_add_i32 s13, s13, s31
	s_mov_b32 m0, s13
	ds_read_b128 v[186:189], v161 offset:49152
	ds_read_b128 v[190:193], v161 offset:50176
	ds_read_b128 v[194:197], v161 offset:51200
	ds_read_b128 v[198:201], v161 offset:52224
	ds_read_b128 v[202:205], v161 offset:53248
	ds_read_b128 v[206:209], v161 offset:54272
	ds_read_b128 v[210:213], v161 offset:55296
	ds_read_b128 v[214:217], v161 offset:56320
	global_load_lds_dwordx4 v140, s[26:27]
	s_add_i32 m0, s13, 0x2000
	s_add_u32 s24, s24, 0xc000
	s_addc_u32 s25, s25, 0
	s_add_i32 s13, s68, s31
	global_load_lds_dwordx4 v136, s[26:27]
	s_mov_b32 m0, s13
	s_nop 0
	global_load_lds_dwordx4 v140, s[24:25]
	s_add_i32 m0, s13, 0x2000
	s_nop 0
	global_load_lds_dwordx4 v136, s[24:25]
	s_mov_b32 m0, s62
	s_nop 0
	global_load_lds_dwordx4 v142, s[22:23]
	s_mov_b32 m0, s63
	s_nop 0
	global_load_lds_dwordx4 v138, s[22:23]
	s_waitcnt vmcnt(8)
	s_waitcnt lgkmcnt(0)
	s_setprio 1
	s_waitcnt lgkmcnt(0)
	v_mfma_f32_16x16x32_bf16 v[68:71], v[152:155], v[186:189], v[68:71]
	v_mfma_f32_16x16x32_bf16 v[64:67], v[162:165], v[186:189], v[64:67]
	v_mfma_f32_16x16x32_bf16 v[52:55], v[152:155], v[194:197], v[52:55]
	v_mfma_f32_16x16x32_bf16 v[48:51], v[162:165], v[194:197], v[48:51]
	v_mfma_f32_16x16x32_bf16 v[32:35], v[152:155], v[202:205], v[32:35]
	v_mfma_f32_16x16x32_bf16 v[28:31], v[162:165], v[202:205], v[28:31]
	v_mfma_f32_16x16x32_bf16 v[16:19], v[152:155], v[210:213], v[16:19]
	v_mfma_f32_16x16x32_bf16 v[12:15], v[162:165], v[210:213], v[12:15]
	v_mfma_f32_16x16x32_bf16 v[68:71], v[156:159], v[190:193], v[68:71]
	v_mfma_f32_16x16x32_bf16 v[64:67], v[166:169], v[190:193], v[64:67]
	v_mfma_f32_16x16x32_bf16 v[52:55], v[156:159], v[198:201], v[52:55]
	v_mfma_f32_16x16x32_bf16 v[48:51], v[166:169], v[198:201], v[48:51]
	v_mfma_f32_16x16x32_bf16 v[32:35], v[156:159], v[206:209], v[32:35]
	v_mfma_f32_16x16x32_bf16 v[28:31], v[166:169], v[206:209], v[28:31]
	v_mfma_f32_16x16x32_bf16 v[16:19], v[156:159], v[214:217], v[16:19]
	v_mfma_f32_16x16x32_bf16 v[12:15], v[166:169], v[214:217], v[12:15]
	s_setprio 0
	s_setprio 1
	v_mfma_f32_16x16x32_bf16 v[60:63], v[170:173], v[186:189], v[60:63]
	v_mfma_f32_16x16x32_bf16 v[56:59], v[178:181], v[186:189], v[56:59]
	v_mfma_f32_16x16x32_bf16 v[44:47], v[170:173], v[194:197], v[44:47]
	v_mfma_f32_16x16x32_bf16 v[40:43], v[178:181], v[194:197], v[40:43]
	v_mfma_f32_16x16x32_bf16 v[24:27], v[170:173], v[202:205], v[24:27]
	v_mfma_f32_16x16x32_bf16 v[20:23], v[178:181], v[202:205], v[20:23]
	v_mfma_f32_16x16x32_bf16 v[8:11], v[170:173], v[210:213], v[8:11]
	v_mfma_f32_16x16x32_bf16 v[4:7], v[178:181], v[210:213], v[4:7]
	v_mfma_f32_16x16x32_bf16 v[60:63], v[174:177], v[190:193], v[60:63]
	v_mfma_f32_16x16x32_bf16 v[56:59], v[182:185], v[190:193], v[56:59]
	v_mfma_f32_16x16x32_bf16 v[44:47], v[174:177], v[198:201], v[44:47]
	v_mfma_f32_16x16x32_bf16 v[40:43], v[182:185], v[198:201], v[40:43]
	v_mfma_f32_16x16x32_bf16 v[24:27], v[174:177], v[206:209], v[24:27]
	v_mfma_f32_16x16x32_bf16 v[20:23], v[182:185], v[206:209], v[20:23]
	v_mfma_f32_16x16x32_bf16 v[8:11], v[174:177], v[214:217], v[8:11]
	v_mfma_f32_16x16x32_bf16 v[4:7], v[182:185], v[214:217], v[4:7]
	s_setprio 0
	s_barrier
	s_add_i32 vcc_hi, vcc_hi, 2
	s_add_u32 s20, s20, 0x10000
	s_addc_u32 s21, s21, 0
	s_add_u32 s77, s77, 0x10000
	s_addc_u32 vcc_lo, vcc_lo, 0
	s_cmp_gt_u32 vcc_hi, 29
	s_cbranch_scc0 .LBB0_185
	s_branch .Lkx_FFN1
; #define PG8_STAGE(bufoff, gbase, voff) do { _Pragma("unroll") for (int _i = 0; _i < 2; ++_i) \
;         __builtin_amdgcn_global_load_lds((const unsigned*)((const char*)(gbase) + (voff)[_i]), (PG8_LAS unsigned*)(lds + (bufoff) + ldsw + _i * 8192), 16, 0, 0); } while (0)
; #define PG8_LDA(dst, b, h) do { _Pragma("unroll") for (int m = 0; m < 4; ++m) _Pragma("unroll") for (int k = 0; k < 2; ++k) dst[m][k] = *(const PG8_LAS bf16x8*)(lds + PG8_SA(b, h) + aoff + m * 2048 + k * 1024); } while (0)
; #define PG8_LDB(dst, b, h) do { _Pragma("unroll") for (int n = 0; n < 2; ++n) _Pragma("unroll") for (int k = 0; k < 2; ++k) dst[n][k] = *(const PG8_LAS bf16x8*)(lds + PG8_SB(b, h) + boff + n * 2048 + k * 1024); } while (0)
; #define PG8_MMA(ai, bj, At, Bt) do { __builtin_amdgcn_s_setprio(1); _Pragma("unroll") for (int m = 0; m < 4; ++m) _Pragma("unroll") for (int n = 0; n < 2; ++n) _Pragma("unroll") for (int k = 0; k < 2; ++k) \
;         acc[ai][bj][m][n] = __builtin_amdgcn_mfma_f32_16x16x32_bf16(Bt[n][k], At[m][k], acc[ai][bj][m][n], 0, 0, 0); __builtin_amdgcn_s_setprio(0); } while (0)
; #define PG8_WAIT_V(n) asm volatile("s_waitcnt vmcnt(" #n ")" ::: "memory")
; #define PG8_WAIT_L(n) asm volatile("s_waitcnt lgkmcnt(" #n ")" ::: "memory")
; #define PG8_BAR __builtin_amdgcn_s_barrier()
; #define PG8_SCHED __builtin_amdgcn_sched_barrier(0)
; template <class Epi, class Sched, bool ALIGN_EPI = false, bool SP2 = false, bool ABLK = false, bool BBLK = false>
; __device__ __forceinline__ void gemm_phase(PG8_LAS unsigned char* lds, const Gemm g, const Sched& S, const Epi& E) {
;     ...
;             PG8_LDB(B0, 0, 0); PG8_LDB(B1, 0, 1); PG8_SCHED; PG8_LDA(At, 0, 0); PG8_STAGE(PG8_SA(1, 1), a1 + hstepA, voffA);
;             PG8_WAIT_V(8); PG8_WAIT_L(0); PG8_BAR; PG8_MMA(0, 0, At, B0); PG8_MMA(0, 1, At, B1); PG8_BAR; PG8_SCHED;
.Lk1_FFN1:
	s_add_u32 s13, s20, 0x4000
	s_addc_u32 s22, s21, 0
	s_cmp_eq_u32 vcc_hi, 28
	s_cselect_b32 s26, s70, s13
	s_cselect_b32 s27, s9, s22
	s_cselect_b32 s24, s71, s77
	s_cselect_b32 s25, s7, vcc_lo
	s_add_u32 s22, s26, 0x8000
	s_addc_u32 s23, s27, 0
	s_add_i32 s13, 0, 0x10000
	v_add_u32_e32 v36, s13, v160
	s_add_i32 s88, 0, 0x14000
	ds_read_b128 v[152:155], v36
	ds_read_b128 v[156:159], v36 offset:1024
	ds_read_b128 v[162:165], v36 offset:2048
	ds_read_b128 v[166:169], v36 offset:3072
	v_add_u32_e32 v36, s88, v160
	ds_read_b128 v[170:173], v36
	ds_read_b128 v[174:177], v36 offset:1024
	ds_read_b128 v[178:181], v36 offset:2048
	ds_read_b128 v[182:185], v36 offset:3072
	s_add_i32 m0, s19, 0xc000
	ds_read_b128 v[186:189], v161
	ds_read_b128 v[190:193], v161 offset:1024
	ds_read_b128 v[194:197], v161 offset:2048
	ds_read_b128 v[198:201], v161 offset:3072
	ds_read_b128 v[202:205], v161 offset:4096
	ds_read_b128 v[206:209], v161 offset:5120
	ds_read_b128 v[210:213], v161 offset:6144
	ds_read_b128 v[214:217], v161 offset:7168
	global_load_lds_dwordx4 v148, s[20:21]
	s_add_i32 m0, s19, 0xe000
	s_nop 0
	global_load_lds_dwordx4 v150, s[20:21]
	s_waitcnt vmcnt(8)
	s_waitcnt lgkmcnt(0)
	s_barrier
	s_setprio 2
	s_waitcnt lgkmcnt(0)
	v_mfma_f32_16x16x32_bf16 v[132:135], v[152:155], v[186:189], v[132:135]
	v_mfma_f32_16x16x32_bf16 v[128:131], v[162:165], v[186:189], v[128:131]
	v_mfma_f32_16x16x32_bf16 v[116:119], v[152:155], v[194:197], v[116:119]
	v_mfma_f32_16x16x32_bf16 v[112:115], v[162:165], v[194:197], v[112:115]
	v_mfma_f32_16x16x32_bf16 v[100:103], v[152:155], v[202:205], v[100:103]
	v_mfma_f32_16x16x32_bf16 v[96:99], v[162:165], v[202:205], v[96:99]
	v_mfma_f32_16x16x32_bf16 v[84:87], v[152:155], v[210:213], v[84:87]
	v_mfma_f32_16x16x32_bf16 v[80:83], v[162:165], v[210:213], v[80:83]
	v_mfma_f32_16x16x32_bf16 v[132:135], v[156:159], v[190:193], v[132:135]
	v_mfma_f32_16x16x32_bf16 v[128:131], v[166:169], v[190:193], v[128:131]
	v_mfma_f32_16x16x32_bf16 v[116:119], v[156:159], v[198:201], v[116:119]
	v_mfma_f32_16x16x32_bf16 v[112:115], v[166:169], v[198:201], v[112:115]
	v_mfma_f32_16x16x32_bf16 v[100:103], v[156:159], v[206:209], v[100:103]
	v_mfma_f32_16x16x32_bf16 v[96:99], v[166:169], v[206:209], v[96:99]
	v_mfma_f32_16x16x32_bf16 v[84:87], v[156:159], v[214:217], v[84:87]
	v_mfma_f32_16x16x32_bf16 v[80:83], v[166:169], v[214:217], v[80:83]
	v_mfma_f32_16x16x32_bf16 v[124:127], v[170:173], v[186:189], v[124:127]
	v_mfma_f32_16x16x32_bf16 v[120:123], v[178:181], v[186:189], v[120:123]
	v_mfma_f32_16x16x32_bf16 v[108:111], v[170:173], v[194:197], v[108:111]
	v_mfma_f32_16x16x32_bf16 v[104:107], v[178:181], v[194:197], v[104:107]
	v_mfma_f32_16x16x32_bf16 v[92:95], v[170:173], v[202:205], v[92:95]
	v_mfma_f32_16x16x32_bf16 v[88:91], v[178:181], v[202:205], v[88:91]
	v_mfma_f32_16x16x32_bf16 v[76:79], v[170:173], v[210:213], v[76:79]
	v_mfma_f32_16x16x32_bf16 v[72:75], v[178:181], v[210:213], v[72:75]
	v_mfma_f32_16x16x32_bf16 v[124:127], v[174:177], v[190:193], v[124:127]
	v_mfma_f32_16x16x32_bf16 v[120:123], v[182:185], v[190:193], v[120:123]
	v_mfma_f32_16x16x32_bf16 v[108:111], v[174:177], v[198:201], v[108:111]
	v_mfma_f32_16x16x32_bf16 v[104:107], v[182:185], v[198:201], v[104:107]
	v_mfma_f32_16x16x32_bf16 v[92:95], v[174:177], v[206:209], v[92:95]
	v_mfma_f32_16x16x32_bf16 v[88:91], v[182:185], v[206:209], v[88:91]
	v_mfma_f32_16x16x32_bf16 v[76:79], v[174:177], v[214:217], v[76:79]
	v_mfma_f32_16x16x32_bf16 v[72:75], v[182:185], v[214:217], v[72:75]
	s_setprio 0
	s_add_i32 s13, s13, s31
	s_mov_b32 m0, s13
	ds_read_b128 v[186:189], v161 offset:16384
	ds_read_b128 v[190:193], v161 offset:17408
	ds_read_b128 v[194:197], v161 offset:18432
	ds_read_b128 v[198:201], v161 offset:19456
	ds_read_b128 v[202:205], v161 offset:20480
	ds_read_b128 v[206:209], v161 offset:21504
	ds_read_b128 v[210:213], v161 offset:22528
	ds_read_b128 v[214:217], v161 offset:23552
	global_load_lds_dwordx4 v140, s[24:25]
	s_add_i32 m0, s13, 0x2000
	s_add_u32 s68, s24, 0x4000
	s_addc_u32 s69, s25, 0
	s_add_i32 s13, s88, s31
	global_load_lds_dwordx4 v136, s[24:25]
	s_mov_b32 m0, s13
	s_nop 0
	global_load_lds_dwordx4 v140, s[68:69]
	s_add_i32 m0, s13, 0x2000
	s_nop 0
	global_load_lds_dwordx4 v136, s[68:69]
	s_mov_b32 m0, s19
	s_nop 0
	global_load_lds_dwordx4 v142, s[26:27]
	s_mov_b32 m0, s35
	s_nop 0
	global_load_lds_dwordx4 v138, s[26:27]
	s_waitcnt vmcnt(8)
	s_waitcnt lgkmcnt(0)
	s_barrier
; #define PG8_STAGE(bufoff, gbase, voff) do { _Pragma("unroll") for (int _i = 0; _i < 2; ++_i) \
;         __builtin_amdgcn_global_load_lds((const unsigned*)((const char*)(gbase) + (voff)[_i]), (PG8_LAS unsigned*)(lds + (bufoff) + ldsw + _i * 8192), 16, 0, 0); } while (0)
; #define PG8_LDA(dst, b, h) do { _Pragma("unroll") for (int m = 0; m < 4; ++m) _Pragma("unroll") for (int k = 0; k < 2; ++k) dst[m][k] = *(const PG8_LAS bf16x8*)(lds + PG8_SA(b, h) + aoff + m * 2048 + k * 1024); } while (0)
; #define PG8_LDB(dst, b, h) do { _Pragma("unroll") for (int n = 0; n < 2; ++n) _Pragma("unroll") for (int k = 0; k < 2; ++k) dst[n][k] = *(const PG8_LAS bf16x8*)(lds + PG8_SB(b, h) + boff + n * 2048 + k * 1024); } while (0)
; #define PG8_MMA(ai, bj, At, Bt) do { __builtin_amdgcn_s_setprio(1); _Pragma("unroll") for (int m = 0; m < 4; ++m) _Pragma("unroll") for (int n = 0; n < 2; ++n) _Pragma("unroll") for (int k = 0; k < 2; ++k) \
;         acc[ai][bj][m][n] = __builtin_amdgcn_mfma_f32_16x16x32_bf16(Bt[n][k], At[m][k], acc[ai][bj][m][n], 0, 0, 0); __builtin_amdgcn_s_setprio(0); } while (0)
; #define PG8_WAIT_V(n) asm volatile("s_waitcnt vmcnt(" #n ")" ::: "memory")
; #define PG8_WAIT_L(n) asm volatile("s_waitcnt lgkmcnt(" #n ")" ::: "memory")
; #define PG8_BAR __builtin_amdgcn_s_barrier()
; #define PG8_SCHED __builtin_amdgcn_sched_barrier(0)
; template <class Epi, class Sched, bool ALIGN_EPI = false, bool SP2 = false, bool ABLK = false, bool BBLK = false>
; __device__ __forceinline__ void gemm_phase(PG8_LAS unsigned char* lds, const Gemm g, const Sched& S, const Epi& E) {
;     ...
;             PG8_WAIT_V(8); PG8_WAIT_L(0); PG8_BAR; PG8_MMA(0, 0, At, B0); PG8_MMA(0, 1, At, B1); PG8_BAR; PG8_SCHED;
;             PG8_LDA(At, 0, 1); PG8_STAGE(PG8_SB(0, 0), b2, voffB); PG8_STAGE(PG8_SB(0, 1), b2 + hstepB, voffB); PG8_STAGE(PG8_SA(0, 0), a2, voffA);
;             PG8_WAIT_V(8); PG8_WAIT_L(0); PG8_BAR; PG8_MMA(1, 0, At, B0); PG8_MMA(1, 1, At, B1); PG8_BAR; PG8_SCHED;
;             PG8_LDB(B0, 1, 0); PG8_LDB(B1, 1, 1); PG8_SCHED; PG8_LDA(At, 1, 0); PG8_STAGE(PG8_SA(0, 1), a2 + hstepA, voffA);
;             PG8_WAIT_V(8); PG8_WAIT_L(0); PG8_BAR; PG8_MMA(0, 0, At, B0); PG8_MMA(0, 1, At, B1); PG8_BAR; PG8_SCHED;
	s_setprio 2
	s_waitcnt lgkmcnt(0)
	v_mfma_f32_16x16x32_bf16 v[68:71], v[152:155], v[186:189], v[68:71]
	v_mfma_f32_16x16x32_bf16 v[64:67], v[162:165], v[186:189], v[64:67]
	v_mfma_f32_16x16x32_bf16 v[52:55], v[152:155], v[194:197], v[52:55]
	v_mfma_f32_16x16x32_bf16 v[48:51], v[162:165], v[194:197], v[48:51]
	v_mfma_f32_16x16x32_bf16 v[32:35], v[152:155], v[202:205], v[32:35]
	v_mfma_f32_16x16x32_bf16 v[28:31], v[162:165], v[202:205], v[28:31]
	v_mfma_f32_16x16x32_bf16 v[16:19], v[152:155], v[210:213], v[16:19]
	v_mfma_f32_16x16x32_bf16 v[12:15], v[162:165], v[210:213], v[12:15]
	v_mfma_f32_16x16x32_bf16 v[68:71], v[156:159], v[190:193], v[68:71]
	v_mfma_f32_16x16x32_bf16 v[64:67], v[166:169], v[190:193], v[64:67]
	v_mfma_f32_16x16x32_bf16 v[52:55], v[156:159], v[198:201], v[52:55]
	v_mfma_f32_16x16x32_bf16 v[48:51], v[166:169], v[198:201], v[48:51]
	v_mfma_f32_16x16x32_bf16 v[32:35], v[156:159], v[206:209], v[32:35]
	v_mfma_f32_16x16x32_bf16 v[28:31], v[166:169], v[206:209], v[28:31]
	v_mfma_f32_16x16x32_bf16 v[16:19], v[156:159], v[214:217], v[16:19]
	v_mfma_f32_16x16x32_bf16 v[12:15], v[166:169], v[214:217], v[12:15]
	v_mfma_f32_16x16x32_bf16 v[60:63], v[170:173], v[186:189], v[60:63]
	v_mfma_f32_16x16x32_bf16 v[56:59], v[178:181], v[186:189], v[56:59]
	v_mfma_f32_16x16x32_bf16 v[44:47], v[170:173], v[194:197], v[44:47]
	v_mfma_f32_16x16x32_bf16 v[40:43], v[178:181], v[194:197], v[40:43]
	v_mfma_f32_16x16x32_bf16 v[24:27], v[170:173], v[202:205], v[24:27]
	v_mfma_f32_16x16x32_bf16 v[20:23], v[178:181], v[202:205], v[20:23]
	v_mfma_f32_16x16x32_bf16 v[8:11], v[170:173], v[210:213], v[8:11]
	v_mfma_f32_16x16x32_bf16 v[4:7], v[178:181], v[210:213], v[4:7]
	v_mfma_f32_16x16x32_bf16 v[60:63], v[174:177], v[190:193], v[60:63]
	v_mfma_f32_16x16x32_bf16 v[56:59], v[182:185], v[190:193], v[56:59]
	v_mfma_f32_16x16x32_bf16 v[44:47], v[174:177], v[198:201], v[44:47]
	v_mfma_f32_16x16x32_bf16 v[40:43], v[182:185], v[198:201], v[40:43]
	v_mfma_f32_16x16x32_bf16 v[24:27], v[174:177], v[206:209], v[24:27]
	v_mfma_f32_16x16x32_bf16 v[20:23], v[182:185], v[206:209], v[20:23]
	v_mfma_f32_16x16x32_bf16 v[8:11], v[174:177], v[214:217], v[8:11]
	v_mfma_f32_16x16x32_bf16 v[4:7], v[182:185], v[214:217], v[4:7]
	s_setprio 0
	s_add_i32 s13, 0, 0x18000
	v_add_u32_e32 v36, s13, v160
	s_add_i32 s68, 0, 0x1c000
	ds_read_b128 v[152:155], v36
	ds_read_b128 v[156:159], v36 offset:1024
	ds_read_b128 v[162:165], v36 offset:2048
	ds_read_b128 v[166:169], v36 offset:3072
	v_add_u32_e32 v36, s68, v160
	ds_read_b128 v[170:173], v36
	ds_read_b128 v[174:177], v36 offset:1024
	ds_read_b128 v[178:181], v36 offset:2048
	ds_read_b128 v[182:185], v36 offset:3072
	s_add_u32 s26, s26, 0x4000
	s_addc_u32 s27, s27, 0
	s_mov_b32 m0, s36
	ds_read_b128 v[186:189], v161 offset:32768
	ds_read_b128 v[190:193], v161 offset:33792
	ds_read_b128 v[194:197], v161 offset:34816
	ds_read_b128 v[198:201], v161 offset:35840
	ds_read_b128 v[202:205], v161 offset:36864
	ds_read_b128 v[206:209], v161 offset:37888
	ds_read_b128 v[210:213], v161 offset:38912
	ds_read_b128 v[214:217], v161 offset:39936
	global_load_lds_dwordx4 v142, s[26:27]
	s_mov_b32 m0, s37
	s_nop 0
	global_load_lds_dwordx4 v138, s[26:27]
	s_waitcnt vmcnt(8)
	s_waitcnt lgkmcnt(0)
	s_barrier
	s_setprio 2
	s_waitcnt lgkmcnt(0)
	v_mfma_f32_16x16x32_bf16 v[132:135], v[152:155], v[186:189], v[132:135]
	v_mfma_f32_16x16x32_bf16 v[128:131], v[162:165], v[186:189], v[128:131]
	v_mfma_f32_16x16x32_bf16 v[116:119], v[152:155], v[194:197], v[116:119]
	v_mfma_f32_16x16x32_bf16 v[112:115], v[162:165], v[194:197], v[112:115]
	v_mfma_f32_16x16x32_bf16 v[100:103], v[152:155], v[202:205], v[100:103]
	v_mfma_f32_16x16x32_bf16 v[96:99], v[162:165], v[202:205], v[96:99]
	v_mfma_f32_16x16x32_bf16 v[84:87], v[152:155], v[210:213], v[84:87]
	v_mfma_f32_16x16x32_bf16 v[80:83], v[162:165], v[210:213], v[80:83]
	v_mfma_f32_16x16x32_bf16 v[132:135], v[156:159], v[190:193], v[132:135]
	v_mfma_f32_16x16x32_bf16 v[128:131], v[166:169], v[190:193], v[128:131]
	v_mfma_f32_16x16x32_bf16 v[116:119], v[156:159], v[198:201], v[116:119]
	v_mfma_f32_16x16x32_bf16 v[112:115], v[166:169], v[198:201], v[112:115]
	v_mfma_f32_16x16x32_bf16 v[100:103], v[156:159], v[206:209], v[100:103]
	v_mfma_f32_16x16x32_bf16 v[96:99], v[166:169], v[206:209], v[96:99]
	v_mfma_f32_16x16x32_bf16 v[84:87], v[156:159], v[214:217], v[84:87]
	v_mfma_f32_16x16x32_bf16 v[80:83], v[166:169], v[214:217], v[80:83]
	v_mfma_f32_16x16x32_bf16 v[124:127], v[170:173], v[186:189], v[124:127]
	v_mfma_f32_16x16x32_bf16 v[120:123], v[178:181], v[186:189], v[120:123]
	v_mfma_f32_16x16x32_bf16 v[108:111], v[170:173], v[194:197], v[108:111]
	v_mfma_f32_16x16x32_bf16 v[104:107], v[178:181], v[194:197], v[104:107]
	v_mfma_f32_16x16x32_bf16 v[92:95], v[170:173], v[202:205], v[92:95]
	v_mfma_f32_16x16x32_bf16 v[88:91], v[178:181], v[202:205], v[88:91]
	v_mfma_f32_16x16x32_bf16 v[76:79], v[170:173], v[210:213], v[76:79]
	v_mfma_f32_16x16x32_bf16 v[72:75], v[178:181], v[210:213], v[72:75]
	v_mfma_f32_16x16x32_bf16 v[124:127], v[174:177], v[190:193], v[124:127]
	v_mfma_f32_16x16x32_bf16 v[120:123], v[182:185], v[190:193], v[120:123]
	v_mfma_f32_16x16x32_bf16 v[108:111], v[174:177], v[198:201], v[108:111]
	v_mfma_f32_16x16x32_bf16 v[104:107], v[182:185], v[198:201], v[104:107]
	v_mfma_f32_16x16x32_bf16 v[92:95], v[174:177], v[206:209], v[92:95]
	v_mfma_f32_16x16x32_bf16 v[88:91], v[182:185], v[206:209], v[88:91]
	v_mfma_f32_16x16x32_bf16 v[76:79], v[174:177], v[214:217], v[76:79]
	v_mfma_f32_16x16x32_bf16 v[72:75], v[182:185], v[214:217], v[72:75]
	s_setprio 0
	s_add_u32 s26, s24, 0x8000
	s_addc_u32 s27, s25, 0
	s_add_i32 s13, s13, s31
	s_mov_b32 m0, s13
	ds_read_b128 v[186:189], v161 offset:49152
	ds_read_b128 v[190:193], v161 offset:50176
	ds_read_b128 v[194:197], v161 offset:51200
	ds_read_b128 v[198:201], v161 offset:52224
	ds_read_b128 v[202:205], v161 offset:53248
	ds_read_b128 v[206:209], v161 offset:54272
	ds_read_b128 v[210:213], v161 offset:55296
	ds_read_b128 v[214:217], v161 offset:56320
	global_load_lds_dwordx4 v140, s[26:27]
	s_add_i32 m0, s13, 0x2000
	s_add_u32 s24, s24, 0xc000
	s_addc_u32 s25, s25, 0
	s_add_i32 s13, s68, s31
	global_load_lds_dwordx4 v136, s[26:27]
	s_mov_b32 m0, s13
	s_nop 0
	global_load_lds_dwordx4 v140, s[24:25]
	s_add_i32 m0, s13, 0x2000
	s_nop 0
	global_load_lds_dwordx4 v136, s[24:25]
	s_mov_b32 m0, s62
	s_nop 0
	global_load_lds_dwordx4 v142, s[22:23]
	s_mov_b32 m0, s63
	s_nop 0
	global_load_lds_dwordx4 v138, s[22:23]
	s_waitcnt vmcnt(8)
	s_waitcnt lgkmcnt(0)
	s_barrier
; #define PG8_LAS __attribute__((address_space(3)))
; __device__ __forceinline__ unsigned cvt_pk_bf16(float lo, float hi) { const hwf2_t v = {lo, hi}; return __builtin_bit_cast(unsigned, __builtin_convertvector(v, hwbf2_t)); }
; #define PG8_BAR __builtin_amdgcn_s_barrier()
;     __device__ __forceinline__ void operator()(const f32x4 (&acc)[2][2][4][2], const Unit& u, int wr, int wc, int fr, int fq, const PG8_LAS unsigned char* area) const {
;     ...
;             for (int m = 0; m < 4; ++m) rsv[ai][m] = *(const PG8_LAS float*)(area + ai * 256 + (m * 16 + fr) * 4);
; #pragma unroll
;         for (int ai = 0; ai < 2; ++ai)
; #pragma unroll
;             for (int m = 0; m < 4; ++m) { bf16_t* rowp = obase + (ai * HALF + m * 16) * BK; const float r_ = rsv[ai][m], r2 = r_ * -1.4426950408889634f, rr = r_ * r_;
;                 const f32x4 t0 = acc[ai][0][m][0] * r2, t1 = acc[ai][0][m][1] * r2;
;                 f32x4 d0, d1, q0, q1;
; #pragma unroll
;                 for (int i = 0; i < 4; ++i) { d0[i] = __builtin_amdgcn_exp2f(t0[i]); d1[i] = __builtin_amdgcn_exp2f(t1[i]); }
;                 d0 = d0 + 1.0f; d1 = d1 + 1.0f;
; #pragma unroll
;                 for (int i = 0; i < 4; ++i) { q0[i] = __builtin_amdgcn_rcpf(d0[i]); q1[i] = __builtin_amdgcn_rcpf(d1[i]); }
;                 const f32x4 o0 = (acc[ai][0][m][0] * acc[ai][1][m][0]) * rr * q0, o1 = (acc[ai][0][m][1] * acc[ai][1][m][1]) * rr * q1;
;                 u32x4 w; w.x = cvt_pk_bf16(o0[0], o0[1]); w.y = cvt_pk_bf16(o0[2], o0[3]); w.z = cvt_pk_bf16(o1[0], o1[1]); w.w = cvt_pk_bf16(o1[2], o1[3]);
;                 *(u32x4*)rowp = w; }
; template <class Epi, class Sched, bool ALIGN_EPI = false, bool SP2 = false, bool ABLK = false, bool BBLK = false>
; __device__ __forceinline__ void gemm_phase(PG8_LAS unsigned char* lds, const Gemm g, const Sched& S, const Epi& E) {
;     ...
;             PG8_WAIT_V(8); PG8_WAIT_L(0); PG8_BAR; PG8_MMA(0, 0, At, B0); PG8_MMA(0, 1, At, B1); PG8_BAR; PG8_SCHED;
;             PG8_LDA(At, 1, 1); PG8_STAGE(PG8_SB(1, 0), b3, voffB); PG8_STAGE(PG8_SB(1, 1), b3 + hstepB, voffB); PG8_STAGE(PG8_SA(1, 0), a3, voffA);
;             PG8_WAIT_V(8); PG8_WAIT_L(0); PG8_BAR; PG8_MMA(1, 0, At, B0); PG8_MMA(1, 1, At, B1); PG8_BAR; PG8_SCHED;
;     ...
;         if constexpr (ALIGN_EPI) { if (wr == 0) PG8_BAR; }
;         if constexpr (!Epi::AFTER_DRAIN) { E(acc, cur, wr, wc, fr, fq, rs_area); S.done(cur); }
	s_setprio 2
	s_waitcnt lgkmcnt(0)
	v_mfma_f32_16x16x32_bf16 v[68:71], v[152:155], v[186:189], v[68:71]
	v_mfma_f32_16x16x32_bf16 v[64:67], v[162:165], v[186:189], v[64:67]
	v_mfma_f32_16x16x32_bf16 v[52:55], v[152:155], v[194:197], v[52:55]
	v_mfma_f32_16x16x32_bf16 v[48:51], v[162:165], v[194:197], v[48:51]
	v_mfma_f32_16x16x32_bf16 v[32:35], v[152:155], v[202:205], v[32:35]
	v_mfma_f32_16x16x32_bf16 v[28:31], v[162:165], v[202:205], v[28:31]
	v_mfma_f32_16x16x32_bf16 v[16:19], v[152:155], v[210:213], v[16:19]
	v_mfma_f32_16x16x32_bf16 v[12:15], v[162:165], v[210:213], v[12:15]
	v_mfma_f32_16x16x32_bf16 v[68:71], v[156:159], v[190:193], v[68:71]
	v_mfma_f32_16x16x32_bf16 v[64:67], v[166:169], v[190:193], v[64:67]
	v_mfma_f32_16x16x32_bf16 v[52:55], v[156:159], v[198:201], v[52:55]
	v_mfma_f32_16x16x32_bf16 v[48:51], v[166:169], v[198:201], v[48:51]
	v_mfma_f32_16x16x32_bf16 v[32:35], v[156:159], v[206:209], v[32:35]
	v_mfma_f32_16x16x32_bf16 v[28:31], v[166:169], v[206:209], v[28:31]
	v_mfma_f32_16x16x32_bf16 v[16:19], v[156:159], v[214:217], v[16:19]
	v_mfma_f32_16x16x32_bf16 v[12:15], v[166:169], v[214:217], v[12:15]
	v_mfma_f32_16x16x32_bf16 v[60:63], v[170:173], v[186:189], v[60:63]
	v_mfma_f32_16x16x32_bf16 v[56:59], v[178:181], v[186:189], v[56:59]
	v_mfma_f32_16x16x32_bf16 v[44:47], v[170:173], v[194:197], v[44:47]
	v_mfma_f32_16x16x32_bf16 v[40:43], v[178:181], v[194:197], v[40:43]
	v_mfma_f32_16x16x32_bf16 v[24:27], v[170:173], v[202:205], v[24:27]
	v_mfma_f32_16x16x32_bf16 v[20:23], v[178:181], v[202:205], v[20:23]
	v_mfma_f32_16x16x32_bf16 v[8:11], v[170:173], v[210:213], v[8:11]
	v_mfma_f32_16x16x32_bf16 v[4:7], v[178:181], v[210:213], v[4:7]
	v_mfma_f32_16x16x32_bf16 v[60:63], v[174:177], v[190:193], v[60:63]
	v_mfma_f32_16x16x32_bf16 v[56:59], v[182:185], v[190:193], v[56:59]
	v_mfma_f32_16x16x32_bf16 v[44:47], v[174:177], v[198:201], v[44:47]
	v_mfma_f32_16x16x32_bf16 v[40:43], v[182:185], v[198:201], v[40:43]
	v_mfma_f32_16x16x32_bf16 v[24:27], v[174:177], v[206:209], v[24:27]
	v_mfma_f32_16x16x32_bf16 v[20:23], v[182:185], v[206:209], v[20:23]
	v_mfma_f32_16x16x32_bf16 v[8:11], v[174:177], v[214:217], v[8:11]
	v_mfma_f32_16x16x32_bf16 v[4:7], v[182:185], v[214:217], v[4:7]
	s_setprio 0
	s_add_i32 vcc_hi, vcc_hi, 2
	s_add_u32 s20, s20, 0x10000
	s_addc_u32 s21, s21, 0
	s_add_u32 s77, s77, 0x10000
	s_addc_u32 vcc_lo, vcc_lo, 0
	s_cmp_gt_u32 vcc_hi, 29
	s_cbranch_scc0 .Lk1_FFN1
.Lkx_FFN1:
	s_and_b64 vcc, exec, s[4:5]
	s_cbranch_vccz .LBB0_188
.LBB0_188:
	v_add_u32_e32 v38, s64, v3
	ds_read2_b32 v[36:37], v38 offset1:16
	ds_read2_b32 v[158:159], v38 offset0:32 offset1:48
	ds_read2_b32 v[154:155], v38 offset0:64 offset1:80
	ds_read2_b32 v[152:153], v38 offset0:96 offset1:112
	s_lshl_b32 s12, s12, 1
	s_waitcnt lgkmcnt(0)
	v_mul_f32_e32 v163, 0xbfb8aa3b, v36
	v_mul_f32_e32 v39, v128, v163
	v_mul_f32_e32 v165, v130, v163
	v_mul_f32_e32 v38, v132, v163
	v_exp_f32_e32 v162, v39
	v_mul_f32_e32 v39, v133, v163
	v_mul_f32_e32 v168, v129, v163
	v_mul_f32_e32 v164, v134, v163
	v_exp_f32_e32 v166, v165
	v_mul_f32_e32 v165, v135, v163
	v_mul_f32_e32 v163, v131, v163
	v_exp_f32_e32 v38, v38
	v_exp_f32_e32 v39, v39
	v_exp_f32_e32 v164, v164
	v_exp_f32_e32 v165, v165
	v_exp_f32_e32 v167, v163
	v_exp_f32_e32 v163, v168
	v_pk_add_f32 v[38:39], v[38:39], 1.0 op_sel_hi:[1,0]
	v_pk_add_f32 v[164:165], v[164:165], 1.0 op_sel_hi:[1,0]
	v_pk_add_f32 v[166:167], v[166:167], 1.0 op_sel_hi:[1,0]
	v_pk_add_f32 v[162:163], v[162:163], 1.0 op_sel_hi:[1,0]
	s_ashr_i32 s13, s12, 31
	v_rcp_f32_e32 v38, v38
	v_rcp_f32_e32 v162, v162
	v_rcp_f32_e32 v39, v39
	v_rcp_f32_e32 v163, v163
	v_rcp_f32_e32 v164, v164
	v_rcp_f32_e32 v166, v166
	v_rcp_f32_e32 v165, v165
	v_rcp_f32_e32 v167, v167
	s_mul_i32 s9, s18, 0x58
	s_or_b64 s[12:13], s[12:13], s[82:83]
	s_mul_hi_i32 s7, s18, 0x58
	s_add_u32 s12, s12, s9
	v_mul_f32_e32 v36, v36, v36
	v_pk_mul_f32 v[126:127], v[134:135], v[126:127]
	v_pk_mul_f32 v[124:125], v[132:133], v[124:125]
	v_pk_mul_f32 v[122:123], v[130:131], v[122:123]
	v_pk_mul_f32 v[120:121], v[128:129], v[120:121]
	s_addc_u32 s13, s13, s7
	v_pk_mul_f32 v[124:125], v[124:125], v[36:37] op_sel_hi:[1,0]
	v_pk_mul_f32 v[126:127], v[126:127], v[36:37] op_sel_hi:[1,0]
	v_pk_mul_f32 v[120:121], v[120:121], v[36:37] op_sel_hi:[1,0]
	v_pk_mul_f32 v[122:123], v[122:123], v[36:37] op_sel_hi:[1,0]
	s_lshl_b64 s[12:13], s[12:13], 15
	v_pk_mul_f32 v[126:127], v[126:127], v[164:165]
	v_pk_mul_f32 v[38:39], v[124:125], v[38:39]
	v_pk_mul_f32 v[124:125], v[122:123], v[166:167]
	v_pk_mul_f32 v[122:123], v[120:121], v[162:163]
	v_mul_f32_e32 v36, 0xbfb8aa3b, v37
	v_lshl_add_u64 v[156:157], v[146:147], 0, s[12:13]
	v_cvt_pk_bf16_f32 v120, v38, v39
	v_cvt_pk_bf16_f32 v121, v126, v127
	v_cvt_pk_bf16_f32 v122, v122, v123
	v_cvt_pk_bf16_f32 v123, v124, v125
	v_mul_f32_e32 v39, v112, v36
	global_store_dwordx4 v[156:157], v[120:123], off
	v_mul_f32_e32 v38, v116, v36
	v_exp_f32_e32 v38, v38
	v_exp_f32_e32 v120, v39
	v_mul_f32_e32 v39, v117, v36
	v_mul_f32_e32 v123, v114, v36
	v_exp_f32_e32 v39, v39
	v_mul_f32_e32 v121, v113, v36
	v_mul_f32_e32 v122, v118, v36
	v_exp_f32_e32 v124, v123
	v_mul_f32_e32 v123, v119, v36
	v_mul_f32_e32 v36, v115, v36
	v_exp_f32_e32 v122, v122
	v_exp_f32_e32 v123, v123
	v_exp_f32_e32 v125, v36
	v_exp_f32_e32 v121, v121
	v_pk_add_f32 v[38:39], v[38:39], 1.0 op_sel_hi:[1,0]
	v_pk_add_f32 v[122:123], v[122:123], 1.0 op_sel_hi:[1,0]
	v_pk_add_f32 v[124:125], v[124:125], 1.0 op_sel_hi:[1,0]
	v_pk_add_f32 v[120:121], v[120:121], 1.0 op_sel_hi:[1,0]
	v_rcp_f32_e32 v38, v38
	v_rcp_f32_e32 v39, v39
	v_rcp_f32_e32 v120, v120
	v_rcp_f32_e32 v121, v121
; __device__ __forceinline__ unsigned cvt_pk_bf16(float lo, float hi) { const hwf2_t v = {lo, hi}; return __builtin_bit_cast(unsigned, __builtin_convertvector(v, hwbf2_t)); }
;     __device__ __forceinline__ void operator()(const f32x4 (&acc)[2][2][4][2], const Unit& u, int wr, int wc, int fr, int fq, const PG8_LAS unsigned char* area) const {
;     ...
;             for (int m = 0; m < 4; ++m) { bf16_t* rowp = obase + (ai * HALF + m * 16) * BK; const float r_ = rsv[ai][m], r2 = r_ * -1.4426950408889634f, rr = r_ * r_;
;                 const f32x4 t0 = acc[ai][0][m][0] * r2, t1 = acc[ai][0][m][1] * r2;
;                 f32x4 d0, d1, q0, q1;
; #pragma unroll
;                 for (int i = 0; i < 4; ++i) { d0[i] = __builtin_amdgcn_exp2f(t0[i]); d1[i] = __builtin_amdgcn_exp2f(t1[i]); }
;                 d0 = d0 + 1.0f; d1 = d1 + 1.0f;
; #pragma unroll
;                 for (int i = 0; i < 4; ++i) { q0[i] = __builtin_amdgcn_rcpf(d0[i]); q1[i] = __builtin_amdgcn_rcpf(d1[i]); }
;                 const f32x4 o0 = (acc[ai][0][m][0] * acc[ai][1][m][0]) * rr * q0, o1 = (acc[ai][0][m][1] * acc[ai][1][m][1]) * rr * q1;
;                 u32x4 w; w.x = cvt_pk_bf16(o0[0], o0[1]); w.y = cvt_pk_bf16(o0[2], o0[3]); w.z = cvt_pk_bf16(o1[0], o1[1]); w.w = cvt_pk_bf16(o1[2], o1[3]);
;                 *(u32x4*)rowp = w; }
	v_rcp_f32_e32 v122, v122
	v_rcp_f32_e32 v124, v124
	v_rcp_f32_e32 v123, v123
	v_rcp_f32_e32 v125, v125
	v_mul_f32_e32 v36, v37, v37
	v_pk_mul_f32 v[108:109], v[116:117], v[108:109]
	v_pk_mul_f32 v[110:111], v[118:119], v[110:111]
	v_pk_mul_f32 v[108:109], v[108:109], v[36:37] op_sel_hi:[1,0]
	v_pk_mul_f32 v[106:107], v[114:115], v[106:107]
	v_pk_mul_f32 v[104:105], v[112:113], v[104:105]
	v_pk_mul_f32 v[110:111], v[110:111], v[36:37] op_sel_hi:[1,0]
	v_pk_mul_f32 v[38:39], v[108:109], v[38:39]
	v_pk_mul_f32 v[104:105], v[104:105], v[36:37] op_sel_hi:[1,0]
	v_pk_mul_f32 v[36:37], v[106:107], v[36:37] op_sel_hi:[1,0]
	v_pk_mul_f32 v[110:111], v[110:111], v[122:123]
	v_pk_mul_f32 v[36:37], v[36:37], v[124:125]
	v_pk_mul_f32 v[106:107], v[104:105], v[120:121]
	v_cvt_pk_bf16_f32 v104, v38, v39
	v_mul_f32_e32 v39, 0xbfb8aa3b, v158
	v_cvt_pk_bf16_f32 v105, v110, v111
	v_cvt_pk_bf16_f32 v106, v106, v107
	v_cvt_pk_bf16_f32 v107, v36, v37
	v_mul_f32_e32 v37, v96, v39
	global_store_dwordx4 v[156:157], v[104:107], off offset:2048
	v_mul_f32_e32 v36, v100, v39
	v_exp_f32_e32 v38, v37
	v_mul_f32_e32 v37, v101, v39
	v_mul_f32_e32 v105, v98, v39
	v_exp_f32_e32 v36, v36
	v_exp_f32_e32 v37, v37
	v_mul_f32_e32 v108, v97, v39
	v_mul_f32_e32 v104, v102, v39
	v_exp_f32_e32 v106, v105
	v_mul_f32_e32 v105, v103, v39
	v_mul_f32_e32 v39, v99, v39
	v_exp_f32_e32 v104, v104
	v_exp_f32_e32 v105, v105
	v_exp_f32_e32 v107, v39
	v_exp_f32_e32 v39, v108
	v_pk_add_f32 v[36:37], v[36:37], 1.0 op_sel_hi:[1,0]
	v_pk_add_f32 v[104:105], v[104:105], 1.0 op_sel_hi:[1,0]
	v_pk_add_f32 v[106:107], v[106:107], 1.0 op_sel_hi:[1,0]
	v_pk_add_f32 v[38:39], v[38:39], 1.0 op_sel_hi:[1,0]
	v_rcp_f32_e32 v36, v36
	v_rcp_f32_e32 v37, v37
	v_rcp_f32_e32 v38, v38
	v_rcp_f32_e32 v39, v39
	v_rcp_f32_e32 v104, v104
	v_rcp_f32_e32 v106, v106
	v_rcp_f32_e32 v105, v105
	v_rcp_f32_e32 v107, v107
	v_mul_f32_e32 v108, v158, v158
	v_pk_mul_f32 v[92:93], v[100:101], v[92:93]
	v_pk_mul_f32 v[94:95], v[102:103], v[94:95]
	v_pk_mul_f32 v[92:93], v[92:93], v[108:109] op_sel_hi:[1,0]
	v_pk_mul_f32 v[90:91], v[98:99], v[90:91]
	v_pk_mul_f32 v[88:89], v[96:97], v[88:89]
	v_pk_mul_f32 v[94:95], v[94:95], v[108:109] op_sel_hi:[1,0]
	v_pk_mul_f32 v[36:37], v[92:93], v[36:37]
	v_pk_mul_f32 v[88:89], v[88:89], v[108:109] op_sel_hi:[1,0]
	v_pk_mul_f32 v[90:91], v[90:91], v[108:109] op_sel_hi:[1,0]
	s_movk_i32 s77, 0x1000
	v_pk_mul_f32 v[94:95], v[94:95], v[104:105]
	v_pk_mul_f32 v[92:93], v[90:91], v[106:107]
	v_pk_mul_f32 v[38:39], v[88:89], v[38:39]
	v_cvt_pk_bf16_f32 v88, v36, v37
	v_add_co_u32_e32 v36, vcc, s77, v156
	v_cvt_pk_bf16_f32 v89, v94, v95
	v_cvt_pk_bf16_f32 v90, v38, v39
	v_cvt_pk_bf16_f32 v91, v92, v93
	v_addc_co_u32_e32 v37, vcc, 0, v157, vcc
	global_store_dwordx4 v[36:37], v[88:91], off
	v_pk_mul_f32 v[78:79], v[86:87], v[78:79]
	v_pk_mul_f32 v[76:77], v[84:85], v[76:77]
	v_mul_f32_e32 v89, 0xbfb8aa3b, v159
	v_mul_f32_e32 v39, v80, v89
	v_mul_f32_e32 v91, v82, v89
	v_mul_f32_e32 v38, v84, v89
	v_exp_f32_e32 v88, v39
	v_mul_f32_e32 v39, v85, v89
	v_mul_f32_e32 v94, v81, v89
	v_mul_f32_e32 v90, v86, v89
	v_exp_f32_e32 v92, v91
	v_mul_f32_e32 v91, v87, v89
	v_mul_f32_e32 v89, v83, v89
	v_exp_f32_e32 v38, v38
	v_exp_f32_e32 v39, v39
	v_exp_f32_e32 v90, v90
	v_exp_f32_e32 v91, v91
	v_exp_f32_e32 v93, v89
	v_exp_f32_e32 v89, v94
	v_pk_add_f32 v[38:39], v[38:39], 1.0 op_sel_hi:[1,0]
	v_pk_add_f32 v[90:91], v[90:91], 1.0 op_sel_hi:[1,0]
	v_pk_add_f32 v[92:93], v[92:93], 1.0 op_sel_hi:[1,0]
	v_pk_add_f32 v[88:89], v[88:89], 1.0 op_sel_hi:[1,0]
	v_rcp_f32_e32 v38, v38
	v_rcp_f32_e32 v88, v88
	v_rcp_f32_e32 v39, v39
	v_rcp_f32_e32 v89, v89
	v_rcp_f32_e32 v90, v90
	v_rcp_f32_e32 v92, v92
	v_rcp_f32_e32 v91, v91
	v_rcp_f32_e32 v93, v93
	v_mul_f32_e32 v94, v159, v159
	v_pk_mul_f32 v[74:75], v[82:83], v[74:75]
	v_pk_mul_f32 v[72:73], v[80:81], v[72:73]
	v_pk_mul_f32 v[76:77], v[76:77], v[94:95] op_sel_hi:[1,0]
	v_pk_mul_f32 v[78:79], v[78:79], v[94:95] op_sel_hi:[1,0]
	v_pk_mul_f32 v[72:73], v[72:73], v[94:95] op_sel_hi:[1,0]
	v_pk_mul_f32 v[74:75], v[74:75], v[94:95] op_sel_hi:[1,0]
	v_pk_mul_f32 v[78:79], v[78:79], v[90:91]
	v_pk_mul_f32 v[38:39], v[76:77], v[38:39]
	v_pk_mul_f32 v[76:77], v[74:75], v[92:93]
	v_pk_mul_f32 v[74:75], v[72:73], v[88:89]
	v_cvt_pk_bf16_f32 v72, v38, v39
	v_cvt_pk_bf16_f32 v73, v78, v79
	v_cvt_pk_bf16_f32 v74, v74, v75
	v_cvt_pk_bf16_f32 v75, v76, v77
	v_mul_f32_e32 v39, 0xbfb8aa3b, v154
	global_store_dwordx4 v[36:37], v[72:75], off offset:2048
	v_mul_f32_e32 v37, v64, v39
	v_mul_f32_e32 v36, v68, v39
	v_exp_f32_e32 v38, v37
	v_mul_f32_e32 v37, v69, v39
	v_mul_f32_e32 v73, v66, v39
	v_exp_f32_e32 v36, v36
	v_exp_f32_e32 v37, v37
	v_mul_f32_e32 v76, v65, v39
	v_mul_f32_e32 v72, v70, v39
	v_exp_f32_e32 v74, v73
	v_mul_f32_e32 v73, v71, v39
	v_mul_f32_e32 v39, v67, v39
	v_exp_f32_e32 v75, v39
	v_exp_f32_e32 v39, v76
	v_exp_f32_e32 v72, v72
	v_exp_f32_e32 v73, v73
	v_pk_add_f32 v[36:37], v[36:37], 1.0 op_sel_hi:[1,0]
	v_pk_add_f32 v[38:39], v[38:39], 1.0 op_sel_hi:[1,0]
	v_rcp_f32_e32 v36, v36
	v_rcp_f32_e32 v37, v37
	v_rcp_f32_e32 v38, v38
	v_rcp_f32_e32 v39, v39
	v_pk_add_f32 v[72:73], v[72:73], 1.0 op_sel_hi:[1,0]
	v_pk_add_f32 v[74:75], v[74:75], 1.0 op_sel_hi:[1,0]
	v_mul_f32_e32 v76, v154, v154
	v_pk_mul_f32 v[60:61], v[68:69], v[60:61]
	v_rcp_f32_e32 v72, v72
	v_rcp_f32_e32 v74, v74
	v_rcp_f32_e32 v73, v73
	v_rcp_f32_e32 v75, v75
	v_pk_mul_f32 v[60:61], v[60:61], v[76:77] op_sel_hi:[1,0]
	v_pk_mul_f32 v[56:57], v[64:65], v[56:57]
	v_pk_mul_f32 v[36:37], v[60:61], v[36:37]
	v_pk_mul_f32 v[56:57], v[56:57], v[76:77] op_sel_hi:[1,0]
	v_pk_mul_f32 v[62:63], v[70:71], v[62:63]
; __device__ __forceinline__ unsigned cvt_pk_bf16(float lo, float hi) { const hwf2_t v = {lo, hi}; return __builtin_bit_cast(unsigned, __builtin_convertvector(v, hwbf2_t)); }
; #define PG8_BAR __builtin_amdgcn_s_barrier()
;     __device__ __forceinline__ void operator()(const f32x4 (&acc)[2][2][4][2], const Unit& u, int wr, int wc, int fr, int fq, const PG8_LAS unsigned char* area) const {
;     ...
;             for (int m = 0; m < 4; ++m) { bf16_t* rowp = obase + (ai * HALF + m * 16) * BK; const float r_ = rsv[ai][m], r2 = r_ * -1.4426950408889634f, rr = r_ * r_;
;                 const f32x4 t0 = acc[ai][0][m][0] * r2, t1 = acc[ai][0][m][1] * r2;
;                 f32x4 d0, d1, q0, q1;
; #pragma unroll
;                 for (int i = 0; i < 4; ++i) { d0[i] = __builtin_amdgcn_exp2f(t0[i]); d1[i] = __builtin_amdgcn_exp2f(t1[i]); }
;                 d0 = d0 + 1.0f; d1 = d1 + 1.0f;
; #pragma unroll
;                 for (int i = 0; i < 4; ++i) { q0[i] = __builtin_amdgcn_rcpf(d0[i]); q1[i] = __builtin_amdgcn_rcpf(d1[i]); }
;                 const f32x4 o0 = (acc[ai][0][m][0] * acc[ai][1][m][0]) * rr * q0, o1 = (acc[ai][0][m][1] * acc[ai][1][m][1]) * rr * q1;
;                 u32x4 w; w.x = cvt_pk_bf16(o0[0], o0[1]); w.y = cvt_pk_bf16(o0[2], o0[3]); w.z = cvt_pk_bf16(o1[0], o1[1]); w.w = cvt_pk_bf16(o1[2], o1[3]);
;                 *(u32x4*)rowp = w; }
; template <class Epi, class Sched, bool ALIGN_EPI = false, bool SP2 = false, bool ABLK = false, bool BBLK = false>
; __device__ __forceinline__ void gemm_phase(PG8_LAS unsigned char* lds, const Gemm g, const Sched& S, const Epi& E) {
;     ...
;         if (!has_next) break;
; #pragma unroll
;         for (int a = 0; a < 2; ++a)
; #pragma unroll
;             for (int b = 0; b < 2; ++b)
; #pragma unroll
;                 for (int m = 0; m < 4; ++m)
; #pragma unroll
;                     for (int n = 0; n < 2; ++n) acc[a][b][m][n] = (f32x4){0.f, 0.f, 0.f, 0.f};
;         cur = nxt; cA = nA; cB = nB; ++ui;
;         if constexpr (ALIGN_EPI) { if (wr == 1) PG8_BAR; }
	v_pk_mul_f32 v[58:59], v[66:67], v[58:59]
	v_pk_mul_f32 v[38:39], v[56:57], v[38:39]
	v_cvt_pk_bf16_f32 v56, v36, v37
	v_add_co_u32_e32 v36, vcc, s86, v156
	v_pk_mul_f32 v[62:63], v[62:63], v[76:77] op_sel_hi:[1,0]
	v_pk_mul_f32 v[58:59], v[58:59], v[76:77] op_sel_hi:[1,0]
	v_addc_co_u32_e32 v37, vcc, 0, v157, vcc
	v_pk_mul_f32 v[62:63], v[62:63], v[72:73]
	v_pk_mul_f32 v[60:61], v[58:59], v[74:75]
	v_cvt_pk_bf16_f32 v58, v38, v39
	v_add_co_u32_e32 v38, vcc, s87, v156
	v_cvt_pk_bf16_f32 v57, v62, v63
	v_cvt_pk_bf16_f32 v59, v60, v61
	v_addc_co_u32_e32 v39, vcc, 0, v157, vcc
	global_store_dwordx4 v[38:39], v[56:59], off offset:-4096
	v_pk_mul_f32 v[46:47], v[54:55], v[46:47]
	v_pk_mul_f32 v[44:45], v[52:53], v[44:45]
	v_mul_f32_e32 v59, 0xbfb8aa3b, v155
	v_mul_f32_e32 v57, v48, v59
	v_mul_f32_e32 v61, v50, v59
	v_mul_f32_e32 v56, v52, v59
	v_exp_f32_e32 v58, v57
	v_mul_f32_e32 v57, v53, v59
	v_mul_f32_e32 v64, v49, v59
	v_mul_f32_e32 v60, v54, v59
	v_exp_f32_e32 v62, v61
	v_mul_f32_e32 v61, v55, v59
	v_mul_f32_e32 v59, v51, v59
	v_exp_f32_e32 v56, v56
	v_exp_f32_e32 v57, v57
	v_exp_f32_e32 v60, v60
	v_exp_f32_e32 v61, v61
	v_exp_f32_e32 v63, v59
	v_exp_f32_e32 v59, v64
	v_pk_add_f32 v[56:57], v[56:57], 1.0 op_sel_hi:[1,0]
	v_pk_add_f32 v[60:61], v[60:61], 1.0 op_sel_hi:[1,0]
	v_pk_add_f32 v[62:63], v[62:63], 1.0 op_sel_hi:[1,0]
	v_pk_add_f32 v[58:59], v[58:59], 1.0 op_sel_hi:[1,0]
	v_rcp_f32_e32 v56, v56
	v_rcp_f32_e32 v58, v58
	v_rcp_f32_e32 v57, v57
	v_rcp_f32_e32 v59, v59
	v_rcp_f32_e32 v60, v60
	v_rcp_f32_e32 v62, v62
	v_rcp_f32_e32 v61, v61
	v_rcp_f32_e32 v63, v63
	v_mul_f32_e32 v64, v155, v155
	v_pk_mul_f32 v[42:43], v[50:51], v[42:43]
	v_pk_mul_f32 v[40:41], v[48:49], v[40:41]
	v_pk_mul_f32 v[44:45], v[44:45], v[64:65] op_sel_hi:[1,0]
	v_pk_mul_f32 v[46:47], v[46:47], v[64:65] op_sel_hi:[1,0]
	v_pk_mul_f32 v[40:41], v[40:41], v[64:65] op_sel_hi:[1,0]
	v_pk_mul_f32 v[42:43], v[42:43], v[64:65] op_sel_hi:[1,0]
	v_pk_mul_f32 v[46:47], v[46:47], v[60:61]
	v_pk_mul_f32 v[44:45], v[44:45], v[56:57]
	v_pk_mul_f32 v[48:49], v[42:43], v[62:63]
	v_pk_mul_f32 v[42:43], v[40:41], v[58:59]
	v_cvt_pk_bf16_f32 v40, v44, v45
	v_cvt_pk_bf16_f32 v41, v46, v47
	v_cvt_pk_bf16_f32 v42, v42, v43
	v_cvt_pk_bf16_f32 v43, v48, v49
	global_store_dwordx4 v[36:37], v[40:43], off offset:2048
	v_pk_mul_f32 v[26:27], v[34:35], v[26:27]
	v_pk_mul_f32 v[24:25], v[32:33], v[24:25]
	v_mul_f32_e32 v41, 0xbfb8aa3b, v152
	v_mul_f32_e32 v37, v28, v41
	v_mul_f32_e32 v43, v30, v41
	v_mul_f32_e32 v36, v32, v41
	v_exp_f32_e32 v40, v37
	v_mul_f32_e32 v37, v33, v41
	v_mul_f32_e32 v46, v29, v41
	v_mul_f32_e32 v42, v34, v41
	v_exp_f32_e32 v44, v43
	v_mul_f32_e32 v43, v35, v41
	v_mul_f32_e32 v41, v31, v41
	v_exp_f32_e32 v36, v36
	v_exp_f32_e32 v37, v37
	v_exp_f32_e32 v42, v42
	v_exp_f32_e32 v43, v43
	v_exp_f32_e32 v45, v41
	v_exp_f32_e32 v41, v46
	v_pk_add_f32 v[36:37], v[36:37], 1.0 op_sel_hi:[1,0]
	v_pk_add_f32 v[42:43], v[42:43], 1.0 op_sel_hi:[1,0]
	v_pk_add_f32 v[44:45], v[44:45], 1.0 op_sel_hi:[1,0]
	v_pk_add_f32 v[40:41], v[40:41], 1.0 op_sel_hi:[1,0]
	v_rcp_f32_e32 v36, v36
	v_rcp_f32_e32 v40, v40
	v_rcp_f32_e32 v37, v37
	v_rcp_f32_e32 v41, v41
	v_rcp_f32_e32 v42, v42
	v_rcp_f32_e32 v44, v44
	v_rcp_f32_e32 v43, v43
	v_rcp_f32_e32 v45, v45
	v_mul_f32_e32 v46, v152, v152
	v_pk_mul_f32 v[22:23], v[30:31], v[22:23]
	v_pk_mul_f32 v[20:21], v[28:29], v[20:21]
	v_pk_mul_f32 v[24:25], v[24:25], v[46:47] op_sel_hi:[1,0]
	v_pk_mul_f32 v[26:27], v[26:27], v[46:47] op_sel_hi:[1,0]
	v_pk_mul_f32 v[20:21], v[20:21], v[46:47] op_sel_hi:[1,0]
	v_pk_mul_f32 v[22:23], v[22:23], v[46:47] op_sel_hi:[1,0]
	v_pk_mul_f32 v[26:27], v[26:27], v[42:43]
	v_pk_mul_f32 v[24:25], v[24:25], v[36:37]
	v_pk_mul_f32 v[28:29], v[22:23], v[44:45]
	v_pk_mul_f32 v[22:23], v[20:21], v[40:41]
	v_cvt_pk_bf16_f32 v20, v24, v25
	v_cvt_pk_bf16_f32 v21, v26, v27
	v_cvt_pk_bf16_f32 v22, v22, v23
	v_cvt_pk_bf16_f32 v23, v28, v29
	global_store_dwordx4 v[38:39], v[20:23], off
	v_pk_mul_f32 v[10:11], v[18:19], v[10:11]
	v_pk_mul_f32 v[8:9], v[16:17], v[8:9]
	v_mul_f32_e32 v23, 0xbfb8aa3b, v153
	v_mul_f32_e32 v21, v12, v23
	v_mul_f32_e32 v25, v14, v23
	v_mul_f32_e32 v20, v16, v23
	v_exp_f32_e32 v22, v21
	v_mul_f32_e32 v21, v17, v23
	v_mul_f32_e32 v28, v13, v23
	v_mul_f32_e32 v24, v18, v23
	v_exp_f32_e32 v26, v25
	v_mul_f32_e32 v25, v19, v23
	v_mul_f32_e32 v23, v15, v23
	v_exp_f32_e32 v20, v20
	v_exp_f32_e32 v21, v21
	v_exp_f32_e32 v24, v24
	v_exp_f32_e32 v25, v25
	v_exp_f32_e32 v27, v23
	v_exp_f32_e32 v23, v28
	v_pk_add_f32 v[20:21], v[20:21], 1.0 op_sel_hi:[1,0]
	v_pk_add_f32 v[24:25], v[24:25], 1.0 op_sel_hi:[1,0]
	v_pk_add_f32 v[26:27], v[26:27], 1.0 op_sel_hi:[1,0]
	v_pk_add_f32 v[22:23], v[22:23], 1.0 op_sel_hi:[1,0]
	v_rcp_f32_e32 v20, v20
	v_rcp_f32_e32 v22, v22
	v_rcp_f32_e32 v21, v21
	v_rcp_f32_e32 v23, v23
	v_rcp_f32_e32 v24, v24
	v_rcp_f32_e32 v26, v26
	v_rcp_f32_e32 v25, v25
	v_rcp_f32_e32 v27, v27
	v_mul_f32_e32 v28, v153, v153
	v_pk_mul_f32 v[6:7], v[14:15], v[6:7]
	v_pk_mul_f32 v[4:5], v[12:13], v[4:5]
	v_pk_mul_f32 v[8:9], v[8:9], v[28:29] op_sel_hi:[1,0]
	v_pk_mul_f32 v[10:11], v[10:11], v[28:29] op_sel_hi:[1,0]
	v_pk_mul_f32 v[4:5], v[4:5], v[28:29] op_sel_hi:[1,0]
	v_pk_mul_f32 v[6:7], v[6:7], v[28:29] op_sel_hi:[1,0]
	v_pk_mul_f32 v[10:11], v[10:11], v[24:25]
	v_pk_mul_f32 v[8:9], v[8:9], v[20:21]
	v_pk_mul_f32 v[12:13], v[6:7], v[26:27]
	v_pk_mul_f32 v[6:7], v[4:5], v[22:23]
	v_cvt_pk_bf16_f32 v4, v8, v9
	v_cvt_pk_bf16_f32 v5, v10, v11
	v_cvt_pk_bf16_f32 v6, v6, v7
	v_cvt_pk_bf16_f32 v7, v12, v13
	s_andn2_b64 vcc, exec, s[2:3]
	s_mov_b64 s[2:3], -1
	v_readlane_b32 s85, v253, 33
	global_store_dwordx4 v[38:39], v[4:7], off offset:2048
	s_cbranch_vccnz .LBB0_181
	s_andn2_b64 vcc, exec, s[0:1]
	s_cbranch_vccnz .LBB0_180
	s_branch .LBB0_180

; __device__ __forceinline__ int otid() { int t = (int)threadIdx.x; asm volatile("" : "+v"(t)); return t; }
; template <class Epi, class Sched, bool ALIGN_EPI = false, bool SP2 = false, bool ABLK = false, bool BBLK = false>
; __device__ __forceinline__ void gemm_phase(PG8_LAS unsigned char* lds, const Gemm g, const Sched& S, const Epi& E) {
;     const int tid = otid(), wid = __builtin_amdgcn_readfirstlane(tid >> 6), lane = tid & 63, wr = wid >> 2, wc = wid & 3, fr = lane & 15, fq = lane >> 4;
;     const int K = g.K, nt = K / BK;
;     unsigned voffA[2], voffB[2];
; #pragma unroll
;     for (int i = 0; i < 2; ++i) { int R, C; stage_rc(tid * 16 + i * 8192, R, C); const int Rb = Epi::PERM ? ((R & ~31) + perm32(R & 31)) : R;
;         voffA[i] = ABLK ? (unsigned)(R * BK + C) * 2u : (unsigned)(R * K + C) * 2u; voffB[i] = BBLK ? (unsigned)(Rb * BK + C) * 2u : (unsigned)(Rb * K + C) * 2u; }
;     const size_t kstepB = BBLK ? (size_t)BM * BK * 2 : (size_t)(BK * 2), kstepA = ABLK ? (size_t)BM * BK * 2 : (size_t)(BK * 2);
;     const size_t hstepB = BBLK ? (size_t)HALF * BK * 2 : (size_t)HALF * K * 2, hstepA = ABLK ? (size_t)HALF * BK * 2 : (size_t)HALF * K * 2;
;     const size_t tstep = (size_t)BM * K * 2;
;     const unsigned ldsw = (unsigned)wid * 1024u;
;     const int aoff = lds_byte(wr * 64 + fr, fq * 8), boff = lds_byte(wc * 32 + fr, fq * 8);
;     ...
;     Unit cur, nxt; int ui = 0;
;     if (!S.next(0, cur)) return;
;     f32x4 acc[2][2][4][2];
; #pragma unroll
;     for (int a = 0; a < 2; ++a)
; #pragma unroll
;         for (int b = 0; b < 2; ++b)
; #pragma unroll
;             for (int m = 0; m < 4; ++m)
; #pragma unroll
;                 for (int n = 0; n < 2; ++n) acc[a][b][m][n] = (f32x4){0.f, 0.f, 0.f, 0.f};
;     bf16x8 At[4][2], B0[2][2], B1[2][2];
;     const char* cA = (const char*)g.A + (size_t)cur.pm * tstep; const char* cB = (const char*)g.Bt + (size_t)cur.pn * tstep;
;     S.a_ready(cur);
;     if constexpr (SP2) {
;         PG8_STAGE(PG8_SB(0, 0), cB, voffB); PG8_STAGE(PG8_SB(0, 1), cB + hstepB, voffB); PG8_STAGE(PG8_SA(0, 0), cA, voffA); PG8_STAGE(PG8_SA(0, 1), cA + hstepA, voffA);
;         if (wr == 1) PG8_BAR;
;         PG8_WAIT_V(2); PG8_BAR;
;         PG8_STAGE(PG8_SB(1, 0), cB + kstepB, voffB); PG8_STAGE(PG8_SA(1, 0), cA + kstepA, voffA); PG8_STAGE(PG8_SB(1, 1), cB + hstepB + kstepB, voffB);
;         PG8_WAIT_V(6); PG8_BAR;
;     } else {
.LBB0_423:
	v_bfe_i32 v5, v10, 27, 1
	v_lshlrev_b32_e32 v3, 4, v10
	v_lshrrev_b32_e32 v5, 22, v5
	v_add_u32_e32 v5, v3, v5
	v_and_b32_e32 v5, 0xfffffc00, v5
	v_sub_u32_e32 v5, v3, v5
	v_lshrrev_b32_e32 v6, 4, v5
	v_bitop3_b32 v6, v6, v5, 32 bitop3:0x6c
	v_ashrrev_i32_e32 v5, 31, v5
	v_lshrrev_b32_e32 v5, 26, v5
	v_ashrrev_i32_e32 v4, 31, v10
	v_add_u32_e32 v5, v6, v5
	v_lshrrev_b32_e32 v4, 26, v4
	v_ashrrev_i32_e32 v5, 6, v5
	v_add_u32_e32 v4, v10, v4
	v_mul_i32_i24_e32 v9, 64, v5
	v_ashrrev_i32_e32 v4, 6, v4
	v_sub_u32_e32 v6, v6, v9
	v_lshlrev_b32_e32 v7, 3, v4
	v_lshlrev_b32_e32 v8, 5, v4
	v_ashrrev_i16_sdwa v6, v1, sext(v6) dst_sel:DWORD dst_unused:UNUSED_PAD src0_sel:DWORD src1_sel:BYTE_0
	v_and_b32_e32 v7, -16, v7
	v_and_b32_e32 v8, 32, v8
	v_bfe_i32 v6, v6, 0, 16
	v_add_u32_e32 v7, v5, v7
	v_and_b32_e32 v12, 3, v5
	s_mov_b32 s0, 0x1ffffe0
	v_add_lshl_u32 v8, v8, v6, 1
	v_add_u32_e32 v3, 0x2000, v3
	v_lshlrev_b32_e32 v9, 1, v7
	v_lshrrev_b32_e32 v11, 2, v7
	v_and_or_b32 v12, v7, s0, v12
	v_lshl_add_u32 v136, v7, 7, v8
	v_ashrrev_i32_e32 v7, 31, v3
	v_lshrrev_b32_e32 v7, 22, v7
	v_and_b32_e32 v9, 24, v9
	v_and_b32_e32 v11, 4, v11
	v_add_u32_e32 v7, v3, v7
	v_or3_b32 v9, v12, v11, v9
	v_ashrrev_i32_e32 v7, 10, v7
	v_lshl_add_u32 v138, v9, 7, v8
	v_mul_i32_i24_e32 v8, 0x400, v7
	v_sub_u32_e32 v3, v3, v8
	v_lshrrev_b32_e32 v8, 4, v3
	v_bitop3_b32 v3, v8, v3, 32 bitop3:0x6c
	v_lshlrev_b32_e32 v8, 3, v7
	v_and_b32_e32 v9, -16, v8
	v_ashrrev_i32_e32 v8, 31, v3
	v_lshrrev_b32_e32 v8, 26, v8
	v_add_u32_e32 v11, v3, v8
	v_ashrrev_i32_e32 v8, 6, v11
	v_add_u32_e32 v12, v8, v9
	v_and_b32_e32 v14, 3, v8
	v_and_or_b32 v14, v12, s0, v14
	s_ashr_i32 s0, s2, 6
	v_readlane_b32 s6, v255, 43
	s_ashr_i32 s1, s2, 8
	s_lshl_b32 s24, s0, 10
	v_readlane_b32 s7, v255, 44
	s_and_b64 s[6:7], s[6:7], exec
	s_mov_b32 s5, 0x5900000
	s_cselect_b32 s5, 0x6f00000, s5
	s_add_u32 s25, s54, s5
	s_addc_u32 s26, s55, 0
	s_add_i32 s3, s3, s4
	s_ashr_i32 s4, s3, 31
	s_lshr_b32 s4, s4, 27
	s_add_i32 s4, s3, s4
	s_ashr_i32 s5, s4, 5
	s_and_b32 s4, s4, 0xffe0
	s_sub_i32 s4, s3, s4
	s_bfe_i32 s3, s4, 0x80000
	s_bfe_u32 s3, s3, 0x2000d
	s_add_i32 s6, s4, s3
	s_bfe_i32 s3, s6, 0x80000
	s_and_b32 s6, s6, 0xfc
	s_sub_i32 s4, s4, s6
	v_lshlrev_b32_e32 v9, 5, v7
	s_lshl_b32 s5, s5, 2
	s_sext_i32_i16 s7, s3
	s_sext_i32_i8 s4, s4
	v_and_b32_e32 v13, 32, v9
	v_and_b32_e32 v9, 0xc0, v11
	s_add_i32 s71, s5, s4
	s_ashr_i32 s4, s7, 2
	v_sub_u32_e32 v3, v3, v9
	s_lshr_b32 s3, s7, 2
	s_mul_hi_i32 s5, s4, 0x2c0000
	s_mul_i32 s4, s4, 0x2c0000
	v_ashrrev_i16_sdwa v3, v1, sext(v3) dst_sel:DWORD dst_unused:UNUSED_PAD src0_sel:DWORD src1_sel:BYTE_0
	s_add_u32 s16, s25, s4
	v_bfe_i32 v9, v3, 0, 16
	v_lshlrev_b32_e32 v3, 1, v12
	v_lshrrev_b32_e32 v11, 2, v12
	s_addc_u32 s17, s26, s5
	s_add_i32 s27, s24, 0
	v_and_b32_e32 v3, 24, v3
	v_and_b32_e32 v11, 4, v11
	s_add_i32 m0, s27, 0x10000
	v_or3_b32 v3, v14, v11, v3
	v_add_lshl_u32 v11, v13, v9, 1
	global_load_lds_dwordx4 v138, s[16:17]
	s_add_i32 m0, s27, 0x12000
	v_lshl_add_u32 v142, v3, 7, v11
	s_add_u32 s4, s16, 0x4000
	global_load_lds_dwordx4 v142, s[16:17]
	s_addc_u32 s5, s17, 0
	s_add_i32 m0, s27, 0x14000
	s_mul_i32 s8, s71, 0x2c0000
	global_load_lds_dwordx4 v138, s[4:5]
	s_add_i32 m0, s27, 0x16000
	s_mul_hi_i32 s6, s71, 0x2c0000
	s_add_u32 s10, s96, s8
	s_addc_u32 s11, s97, s6
	s_add_i32 s28, s27, 0x2000
	global_load_lds_dwordx4 v142, s[4:5]
	s_mov_b32 m0, s27
	s_add_u32 s4, s10, 0x4000
	v_lshl_add_u32 v140, v12, 7, v11
	global_load_lds_dwordx4 v136, s[10:11]
	s_mov_b32 m0, s28
	s_addc_u32 s5, s11, 0
	s_add_i32 s29, s27, 0x4000
	global_load_lds_dwordx4 v140, s[10:11]
	s_mov_b32 m0, s29
	s_add_i32 s30, s27, 0x6000
	global_load_lds_dwordx4 v136, s[4:5]
	s_mov_b32 m0, s30
	s_cmp_eq_u32 s1, 1
	global_load_lds_dwordx4 v140, s[4:5]
	v_readlane_b32 s4, v252, 21
	v_readlane_b32 s5, v252, 22
	s_load_dword s31, s[4:5], 0x0
	s_mov_b32 s57, s37
	s_cselect_b64 s[4:5], -1, 0
	s_cmp_lg_u32 s1, 1
	s_cbranch_scc1 .LBB0_425
.LBB0_425:
	v_lshrrev_b32_e32 v12, 1, v10
	v_and_b32_e32 v12, 24, v12
	s_lshl_b32 s0, s0, 5
	s_sext_i32_i8 s37, s3
	v_and_b32_e32 v11, 15, v10
	v_lshlrev_b32_e32 v13, 1, v12
	v_lshlrev_b32_e32 v10, 2, v10
	s_and_b32 s3, s0, 0x60
	s_waitcnt lgkmcnt(0)
	s_ashr_i32 s34, s31, 31
	v_lshl_or_b32 v3, s1, 6, v11
	v_lshl_or_b32 v11, v11, 6, v13
	s_lshl_b32 s1, s1, 13
	v_and_b32_e32 v10, 32, v10
	s_lshl_b32 s0, s3, 7
	v_bitop3_b32 v148, v11, s0, v10 bitop3:0xde
	s_add_u32 s0, s16, 0x8000
	v_mov_b32_e32 v139, v2
	v_bitop3_b32 v13, v11, s1, v10 bitop3:0xde
	s_addc_u32 s1, s17, 0
	s_add_i32 m0, s27, 0x18000
	v_lshl_add_u64 v[10:11], s[0:1], 0, v[138:139]
	v_mov_b32_e32 v143, v2
	s_waitcnt vmcnt(2)
	s_barrier
	global_load_lds_dwordx4 v[10:11], off
	s_add_i32 m0, s27, 0x1a000
	v_lshl_add_u64 v[10:11], s[0:1], 0, v[142:143]
	s_add_u32 s0, s10, 0x8000
	v_mov_b32_e32 v137, v2
	s_addc_u32 s1, s11, 0
	s_add_i32 s35, s27, 0x8000
	v_mov_b32_e32 v141, v2
	global_load_lds_dwordx4 v[10:11], off
	v_lshl_add_u64 v[10:11], s[0:1], 0, v[136:137]
	s_mov_b32 m0, s35
	s_add_i32 s70, s27, 0xa000
	global_load_lds_dwordx4 v[10:11], off
	v_lshl_add_u64 v[10:11], s[0:1], 0, v[140:141]
	s_add_u32 s0, s16, 0xc000
	s_mov_b32 m0, s70
	s_addc_u32 s1, s17, 0
	global_load_lds_dwordx4 v[10:11], off
	s_add_i32 m0, s27, 0x1c000
	v_lshl_add_u64 v[10:11], s[0:1], 0, v[138:139]
	global_load_lds_dwordx4 v[10:11], off
	v_lshl_add_u64 v[10:11], s[0:1], 0, v[142:143]
	s_add_i32 m0, s27, 0x1e000
	s_cmpk_lt_u32 s2, 0x100
	global_load_lds_dwordx4 v[10:11], off
	v_lshlrev_b32_e32 v10, 10, v4
	v_and_b32_e32 v10, 0xfffff800, v10
	v_lshl_add_u32 v5, v5, 7, v10
	v_and_b32_e32 v4, 1, v4
	v_lshl_or_b32 v4, v4, 6, v5
	v_lshl_add_u32 v144, v6, 1, v4
	v_lshlrev_b32_e32 v4, 10, v7
	v_and_b32_e32 v4, 0xfffff800, v4
	s_waitcnt vmcnt(6)
	v_lshl_add_u32 v4, v8, 7, v4
	v_and_b32_e32 v5, 1, v7
	v_lshl_or_b32 v4, v5, 6, v4
	s_cselect_b64 s[6:7], -1, 0
	v_or_b32_e32 v149, s3, v12
	v_mov_b32_e32 v145, v2
	v_lshl_add_u32 v146, v9, 1, v4
	v_mov_b32_e32 v147, v2
	s_mov_b32 s82, 0
	v_add_u32_e32 v150, 0, v13
	s_barrier
	s_branch .LBB0_428

; #define PG8_STAGE(bufoff, gbase, voff) do { _Pragma("unroll") for (int _i = 0; _i < 2; ++_i) \
;         __builtin_amdgcn_global_load_lds((const unsigned*)((const char*)(gbase) + (voff)[_i]), (PG8_LAS unsigned*)(lds + (bufoff) + ldsw + _i * 8192), 16, 0, 0); } while (0)
; #define PG8_LDA(dst, b, h) do { _Pragma("unroll") for (int m = 0; m < 4; ++m) _Pragma("unroll") for (int k = 0; k < 2; ++k) dst[m][k] = *(const PG8_LAS bf16x8*)(lds + PG8_SA(b, h) + aoff + m * 2048 + k * 1024); } while (0)
; #define PG8_LDB(dst, b, h) do { _Pragma("unroll") for (int n = 0; n < 2; ++n) _Pragma("unroll") for (int k = 0; k < 2; ++k) dst[n][k] = *(const PG8_LAS bf16x8*)(lds + PG8_SB(b, h) + boff + n * 2048 + k * 1024); } while (0)
; #define PG8_MMA(ai, bj, At, Bt) do { __builtin_amdgcn_s_setprio(1); _Pragma("unroll") for (int m = 0; m < 4; ++m) _Pragma("unroll") for (int n = 0; n < 2; ++n) _Pragma("unroll") for (int k = 0; k < 2; ++k) \
;         acc[ai][bj][m][n] = __builtin_amdgcn_mfma_f32_16x16x32_bf16(Bt[n][k], At[m][k], acc[ai][bj][m][n], 0, 0, 0); __builtin_amdgcn_s_setprio(0); } while (0)
; #define PG8_WAIT_V(n) asm volatile("s_waitcnt vmcnt(" #n ")" ::: "memory")
; #define PG8_WAIT_L(n) asm volatile("s_waitcnt lgkmcnt(" #n ")" ::: "memory")
; #define PG8_BAR __builtin_amdgcn_s_barrier()
; #define PG8_SCHED __builtin_amdgcn_sched_barrier(0)
; template <class Epi, class Sched, bool ALIGN_EPI = false, bool SP2 = false, bool ABLK = false, bool BBLK = false>
; __device__ __forceinline__ void gemm_phase(PG8_LAS unsigned char* lds, const Gemm g, const Sched& S, const Epi& E) {
;     ...
;             PG8_LDB(B0, 0, 0); PG8_LDB(B1, 0, 1); PG8_SCHED; PG8_LDA(At, 0, 0); PG8_STAGE(PG8_SA(1, 1), a1 + hstepA, voffA);
;             PG8_WAIT_V(8); PG8_WAIT_L(0); PG8_BAR; PG8_MMA(0, 0, At, B0); PG8_MMA(0, 1, At, B1); PG8_BAR; PG8_SCHED;
;     ...
; #pragma unroll
;         for (int a = 0; a < 2; ++a)
; #pragma unroll
;             for (int b = 0; b < 2; ++b)
; #pragma unroll
;                 for (int m = 0; m < 4; ++m)
; #pragma unroll
;                     for (int n = 0; n < 2; ++n) acc[a][b][m][n] = (f32x4){0.f, 0.f, 0.f, 0.f};
.LBB0_438:
	s_add_u32 s10, s10, 0xc000
	s_addc_u32 s11, s11, 0
	s_add_u32 vcc_lo, s16, 0x10000
	v_mov_b32_e32 v4, 0
	s_addc_u32 vcc_hi, s17, 0
	s_mov_b32 s13, -2
	v_mov_b32_e32 v5, v4
	v_mov_b32_e32 v6, v4
	v_mov_b32_e32 v7, v4
	v_mov_b32_e32 v8, v4
	v_mov_b32_e32 v9, v4
	v_mov_b32_e32 v10, v4
	v_mov_b32_e32 v11, v4
	v_mov_b32_e32 v12, v4
	v_mov_b32_e32 v13, v4
	v_mov_b32_e32 v14, v4
	v_mov_b32_e32 v15, v4
	v_mov_b32_e32 v16, v4
	v_mov_b32_e32 v17, v4
	v_mov_b32_e32 v18, v4
	v_mov_b32_e32 v19, v4
	v_mov_b32_e32 v28, v4
	v_mov_b32_e32 v29, v4
	v_mov_b32_e32 v30, v4
	v_mov_b32_e32 v31, v4
	v_mov_b32_e32 v32, v4
	v_mov_b32_e32 v33, v4
	v_mov_b32_e32 v34, v4
	v_mov_b32_e32 v35, v4
	v_mov_b32_e32 v48, v4
	v_mov_b32_e32 v49, v4
	v_mov_b32_e32 v50, v4
	v_mov_b32_e32 v51, v4
	v_mov_b32_e32 v52, v4
	v_mov_b32_e32 v53, v4
	v_mov_b32_e32 v54, v4
	v_mov_b32_e32 v55, v4
	v_mov_b32_e32 v20, v4
	v_mov_b32_e32 v21, v4
	v_mov_b32_e32 v22, v4
	v_mov_b32_e32 v23, v4
	v_mov_b32_e32 v24, v4
	v_mov_b32_e32 v25, v4
	v_mov_b32_e32 v26, v4
	v_mov_b32_e32 v27, v4
	v_mov_b32_e32 v40, v4
	v_mov_b32_e32 v41, v4
	v_mov_b32_e32 v42, v4
	v_mov_b32_e32 v43, v4
	v_mov_b32_e32 v44, v4
	v_mov_b32_e32 v45, v4
	v_mov_b32_e32 v46, v4
	v_mov_b32_e32 v47, v4
	v_mov_b32_e32 v56, v4
	v_mov_b32_e32 v57, v4
	v_mov_b32_e32 v58, v4
	v_mov_b32_e32 v59, v4
	v_mov_b32_e32 v60, v4
	v_mov_b32_e32 v61, v4
	v_mov_b32_e32 v62, v4
	v_mov_b32_e32 v63, v4
	v_mov_b32_e32 v64, v4
	v_mov_b32_e32 v65, v4
	v_mov_b32_e32 v66, v4
	v_mov_b32_e32 v67, v4
	v_mov_b32_e32 v68, v4
	v_mov_b32_e32 v69, v4
	v_mov_b32_e32 v70, v4
	v_mov_b32_e32 v71, v4
	v_mov_b32_e32 v72, v4
	v_mov_b32_e32 v73, v4
	v_mov_b32_e32 v74, v4
	v_mov_b32_e32 v75, v4
	v_mov_b32_e32 v76, v4
	v_mov_b32_e32 v77, v4
	v_mov_b32_e32 v78, v4
	v_mov_b32_e32 v79, v4
	v_mov_b32_e32 v80, v4
	v_mov_b32_e32 v81, v4
	v_mov_b32_e32 v82, v4
	v_mov_b32_e32 v83, v4
	v_mov_b32_e32 v84, v4
	v_mov_b32_e32 v85, v4
	v_mov_b32_e32 v86, v4
	v_mov_b32_e32 v87, v4
	v_mov_b32_e32 v96, v4
	v_mov_b32_e32 v97, v4
	v_mov_b32_e32 v98, v4
	v_mov_b32_e32 v99, v4
	v_mov_b32_e32 v100, v4
	v_mov_b32_e32 v101, v4
	v_mov_b32_e32 v102, v4
	v_mov_b32_e32 v103, v4
	v_mov_b32_e32 v112, v4
	v_mov_b32_e32 v113, v4
	v_mov_b32_e32 v114, v4
	v_mov_b32_e32 v115, v4
	v_mov_b32_e32 v116, v4
	v_mov_b32_e32 v117, v4
	v_mov_b32_e32 v118, v4
	v_mov_b32_e32 v119, v4
	v_mov_b32_e32 v88, v4
	v_mov_b32_e32 v89, v4
	v_mov_b32_e32 v90, v4
	v_mov_b32_e32 v91, v4
	v_mov_b32_e32 v92, v4
	v_mov_b32_e32 v93, v4
	v_mov_b32_e32 v94, v4
	v_mov_b32_e32 v95, v4
	v_mov_b32_e32 v104, v4
	v_mov_b32_e32 v105, v4
	v_mov_b32_e32 v106, v4
	v_mov_b32_e32 v107, v4
	v_mov_b32_e32 v108, v4
	v_mov_b32_e32 v109, v4
	v_mov_b32_e32 v110, v4
	v_mov_b32_e32 v111, v4
	v_mov_b32_e32 v120, v4
	v_mov_b32_e32 v121, v4
	v_mov_b32_e32 v122, v4
	v_mov_b32_e32 v123, v4
	v_mov_b32_e32 v124, v4
	v_mov_b32_e32 v125, v4
	v_mov_b32_e32 v126, v4
	v_mov_b32_e32 v127, v4
	v_mov_b32_e32 v128, v4
	v_mov_b32_e32 v129, v4
	v_mov_b32_e32 v130, v4
	v_mov_b32_e32 v131, v4
	v_mov_b32_e32 v132, v4
	v_mov_b32_e32 v133, v4
	v_mov_b32_e32 v134, v4
	v_mov_b32_e32 v135, v4
	s_cmp_eq_u32 s100, 0
	s_cbranch_scc0 .Lk1_FFN2
.LBB0_439:
	s_add_u32 s16, s10, 0x4000
	s_addc_u32 s17, s11, 0
	s_cmpk_eq_i32 s13, 0x54
	s_cselect_b32 s20, s0, s16
	s_cselect_b32 s21, s1, s17
	s_cselect_b32 s18, s8, vcc_lo
	s_cselect_b32 s19, s9, vcc_hi
	s_add_u32 s16, s20, 0x8000
	s_addc_u32 s17, s21, 0
	s_add_i32 s68, 0, 0x10000
	v_add_u32_e32 v36, s68, v148
	s_add_i32 s88, 0, 0x14000
	ds_read_b128 v[152:155], v36
	ds_read_b128 v[156:159], v36 offset:1024
	ds_read_b128 v[160:163], v36 offset:2048
	ds_read_b128 v[164:167], v36 offset:3072
	v_add_u32_e32 v36, s88, v148
	ds_read_b128 v[168:171], v36
	ds_read_b128 v[172:175], v36 offset:1024
	ds_read_b128 v[176:179], v36 offset:2048
	ds_read_b128 v[180:183], v36 offset:3072
	s_add_i32 m0, s27, 0xc000
	ds_read_b128 v[184:187], v150
	ds_read_b128 v[188:191], v150 offset:1024
	ds_read_b128 v[192:195], v150 offset:2048
	ds_read_b128 v[196:199], v150 offset:3072
	ds_read_b128 v[200:203], v150 offset:4096
	ds_read_b128 v[204:207], v150 offset:5120
	ds_read_b128 v[208:211], v150 offset:6144
	ds_read_b128 v[212:215], v150 offset:7168
	global_load_lds_dwordx4 v144, s[10:11]
	s_add_i32 m0, s27, 0xe000
	s_nop 0
	global_load_lds_dwordx4 v146, s[10:11]
	s_waitcnt vmcnt(8)
	s_waitcnt lgkmcnt(0)
	s_setprio 1
	s_waitcnt lgkmcnt(0)
	v_mfma_f32_16x16x32_bf16 v[132:135], v[152:155], v[184:187], v[132:135]
	v_mfma_f32_16x16x32_bf16 v[128:131], v[160:163], v[184:187], v[128:131]
	v_mfma_f32_16x16x32_bf16 v[124:127], v[152:155], v[192:195], v[124:127]
	v_mfma_f32_16x16x32_bf16 v[120:123], v[160:163], v[192:195], v[120:123]
	v_mfma_f32_16x16x32_bf16 v[108:111], v[152:155], v[200:203], v[108:111]
	v_mfma_f32_16x16x32_bf16 v[104:107], v[160:163], v[200:203], v[104:107]
	v_mfma_f32_16x16x32_bf16 v[92:95], v[152:155], v[208:211], v[92:95]
	v_mfma_f32_16x16x32_bf16 v[88:91], v[160:163], v[208:211], v[88:91]
	v_mfma_f32_16x16x32_bf16 v[132:135], v[156:159], v[188:191], v[132:135]
	v_mfma_f32_16x16x32_bf16 v[128:131], v[164:167], v[188:191], v[128:131]
	v_mfma_f32_16x16x32_bf16 v[124:127], v[156:159], v[196:199], v[124:127]
	v_mfma_f32_16x16x32_bf16 v[120:123], v[164:167], v[196:199], v[120:123]
	v_mfma_f32_16x16x32_bf16 v[108:111], v[156:159], v[204:207], v[108:111]
	v_mfma_f32_16x16x32_bf16 v[104:107], v[164:167], v[204:207], v[104:107]
	v_mfma_f32_16x16x32_bf16 v[92:95], v[156:159], v[212:215], v[92:95]
	v_mfma_f32_16x16x32_bf16 v[88:91], v[164:167], v[212:215], v[88:91]
	s_setprio 0
	s_setprio 1
	v_mfma_f32_16x16x32_bf16 v[116:119], v[168:171], v[184:187], v[116:119]
	v_mfma_f32_16x16x32_bf16 v[112:115], v[176:179], v[184:187], v[112:115]
	v_mfma_f32_16x16x32_bf16 v[100:103], v[168:171], v[192:195], v[100:103]
	v_mfma_f32_16x16x32_bf16 v[96:99], v[176:179], v[192:195], v[96:99]
	v_mfma_f32_16x16x32_bf16 v[84:87], v[168:171], v[200:203], v[84:87]
	v_mfma_f32_16x16x32_bf16 v[80:83], v[176:179], v[200:203], v[80:83]
	v_mfma_f32_16x16x32_bf16 v[76:79], v[168:171], v[208:211], v[76:79]
	v_mfma_f32_16x16x32_bf16 v[72:75], v[176:179], v[208:211], v[72:75]
	v_mfma_f32_16x16x32_bf16 v[116:119], v[172:175], v[188:191], v[116:119]
	v_mfma_f32_16x16x32_bf16 v[112:115], v[180:183], v[188:191], v[112:115]
	v_mfma_f32_16x16x32_bf16 v[100:103], v[172:175], v[196:199], v[100:103]
	v_mfma_f32_16x16x32_bf16 v[96:99], v[180:183], v[196:199], v[96:99]
	v_mfma_f32_16x16x32_bf16 v[84:87], v[172:175], v[204:207], v[84:87]
	v_mfma_f32_16x16x32_bf16 v[80:83], v[180:183], v[204:207], v[80:83]
	v_mfma_f32_16x16x32_bf16 v[76:79], v[172:175], v[212:215], v[76:79]
	v_mfma_f32_16x16x32_bf16 v[72:75], v[180:183], v[212:215], v[72:75]
	s_setprio 0
	s_barrier
; #define PG8_STAGE(bufoff, gbase, voff) do { _Pragma("unroll") for (int _i = 0; _i < 2; ++_i) \
;         __builtin_amdgcn_global_load_lds((const unsigned*)((const char*)(gbase) + (voff)[_i]), (PG8_LAS unsigned*)(lds + (bufoff) + ldsw + _i * 8192), 16, 0, 0); } while (0)
; #define PG8_LDA(dst, b, h) do { _Pragma("unroll") for (int m = 0; m < 4; ++m) _Pragma("unroll") for (int k = 0; k < 2; ++k) dst[m][k] = *(const PG8_LAS bf16x8*)(lds + PG8_SA(b, h) + aoff + m * 2048 + k * 1024); } while (0)
; #define PG8_LDB(dst, b, h) do { _Pragma("unroll") for (int n = 0; n < 2; ++n) _Pragma("unroll") for (int k = 0; k < 2; ++k) dst[n][k] = *(const PG8_LAS bf16x8*)(lds + PG8_SB(b, h) + boff + n * 2048 + k * 1024); } while (0)
; #define PG8_MMA(ai, bj, At, Bt) do { __builtin_amdgcn_s_setprio(1); _Pragma("unroll") for (int m = 0; m < 4; ++m) _Pragma("unroll") for (int n = 0; n < 2; ++n) _Pragma("unroll") for (int k = 0; k < 2; ++k) \
;         acc[ai][bj][m][n] = __builtin_amdgcn_mfma_f32_16x16x32_bf16(Bt[n][k], At[m][k], acc[ai][bj][m][n], 0, 0, 0); __builtin_amdgcn_s_setprio(0); } while (0)
; #define PG8_WAIT_V(n) asm volatile("s_waitcnt vmcnt(" #n ")" ::: "memory")
; #define PG8_WAIT_L(n) asm volatile("s_waitcnt lgkmcnt(" #n ")" ::: "memory")
; #define PG8_BAR __builtin_amdgcn_s_barrier()
; #define PG8_SCHED __builtin_amdgcn_sched_barrier(0)
; template <class Epi, class Sched, bool ALIGN_EPI = false, bool SP2 = false, bool ABLK = false, bool BBLK = false>
; __device__ __forceinline__ void gemm_phase(PG8_LAS unsigned char* lds, const Gemm g, const Sched& S, const Epi& E) {
;     ...
;             PG8_WAIT_V(8); PG8_WAIT_L(0); PG8_BAR; PG8_MMA(0, 0, At, B0); PG8_MMA(0, 1, At, B1); PG8_BAR; PG8_SCHED;
;             PG8_LDA(At, 0, 1); PG8_STAGE(PG8_SB(0, 0), b2, voffB); PG8_STAGE(PG8_SB(0, 1), b2 + hstepB, voffB); PG8_STAGE(PG8_SA(0, 0), a2, voffA);
;             PG8_WAIT_V(8); PG8_WAIT_L(0); PG8_BAR; PG8_MMA(1, 0, At, B0); PG8_MMA(1, 1, At, B1); PG8_BAR; PG8_SCHED;
;             PG8_LDB(B0, 1, 0); PG8_LDB(B1, 1, 1); PG8_SCHED; PG8_LDA(At, 1, 0); PG8_STAGE(PG8_SA(0, 1), a2 + hstepA, voffA);
;             PG8_WAIT_V(8); PG8_WAIT_L(0); PG8_BAR; PG8_MMA(0, 0, At, B0); PG8_MMA(0, 1, At, B1); PG8_BAR; PG8_SCHED;
	s_add_i32 s68, s68, s24
	s_mov_b32 m0, s68
	ds_read_b128 v[184:187], v150 offset:16384
	ds_read_b128 v[188:191], v150 offset:17408
	ds_read_b128 v[192:195], v150 offset:18432
	ds_read_b128 v[196:199], v150 offset:19456
	ds_read_b128 v[200:203], v150 offset:20480
	ds_read_b128 v[204:207], v150 offset:21504
	ds_read_b128 v[208:211], v150 offset:22528
	ds_read_b128 v[212:215], v150 offset:23552
	global_load_lds_dwordx4 v138, s[18:19]
	s_add_i32 m0, s68, 0x2000
	s_add_u32 s68, s18, 0x4000
	s_addc_u32 s69, s19, 0
	s_add_i32 s88, s88, s24
	global_load_lds_dwordx4 v142, s[18:19]
	s_mov_b32 m0, s88
	s_nop 0
	global_load_lds_dwordx4 v138, s[68:69]
	s_add_i32 m0, s88, 0x2000
	s_nop 0
	global_load_lds_dwordx4 v142, s[68:69]
	s_mov_b32 m0, s27
	s_nop 0
	global_load_lds_dwordx4 v136, s[20:21]
	s_mov_b32 m0, s28
	s_nop 0
	global_load_lds_dwordx4 v140, s[20:21]
	s_waitcnt vmcnt(8)
	s_waitcnt lgkmcnt(0)
	s_setprio 1
	s_waitcnt lgkmcnt(0)
	v_mfma_f32_16x16x32_bf16 v[68:71], v[152:155], v[184:187], v[68:71]
	v_mfma_f32_16x16x32_bf16 v[64:67], v[160:163], v[184:187], v[64:67]
	v_mfma_f32_16x16x32_bf16 v[60:63], v[152:155], v[192:195], v[60:63]
	v_mfma_f32_16x16x32_bf16 v[56:59], v[160:163], v[192:195], v[56:59]
	v_mfma_f32_16x16x32_bf16 v[44:47], v[152:155], v[200:203], v[44:47]
	v_mfma_f32_16x16x32_bf16 v[40:43], v[160:163], v[200:203], v[40:43]
	v_mfma_f32_16x16x32_bf16 v[24:27], v[152:155], v[208:211], v[24:27]
	v_mfma_f32_16x16x32_bf16 v[20:23], v[160:163], v[208:211], v[20:23]
	v_mfma_f32_16x16x32_bf16 v[68:71], v[156:159], v[188:191], v[68:71]
	v_mfma_f32_16x16x32_bf16 v[64:67], v[164:167], v[188:191], v[64:67]
	v_mfma_f32_16x16x32_bf16 v[60:63], v[156:159], v[196:199], v[60:63]
	v_mfma_f32_16x16x32_bf16 v[56:59], v[164:167], v[196:199], v[56:59]
	v_mfma_f32_16x16x32_bf16 v[44:47], v[156:159], v[204:207], v[44:47]
	v_mfma_f32_16x16x32_bf16 v[40:43], v[164:167], v[204:207], v[40:43]
	v_mfma_f32_16x16x32_bf16 v[24:27], v[156:159], v[212:215], v[24:27]
	v_mfma_f32_16x16x32_bf16 v[20:23], v[164:167], v[212:215], v[20:23]
	s_setprio 0
	s_setprio 1
	v_mfma_f32_16x16x32_bf16 v[52:55], v[168:171], v[184:187], v[52:55]
	v_mfma_f32_16x16x32_bf16 v[48:51], v[176:179], v[184:187], v[48:51]
	v_mfma_f32_16x16x32_bf16 v[32:35], v[168:171], v[192:195], v[32:35]
	v_mfma_f32_16x16x32_bf16 v[28:31], v[176:179], v[192:195], v[28:31]
	v_mfma_f32_16x16x32_bf16 v[16:19], v[168:171], v[200:203], v[16:19]
	v_mfma_f32_16x16x32_bf16 v[12:15], v[176:179], v[200:203], v[12:15]
	v_mfma_f32_16x16x32_bf16 v[8:11], v[168:171], v[208:211], v[8:11]
	v_mfma_f32_16x16x32_bf16 v[4:7], v[176:179], v[208:211], v[4:7]
	v_mfma_f32_16x16x32_bf16 v[52:55], v[172:175], v[188:191], v[52:55]
	v_mfma_f32_16x16x32_bf16 v[48:51], v[180:183], v[188:191], v[48:51]
	v_mfma_f32_16x16x32_bf16 v[32:35], v[172:175], v[196:199], v[32:35]
	v_mfma_f32_16x16x32_bf16 v[28:31], v[180:183], v[196:199], v[28:31]
	v_mfma_f32_16x16x32_bf16 v[16:19], v[172:175], v[204:207], v[16:19]
	v_mfma_f32_16x16x32_bf16 v[12:15], v[180:183], v[204:207], v[12:15]
	v_mfma_f32_16x16x32_bf16 v[8:11], v[172:175], v[212:215], v[8:11]
	v_mfma_f32_16x16x32_bf16 v[4:7], v[180:183], v[212:215], v[4:7]
	s_setprio 0
	s_barrier
	s_add_i32 s68, 0, 0x18000
	v_add_u32_e32 v36, s68, v148
	s_add_i32 s69, 0, 0x1c000
	ds_read_b128 v[152:155], v36
	ds_read_b128 v[156:159], v36 offset:1024
	ds_read_b128 v[160:163], v36 offset:2048
	ds_read_b128 v[164:167], v36 offset:3072
	v_add_u32_e32 v36, s69, v148
	ds_read_b128 v[168:171], v36
	ds_read_b128 v[172:175], v36 offset:1024
	ds_read_b128 v[176:179], v36 offset:2048
	ds_read_b128 v[180:183], v36 offset:3072
	s_add_u32 s20, s20, 0x4000
	s_addc_u32 s21, s21, 0
	s_mov_b32 m0, s29
	ds_read_b128 v[184:187], v150 offset:32768
	ds_read_b128 v[188:191], v150 offset:33792
	ds_read_b128 v[192:195], v150 offset:34816
	ds_read_b128 v[196:199], v150 offset:35840
	ds_read_b128 v[200:203], v150 offset:36864
	ds_read_b128 v[204:207], v150 offset:37888
	ds_read_b128 v[208:211], v150 offset:38912
	ds_read_b128 v[212:215], v150 offset:39936
	global_load_lds_dwordx4 v136, s[20:21]
	s_mov_b32 m0, s30
	s_nop 0
	global_load_lds_dwordx4 v140, s[20:21]
	s_waitcnt vmcnt(8)
	s_waitcnt lgkmcnt(0)
	s_setprio 1
	s_waitcnt lgkmcnt(0)
	v_mfma_f32_16x16x32_bf16 v[132:135], v[152:155], v[184:187], v[132:135]
	v_mfma_f32_16x16x32_bf16 v[128:131], v[160:163], v[184:187], v[128:131]
	v_mfma_f32_16x16x32_bf16 v[124:127], v[152:155], v[192:195], v[124:127]
	v_mfma_f32_16x16x32_bf16 v[120:123], v[160:163], v[192:195], v[120:123]
	v_mfma_f32_16x16x32_bf16 v[108:111], v[152:155], v[200:203], v[108:111]
	v_mfma_f32_16x16x32_bf16 v[104:107], v[160:163], v[200:203], v[104:107]
	v_mfma_f32_16x16x32_bf16 v[92:95], v[152:155], v[208:211], v[92:95]
	v_mfma_f32_16x16x32_bf16 v[88:91], v[160:163], v[208:211], v[88:91]
	v_mfma_f32_16x16x32_bf16 v[132:135], v[156:159], v[188:191], v[132:135]
	v_mfma_f32_16x16x32_bf16 v[128:131], v[164:167], v[188:191], v[128:131]
	v_mfma_f32_16x16x32_bf16 v[124:127], v[156:159], v[196:199], v[124:127]
	v_mfma_f32_16x16x32_bf16 v[120:123], v[164:167], v[196:199], v[120:123]
	v_mfma_f32_16x16x32_bf16 v[108:111], v[156:159], v[204:207], v[108:111]
	v_mfma_f32_16x16x32_bf16 v[104:107], v[164:167], v[204:207], v[104:107]
	v_mfma_f32_16x16x32_bf16 v[92:95], v[156:159], v[212:215], v[92:95]
	v_mfma_f32_16x16x32_bf16 v[88:91], v[164:167], v[212:215], v[88:91]
	s_setprio 0
	s_setprio 1
	v_mfma_f32_16x16x32_bf16 v[116:119], v[168:171], v[184:187], v[116:119]
	v_mfma_f32_16x16x32_bf16 v[112:115], v[176:179], v[184:187], v[112:115]
	v_mfma_f32_16x16x32_bf16 v[100:103], v[168:171], v[192:195], v[100:103]
	v_mfma_f32_16x16x32_bf16 v[96:99], v[176:179], v[192:195], v[96:99]
	v_mfma_f32_16x16x32_bf16 v[84:87], v[168:171], v[200:203], v[84:87]
	v_mfma_f32_16x16x32_bf16 v[80:83], v[176:179], v[200:203], v[80:83]
	v_mfma_f32_16x16x32_bf16 v[76:79], v[168:171], v[208:211], v[76:79]
	v_mfma_f32_16x16x32_bf16 v[72:75], v[176:179], v[208:211], v[72:75]
	v_mfma_f32_16x16x32_bf16 v[116:119], v[172:175], v[188:191], v[116:119]
	v_mfma_f32_16x16x32_bf16 v[112:115], v[180:183], v[188:191], v[112:115]
	v_mfma_f32_16x16x32_bf16 v[100:103], v[172:175], v[196:199], v[100:103]
	v_mfma_f32_16x16x32_bf16 v[96:99], v[180:183], v[196:199], v[96:99]
	v_mfma_f32_16x16x32_bf16 v[84:87], v[172:175], v[204:207], v[84:87]
	v_mfma_f32_16x16x32_bf16 v[80:83], v[180:183], v[204:207], v[80:83]
	v_mfma_f32_16x16x32_bf16 v[76:79], v[172:175], v[212:215], v[76:79]
	v_mfma_f32_16x16x32_bf16 v[72:75], v[180:183], v[212:215], v[72:75]
	s_setprio 0
	s_barrier
; #define PG8_STAGE(bufoff, gbase, voff) do { _Pragma("unroll") for (int _i = 0; _i < 2; ++_i) \
;         __builtin_amdgcn_global_load_lds((const unsigned*)((const char*)(gbase) + (voff)[_i]), (PG8_LAS unsigned*)(lds + (bufoff) + ldsw + _i * 8192), 16, 0, 0); } while (0)
; #define PG8_LDA(dst, b, h) do { _Pragma("unroll") for (int m = 0; m < 4; ++m) _Pragma("unroll") for (int k = 0; k < 2; ++k) dst[m][k] = *(const PG8_LAS bf16x8*)(lds + PG8_SA(b, h) + aoff + m * 2048 + k * 1024); } while (0)
; #define PG8_LDB(dst, b, h) do { _Pragma("unroll") for (int n = 0; n < 2; ++n) _Pragma("unroll") for (int k = 0; k < 2; ++k) dst[n][k] = *(const PG8_LAS bf16x8*)(lds + PG8_SB(b, h) + boff + n * 2048 + k * 1024); } while (0)
; #define PG8_MMA(ai, bj, At, Bt) do { __builtin_amdgcn_s_setprio(1); _Pragma("unroll") for (int m = 0; m < 4; ++m) _Pragma("unroll") for (int n = 0; n < 2; ++n) _Pragma("unroll") for (int k = 0; k < 2; ++k) \
;         acc[ai][bj][m][n] = __builtin_amdgcn_mfma_f32_16x16x32_bf16(Bt[n][k], At[m][k], acc[ai][bj][m][n], 0, 0, 0); __builtin_amdgcn_s_setprio(0); } while (0)
; #define PG8_WAIT_V(n) asm volatile("s_waitcnt vmcnt(" #n ")" ::: "memory")
; #define PG8_WAIT_L(n) asm volatile("s_waitcnt lgkmcnt(" #n ")" ::: "memory")
; #define PG8_BAR __builtin_amdgcn_s_barrier()
; #define PG8_SCHED __builtin_amdgcn_sched_barrier(0)
; template <class Epi, class Sched, bool ALIGN_EPI = false, bool SP2 = false, bool ABLK = false, bool BBLK = false>
; __device__ __forceinline__ void gemm_phase(PG8_LAS unsigned char* lds, const Gemm g, const Sched& S, const Epi& E) {
;     ...
;             PG8_LDB(B0, 0, 0); PG8_LDB(B1, 0, 1); PG8_SCHED; PG8_LDA(At, 0, 0); PG8_STAGE(PG8_SA(1, 1), a1 + hstepA, voffA);
;             PG8_WAIT_V(8); PG8_WAIT_L(0); PG8_BAR; PG8_MMA(0, 0, At, B0); PG8_MMA(0, 1, At, B1); PG8_BAR; PG8_SCHED;
;     ...
;             PG8_LDA(At, 1, 1); PG8_STAGE(PG8_SB(1, 0), b3, voffB); PG8_STAGE(PG8_SB(1, 1), b3 + hstepB, voffB); PG8_STAGE(PG8_SA(1, 0), a3, voffA);
;             PG8_WAIT_V(8); PG8_WAIT_L(0); PG8_BAR; PG8_MMA(1, 0, At, B0); PG8_MMA(1, 1, At, B1); PG8_BAR; PG8_SCHED;
	s_add_u32 s20, s18, 0x8000
	s_addc_u32 s21, s19, 0
	s_add_i32 s68, s68, s24
	s_mov_b32 m0, s68
	ds_read_b128 v[184:187], v150 offset:49152
	ds_read_b128 v[188:191], v150 offset:50176
	ds_read_b128 v[192:195], v150 offset:51200
	ds_read_b128 v[196:199], v150 offset:52224
	ds_read_b128 v[200:203], v150 offset:53248
	ds_read_b128 v[204:207], v150 offset:54272
	ds_read_b128 v[208:211], v150 offset:55296
	ds_read_b128 v[212:215], v150 offset:56320
	global_load_lds_dwordx4 v138, s[20:21]
	s_add_i32 m0, s68, 0x2000
	s_add_u32 s18, s18, 0xc000
	s_addc_u32 s19, s19, 0
	global_load_lds_dwordx4 v142, s[20:21]
	s_add_i32 s20, s69, s24
	s_mov_b32 m0, s20
	s_nop 0
	global_load_lds_dwordx4 v138, s[18:19]
	s_add_i32 m0, s20, 0x2000
	s_nop 0
	global_load_lds_dwordx4 v142, s[18:19]
	s_mov_b32 m0, s35
	s_nop 0
	global_load_lds_dwordx4 v136, s[16:17]
	s_mov_b32 m0, s70
	s_nop 0
	global_load_lds_dwordx4 v140, s[16:17]
	s_waitcnt vmcnt(8)
	s_waitcnt lgkmcnt(0)
	s_setprio 1
	s_waitcnt lgkmcnt(0)
	v_mfma_f32_16x16x32_bf16 v[68:71], v[152:155], v[184:187], v[68:71]
	v_mfma_f32_16x16x32_bf16 v[64:67], v[160:163], v[184:187], v[64:67]
	v_mfma_f32_16x16x32_bf16 v[60:63], v[152:155], v[192:195], v[60:63]
	v_mfma_f32_16x16x32_bf16 v[56:59], v[160:163], v[192:195], v[56:59]
	v_mfma_f32_16x16x32_bf16 v[44:47], v[152:155], v[200:203], v[44:47]
	v_mfma_f32_16x16x32_bf16 v[40:43], v[160:163], v[200:203], v[40:43]
	v_mfma_f32_16x16x32_bf16 v[24:27], v[152:155], v[208:211], v[24:27]
	v_mfma_f32_16x16x32_bf16 v[20:23], v[160:163], v[208:211], v[20:23]
	v_mfma_f32_16x16x32_bf16 v[68:71], v[156:159], v[188:191], v[68:71]
	v_mfma_f32_16x16x32_bf16 v[64:67], v[164:167], v[188:191], v[64:67]
	v_mfma_f32_16x16x32_bf16 v[60:63], v[156:159], v[196:199], v[60:63]
	v_mfma_f32_16x16x32_bf16 v[56:59], v[164:167], v[196:199], v[56:59]
	v_mfma_f32_16x16x32_bf16 v[44:47], v[156:159], v[204:207], v[44:47]
	v_mfma_f32_16x16x32_bf16 v[40:43], v[164:167], v[204:207], v[40:43]
	v_mfma_f32_16x16x32_bf16 v[24:27], v[156:159], v[212:215], v[24:27]
	v_mfma_f32_16x16x32_bf16 v[20:23], v[164:167], v[212:215], v[20:23]
	s_setprio 0
	s_setprio 1
	v_mfma_f32_16x16x32_bf16 v[52:55], v[168:171], v[184:187], v[52:55]
	v_mfma_f32_16x16x32_bf16 v[48:51], v[176:179], v[184:187], v[48:51]
	v_mfma_f32_16x16x32_bf16 v[32:35], v[168:171], v[192:195], v[32:35]
	v_mfma_f32_16x16x32_bf16 v[28:31], v[176:179], v[192:195], v[28:31]
	v_mfma_f32_16x16x32_bf16 v[16:19], v[168:171], v[200:203], v[16:19]
	v_mfma_f32_16x16x32_bf16 v[12:15], v[176:179], v[200:203], v[12:15]
	v_mfma_f32_16x16x32_bf16 v[8:11], v[168:171], v[208:211], v[8:11]
	v_mfma_f32_16x16x32_bf16 v[4:7], v[176:179], v[208:211], v[4:7]
	v_mfma_f32_16x16x32_bf16 v[52:55], v[172:175], v[188:191], v[52:55]
	v_mfma_f32_16x16x32_bf16 v[48:51], v[180:183], v[188:191], v[48:51]
	v_mfma_f32_16x16x32_bf16 v[32:35], v[172:175], v[196:199], v[32:35]
	v_mfma_f32_16x16x32_bf16 v[28:31], v[180:183], v[196:199], v[28:31]
	v_mfma_f32_16x16x32_bf16 v[16:19], v[172:175], v[204:207], v[16:19]
	v_mfma_f32_16x16x32_bf16 v[12:15], v[180:183], v[204:207], v[12:15]
	v_mfma_f32_16x16x32_bf16 v[8:11], v[172:175], v[212:215], v[8:11]
	v_mfma_f32_16x16x32_bf16 v[4:7], v[180:183], v[212:215], v[4:7]
	s_setprio 0
	s_barrier
	s_add_i32 s13, s13, 2
	s_add_u32 s10, s10, 0x10000
	s_addc_u32 s11, s11, 0
	s_add_u32 vcc_lo, vcc_lo, 0x10000
	s_addc_u32 vcc_hi, vcc_hi, 0
	s_cmpk_gt_u32 s13, 0x55
	s_cbranch_scc0 .LBB0_439
	s_branch .Lkx_FFN2
.Lk1_FFN2:
	s_add_u32 s16, s10, 0x4000
	s_addc_u32 s17, s11, 0
	s_cmpk_eq_i32 s13, 0x54
	s_cselect_b32 s20, s0, s16
	s_cselect_b32 s21, s1, s17
	s_cselect_b32 s18, s8, vcc_lo
	s_cselect_b32 s19, s9, vcc_hi
	s_add_u32 s16, s20, 0x8000
	s_addc_u32 s17, s21, 0
	s_add_i32 s68, 0, 0x10000
	v_add_u32_e32 v36, s68, v148
	s_add_i32 s88, 0, 0x14000
	ds_read_b128 v[152:155], v36
	ds_read_b128 v[156:159], v36 offset:1024
	ds_read_b128 v[160:163], v36 offset:2048
	ds_read_b128 v[164:167], v36 offset:3072
	v_add_u32_e32 v36, s88, v148
	ds_read_b128 v[168:171], v36
	ds_read_b128 v[172:175], v36 offset:1024
	ds_read_b128 v[176:179], v36 offset:2048
	ds_read_b128 v[180:183], v36 offset:3072
	s_add_i32 m0, s27, 0xc000
	ds_read_b128 v[184:187], v150
	ds_read_b128 v[188:191], v150 offset:1024
	ds_read_b128 v[192:195], v150 offset:2048
	ds_read_b128 v[196:199], v150 offset:3072
	ds_read_b128 v[200:203], v150 offset:4096
	ds_read_b128 v[204:207], v150 offset:5120
	ds_read_b128 v[208:211], v150 offset:6144
	ds_read_b128 v[212:215], v150 offset:7168
	global_load_lds_dwordx4 v144, s[10:11]
	s_add_i32 m0, s27, 0xe000
	s_nop 0
	global_load_lds_dwordx4 v146, s[10:11]
	s_waitcnt vmcnt(8)
	s_waitcnt lgkmcnt(0)
	s_barrier
; #define PG8_STAGE(bufoff, gbase, voff) do { _Pragma("unroll") for (int _i = 0; _i < 2; ++_i) \
;         __builtin_amdgcn_global_load_lds((const unsigned*)((const char*)(gbase) + (voff)[_i]), (PG8_LAS unsigned*)(lds + (bufoff) + ldsw + _i * 8192), 16, 0, 0); } while (0)
; #define PG8_LDA(dst, b, h) do { _Pragma("unroll") for (int m = 0; m < 4; ++m) _Pragma("unroll") for (int k = 0; k < 2; ++k) dst[m][k] = *(const PG8_LAS bf16x8*)(lds + PG8_SA(b, h) + aoff + m * 2048 + k * 1024); } while (0)
; #define PG8_LDB(dst, b, h) do { _Pragma("unroll") for (int n = 0; n < 2; ++n) _Pragma("unroll") for (int k = 0; k < 2; ++k) dst[n][k] = *(const PG8_LAS bf16x8*)(lds + PG8_SB(b, h) + boff + n * 2048 + k * 1024); } while (0)
; #define PG8_MMA(ai, bj, At, Bt) do { __builtin_amdgcn_s_setprio(1); _Pragma("unroll") for (int m = 0; m < 4; ++m) _Pragma("unroll") for (int n = 0; n < 2; ++n) _Pragma("unroll") for (int k = 0; k < 2; ++k) \
;         acc[ai][bj][m][n] = __builtin_amdgcn_mfma_f32_16x16x32_bf16(Bt[n][k], At[m][k], acc[ai][bj][m][n], 0, 0, 0); __builtin_amdgcn_s_setprio(0); } while (0)
; #define PG8_WAIT_V(n) asm volatile("s_waitcnt vmcnt(" #n ")" ::: "memory")
; #define PG8_WAIT_L(n) asm volatile("s_waitcnt lgkmcnt(" #n ")" ::: "memory")
; #define PG8_BAR __builtin_amdgcn_s_barrier()
; #define PG8_SCHED __builtin_amdgcn_sched_barrier(0)
; template <class Epi, class Sched, bool ALIGN_EPI = false, bool SP2 = false, bool ABLK = false, bool BBLK = false>
; __device__ __forceinline__ void gemm_phase(PG8_LAS unsigned char* lds, const Gemm g, const Sched& S, const Epi& E) {
;     ...
;             PG8_WAIT_V(8); PG8_WAIT_L(0); PG8_BAR; PG8_MMA(0, 0, At, B0); PG8_MMA(0, 1, At, B1); PG8_BAR; PG8_SCHED;
;             PG8_LDA(At, 0, 1); PG8_STAGE(PG8_SB(0, 0), b2, voffB); PG8_STAGE(PG8_SB(0, 1), b2 + hstepB, voffB); PG8_STAGE(PG8_SA(0, 0), a2, voffA);
;             PG8_WAIT_V(8); PG8_WAIT_L(0); PG8_BAR; PG8_MMA(1, 0, At, B0); PG8_MMA(1, 1, At, B1); PG8_BAR; PG8_SCHED;
;             PG8_LDB(B0, 1, 0); PG8_LDB(B1, 1, 1); PG8_SCHED; PG8_LDA(At, 1, 0); PG8_STAGE(PG8_SA(0, 1), a2 + hstepA, voffA);
;             PG8_WAIT_V(8); PG8_WAIT_L(0); PG8_BAR; PG8_MMA(0, 0, At, B0); PG8_MMA(0, 1, At, B1); PG8_BAR; PG8_SCHED;
	s_setprio 2
	s_waitcnt lgkmcnt(0)
	v_mfma_f32_16x16x32_bf16 v[132:135], v[152:155], v[184:187], v[132:135]
	v_mfma_f32_16x16x32_bf16 v[128:131], v[160:163], v[184:187], v[128:131]
	v_mfma_f32_16x16x32_bf16 v[124:127], v[152:155], v[192:195], v[124:127]
	v_mfma_f32_16x16x32_bf16 v[120:123], v[160:163], v[192:195], v[120:123]
	v_mfma_f32_16x16x32_bf16 v[108:111], v[152:155], v[200:203], v[108:111]
	v_mfma_f32_16x16x32_bf16 v[104:107], v[160:163], v[200:203], v[104:107]
	v_mfma_f32_16x16x32_bf16 v[92:95], v[152:155], v[208:211], v[92:95]
	v_mfma_f32_16x16x32_bf16 v[88:91], v[160:163], v[208:211], v[88:91]
	v_mfma_f32_16x16x32_bf16 v[132:135], v[156:159], v[188:191], v[132:135]
	v_mfma_f32_16x16x32_bf16 v[128:131], v[164:167], v[188:191], v[128:131]
	v_mfma_f32_16x16x32_bf16 v[124:127], v[156:159], v[196:199], v[124:127]
	v_mfma_f32_16x16x32_bf16 v[120:123], v[164:167], v[196:199], v[120:123]
	v_mfma_f32_16x16x32_bf16 v[108:111], v[156:159], v[204:207], v[108:111]
	v_mfma_f32_16x16x32_bf16 v[104:107], v[164:167], v[204:207], v[104:107]
	v_mfma_f32_16x16x32_bf16 v[92:95], v[156:159], v[212:215], v[92:95]
	v_mfma_f32_16x16x32_bf16 v[88:91], v[164:167], v[212:215], v[88:91]
	v_mfma_f32_16x16x32_bf16 v[116:119], v[168:171], v[184:187], v[116:119]
	v_mfma_f32_16x16x32_bf16 v[112:115], v[176:179], v[184:187], v[112:115]
	v_mfma_f32_16x16x32_bf16 v[100:103], v[168:171], v[192:195], v[100:103]
	v_mfma_f32_16x16x32_bf16 v[96:99], v[176:179], v[192:195], v[96:99]
	v_mfma_f32_16x16x32_bf16 v[84:87], v[168:171], v[200:203], v[84:87]
	v_mfma_f32_16x16x32_bf16 v[80:83], v[176:179], v[200:203], v[80:83]
	v_mfma_f32_16x16x32_bf16 v[76:79], v[168:171], v[208:211], v[76:79]
	v_mfma_f32_16x16x32_bf16 v[72:75], v[176:179], v[208:211], v[72:75]
	v_mfma_f32_16x16x32_bf16 v[116:119], v[172:175], v[188:191], v[116:119]
	v_mfma_f32_16x16x32_bf16 v[112:115], v[180:183], v[188:191], v[112:115]
	v_mfma_f32_16x16x32_bf16 v[100:103], v[172:175], v[196:199], v[100:103]
	v_mfma_f32_16x16x32_bf16 v[96:99], v[180:183], v[196:199], v[96:99]
	v_mfma_f32_16x16x32_bf16 v[84:87], v[172:175], v[204:207], v[84:87]
	v_mfma_f32_16x16x32_bf16 v[80:83], v[180:183], v[204:207], v[80:83]
	v_mfma_f32_16x16x32_bf16 v[76:79], v[172:175], v[212:215], v[76:79]
	v_mfma_f32_16x16x32_bf16 v[72:75], v[180:183], v[212:215], v[72:75]
	s_setprio 0
	s_add_i32 s68, s68, s24
	s_mov_b32 m0, s68
	ds_read_b128 v[184:187], v150 offset:16384
	ds_read_b128 v[188:191], v150 offset:17408
	ds_read_b128 v[192:195], v150 offset:18432
	ds_read_b128 v[196:199], v150 offset:19456
	ds_read_b128 v[200:203], v150 offset:20480
	ds_read_b128 v[204:207], v150 offset:21504
	ds_read_b128 v[208:211], v150 offset:22528
	ds_read_b128 v[212:215], v150 offset:23552
	global_load_lds_dwordx4 v138, s[18:19]
	s_add_i32 m0, s68, 0x2000
	s_add_u32 s68, s18, 0x4000
	s_addc_u32 s69, s19, 0
	s_add_i32 s88, s88, s24
	global_load_lds_dwordx4 v142, s[18:19]
	s_mov_b32 m0, s88
	s_nop 0
	global_load_lds_dwordx4 v138, s[68:69]
	s_add_i32 m0, s88, 0x2000
	s_nop 0
	global_load_lds_dwordx4 v142, s[68:69]
	s_mov_b32 m0, s27
	s_nop 0
	global_load_lds_dwordx4 v136, s[20:21]
	s_mov_b32 m0, s28
	s_nop 0
	global_load_lds_dwordx4 v140, s[20:21]
	s_waitcnt vmcnt(8)
	s_waitcnt lgkmcnt(0)
	s_barrier
	s_setprio 2
	s_waitcnt lgkmcnt(0)
	v_mfma_f32_16x16x32_bf16 v[68:71], v[152:155], v[184:187], v[68:71]
	v_mfma_f32_16x16x32_bf16 v[64:67], v[160:163], v[184:187], v[64:67]
	v_mfma_f32_16x16x32_bf16 v[60:63], v[152:155], v[192:195], v[60:63]
	v_mfma_f32_16x16x32_bf16 v[56:59], v[160:163], v[192:195], v[56:59]
	v_mfma_f32_16x16x32_bf16 v[44:47], v[152:155], v[200:203], v[44:47]
	v_mfma_f32_16x16x32_bf16 v[40:43], v[160:163], v[200:203], v[40:43]
	v_mfma_f32_16x16x32_bf16 v[24:27], v[152:155], v[208:211], v[24:27]
	v_mfma_f32_16x16x32_bf16 v[20:23], v[160:163], v[208:211], v[20:23]
	v_mfma_f32_16x16x32_bf16 v[68:71], v[156:159], v[188:191], v[68:71]
	v_mfma_f32_16x16x32_bf16 v[64:67], v[164:167], v[188:191], v[64:67]
	v_mfma_f32_16x16x32_bf16 v[60:63], v[156:159], v[196:199], v[60:63]
	v_mfma_f32_16x16x32_bf16 v[56:59], v[164:167], v[196:199], v[56:59]
	v_mfma_f32_16x16x32_bf16 v[44:47], v[156:159], v[204:207], v[44:47]
	v_mfma_f32_16x16x32_bf16 v[40:43], v[164:167], v[204:207], v[40:43]
	v_mfma_f32_16x16x32_bf16 v[24:27], v[156:159], v[212:215], v[24:27]
	v_mfma_f32_16x16x32_bf16 v[20:23], v[164:167], v[212:215], v[20:23]
	v_mfma_f32_16x16x32_bf16 v[52:55], v[168:171], v[184:187], v[52:55]
	v_mfma_f32_16x16x32_bf16 v[48:51], v[176:179], v[184:187], v[48:51]
	v_mfma_f32_16x16x32_bf16 v[32:35], v[168:171], v[192:195], v[32:35]
	v_mfma_f32_16x16x32_bf16 v[28:31], v[176:179], v[192:195], v[28:31]
	v_mfma_f32_16x16x32_bf16 v[16:19], v[168:171], v[200:203], v[16:19]
	v_mfma_f32_16x16x32_bf16 v[12:15], v[176:179], v[200:203], v[12:15]
	v_mfma_f32_16x16x32_bf16 v[8:11], v[168:171], v[208:211], v[8:11]
	v_mfma_f32_16x16x32_bf16 v[4:7], v[176:179], v[208:211], v[4:7]
	v_mfma_f32_16x16x32_bf16 v[52:55], v[172:175], v[188:191], v[52:55]
	v_mfma_f32_16x16x32_bf16 v[48:51], v[180:183], v[188:191], v[48:51]
	v_mfma_f32_16x16x32_bf16 v[32:35], v[172:175], v[196:199], v[32:35]
	v_mfma_f32_16x16x32_bf16 v[28:31], v[180:183], v[196:199], v[28:31]
	v_mfma_f32_16x16x32_bf16 v[16:19], v[172:175], v[204:207], v[16:19]
	v_mfma_f32_16x16x32_bf16 v[12:15], v[180:183], v[204:207], v[12:15]
	v_mfma_f32_16x16x32_bf16 v[8:11], v[172:175], v[212:215], v[8:11]
	v_mfma_f32_16x16x32_bf16 v[4:7], v[180:183], v[212:215], v[4:7]
	s_setprio 0
	s_add_i32 s68, 0, 0x18000
	v_add_u32_e32 v36, s68, v148
	s_add_i32 s69, 0, 0x1c000
	ds_read_b128 v[152:155], v36
	ds_read_b128 v[156:159], v36 offset:1024
	ds_read_b128 v[160:163], v36 offset:2048
	ds_read_b128 v[164:167], v36 offset:3072
	v_add_u32_e32 v36, s69, v148
	ds_read_b128 v[168:171], v36
	ds_read_b128 v[172:175], v36 offset:1024
	ds_read_b128 v[176:179], v36 offset:2048
	ds_read_b128 v[180:183], v36 offset:3072
	s_add_u32 s20, s20, 0x4000
	s_addc_u32 s21, s21, 0
	s_mov_b32 m0, s29
	ds_read_b128 v[184:187], v150 offset:32768
	ds_read_b128 v[188:191], v150 offset:33792
	ds_read_b128 v[192:195], v150 offset:34816
	ds_read_b128 v[196:199], v150 offset:35840
	ds_read_b128 v[200:203], v150 offset:36864
	ds_read_b128 v[204:207], v150 offset:37888
	ds_read_b128 v[208:211], v150 offset:38912
	ds_read_b128 v[212:215], v150 offset:39936
	global_load_lds_dwordx4 v136, s[20:21]
	s_mov_b32 m0, s30
	s_nop 0
	global_load_lds_dwordx4 v140, s[20:21]
	s_waitcnt vmcnt(8)
	s_waitcnt lgkmcnt(0)
	s_barrier
; #define PG8_STAGE(bufoff, gbase, voff) do { _Pragma("unroll") for (int _i = 0; _i < 2; ++_i) \
;         __builtin_amdgcn_global_load_lds((const unsigned*)((const char*)(gbase) + (voff)[_i]), (PG8_LAS unsigned*)(lds + (bufoff) + ldsw + _i * 8192), 16, 0, 0); } while (0)
; #define PG8_LDA(dst, b, h) do { _Pragma("unroll") for (int m = 0; m < 4; ++m) _Pragma("unroll") for (int k = 0; k < 2; ++k) dst[m][k] = *(const PG8_LAS bf16x8*)(lds + PG8_SA(b, h) + aoff + m * 2048 + k * 1024); } while (0)
; #define PG8_MMA(ai, bj, At, Bt) do { __builtin_amdgcn_s_setprio(1); _Pragma("unroll") for (int m = 0; m < 4; ++m) _Pragma("unroll") for (int n = 0; n < 2; ++n) _Pragma("unroll") for (int k = 0; k < 2; ++k) \
;         acc[ai][bj][m][n] = __builtin_amdgcn_mfma_f32_16x16x32_bf16(Bt[n][k], At[m][k], acc[ai][bj][m][n], 0, 0, 0); __builtin_amdgcn_s_setprio(0); } while (0)
; #define PG8_WAIT_V(n) asm volatile("s_waitcnt vmcnt(" #n ")" ::: "memory")
; #define PG8_WAIT_L(n) asm volatile("s_waitcnt lgkmcnt(" #n ")" ::: "memory")
; #define PG8_BAR __builtin_amdgcn_s_barrier()
; #define PG8_SCHED __builtin_amdgcn_sched_barrier(0)
; template <class Epi, class Sched, bool ALIGN_EPI = false, bool SP2 = false, bool ABLK = false, bool BBLK = false>
; __device__ __forceinline__ void gemm_phase(PG8_LAS unsigned char* lds, const Gemm g, const Sched& S, const Epi& E) {
;     ...
;             PG8_WAIT_V(8); PG8_WAIT_L(0); PG8_BAR; PG8_MMA(0, 0, At, B0); PG8_MMA(0, 1, At, B1); PG8_BAR; PG8_SCHED;
;             PG8_LDA(At, 1, 1); PG8_STAGE(PG8_SB(1, 0), b3, voffB); PG8_STAGE(PG8_SB(1, 1), b3 + hstepB, voffB); PG8_STAGE(PG8_SA(1, 0), a3, voffA);
;             PG8_WAIT_V(8); PG8_WAIT_L(0); PG8_BAR; PG8_MMA(1, 0, At, B0); PG8_MMA(1, 1, At, B1); PG8_BAR; PG8_SCHED;
	s_setprio 2
	s_waitcnt lgkmcnt(0)
	v_mfma_f32_16x16x32_bf16 v[132:135], v[152:155], v[184:187], v[132:135]
	v_mfma_f32_16x16x32_bf16 v[128:131], v[160:163], v[184:187], v[128:131]
	v_mfma_f32_16x16x32_bf16 v[124:127], v[152:155], v[192:195], v[124:127]
	v_mfma_f32_16x16x32_bf16 v[120:123], v[160:163], v[192:195], v[120:123]
	v_mfma_f32_16x16x32_bf16 v[108:111], v[152:155], v[200:203], v[108:111]
	v_mfma_f32_16x16x32_bf16 v[104:107], v[160:163], v[200:203], v[104:107]
	v_mfma_f32_16x16x32_bf16 v[92:95], v[152:155], v[208:211], v[92:95]
	v_mfma_f32_16x16x32_bf16 v[88:91], v[160:163], v[208:211], v[88:91]
	v_mfma_f32_16x16x32_bf16 v[132:135], v[156:159], v[188:191], v[132:135]
	v_mfma_f32_16x16x32_bf16 v[128:131], v[164:167], v[188:191], v[128:131]
	v_mfma_f32_16x16x32_bf16 v[124:127], v[156:159], v[196:199], v[124:127]
	v_mfma_f32_16x16x32_bf16 v[120:123], v[164:167], v[196:199], v[120:123]
	v_mfma_f32_16x16x32_bf16 v[108:111], v[156:159], v[204:207], v[108:111]
	v_mfma_f32_16x16x32_bf16 v[104:107], v[164:167], v[204:207], v[104:107]
	v_mfma_f32_16x16x32_bf16 v[92:95], v[156:159], v[212:215], v[92:95]
	v_mfma_f32_16x16x32_bf16 v[88:91], v[164:167], v[212:215], v[88:91]
	v_mfma_f32_16x16x32_bf16 v[116:119], v[168:171], v[184:187], v[116:119]
	v_mfma_f32_16x16x32_bf16 v[112:115], v[176:179], v[184:187], v[112:115]
	v_mfma_f32_16x16x32_bf16 v[100:103], v[168:171], v[192:195], v[100:103]
	v_mfma_f32_16x16x32_bf16 v[96:99], v[176:179], v[192:195], v[96:99]
	v_mfma_f32_16x16x32_bf16 v[84:87], v[168:171], v[200:203], v[84:87]
	v_mfma_f32_16x16x32_bf16 v[80:83], v[176:179], v[200:203], v[80:83]
	v_mfma_f32_16x16x32_bf16 v[76:79], v[168:171], v[208:211], v[76:79]
	v_mfma_f32_16x16x32_bf16 v[72:75], v[176:179], v[208:211], v[72:75]
	v_mfma_f32_16x16x32_bf16 v[116:119], v[172:175], v[188:191], v[116:119]
	v_mfma_f32_16x16x32_bf16 v[112:115], v[180:183], v[188:191], v[112:115]
	v_mfma_f32_16x16x32_bf16 v[100:103], v[172:175], v[196:199], v[100:103]
	v_mfma_f32_16x16x32_bf16 v[96:99], v[180:183], v[196:199], v[96:99]
	v_mfma_f32_16x16x32_bf16 v[84:87], v[172:175], v[204:207], v[84:87]
	v_mfma_f32_16x16x32_bf16 v[80:83], v[180:183], v[204:207], v[80:83]
	v_mfma_f32_16x16x32_bf16 v[76:79], v[172:175], v[212:215], v[76:79]
	v_mfma_f32_16x16x32_bf16 v[72:75], v[180:183], v[212:215], v[72:75]
	s_setprio 0
	s_add_u32 s20, s18, 0x8000
	s_addc_u32 s21, s19, 0
	s_add_i32 s68, s68, s24
	s_mov_b32 m0, s68
	ds_read_b128 v[184:187], v150 offset:49152
	ds_read_b128 v[188:191], v150 offset:50176
	ds_read_b128 v[192:195], v150 offset:51200
	ds_read_b128 v[196:199], v150 offset:52224
	ds_read_b128 v[200:203], v150 offset:53248
	ds_read_b128 v[204:207], v150 offset:54272
	ds_read_b128 v[208:211], v150 offset:55296
	ds_read_b128 v[212:215], v150 offset:56320
	global_load_lds_dwordx4 v138, s[20:21]
	s_add_i32 m0, s68, 0x2000
	s_add_u32 s18, s18, 0xc000
	s_addc_u32 s19, s19, 0
	global_load_lds_dwordx4 v142, s[20:21]
	s_add_i32 s20, s69, s24
	s_mov_b32 m0, s20
	s_nop 0
	global_load_lds_dwordx4 v138, s[18:19]
	s_add_i32 m0, s20, 0x2000
	s_nop 0
	global_load_lds_dwordx4 v142, s[18:19]
	s_mov_b32 m0, s35
	s_nop 0
	global_load_lds_dwordx4 v136, s[16:17]
	s_mov_b32 m0, s70
	s_nop 0
	global_load_lds_dwordx4 v140, s[16:17]
	s_waitcnt vmcnt(8)
	s_waitcnt lgkmcnt(0)
	s_barrier
	s_setprio 2
	s_waitcnt lgkmcnt(0)
	v_mfma_f32_16x16x32_bf16 v[68:71], v[152:155], v[184:187], v[68:71]
	v_mfma_f32_16x16x32_bf16 v[64:67], v[160:163], v[184:187], v[64:67]
	v_mfma_f32_16x16x32_bf16 v[60:63], v[152:155], v[192:195], v[60:63]
	v_mfma_f32_16x16x32_bf16 v[56:59], v[160:163], v[192:195], v[56:59]
	v_mfma_f32_16x16x32_bf16 v[44:47], v[152:155], v[200:203], v[44:47]
	v_mfma_f32_16x16x32_bf16 v[40:43], v[160:163], v[200:203], v[40:43]
	v_mfma_f32_16x16x32_bf16 v[24:27], v[152:155], v[208:211], v[24:27]
	v_mfma_f32_16x16x32_bf16 v[20:23], v[160:163], v[208:211], v[20:23]
	v_mfma_f32_16x16x32_bf16 v[68:71], v[156:159], v[188:191], v[68:71]
	v_mfma_f32_16x16x32_bf16 v[64:67], v[164:167], v[188:191], v[64:67]
	v_mfma_f32_16x16x32_bf16 v[60:63], v[156:159], v[196:199], v[60:63]
	v_mfma_f32_16x16x32_bf16 v[56:59], v[164:167], v[196:199], v[56:59]
	v_mfma_f32_16x16x32_bf16 v[44:47], v[156:159], v[204:207], v[44:47]
	v_mfma_f32_16x16x32_bf16 v[40:43], v[164:167], v[204:207], v[40:43]
	v_mfma_f32_16x16x32_bf16 v[24:27], v[156:159], v[212:215], v[24:27]
	v_mfma_f32_16x16x32_bf16 v[20:23], v[164:167], v[212:215], v[20:23]
	v_mfma_f32_16x16x32_bf16 v[52:55], v[168:171], v[184:187], v[52:55]
	v_mfma_f32_16x16x32_bf16 v[48:51], v[176:179], v[184:187], v[48:51]
	v_mfma_f32_16x16x32_bf16 v[32:35], v[168:171], v[192:195], v[32:35]
	v_mfma_f32_16x16x32_bf16 v[28:31], v[176:179], v[192:195], v[28:31]
	v_mfma_f32_16x16x32_bf16 v[16:19], v[168:171], v[200:203], v[16:19]
	v_mfma_f32_16x16x32_bf16 v[12:15], v[176:179], v[200:203], v[12:15]
	v_mfma_f32_16x16x32_bf16 v[8:11], v[168:171], v[208:211], v[8:11]
	v_mfma_f32_16x16x32_bf16 v[4:7], v[176:179], v[208:211], v[4:7]
	v_mfma_f32_16x16x32_bf16 v[52:55], v[172:175], v[188:191], v[52:55]
	v_mfma_f32_16x16x32_bf16 v[48:51], v[180:183], v[188:191], v[48:51]
	v_mfma_f32_16x16x32_bf16 v[32:35], v[172:175], v[196:199], v[32:35]
	v_mfma_f32_16x16x32_bf16 v[28:31], v[180:183], v[196:199], v[28:31]
	v_mfma_f32_16x16x32_bf16 v[16:19], v[172:175], v[204:207], v[16:19]
	v_mfma_f32_16x16x32_bf16 v[12:15], v[180:183], v[204:207], v[12:15]
	v_mfma_f32_16x16x32_bf16 v[8:11], v[172:175], v[212:215], v[8:11]
	v_mfma_f32_16x16x32_bf16 v[4:7], v[180:183], v[212:215], v[4:7]
	s_setprio 0
	s_add_i32 s13, s13, 2
	s_add_u32 s10, s10, 0x10000
	s_addc_u32 s11, s11, 0
	s_add_u32 vcc_lo, vcc_lo, 0x10000
	s_addc_u32 vcc_hi, vcc_hi, 0
	s_cmpk_gt_u32 s13, 0x55
	s_cbranch_scc0 .Lk1_FFN2
; __device__ __forceinline__ unsigned cvt_pk_bf16(float lo, float hi) { const hwf2_t v = {lo, hi}; return __builtin_bit_cast(unsigned, __builtin_convertvector(v, hwbf2_t)); }
; #define PG8_BAR __builtin_amdgcn_s_barrier()
;     __device__ __forceinline__ void operator()(const f32x4 (&acc)[2][2][4][2], const Unit& u, int wr, int wc, int fr, int fq, const PG8_LAS unsigned char* area) const {
;     ...
;             for (int m = 0; m < 4; ++m) { bf16_t* rowp = O + (size_t)(row0 + ai * HALF + m * 16) * ldc + col0; const float r_ = rsv[ai][m];
; #pragma unroll
;                 for (int bj = 0; bj < 2; ++bj) { const f32x4 v0 = acc[ai][bj][m][0] * r_, v1 = acc[ai][bj][m][1] * r_;
;                     u32x4 w; w.x = cvt_pk_bf16(v0[0], v0[1]); w.y = cvt_pk_bf16(v0[2], v0[3]); w.z = cvt_pk_bf16(v1[0], v1[1]); w.w = cvt_pk_bf16(v1[2], v1[3]);
;                     *(u32x4*)(rowp + bj * HALF) = w; } }
; template <class Epi, class Sched, bool ALIGN_EPI = false, bool SP2 = false, bool ABLK = false, bool BBLK = false>
; __device__ __forceinline__ void gemm_phase(PG8_LAS unsigned char* lds, const Gemm g, const Sched& S, const Epi& E) {
;     ...
;         if constexpr (ALIGN_EPI) { if (wr == 0) PG8_BAR; }
;         if constexpr (!Epi::AFTER_DRAIN) { E(acc, cur, wr, wc, fr, fq, rs_area); S.done(cur); }
;         if (!has_next) break;
; #pragma unroll
;         for (int a = 0; a < 2; ++a)
; #pragma unroll
;             for (int b = 0; b < 2; ++b)
; #pragma unroll
;                 for (int m = 0; m < 4; ++m)
; #pragma unroll
;                     for (int n = 0; n < 2; ++n) acc[a][b][m][n] = (f32x4){0.f, 0.f, 0.f, 0.f};
;         cur = nxt; cA = nA; cB = nB; ++ui;
;         if constexpr (ALIGN_EPI) { if (wr == 1) PG8_BAR; }
.Lkx_FFN2:
	s_and_b64 vcc, exec, s[6:7]
	s_cbranch_vccz .LBB0_442
.LBB0_442:
	v_lshl_add_u32 v36, s71, 8, v3
	v_ashrrev_i32_e32 v37, 31, v36
	v_lshlrev_b64 v[152:153], 12, v[36:37]
	v_cvt_pk_bf16_f32 v116, v116, v117
	v_cvt_pk_bf16_f32 v117, v118, v119
	v_cvt_pk_bf16_f32 v118, v112, v113
	v_or_b32_e32 v112, 16, v36
	v_cvt_pk_bf16_f32 v100, v100, v101
	v_cvt_pk_bf16_f32 v101, v102, v103
	v_cvt_pk_bf16_f32 v102, v96, v97
	v_or_b32_e32 v96, 32, v36
	v_or_b32_e32 v36, 48, v36
	v_lshl_or_b32 v38, s37, 8, v149
	v_ashrrev_i32_e32 v37, 31, v36
	v_ashrrev_i32_e32 v39, 31, v38
	v_ashrrev_i32_e32 v113, 31, v112
	v_lshlrev_b64 v[36:37], 12, v[36:37]
	v_lshl_add_u64 v[152:153], s[92:93], 0, v[152:153]
	v_lshlrev_b64 v[38:39], 1, v[38:39]
	v_lshlrev_b64 v[112:113], 12, v[112:113]
	v_ashrrev_i32_e32 v97, 31, v96
	v_lshl_add_u64 v[36:37], s[92:93], 0, v[36:37]
	v_lshl_add_u64 v[152:153], v[152:153], 0, v[38:39]
	v_cvt_pk_bf16_f32 v119, v114, v115
	v_lshl_add_u64 v[112:113], s[92:93], 0, v[112:113]
	v_lshlrev_b64 v[96:97], 12, v[96:97]
	v_cvt_pk_bf16_f32 v84, v84, v85
	v_cvt_pk_bf16_f32 v85, v86, v87
	v_cvt_pk_bf16_f32 v86, v80, v81
	v_cvt_pk_bf16_f32 v87, v82, v83
	v_lshl_add_u64 v[36:37], v[36:37], 0, v[38:39]
	v_cvt_pk_bf16_f32 v80, v92, v93
	v_cvt_pk_bf16_f32 v81, v94, v95
	v_cvt_pk_bf16_f32 v82, v88, v89
	v_cvt_pk_bf16_f32 v83, v90, v91
	v_cvt_pk_bf16_f32 v76, v76, v77
	v_cvt_pk_bf16_f32 v77, v78, v79
	v_cvt_pk_bf16_f32 v78, v72, v73
	v_cvt_pk_bf16_f32 v79, v74, v75
	s_mov_b64 s[10:11], 0x80000
	global_store_dwordx4 v[152:153], v[116:119], off offset:256
	v_cvt_pk_bf16_f32 v103, v98, v99
	v_lshl_add_u64 v[96:97], s[92:93], 0, v[96:97]
	v_lshl_add_u64 v[116:117], v[112:113], 0, v[38:39]
	global_store_dwordx4 v[36:37], v[80:83], off
	global_store_dwordx4 v[36:37], v[76:79], off offset:256
	v_lshl_add_u64 v[36:37], v[152:153], 0, s[10:11]
	s_mov_b32 s10, 0x80000
	global_store_dwordx4 v[116:117], v[100:103], off offset:256
	v_cvt_pk_bf16_f32 v52, v52, v53
	v_cvt_pk_bf16_f32 v53, v54, v55
	v_lshl_add_u64 v[100:101], v[96:97], 0, v[38:39]
	v_add_co_u32_e32 v38, vcc, s10, v152
	v_cvt_pk_bf16_f32 v54, v48, v49
	v_cvt_pk_bf16_f32 v55, v50, v51
	s_mov_b64 s[10:11], 0x90000
	v_cvt_pk_bf16_f32 v68, v68, v69
	v_cvt_pk_bf16_f32 v69, v70, v71
	v_cvt_pk_bf16_f32 v70, v64, v65
	v_cvt_pk_bf16_f32 v71, v66, v67
	v_addc_co_u32_e32 v39, vcc, 0, v153, vcc
	global_store_dwordx4 v[36:37], v[52:55], off offset:256
	v_lshl_add_u64 v[36:37], v[152:153], 0, s[10:11]
	s_mov_b32 s10, 0x90000
	global_store_dwordx4 v[38:39], v[68:71], off
	v_add_co_u32_e32 v38, vcc, s10, v152
	v_cvt_pk_bf16_f32 v32, v32, v33
	v_cvt_pk_bf16_f32 v33, v34, v35
	v_cvt_pk_bf16_f32 v34, v28, v29
	v_cvt_pk_bf16_f32 v35, v30, v31
	s_mov_b64 s[10:11], 0xa0000
	v_addc_co_u32_e32 v39, vcc, 0, v153, vcc
	global_store_dwordx4 v[36:37], v[32:35], off offset:256
	v_cvt_pk_bf16_f32 v16, v16, v17
	v_cvt_pk_bf16_f32 v17, v18, v19
	v_lshl_add_u64 v[32:33], v[152:153], 0, s[10:11]
	s_mov_b32 s10, 0xa0000
	v_add_co_u32_e32 v34, vcc, s10, v152
	v_cvt_pk_bf16_f32 v18, v12, v13
	v_cvt_pk_bf16_f32 v19, v14, v15
	s_mov_b64 s[10:11], 0xb0000
	v_addc_co_u32_e32 v35, vcc, 0, v153, vcc
	global_store_dwordx4 v[32:33], v[16:19], off offset:256
	v_cvt_pk_bf16_f32 v132, v132, v133
	v_cvt_pk_bf16_f32 v133, v134, v135
	v_lshl_add_u64 v[16:17], v[152:153], 0, s[10:11]
	s_mov_b32 s10, 0xb0000
	v_add_co_u32_e32 v18, vcc, s10, v152
	v_cvt_pk_bf16_f32 v134, v128, v129
	s_nop 0
	v_addc_co_u32_e32 v19, vcc, 0, v153, vcc
	v_cvt_pk_bf16_f32 v135, v130, v131
	v_cvt_pk_bf16_f32 v112, v124, v125
	v_cvt_pk_bf16_f32 v113, v126, v127
	v_cvt_pk_bf16_f32 v114, v120, v121
	v_cvt_pk_bf16_f32 v115, v122, v123
	v_cvt_pk_bf16_f32 v96, v108, v109
	v_cvt_pk_bf16_f32 v97, v110, v111
	v_cvt_pk_bf16_f32 v98, v104, v105
	v_cvt_pk_bf16_f32 v99, v106, v107
	v_cvt_pk_bf16_f32 v48, v60, v61
	v_cvt_pk_bf16_f32 v49, v62, v63
	v_cvt_pk_bf16_f32 v50, v56, v57
	v_cvt_pk_bf16_f32 v51, v58, v59
	v_cvt_pk_bf16_f32 v28, v44, v45
	v_cvt_pk_bf16_f32 v29, v46, v47
	v_cvt_pk_bf16_f32 v30, v40, v41
	v_cvt_pk_bf16_f32 v31, v42, v43
	v_cvt_pk_bf16_f32 v12, v24, v25
	v_cvt_pk_bf16_f32 v13, v26, v27
	v_cvt_pk_bf16_f32 v14, v20, v21
	v_cvt_pk_bf16_f32 v15, v22, v23
	v_cvt_pk_bf16_f32 v8, v8, v9
	v_cvt_pk_bf16_f32 v9, v10, v11
	v_cvt_pk_bf16_f32 v10, v4, v5
	v_cvt_pk_bf16_f32 v11, v6, v7
	s_and_b64 vcc, exec, s[2:3]
	s_mov_b64 s[2:3], -1
	v_readlane_b32 s85, v253, 33
	global_store_dwordx4 v[152:153], v[132:135], off
	global_store_dwordx4 v[116:117], v[112:115], off
	global_store_dwordx4 v[100:101], v[96:99], off
	global_store_dwordx4 v[100:101], v[84:87], off offset:256
	global_store_dwordx4 v[38:39], v[48:51], off
	global_store_dwordx4 v[34:35], v[28:31], off
	global_store_dwordx4 v[18:19], v[12:15], off
	global_store_dwordx4 v[16:17], v[8:11], off offset:256
	s_cbranch_vccnz .LBB0_427
	s_andn2_b64 vcc, exec, s[4:5]
	s_cbranch_vccnz .LBB0_426
	s_branch .LBB0_426

; __device__ __forceinline__ int otid() { int t = (int)threadIdx.x; asm volatile("" : "+v"(t)); return t; }
; template <class Epi, class Sched, bool ALIGN_EPI = false, bool SP2 = false, bool ABLK = false, bool BBLK = false>
; __device__ __forceinline__ void gemm_phase(PG8_LAS unsigned char* lds, const Gemm g, const Sched& S, const Epi& E) {
;     const int tid = otid(), wid = __builtin_amdgcn_readfirstlane(tid >> 6), lane = tid & 63, wr = wid >> 2, wc = wid & 3, fr = lane & 15, fq = lane >> 4;
;     const int K = g.K, nt = K / BK;
;     unsigned voffA[2], voffB[2];
; #pragma unroll
;     for (int i = 0; i < 2; ++i) { int R, C; stage_rc(tid * 16 + i * 8192, R, C); const int Rb = Epi::PERM ? ((R & ~31) + perm32(R & 31)) : R;
;         voffA[i] = ABLK ? (unsigned)(R * BK + C) * 2u : (unsigned)(R * K + C) * 2u; voffB[i] = BBLK ? (unsigned)(Rb * BK + C) * 2u : (unsigned)(Rb * K + C) * 2u; }
;     const size_t kstepB = BBLK ? (size_t)BM * BK * 2 : (size_t)(BK * 2), kstepA = ABLK ? (size_t)BM * BK * 2 : (size_t)(BK * 2);
;     const size_t hstepB = BBLK ? (size_t)HALF * BK * 2 : (size_t)HALF * K * 2, hstepA = ABLK ? (size_t)HALF * BK * 2 : (size_t)HALF * K * 2;
;     const size_t tstep = (size_t)BM * K * 2;
;     const unsigned ldsw = (unsigned)wid * 1024u;
;     const int aoff = lds_byte(wr * 64 + fr, fq * 8), boff = lds_byte(wc * 32 + fr, fq * 8);
;     ...
;     Unit cur, nxt; int ui = 0;
;     if (!S.next(0, cur)) return;
;     f32x4 acc[2][2][4][2];
; #pragma unroll
;     for (int a = 0; a < 2; ++a)
; #pragma unroll
;         for (int b = 0; b < 2; ++b)
; #pragma unroll
;             for (int m = 0; m < 4; ++m)
; #pragma unroll
;                 for (int n = 0; n < 2; ++n) acc[a][b][m][n] = (f32x4){0.f, 0.f, 0.f, 0.f};
;     bf16x8 At[4][2], B0[2][2], B1[2][2];
;     const char* cA = (const char*)g.A + (size_t)cur.pm * tstep; const char* cB = (const char*)g.Bt + (size_t)cur.pn * tstep;
;     S.a_ready(cur);
;     if constexpr (SP2) {
;         PG8_STAGE(PG8_SB(0, 0), cB, voffB); PG8_STAGE(PG8_SB(0, 1), cB + hstepB, voffB); PG8_STAGE(PG8_SA(0, 0), cA, voffA); PG8_STAGE(PG8_SA(0, 1), cA + hstepA, voffA);
;         if (wr == 1) PG8_BAR;
;         PG8_WAIT_V(2); PG8_BAR;
;         PG8_STAGE(PG8_SB(1, 0), cB + kstepB, voffB); PG8_STAGE(PG8_SA(1, 0), cA + kstepA, voffA); PG8_STAGE(PG8_SB(1, 1), cB + hstepB + kstepB, voffB);
;         PG8_WAIT_V(6); PG8_BAR;
;     } else {
.LBB0_907:
	s_waitcnt lgkmcnt(0)
	s_mov_b32 s28, s85
	v_mov_b32_e32 v6, v0
	v_readlane_b32 s0, v255, 18
	s_cmp_lt_i32 s28, s0
	v_readfirstlane_b32 s3, v6
	v_readlane_b32 s57, v254, 45
	v_readlane_b32 s86, v254, 40
	v_readlane_b32 s58, v255, 34
	v_readlane_b32 s59, v254, 39
	v_readlane_b32 s60, v255, 16
	v_readlane_b32 s61, v255, 17
	v_readlane_b32 s82, v255, 35
	v_readlane_b32 s1, v255, 19
	s_cbranch_scc0 .LBB0_923
	v_lshlrev_b32_e32 v3, 4, v6
	v_add_u32_e32 v5, 0x2000, v3
	v_ashrrev_i32_e32 v4, 31, v5
	v_lshrrev_b32_e32 v4, 22, v4
	v_add_u32_e32 v4, v5, v4
	v_ashrrev_i32_e32 v4, 10, v4
	v_mul_i32_i24_e32 v7, 0x400, v4
	v_sub_u32_e32 v5, v5, v7
	v_lshrrev_b32_e32 v7, 4, v5
	v_bitop3_b32 v7, v7, v5, 32 bitop3:0x6c
	v_ashrrev_i32_e32 v5, 31, v7
	v_lshrrev_b32_e32 v5, 26, v5
	v_add_u32_e32 v8, v7, v5
	v_lshlrev_b32_e32 v9, 3, v4
	v_ashrrev_i32_e32 v5, 6, v8
	v_and_b32_e32 v9, -16, v9
	v_add_u32_e32 v9, v5, v9
	v_and_b32_e32 v10, 3, v5
	s_mov_b32 s0, 0x1ffffe0
	v_lshrrev_b32_e32 v11, 2, v9
	v_lshlrev_b32_e32 v12, 1, v9
	v_and_b32_e32 v8, 0xc0, v8
	v_and_or_b32 v10, v9, s0, v10
	v_and_b32_e32 v11, 4, v11
	v_and_b32_e32 v12, 24, v12
	v_sub_u32_e32 v7, v7, v8
	v_or3_b32 v10, v10, v11, v12
	v_lshlrev_b32_e32 v11, 5, v4
	v_ashrrev_i16_sdwa v7, v1, sext(v7) dst_sel:DWORD dst_unused:UNUSED_PAD src0_sel:DWORD src1_sel:BYTE_0
	v_and_b32_e32 v11, 32, v11
	v_bfe_i32 v7, v7, 0, 16
	v_add_lshl_u32 v8, v11, v7, 1
	v_lshl_add_u32 v136, v10, 7, v8
	v_lshl_add_u32 v138, v9, 7, v8
	v_bfe_i32 v8, v6, 27, 1
	v_lshrrev_b32_e32 v8, 22, v8
	v_add_u32_e32 v8, v3, v8
	v_and_b32_e32 v8, 0xfffffc00, v8
	v_sub_u32_e32 v3, v3, v8
	v_lshrrev_b32_e32 v8, 4, v3
	v_bitop3_b32 v10, v8, v3, 32 bitop3:0x6c
	v_ashrrev_i32_e32 v3, 31, v3
	v_lshrrev_b32_e32 v3, 26, v3
	v_add_u32_e32 v3, v10, v3
	v_ashrrev_i32_e32 v8, 6, v3
	v_ashrrev_i32_e32 v3, 31, v6
	v_lshrrev_b32_e32 v3, 26, v3
	v_add_u32_e32 v3, v6, v3
	v_ashrrev_i32_e32 v9, 6, v3
	v_lshlrev_b32_e32 v3, 3, v9
	v_and_b32_e32 v3, -16, v3
	v_add_u32_e32 v3, v8, v3
	v_and_b32_e32 v11, 3, v8
	s_ashr_i32 s30, s28, 31
	v_and_or_b32 v11, v3, s0, v11
	s_lshr_b32 s0, s30, 29
	s_add_i32 s0, s28, s0
	s_ashr_i32 s1, s0, 3
	s_and_b32 s0, s0, -8
	s_sub_i32 s0, s28, s0
	s_lshr_b32 s2, s0, 31
	s_or_b32 s2, s2, s59
	s_mul_i32 s0, s2, s0
	s_add_i32 s0, s0, s1
	s_abs_i32 s2, s0
	s_mul_hi_u32 s4, s2, s61
	s_mul_i32 s5, s4, s60
	s_ashr_i32 s6, s3, 6
	s_ashr_i32 s1, s0, 31
	s_sub_i32 s2, s2, s5
	s_ashr_i32 s7, s3, 8
	s_lshl_b32 s29, s6, 10
	s_xor_b32 s1, s1, s82
	s_add_i32 s5, s4, 1
	s_sub_i32 s8, s2, s60
	s_cmp_ge_u32 s2, s60
	s_cselect_b32 s4, s5, s4
	s_cselect_b32 s2, s8, s2
	s_add_i32 s5, s4, 1
	v_lshrrev_b32_e32 v12, 2, v3
	v_lshlrev_b32_e32 v13, 1, v3
	s_cmp_ge_u32 s2, s60
	v_and_b32_e32 v12, 4, v12
	v_and_b32_e32 v13, 24, v13
	s_cselect_b32 s2, s5, s4
	v_or3_b32 v11, v11, v12, v13
	v_mul_i32_i24_e32 v13, 64, v8
	s_xor_b32 s2, s2, s1
	v_sub_u32_e32 v10, v10, v13
	s_sub_i32 s1, s2, s1
	v_lshlrev_b32_e32 v12, 5, v9
	v_ashrrev_i16_sdwa v10, v1, sext(v10) dst_sel:DWORD dst_unused:UNUSED_PAD src0_sel:DWORD src1_sel:BYTE_0
	s_lshl_b32 s4, s1, 2
	v_and_b32_e32 v12, 32, v12
	v_bfe_i32 v10, v10, 0, 16
	s_sub_i32 s2, 0x80, s4
	v_add_lshl_u32 v12, v12, v10, 1
	s_min_i32 s5, s2, 4
	v_lshl_add_u32 v142, v3, 7, v12
	v_cvt_f32_i32_e32 v3, s5
	s_mul_i32 s1, s1, s58
	s_sub_i32 s8, s0, s1
	v_lshl_add_u32 v140, v11, 7, v12
	v_cvt_f32_i32_e32 v11, s8
	v_rcp_iflag_f32_e32 v12, v3
	s_xor_b32 s0, s8, s5
	s_ashr_i32 s0, s0, 30
	s_or_b32 s2, s0, 1
	v_mul_f32_e32 v12, v11, v12
	v_trunc_f32_e32 v12, v12
	v_fma_f32 v11, -v12, v3, v11
	v_cvt_i32_f32_e32 v12, v12
	v_cmp_ge_f32_e64 s[0:1], |v11|, |v3|
	s_and_b64 s[0:1], s[0:1], exec
	s_cselect_b32 s0, s2, 0
	v_readfirstlane_b32 s1, v12
	s_add_i32 s2, s1, s0
	s_mul_i32 s0, s2, s5
	s_sub_i32 s0, s8, s0
	s_sext_i32_i8 s0, s0
	s_add_i32 s0, s4, s0
	s_ashr_i32 s1, s0, 31
	s_bfe_i64 s[8:9], s[2:3], 0x80000
	s_lshl_b64 s[4:5], s[0:1], 20
	s_lshl_b64 s[8:9], s[8:9], 20
	v_readlane_b32 s10, v254, 5
	v_readlane_b32 s11, v254, 6
	s_add_u32 s22, s10, s8
	s_addc_u32 s23, s11, s9
	s_add_i32 s31, s29, 0
	s_add_i32 m0, s31, 0x10000
	s_nop 0
	global_load_lds_dwordx4 v140, s[22:23]
	s_add_i32 m0, s31, 0x12000
	s_add_u32 s8, s22, 0x4000
	global_load_lds_dwordx4 v136, s[22:23]
	s_addc_u32 s9, s23, 0
	s_add_i32 m0, s31, 0x14000
	s_nop 0
	global_load_lds_dwordx4 v140, s[8:9]
	s_add_i32 m0, s31, 0x16000
	s_nop 0
	global_load_lds_dwordx4 v136, s[8:9]
	v_readlane_b32 s8, v252, 27
	v_readlane_b32 s9, v252, 28
	s_add_u32 s20, s8, s4
	s_addc_u32 s21, s9, s5
	s_add_i32 s34, s31, 0x2000
	s_mov_b32 m0, s31
	s_add_u32 s4, s20, 0x4000
	global_load_lds_dwordx4 v142, s[20:21]
	s_mov_b32 m0, s34
	s_addc_u32 s5, s21, 0
	s_add_i32 s35, s31, 0x4000
	global_load_lds_dwordx4 v138, s[20:21]
	s_mov_b32 m0, s35
	s_add_i32 s36, s31, 0x6000
	global_load_lds_dwordx4 v142, s[4:5]
	s_mov_b32 m0, s36
	s_cmp_eq_u32 s7, 1
	global_load_lds_dwordx4 v138, s[4:5]
	s_cselect_b64 s[4:5], -1, 0
	s_cmp_lg_u32 s7, 1
	s_cbranch_scc1 .LBB0_910
; __device__ __forceinline__ int otid() { int t = (int)threadIdx.x; asm volatile("" : "+v"(t)); return t; }
; #define PG8_STAGE(bufoff, gbase, voff) do { _Pragma("unroll") for (int _i = 0; _i < 2; ++_i) \
;         __builtin_amdgcn_global_load_lds((const unsigned*)((const char*)(gbase) + (voff)[_i]), (PG8_LAS unsigned*)(lds + (bufoff) + ldsw + _i * 8192), 16, 0, 0); } while (0)
; #define PG8_WAIT_V(n) asm volatile("s_waitcnt vmcnt(" #n ")" ::: "memory")
; #define PG8_BAR __builtin_amdgcn_s_barrier()
; template <class Epi, class Sched, bool ALIGN_EPI = false, bool SP2 = false, bool ABLK = false, bool BBLK = false>
; __device__ __forceinline__ void gemm_phase(PG8_LAS unsigned char* lds, const Gemm g, const Sched& S, const Epi& E) {
;     const int tid = otid(), wid = __builtin_amdgcn_readfirstlane(tid >> 6), lane = tid & 63, wr = wid >> 2, wc = wid & 3, fr = lane & 15, fq = lane >> 4;
;     const int K = g.K, nt = K / BK;
;     unsigned voffA[2], voffB[2];
; #pragma unroll
;     for (int i = 0; i < 2; ++i) { int R, C; stage_rc(tid * 16 + i * 8192, R, C); const int Rb = Epi::PERM ? ((R & ~31) + perm32(R & 31)) : R;
;         voffA[i] = ABLK ? (unsigned)(R * BK + C) * 2u : (unsigned)(R * K + C) * 2u; voffB[i] = BBLK ? (unsigned)(Rb * BK + C) * 2u : (unsigned)(Rb * K + C) * 2u; }
;     const size_t kstepB = BBLK ? (size_t)BM * BK * 2 : (size_t)(BK * 2), kstepA = ABLK ? (size_t)BM * BK * 2 : (size_t)(BK * 2);
;     const size_t hstepB = BBLK ? (size_t)HALF * BK * 2 : (size_t)HALF * K * 2, hstepA = ABLK ? (size_t)HALF * BK * 2 : (size_t)HALF * K * 2;
;     const size_t tstep = (size_t)BM * K * 2;
;     const unsigned ldsw = (unsigned)wid * 1024u;
;     const int aoff = lds_byte(wr * 64 + fr, fq * 8), boff = lds_byte(wc * 32 + fr, fq * 8);
;     ...
;         if (wr == 1) PG8_BAR;
;         PG8_WAIT_V(4); PG8_BAR;
;         PG8_STAGE(PG8_SB(1, 0), cB + kstepB, voffB); PG8_STAGE(PG8_SA(1, 0), cA + kstepA, voffA); PG8_STAGE(PG8_SB(1, 1), cB + hstepB + kstepB, voffB);
;         PG8_WAIT_V(6); PG8_BAR;
.LBB0_910:
	s_lshl_b32 s8, s7, 6
	s_lshl_b32 s1, s7, 13
	s_lshl_b32 s7, s6, 5
	s_and_b32 s13, s7, 0x60
	s_lshl_b32 s7, s13, 7
	s_add_u32 s10, s22, 0x8000
	v_mov_b32_e32 v141, v2
	s_addc_u32 s11, s23, 0
	s_add_i32 m0, s31, 0x18000
	v_lshl_add_u64 v[12:13], s[10:11], 0, v[140:141]
	v_mov_b32_e32 v137, v2
	s_waitcnt vmcnt(2)
	s_barrier
	global_load_lds_dwordx4 v[12:13], off
	s_add_i32 m0, s31, 0x1a000
	v_lshl_add_u64 v[12:13], s[10:11], 0, v[136:137]
	s_add_u32 s10, s20, 0x8000
	v_mov_b32_e32 v143, v2
	s_addc_u32 s11, s21, 0
	s_add_i32 s37, s31, 0x8000
	v_mov_b32_e32 v139, v2
	global_load_lds_dwordx4 v[12:13], off
	v_lshl_add_u64 v[12:13], s[10:11], 0, v[142:143]
	s_mov_b32 m0, s37
	s_add_i32 s62, s31, 0xa000
	global_load_lds_dwordx4 v[12:13], off
	v_lshl_add_u64 v[12:13], s[10:11], 0, v[138:139]
	s_add_u32 s10, s22, 0xc000
	s_mov_b32 m0, s62
	s_addc_u32 s11, s23, 0
	global_load_lds_dwordx4 v[12:13], off
	s_add_i32 m0, s31, 0x1c000
	v_lshl_add_u64 v[12:13], s[10:11], 0, v[140:141]
	global_load_lds_dwordx4 v[12:13], off
	v_lshl_add_u64 v[12:13], s[10:11], 0, v[136:137]
	s_add_i32 m0, s31, 0x1e000
	v_and_b32_e32 v11, 63, v6
	global_load_lds_dwordx4 v[12:13], off
	v_and_b32_e32 v12, 15, v6
	v_lshrrev_b32_e32 v6, 1, v6
	v_and_b32_e32 v6, 24, v6
	v_lshlrev_b32_e32 v13, 1, v6
	v_lshlrev_b32_e32 v154, 2, v12
	v_or_b32_e32 v3, s8, v12
	v_lshl_or_b32 v13, v12, 6, v13
	v_and_b32_e32 v12, 32, v154
	v_or_b32_e32 v156, s13, v6
	v_lshlrev_b32_e32 v6, 10, v9
	v_bitop3_b32 v14, v13, s1, v12 bitop3:0xde
	s_lshl_b32 s1, s6, 9
	v_and_b32_e32 v6, 0xfffff800, v6
	s_add_i32 s63, s1, 0
	v_lshl_add_u32 v6, v8, 7, v6
	v_and_b32_e32 v8, 1, v9
	s_add_i32 s63, s63, 0x20000
	s_ashr_i32 s9, s8, 31
	v_lshl_or_b32 v6, v8, 6, v6
	s_cmpk_lt_u32 s3, 0x100
	v_lshl_add_u32 v146, v10, 1, v6
	v_lshlrev_b32_e32 v6, 10, v4
	s_sext_i32_i8 s12, s2
	v_bitop3_b32 v155, v13, s7, v12 bitop3:0xde
	s_cselect_b64 s[6:7], -1, 0
	s_lshl_b64 s[2:3], s[8:9], 2
	v_readlane_b32 s1, v252, 25
	v_and_b32_e32 v6, 0xfffff800, v6
	s_waitcnt vmcnt(6)
	s_add_u32 s2, s1, s2
	v_readlane_b32 s1, v252, 26
	v_lshl_add_u32 v5, v5, 7, v6
	v_and_b32_e32 v4, 1, v4
	s_addc_u32 s3, s1, s3
	v_lshlrev_b32_e32 v12, 2, v11
	v_mov_b32_e32 v13, v2
	v_lshl_or_b32 v4, v4, 6, v5
	v_lshl_add_u64 v[144:145], s[2:3], 0, v[12:13]
	v_mov_b32_e32 v147, v2
	v_lshl_add_u32 v148, v7, 1, v4
	v_mov_b32_e32 v149, v2
	s_mov_b32 s64, 0
	v_add_u32_e32 v157, 0, v14
	s_barrier
	s_branch .LBB0_913

; #define PG8_LAS __attribute__((address_space(3)))
; #define PG8_STAGE(bufoff, gbase, voff) do { _Pragma("unroll") for (int _i = 0; _i < 2; ++_i) \
;         __builtin_amdgcn_global_load_lds((const unsigned*)((const char*)(gbase) + (voff)[_i]), (PG8_LAS unsigned*)(lds + (bufoff) + ldsw + _i * 8192), 16, 0, 0); } while (0)
; #define PG8_LDA(dst, b, h) do { _Pragma("unroll") for (int m = 0; m < 4; ++m) _Pragma("unroll") for (int k = 0; k < 2; ++k) dst[m][k] = *(const PG8_LAS bf16x8*)(lds + PG8_SA(b, h) + aoff + m * 2048 + k * 1024); } while (0)
; #define PG8_WAIT_V(n) asm volatile("s_waitcnt vmcnt(" #n ")" ::: "memory")
; #define PG8_BAR __builtin_amdgcn_s_barrier()
; template <class Epi, class Sched, bool ALIGN_EPI = false, bool SP2 = false, bool ABLK = false, bool BBLK = false>
; __device__ __forceinline__ void gemm_phase(PG8_LAS unsigned char* lds, const Gemm g, const Sched& S, const Epi& E) {
;     ...
;         const bool has_next = S.next(ui + 1, nxt);
;         PG8_LAS unsigned char* const rs_area = lds + STAGE_BYTES + wid * 512;
;         E.stage(cur, rs_area, wr, lane);
;         const char* nA = has_next ? (const char*)g.A + (size_t)nxt.pm * tstep : cA; const char* nB = has_next ? (const char*)g.Bt + (size_t)nxt.pn * tstep : cB;
;         for (int t = 0; t < nt; t += 2) {
;             const bool last = (t == nt - 2);
;             const char* a1 = cA + (size_t)(t + 1) * kstepA;
;             const char* a2 = last ? nA : cA + (size_t)(t + 2) * kstepA; const char* b2 = last ? nB : cB + (size_t)(t + 2) * kstepB;
;             const char* a3 = a2 + kstepA; const char* b3 = b2 + kstepB;
;             if (last && has_next) S.a_ready(nxt);
;             if constexpr (SP2) {
;             PG8_LDB(B0, 0, 0); PG8_LDB(B1, 0, 1); PG8_SCHED; PG8_LDA(At, 0, 0); PG8_STAGE(PG8_SA(1, 1), a1 + hstepA, voffA);
;             PG8_WAIT_V(8); PG8_WAIT_L(0); PG8_BAR; PG8_MMA(0, 0, At, B0); PG8_MMA(0, 1, At, B1); PG8_BAR; PG8_SCHED;
;             PG8_LDA(At, 0, 1); PG8_STAGE(PG8_SB(0, 0), b2, voffB); PG8_STAGE(PG8_SB(0, 1), b2 + hstepB, voffB); PG8_STAGE(PG8_SA(0, 0), a2, voffA);
;     ...
; #pragma unroll
;         for (int a = 0; a < 2; ++a)
; #pragma unroll
;             for (int b = 0; b < 2; ++b)
; #pragma unroll
;                 for (int m = 0; m < 4; ++m)
; #pragma unroll
;                     for (int n = 0; n < 2; ++n) acc[a][b][m][n] = (f32x4){0.f, 0.f, 0.f, 0.f};
.LBB0_915:
	s_lshl_b32 s18, s0, 8
	s_ashr_i32 s19, s18, 31
	s_mov_b32 m0, s63
	v_lshl_add_u64 v[4:5], s[18:19], 2, v[144:145]
	v_lshl_add_u64 v[6:7], v[4:5], 0, s[90:91]
	global_load_lds_dword v[4:5], off
	s_add_i32 m0, s63, 0x100
	s_mov_b32 s0, s1
	global_load_lds_dword v[6:7], off
	s_ashr_i32 s1, s1, 31
	s_lshl_b64 s[10:11], s[0:1], 20
	v_readlane_b32 s16, v252, 27
	v_readlane_b32 s17, v252, 28
	s_add_u32 s10, s16, s10
	s_addc_u32 s11, s17, s11
	s_and_b64 s[16:17], s[2:3], exec
	s_cselect_b32 s1, s11, s21
	s_cselect_b32 s19, s10, s20
	s_ashr_i32 s9, s8, 31
	s_lshl_b64 s[16:17], s[8:9], 20
	v_readlane_b32 s24, v254, 5
	v_readlane_b32 s25, v254, 6
	s_add_u32 s16, s24, s16
	s_addc_u32 s17, s25, s17
	s_and_b64 s[24:25], s[2:3], exec
	s_cselect_b32 s9, s17, s23
	s_cselect_b32 s65, s16, s22
	s_add_u32 s20, s20, 0xc000
	s_addc_u32 s21, s21, 0
	s_add_u32 s70, s22, 0x10000
	v_mov_b32_e32 v4, 0
	s_addc_u32 s71, s23, 0
	s_mov_b32 s13, -2
	v_mov_b32_e32 v5, v4
	v_mov_b32_e32 v6, v4
	v_mov_b32_e32 v7, v4
	v_mov_b32_e32 v8, v4
	v_mov_b32_e32 v9, v4
	v_mov_b32_e32 v10, v4
	v_mov_b32_e32 v11, v4
	v_mov_b32_e32 v12, v4
	v_mov_b32_e32 v13, v4
	v_mov_b32_e32 v14, v4
	v_mov_b32_e32 v15, v4
	v_mov_b32_e32 v20, v4
	v_mov_b32_e32 v21, v4
	v_mov_b32_e32 v22, v4
	v_mov_b32_e32 v23, v4
	v_mov_b32_e32 v28, v4
	v_mov_b32_e32 v29, v4
	v_mov_b32_e32 v30, v4
	v_mov_b32_e32 v31, v4
	v_mov_b32_e32 v40, v4
	v_mov_b32_e32 v41, v4
	v_mov_b32_e32 v42, v4
	v_mov_b32_e32 v43, v4
	v_mov_b32_e32 v48, v4
	v_mov_b32_e32 v49, v4
	v_mov_b32_e32 v50, v4
	v_mov_b32_e32 v51, v4
	v_mov_b32_e32 v56, v4
	v_mov_b32_e32 v57, v4
	v_mov_b32_e32 v58, v4
	v_mov_b32_e32 v59, v4
	v_mov_b32_e32 v16, v4
	v_mov_b32_e32 v17, v4
	v_mov_b32_e32 v18, v4
	v_mov_b32_e32 v19, v4
	v_mov_b32_e32 v24, v4
	v_mov_b32_e32 v25, v4
	v_mov_b32_e32 v26, v4
	v_mov_b32_e32 v27, v4
	v_mov_b32_e32 v32, v4
	v_mov_b32_e32 v33, v4
	v_mov_b32_e32 v34, v4
	v_mov_b32_e32 v35, v4
	v_mov_b32_e32 v44, v4
	v_mov_b32_e32 v45, v4
	v_mov_b32_e32 v46, v4
	v_mov_b32_e32 v47, v4
	v_mov_b32_e32 v52, v4
	v_mov_b32_e32 v53, v4
	v_mov_b32_e32 v54, v4
	v_mov_b32_e32 v55, v4
	v_mov_b32_e32 v60, v4
	v_mov_b32_e32 v61, v4
	v_mov_b32_e32 v62, v4
	v_mov_b32_e32 v63, v4
	v_mov_b32_e32 v64, v4
	v_mov_b32_e32 v65, v4
	v_mov_b32_e32 v66, v4
	v_mov_b32_e32 v67, v4
	v_mov_b32_e32 v68, v4
	v_mov_b32_e32 v69, v4
	v_mov_b32_e32 v70, v4
	v_mov_b32_e32 v71, v4
	v_mov_b32_e32 v72, v4
	v_mov_b32_e32 v73, v4
	v_mov_b32_e32 v74, v4
	v_mov_b32_e32 v75, v4
	v_mov_b32_e32 v76, v4
	v_mov_b32_e32 v77, v4
	v_mov_b32_e32 v78, v4
	v_mov_b32_e32 v79, v4
	v_mov_b32_e32 v80, v4
	v_mov_b32_e32 v81, v4
	v_mov_b32_e32 v82, v4
	v_mov_b32_e32 v83, v4
	v_mov_b32_e32 v88, v4
	v_mov_b32_e32 v89, v4
	v_mov_b32_e32 v90, v4
	v_mov_b32_e32 v91, v4
	v_mov_b32_e32 v96, v4
	v_mov_b32_e32 v97, v4
	v_mov_b32_e32 v98, v4
	v_mov_b32_e32 v99, v4
	v_mov_b32_e32 v104, v4
	v_mov_b32_e32 v105, v4
	v_mov_b32_e32 v106, v4
	v_mov_b32_e32 v107, v4
	v_mov_b32_e32 v112, v4
	v_mov_b32_e32 v113, v4
	v_mov_b32_e32 v114, v4
	v_mov_b32_e32 v115, v4
	v_mov_b32_e32 v120, v4
	v_mov_b32_e32 v121, v4
	v_mov_b32_e32 v122, v4
	v_mov_b32_e32 v123, v4
	v_mov_b32_e32 v84, v4
	v_mov_b32_e32 v85, v4
	v_mov_b32_e32 v86, v4
	v_mov_b32_e32 v87, v4
	v_mov_b32_e32 v92, v4
	v_mov_b32_e32 v93, v4
	v_mov_b32_e32 v94, v4
	v_mov_b32_e32 v95, v4
	v_mov_b32_e32 v100, v4
	v_mov_b32_e32 v101, v4
	v_mov_b32_e32 v102, v4
	v_mov_b32_e32 v103, v4
	v_mov_b32_e32 v108, v4
	v_mov_b32_e32 v109, v4
	v_mov_b32_e32 v110, v4
	v_mov_b32_e32 v111, v4
	v_mov_b32_e32 v116, v4
	v_mov_b32_e32 v117, v4
	v_mov_b32_e32 v118, v4
	v_mov_b32_e32 v119, v4
	v_mov_b32_e32 v124, v4
	v_mov_b32_e32 v125, v4
	v_mov_b32_e32 v126, v4
	v_mov_b32_e32 v127, v4
	v_mov_b32_e32 v128, v4
	v_mov_b32_e32 v129, v4
	v_mov_b32_e32 v130, v4
	v_mov_b32_e32 v131, v4
	v_mov_b32_e32 v132, v4
	v_mov_b32_e32 v133, v4
	v_mov_b32_e32 v134, v4
	v_mov_b32_e32 v135, v4
	s_cmp_eq_u32 s100, 0
	s_cbranch_scc0 .Lk1_MIN
.LBB0_916:
	s_add_u32 s22, s20, 0x4000
	s_addc_u32 s23, s21, 0
	s_cmp_eq_u32 s13, 28
	s_cselect_b32 s26, s19, s22
	s_cselect_b32 s27, s1, s23
	s_cselect_b32 s24, s65, s70
	s_cselect_b32 s25, s9, s71
	s_add_u32 s22, s26, 0x8000
	s_addc_u32 s23, s27, 0
	s_add_i32 s68, 0, 0x10000
	v_add_u32_e32 v36, s68, v155
	s_add_i32 s77, 0, 0x14000
	ds_read_b128 v[150:153], v36
	ds_read_b128 v[158:161], v36 offset:1024
	ds_read_b128 v[162:165], v36 offset:2048
	ds_read_b128 v[166:169], v36 offset:3072
	v_add_u32_e32 v36, s77, v155
	ds_read_b128 v[170:173], v36
	ds_read_b128 v[174:177], v36 offset:1024
	ds_read_b128 v[178:181], v36 offset:2048
	ds_read_b128 v[182:185], v36 offset:3072
	s_add_i32 m0, s31, 0xc000
	ds_read_b128 v[186:189], v157
	ds_read_b128 v[190:193], v157 offset:1024
	ds_read_b128 v[194:197], v157 offset:2048
	ds_read_b128 v[198:201], v157 offset:3072
	ds_read_b128 v[202:205], v157 offset:4096
	ds_read_b128 v[206:209], v157 offset:5120
	ds_read_b128 v[210:213], v157 offset:6144
	ds_read_b128 v[214:217], v157 offset:7168
	global_load_lds_dwordx4 v146, s[20:21]
	s_add_i32 m0, s31, 0xe000
	s_nop 0
	global_load_lds_dwordx4 v148, s[20:21]
	s_waitcnt vmcnt(8)
	s_waitcnt lgkmcnt(0)
	s_setprio 1
	s_waitcnt lgkmcnt(0)
; #define PG8_STAGE(bufoff, gbase, voff) do { _Pragma("unroll") for (int _i = 0; _i < 2; ++_i) \
;         __builtin_amdgcn_global_load_lds((const unsigned*)((const char*)(gbase) + (voff)[_i]), (PG8_LAS unsigned*)(lds + (bufoff) + ldsw + _i * 8192), 16, 0, 0); } while (0)
; #define PG8_LDA(dst, b, h) do { _Pragma("unroll") for (int m = 0; m < 4; ++m) _Pragma("unroll") for (int k = 0; k < 2; ++k) dst[m][k] = *(const PG8_LAS bf16x8*)(lds + PG8_SA(b, h) + aoff + m * 2048 + k * 1024); } while (0)
; #define PG8_LDB(dst, b, h) do { _Pragma("unroll") for (int n = 0; n < 2; ++n) _Pragma("unroll") for (int k = 0; k < 2; ++k) dst[n][k] = *(const PG8_LAS bf16x8*)(lds + PG8_SB(b, h) + boff + n * 2048 + k * 1024); } while (0)
; #define PG8_MMA(ai, bj, At, Bt) do { __builtin_amdgcn_s_setprio(1); _Pragma("unroll") for (int m = 0; m < 4; ++m) _Pragma("unroll") for (int n = 0; n < 2; ++n) _Pragma("unroll") for (int k = 0; k < 2; ++k) \
;         acc[ai][bj][m][n] = __builtin_amdgcn_mfma_f32_16x16x32_bf16(Bt[n][k], At[m][k], acc[ai][bj][m][n], 0, 0, 0); __builtin_amdgcn_s_setprio(0); } while (0)
; #define PG8_WAIT_V(n) asm volatile("s_waitcnt vmcnt(" #n ")" ::: "memory")
; #define PG8_WAIT_L(n) asm volatile("s_waitcnt lgkmcnt(" #n ")" ::: "memory")
; #define PG8_BAR __builtin_amdgcn_s_barrier()
; #define PG8_SCHED __builtin_amdgcn_sched_barrier(0)
; template <class Epi, class Sched, bool ALIGN_EPI = false, bool SP2 = false, bool ABLK = false, bool BBLK = false>
; __device__ __forceinline__ void gemm_phase(PG8_LAS unsigned char* lds, const Gemm g, const Sched& S, const Epi& E) {
;     ...
;             PG8_LDB(B0, 0, 0); PG8_LDB(B1, 0, 1); PG8_SCHED; PG8_LDA(At, 0, 0); PG8_STAGE(PG8_SA(1, 1), a1 + hstepA, voffA);
;             PG8_WAIT_V(8); PG8_WAIT_L(0); PG8_BAR; PG8_MMA(0, 0, At, B0); PG8_MMA(0, 1, At, B1); PG8_BAR; PG8_SCHED;
;             PG8_LDA(At, 0, 1); PG8_STAGE(PG8_SB(0, 0), b2, voffB); PG8_STAGE(PG8_SB(0, 1), b2 + hstepB, voffB); PG8_STAGE(PG8_SA(0, 0), a2, voffA);
;             PG8_WAIT_V(8); PG8_WAIT_L(0); PG8_BAR; PG8_MMA(1, 0, At, B0); PG8_MMA(1, 1, At, B1); PG8_BAR; PG8_SCHED;
	v_mfma_f32_16x16x32_bf16 v[132:135], v[150:153], v[186:189], v[132:135]
	v_mfma_f32_16x16x32_bf16 v[128:131], v[162:165], v[186:189], v[128:131]
	v_mfma_f32_16x16x32_bf16 v[124:127], v[150:153], v[194:197], v[124:127]
	v_mfma_f32_16x16x32_bf16 v[116:119], v[162:165], v[194:197], v[116:119]
	v_mfma_f32_16x16x32_bf16 v[108:111], v[150:153], v[202:205], v[108:111]
	v_mfma_f32_16x16x32_bf16 v[100:103], v[162:165], v[202:205], v[100:103]
	v_mfma_f32_16x16x32_bf16 v[92:95], v[150:153], v[210:213], v[92:95]
	v_mfma_f32_16x16x32_bf16 v[84:87], v[162:165], v[210:213], v[84:87]
	v_mfma_f32_16x16x32_bf16 v[132:135], v[158:161], v[190:193], v[132:135]
	v_mfma_f32_16x16x32_bf16 v[128:131], v[166:169], v[190:193], v[128:131]
	v_mfma_f32_16x16x32_bf16 v[124:127], v[158:161], v[198:201], v[124:127]
	v_mfma_f32_16x16x32_bf16 v[116:119], v[166:169], v[198:201], v[116:119]
	v_mfma_f32_16x16x32_bf16 v[108:111], v[158:161], v[206:209], v[108:111]
	v_mfma_f32_16x16x32_bf16 v[100:103], v[166:169], v[206:209], v[100:103]
	v_mfma_f32_16x16x32_bf16 v[92:95], v[158:161], v[214:217], v[92:95]
	v_mfma_f32_16x16x32_bf16 v[84:87], v[166:169], v[214:217], v[84:87]
	s_setprio 0
	s_setprio 1
	v_mfma_f32_16x16x32_bf16 v[120:123], v[170:173], v[186:189], v[120:123]
	v_mfma_f32_16x16x32_bf16 v[112:115], v[178:181], v[186:189], v[112:115]
	v_mfma_f32_16x16x32_bf16 v[104:107], v[170:173], v[194:197], v[104:107]
	v_mfma_f32_16x16x32_bf16 v[96:99], v[178:181], v[194:197], v[96:99]
	v_mfma_f32_16x16x32_bf16 v[88:91], v[170:173], v[202:205], v[88:91]
	v_mfma_f32_16x16x32_bf16 v[80:83], v[178:181], v[202:205], v[80:83]
	v_mfma_f32_16x16x32_bf16 v[76:79], v[170:173], v[210:213], v[76:79]
	v_mfma_f32_16x16x32_bf16 v[72:75], v[178:181], v[210:213], v[72:75]
	v_mfma_f32_16x16x32_bf16 v[120:123], v[174:177], v[190:193], v[120:123]
	v_mfma_f32_16x16x32_bf16 v[112:115], v[182:185], v[190:193], v[112:115]
	v_mfma_f32_16x16x32_bf16 v[104:107], v[174:177], v[198:201], v[104:107]
	v_mfma_f32_16x16x32_bf16 v[96:99], v[182:185], v[198:201], v[96:99]
	v_mfma_f32_16x16x32_bf16 v[88:91], v[174:177], v[206:209], v[88:91]
	v_mfma_f32_16x16x32_bf16 v[80:83], v[182:185], v[206:209], v[80:83]
	v_mfma_f32_16x16x32_bf16 v[76:79], v[174:177], v[214:217], v[76:79]
	v_mfma_f32_16x16x32_bf16 v[72:75], v[182:185], v[214:217], v[72:75]
	s_setprio 0
	s_barrier
	s_add_i32 s68, s68, s29
	s_mov_b32 m0, s68
	ds_read_b128 v[186:189], v157 offset:16384
	ds_read_b128 v[190:193], v157 offset:17408
	ds_read_b128 v[194:197], v157 offset:18432
	ds_read_b128 v[198:201], v157 offset:19456
	ds_read_b128 v[202:205], v157 offset:20480
	ds_read_b128 v[206:209], v157 offset:21504
	ds_read_b128 v[210:213], v157 offset:22528
	ds_read_b128 v[214:217], v157 offset:23552
	global_load_lds_dwordx4 v140, s[24:25]
	s_add_i32 m0, s68, 0x2000
	s_add_u32 s68, s24, 0x4000
	s_addc_u32 s69, s25, 0
	s_add_i32 s77, s77, s29
	global_load_lds_dwordx4 v136, s[24:25]
	s_mov_b32 m0, s77
	s_nop 0
	global_load_lds_dwordx4 v140, s[68:69]
	s_add_i32 m0, s77, 0x2000
	s_nop 0
	global_load_lds_dwordx4 v136, s[68:69]
	s_mov_b32 m0, s31
	s_nop 0
	global_load_lds_dwordx4 v142, s[26:27]
	s_mov_b32 m0, s34
	s_nop 0
	global_load_lds_dwordx4 v138, s[26:27]
	s_waitcnt vmcnt(8)
	s_waitcnt lgkmcnt(0)
	s_setprio 1
	s_waitcnt lgkmcnt(0)
	v_mfma_f32_16x16x32_bf16 v[68:71], v[150:153], v[186:189], v[68:71]
	v_mfma_f32_16x16x32_bf16 v[64:67], v[162:165], v[186:189], v[64:67]
	v_mfma_f32_16x16x32_bf16 v[60:63], v[150:153], v[194:197], v[60:63]
	v_mfma_f32_16x16x32_bf16 v[52:55], v[162:165], v[194:197], v[52:55]
	v_mfma_f32_16x16x32_bf16 v[44:47], v[150:153], v[202:205], v[44:47]
	v_mfma_f32_16x16x32_bf16 v[32:35], v[162:165], v[202:205], v[32:35]
	v_mfma_f32_16x16x32_bf16 v[24:27], v[150:153], v[210:213], v[24:27]
	v_mfma_f32_16x16x32_bf16 v[16:19], v[162:165], v[210:213], v[16:19]
	v_mfma_f32_16x16x32_bf16 v[68:71], v[158:161], v[190:193], v[68:71]
	v_mfma_f32_16x16x32_bf16 v[64:67], v[166:169], v[190:193], v[64:67]
	v_mfma_f32_16x16x32_bf16 v[60:63], v[158:161], v[198:201], v[60:63]
	v_mfma_f32_16x16x32_bf16 v[52:55], v[166:169], v[198:201], v[52:55]
	v_mfma_f32_16x16x32_bf16 v[44:47], v[158:161], v[206:209], v[44:47]
	v_mfma_f32_16x16x32_bf16 v[32:35], v[166:169], v[206:209], v[32:35]
	v_mfma_f32_16x16x32_bf16 v[24:27], v[158:161], v[214:217], v[24:27]
	v_mfma_f32_16x16x32_bf16 v[16:19], v[166:169], v[214:217], v[16:19]
	s_setprio 0
	s_setprio 1
	v_mfma_f32_16x16x32_bf16 v[56:59], v[170:173], v[186:189], v[56:59]
	v_mfma_f32_16x16x32_bf16 v[48:51], v[178:181], v[186:189], v[48:51]
	v_mfma_f32_16x16x32_bf16 v[40:43], v[170:173], v[194:197], v[40:43]
	v_mfma_f32_16x16x32_bf16 v[28:31], v[178:181], v[194:197], v[28:31]
	v_mfma_f32_16x16x32_bf16 v[20:23], v[170:173], v[202:205], v[20:23]
	v_mfma_f32_16x16x32_bf16 v[12:15], v[178:181], v[202:205], v[12:15]
	v_mfma_f32_16x16x32_bf16 v[8:11], v[170:173], v[210:213], v[8:11]
	v_mfma_f32_16x16x32_bf16 v[4:7], v[178:181], v[210:213], v[4:7]
	v_mfma_f32_16x16x32_bf16 v[56:59], v[174:177], v[190:193], v[56:59]
	v_mfma_f32_16x16x32_bf16 v[48:51], v[182:185], v[190:193], v[48:51]
	v_mfma_f32_16x16x32_bf16 v[40:43], v[174:177], v[198:201], v[40:43]
	v_mfma_f32_16x16x32_bf16 v[28:31], v[182:185], v[198:201], v[28:31]
	v_mfma_f32_16x16x32_bf16 v[20:23], v[174:177], v[206:209], v[20:23]
	v_mfma_f32_16x16x32_bf16 v[12:15], v[182:185], v[206:209], v[12:15]
	v_mfma_f32_16x16x32_bf16 v[8:11], v[174:177], v[214:217], v[8:11]
	v_mfma_f32_16x16x32_bf16 v[4:7], v[182:185], v[214:217], v[4:7]
	s_setprio 0
	s_barrier
; #define PG8_STAGE(bufoff, gbase, voff) do { _Pragma("unroll") for (int _i = 0; _i < 2; ++_i) \
;         __builtin_amdgcn_global_load_lds((const unsigned*)((const char*)(gbase) + (voff)[_i]), (PG8_LAS unsigned*)(lds + (bufoff) + ldsw + _i * 8192), 16, 0, 0); } while (0)
; #define PG8_LDA(dst, b, h) do { _Pragma("unroll") for (int m = 0; m < 4; ++m) _Pragma("unroll") for (int k = 0; k < 2; ++k) dst[m][k] = *(const PG8_LAS bf16x8*)(lds + PG8_SA(b, h) + aoff + m * 2048 + k * 1024); } while (0)
; #define PG8_LDB(dst, b, h) do { _Pragma("unroll") for (int n = 0; n < 2; ++n) _Pragma("unroll") for (int k = 0; k < 2; ++k) dst[n][k] = *(const PG8_LAS bf16x8*)(lds + PG8_SB(b, h) + boff + n * 2048 + k * 1024); } while (0)
; #define PG8_MMA(ai, bj, At, Bt) do { __builtin_amdgcn_s_setprio(1); _Pragma("unroll") for (int m = 0; m < 4; ++m) _Pragma("unroll") for (int n = 0; n < 2; ++n) _Pragma("unroll") for (int k = 0; k < 2; ++k) \
;         acc[ai][bj][m][n] = __builtin_amdgcn_mfma_f32_16x16x32_bf16(Bt[n][k], At[m][k], acc[ai][bj][m][n], 0, 0, 0); __builtin_amdgcn_s_setprio(0); } while (0)
; #define PG8_WAIT_V(n) asm volatile("s_waitcnt vmcnt(" #n ")" ::: "memory")
; #define PG8_WAIT_L(n) asm volatile("s_waitcnt lgkmcnt(" #n ")" ::: "memory")
; #define PG8_BAR __builtin_amdgcn_s_barrier()
; #define PG8_SCHED __builtin_amdgcn_sched_barrier(0)
; template <class Epi, class Sched, bool ALIGN_EPI = false, bool SP2 = false, bool ABLK = false, bool BBLK = false>
; __device__ __forceinline__ void gemm_phase(PG8_LAS unsigned char* lds, const Gemm g, const Sched& S, const Epi& E) {
;     ...
;             PG8_LDB(B0, 1, 0); PG8_LDB(B1, 1, 1); PG8_SCHED; PG8_LDA(At, 1, 0); PG8_STAGE(PG8_SA(0, 1), a2 + hstepA, voffA);
;             PG8_WAIT_V(8); PG8_WAIT_L(0); PG8_BAR; PG8_MMA(0, 0, At, B0); PG8_MMA(0, 1, At, B1); PG8_BAR; PG8_SCHED;
;             PG8_LDA(At, 1, 1); PG8_STAGE(PG8_SB(1, 0), b3, voffB); PG8_STAGE(PG8_SB(1, 1), b3 + hstepB, voffB); PG8_STAGE(PG8_SA(1, 0), a3, voffA);
;             PG8_WAIT_V(8); PG8_WAIT_L(0); PG8_BAR; PG8_MMA(1, 0, At, B0); PG8_MMA(1, 1, At, B1); PG8_BAR; PG8_SCHED;
	s_add_i32 s68, 0, 0x18000
	v_add_u32_e32 v36, s68, v155
	s_add_i32 s69, 0, 0x1c000
	ds_read_b128 v[150:153], v36
	ds_read_b128 v[158:161], v36 offset:1024
	ds_read_b128 v[162:165], v36 offset:2048
	ds_read_b128 v[166:169], v36 offset:3072
	v_add_u32_e32 v36, s69, v155
	ds_read_b128 v[170:173], v36
	ds_read_b128 v[174:177], v36 offset:1024
	ds_read_b128 v[178:181], v36 offset:2048
	ds_read_b128 v[182:185], v36 offset:3072
	s_add_u32 s26, s26, 0x4000
	s_addc_u32 s27, s27, 0
	s_mov_b32 m0, s35
	ds_read_b128 v[186:189], v157 offset:32768
	ds_read_b128 v[190:193], v157 offset:33792
	ds_read_b128 v[194:197], v157 offset:34816
	ds_read_b128 v[198:201], v157 offset:35840
	ds_read_b128 v[202:205], v157 offset:36864
	ds_read_b128 v[206:209], v157 offset:37888
	ds_read_b128 v[210:213], v157 offset:38912
	ds_read_b128 v[214:217], v157 offset:39936
	global_load_lds_dwordx4 v142, s[26:27]
	s_mov_b32 m0, s36
	s_nop 0
	global_load_lds_dwordx4 v138, s[26:27]
	s_waitcnt vmcnt(8)
	s_waitcnt lgkmcnt(0)
	s_setprio 1
	s_waitcnt lgkmcnt(0)
	v_mfma_f32_16x16x32_bf16 v[132:135], v[150:153], v[186:189], v[132:135]
	v_mfma_f32_16x16x32_bf16 v[128:131], v[162:165], v[186:189], v[128:131]
	v_mfma_f32_16x16x32_bf16 v[124:127], v[150:153], v[194:197], v[124:127]
	v_mfma_f32_16x16x32_bf16 v[116:119], v[162:165], v[194:197], v[116:119]
	v_mfma_f32_16x16x32_bf16 v[108:111], v[150:153], v[202:205], v[108:111]
	v_mfma_f32_16x16x32_bf16 v[100:103], v[162:165], v[202:205], v[100:103]
	v_mfma_f32_16x16x32_bf16 v[92:95], v[150:153], v[210:213], v[92:95]
	v_mfma_f32_16x16x32_bf16 v[84:87], v[162:165], v[210:213], v[84:87]
	v_mfma_f32_16x16x32_bf16 v[132:135], v[158:161], v[190:193], v[132:135]
	v_mfma_f32_16x16x32_bf16 v[128:131], v[166:169], v[190:193], v[128:131]
	v_mfma_f32_16x16x32_bf16 v[124:127], v[158:161], v[198:201], v[124:127]
	v_mfma_f32_16x16x32_bf16 v[116:119], v[166:169], v[198:201], v[116:119]
	v_mfma_f32_16x16x32_bf16 v[108:111], v[158:161], v[206:209], v[108:111]
	v_mfma_f32_16x16x32_bf16 v[100:103], v[166:169], v[206:209], v[100:103]
	v_mfma_f32_16x16x32_bf16 v[92:95], v[158:161], v[214:217], v[92:95]
	v_mfma_f32_16x16x32_bf16 v[84:87], v[166:169], v[214:217], v[84:87]
	s_setprio 0
	s_setprio 1
	v_mfma_f32_16x16x32_bf16 v[120:123], v[170:173], v[186:189], v[120:123]
	v_mfma_f32_16x16x32_bf16 v[112:115], v[178:181], v[186:189], v[112:115]
	v_mfma_f32_16x16x32_bf16 v[104:107], v[170:173], v[194:197], v[104:107]
	v_mfma_f32_16x16x32_bf16 v[96:99], v[178:181], v[194:197], v[96:99]
	v_mfma_f32_16x16x32_bf16 v[88:91], v[170:173], v[202:205], v[88:91]
	v_mfma_f32_16x16x32_bf16 v[80:83], v[178:181], v[202:205], v[80:83]
	v_mfma_f32_16x16x32_bf16 v[76:79], v[170:173], v[210:213], v[76:79]
	v_mfma_f32_16x16x32_bf16 v[72:75], v[178:181], v[210:213], v[72:75]
	v_mfma_f32_16x16x32_bf16 v[120:123], v[174:177], v[190:193], v[120:123]
	v_mfma_f32_16x16x32_bf16 v[112:115], v[182:185], v[190:193], v[112:115]
	v_mfma_f32_16x16x32_bf16 v[104:107], v[174:177], v[198:201], v[104:107]
	v_mfma_f32_16x16x32_bf16 v[96:99], v[182:185], v[198:201], v[96:99]
	v_mfma_f32_16x16x32_bf16 v[88:91], v[174:177], v[206:209], v[88:91]
	v_mfma_f32_16x16x32_bf16 v[80:83], v[182:185], v[206:209], v[80:83]
	v_mfma_f32_16x16x32_bf16 v[76:79], v[174:177], v[214:217], v[76:79]
	v_mfma_f32_16x16x32_bf16 v[72:75], v[182:185], v[214:217], v[72:75]
	s_setprio 0
	s_barrier
	s_add_u32 s26, s24, 0x8000
	s_addc_u32 s27, s25, 0
	s_add_i32 s68, s68, s29
	s_mov_b32 m0, s68
	ds_read_b128 v[186:189], v157 offset:49152
	ds_read_b128 v[190:193], v157 offset:50176
	ds_read_b128 v[194:197], v157 offset:51200
	ds_read_b128 v[198:201], v157 offset:52224
	ds_read_b128 v[202:205], v157 offset:53248
	ds_read_b128 v[206:209], v157 offset:54272
	ds_read_b128 v[210:213], v157 offset:55296
	ds_read_b128 v[214:217], v157 offset:56320
	global_load_lds_dwordx4 v140, s[26:27]
	s_add_i32 m0, s68, 0x2000
	s_add_u32 s24, s24, 0xc000
	s_addc_u32 s25, s25, 0
	global_load_lds_dwordx4 v136, s[26:27]
	s_add_i32 s26, s69, s29
	s_mov_b32 m0, s26
	s_nop 0
	global_load_lds_dwordx4 v140, s[24:25]
	s_add_i32 m0, s26, 0x2000
	s_nop 0
	global_load_lds_dwordx4 v136, s[24:25]
	s_mov_b32 m0, s37
	s_nop 0
	global_load_lds_dwordx4 v142, s[22:23]
	s_mov_b32 m0, s62
	s_nop 0
	global_load_lds_dwordx4 v138, s[22:23]
	s_waitcnt vmcnt(8)
	s_waitcnt lgkmcnt(0)
	s_setprio 1
	s_waitcnt lgkmcnt(0)
	v_mfma_f32_16x16x32_bf16 v[68:71], v[150:153], v[186:189], v[68:71]
	v_mfma_f32_16x16x32_bf16 v[64:67], v[162:165], v[186:189], v[64:67]
	v_mfma_f32_16x16x32_bf16 v[60:63], v[150:153], v[194:197], v[60:63]
	v_mfma_f32_16x16x32_bf16 v[52:55], v[162:165], v[194:197], v[52:55]
	v_mfma_f32_16x16x32_bf16 v[44:47], v[150:153], v[202:205], v[44:47]
	v_mfma_f32_16x16x32_bf16 v[32:35], v[162:165], v[202:205], v[32:35]
	v_mfma_f32_16x16x32_bf16 v[24:27], v[150:153], v[210:213], v[24:27]
	v_mfma_f32_16x16x32_bf16 v[16:19], v[162:165], v[210:213], v[16:19]
	v_mfma_f32_16x16x32_bf16 v[68:71], v[158:161], v[190:193], v[68:71]
	v_mfma_f32_16x16x32_bf16 v[64:67], v[166:169], v[190:193], v[64:67]
	v_mfma_f32_16x16x32_bf16 v[60:63], v[158:161], v[198:201], v[60:63]
	v_mfma_f32_16x16x32_bf16 v[52:55], v[166:169], v[198:201], v[52:55]
	v_mfma_f32_16x16x32_bf16 v[44:47], v[158:161], v[206:209], v[44:47]
	v_mfma_f32_16x16x32_bf16 v[32:35], v[166:169], v[206:209], v[32:35]
	v_mfma_f32_16x16x32_bf16 v[24:27], v[158:161], v[214:217], v[24:27]
	v_mfma_f32_16x16x32_bf16 v[16:19], v[166:169], v[214:217], v[16:19]
	s_setprio 0
	s_setprio 1
	v_mfma_f32_16x16x32_bf16 v[56:59], v[170:173], v[186:189], v[56:59]
	v_mfma_f32_16x16x32_bf16 v[48:51], v[178:181], v[186:189], v[48:51]
	v_mfma_f32_16x16x32_bf16 v[40:43], v[170:173], v[194:197], v[40:43]
	v_mfma_f32_16x16x32_bf16 v[28:31], v[178:181], v[194:197], v[28:31]
	v_mfma_f32_16x16x32_bf16 v[20:23], v[170:173], v[202:205], v[20:23]
	v_mfma_f32_16x16x32_bf16 v[12:15], v[178:181], v[202:205], v[12:15]
	v_mfma_f32_16x16x32_bf16 v[8:11], v[170:173], v[210:213], v[8:11]
	v_mfma_f32_16x16x32_bf16 v[4:7], v[178:181], v[210:213], v[4:7]
	v_mfma_f32_16x16x32_bf16 v[56:59], v[174:177], v[190:193], v[56:59]
	v_mfma_f32_16x16x32_bf16 v[48:51], v[182:185], v[190:193], v[48:51]
	v_mfma_f32_16x16x32_bf16 v[40:43], v[174:177], v[198:201], v[40:43]
	v_mfma_f32_16x16x32_bf16 v[28:31], v[182:185], v[198:201], v[28:31]
	v_mfma_f32_16x16x32_bf16 v[20:23], v[174:177], v[206:209], v[20:23]
	v_mfma_f32_16x16x32_bf16 v[12:15], v[182:185], v[206:209], v[12:15]
	v_mfma_f32_16x16x32_bf16 v[8:11], v[174:177], v[214:217], v[8:11]
	v_mfma_f32_16x16x32_bf16 v[4:7], v[182:185], v[214:217], v[4:7]
	s_setprio 0
	s_barrier
	s_add_i32 s13, s13, 2
	s_add_u32 s20, s20, 0x10000
	s_addc_u32 s21, s21, 0
	s_add_u32 s70, s70, 0x10000
	s_addc_u32 s71, s71, 0
	s_cmp_gt_u32 s13, 29
	s_cbranch_scc0 .LBB0_916
	s_branch .Lkx_MIN
; #define PG8_STAGE(bufoff, gbase, voff) do { _Pragma("unroll") for (int _i = 0; _i < 2; ++_i) \
;         __builtin_amdgcn_global_load_lds((const unsigned*)((const char*)(gbase) + (voff)[_i]), (PG8_LAS unsigned*)(lds + (bufoff) + ldsw + _i * 8192), 16, 0, 0); } while (0)
; #define PG8_LDA(dst, b, h) do { _Pragma("unroll") for (int m = 0; m < 4; ++m) _Pragma("unroll") for (int k = 0; k < 2; ++k) dst[m][k] = *(const PG8_LAS bf16x8*)(lds + PG8_SA(b, h) + aoff + m * 2048 + k * 1024); } while (0)
; #define PG8_LDB(dst, b, h) do { _Pragma("unroll") for (int n = 0; n < 2; ++n) _Pragma("unroll") for (int k = 0; k < 2; ++k) dst[n][k] = *(const PG8_LAS bf16x8*)(lds + PG8_SB(b, h) + boff + n * 2048 + k * 1024); } while (0)
; #define PG8_MMA(ai, bj, At, Bt) do { __builtin_amdgcn_s_setprio(1); _Pragma("unroll") for (int m = 0; m < 4; ++m) _Pragma("unroll") for (int n = 0; n < 2; ++n) _Pragma("unroll") for (int k = 0; k < 2; ++k) \
;         acc[ai][bj][m][n] = __builtin_amdgcn_mfma_f32_16x16x32_bf16(Bt[n][k], At[m][k], acc[ai][bj][m][n], 0, 0, 0); __builtin_amdgcn_s_setprio(0); } while (0)
; #define PG8_WAIT_V(n) asm volatile("s_waitcnt vmcnt(" #n ")" ::: "memory")
; #define PG8_WAIT_L(n) asm volatile("s_waitcnt lgkmcnt(" #n ")" ::: "memory")
; #define PG8_BAR __builtin_amdgcn_s_barrier()
; #define PG8_SCHED __builtin_amdgcn_sched_barrier(0)
; template <class Epi, class Sched, bool ALIGN_EPI = false, bool SP2 = false, bool ABLK = false, bool BBLK = false>
; __device__ __forceinline__ void gemm_phase(PG8_LAS unsigned char* lds, const Gemm g, const Sched& S, const Epi& E) {
;     ...
;             PG8_LDB(B0, 0, 0); PG8_LDB(B1, 0, 1); PG8_SCHED; PG8_LDA(At, 0, 0); PG8_STAGE(PG8_SA(1, 1), a1 + hstepA, voffA);
;             PG8_WAIT_V(8); PG8_WAIT_L(0); PG8_BAR; PG8_MMA(0, 0, At, B0); PG8_MMA(0, 1, At, B1); PG8_BAR; PG8_SCHED;
;             PG8_LDA(At, 0, 1); PG8_STAGE(PG8_SB(0, 0), b2, voffB); PG8_STAGE(PG8_SB(0, 1), b2 + hstepB, voffB); PG8_STAGE(PG8_SA(0, 0), a2, voffA);
.Lk1_MIN:
	s_add_u32 s22, s20, 0x4000
	s_addc_u32 s23, s21, 0
	s_cmp_eq_u32 s13, 28
	s_cselect_b32 s26, s19, s22
	s_cselect_b32 s27, s1, s23
	s_cselect_b32 s24, s65, s70
	s_cselect_b32 s25, s9, s71
	s_add_u32 s22, s26, 0x8000
	s_addc_u32 s23, s27, 0
	s_add_i32 s68, 0, 0x10000
	v_add_u32_e32 v36, s68, v155
	s_add_i32 s77, 0, 0x14000
	ds_read_b128 v[150:153], v36
	ds_read_b128 v[158:161], v36 offset:1024
	ds_read_b128 v[162:165], v36 offset:2048
	ds_read_b128 v[166:169], v36 offset:3072
	v_add_u32_e32 v36, s77, v155
	ds_read_b128 v[170:173], v36
	ds_read_b128 v[174:177], v36 offset:1024
	ds_read_b128 v[178:181], v36 offset:2048
	ds_read_b128 v[182:185], v36 offset:3072
	s_add_i32 m0, s31, 0xc000
	ds_read_b128 v[186:189], v157
	ds_read_b128 v[190:193], v157 offset:1024
	ds_read_b128 v[194:197], v157 offset:2048
	ds_read_b128 v[198:201], v157 offset:3072
	ds_read_b128 v[202:205], v157 offset:4096
	ds_read_b128 v[206:209], v157 offset:5120
	ds_read_b128 v[210:213], v157 offset:6144
	ds_read_b128 v[214:217], v157 offset:7168
	global_load_lds_dwordx4 v146, s[20:21]
	s_add_i32 m0, s31, 0xe000
	s_nop 0
	global_load_lds_dwordx4 v148, s[20:21]
	s_waitcnt vmcnt(8)
	s_waitcnt lgkmcnt(0)
	s_barrier
	s_setprio 2
	s_waitcnt lgkmcnt(0)
	v_mfma_f32_16x16x32_bf16 v[132:135], v[150:153], v[186:189], v[132:135]
	v_mfma_f32_16x16x32_bf16 v[128:131], v[162:165], v[186:189], v[128:131]
	v_mfma_f32_16x16x32_bf16 v[124:127], v[150:153], v[194:197], v[124:127]
	v_mfma_f32_16x16x32_bf16 v[116:119], v[162:165], v[194:197], v[116:119]
	v_mfma_f32_16x16x32_bf16 v[108:111], v[150:153], v[202:205], v[108:111]
	v_mfma_f32_16x16x32_bf16 v[100:103], v[162:165], v[202:205], v[100:103]
	v_mfma_f32_16x16x32_bf16 v[92:95], v[150:153], v[210:213], v[92:95]
	v_mfma_f32_16x16x32_bf16 v[84:87], v[162:165], v[210:213], v[84:87]
	v_mfma_f32_16x16x32_bf16 v[132:135], v[158:161], v[190:193], v[132:135]
	v_mfma_f32_16x16x32_bf16 v[128:131], v[166:169], v[190:193], v[128:131]
	v_mfma_f32_16x16x32_bf16 v[124:127], v[158:161], v[198:201], v[124:127]
	v_mfma_f32_16x16x32_bf16 v[116:119], v[166:169], v[198:201], v[116:119]
	v_mfma_f32_16x16x32_bf16 v[108:111], v[158:161], v[206:209], v[108:111]
	v_mfma_f32_16x16x32_bf16 v[100:103], v[166:169], v[206:209], v[100:103]
	v_mfma_f32_16x16x32_bf16 v[92:95], v[158:161], v[214:217], v[92:95]
	v_mfma_f32_16x16x32_bf16 v[84:87], v[166:169], v[214:217], v[84:87]
	v_mfma_f32_16x16x32_bf16 v[120:123], v[170:173], v[186:189], v[120:123]
	v_mfma_f32_16x16x32_bf16 v[112:115], v[178:181], v[186:189], v[112:115]
	v_mfma_f32_16x16x32_bf16 v[104:107], v[170:173], v[194:197], v[104:107]
	v_mfma_f32_16x16x32_bf16 v[96:99], v[178:181], v[194:197], v[96:99]
	v_mfma_f32_16x16x32_bf16 v[88:91], v[170:173], v[202:205], v[88:91]
	v_mfma_f32_16x16x32_bf16 v[80:83], v[178:181], v[202:205], v[80:83]
	v_mfma_f32_16x16x32_bf16 v[76:79], v[170:173], v[210:213], v[76:79]
	v_mfma_f32_16x16x32_bf16 v[72:75], v[178:181], v[210:213], v[72:75]
	v_mfma_f32_16x16x32_bf16 v[120:123], v[174:177], v[190:193], v[120:123]
	v_mfma_f32_16x16x32_bf16 v[112:115], v[182:185], v[190:193], v[112:115]
	v_mfma_f32_16x16x32_bf16 v[104:107], v[174:177], v[198:201], v[104:107]
	v_mfma_f32_16x16x32_bf16 v[96:99], v[182:185], v[198:201], v[96:99]
	v_mfma_f32_16x16x32_bf16 v[88:91], v[174:177], v[206:209], v[88:91]
	v_mfma_f32_16x16x32_bf16 v[80:83], v[182:185], v[206:209], v[80:83]
	v_mfma_f32_16x16x32_bf16 v[76:79], v[174:177], v[214:217], v[76:79]
	v_mfma_f32_16x16x32_bf16 v[72:75], v[182:185], v[214:217], v[72:75]
	s_setprio 0
	s_add_i32 s68, s68, s29
	s_mov_b32 m0, s68
	ds_read_b128 v[186:189], v157 offset:16384
	ds_read_b128 v[190:193], v157 offset:17408
	ds_read_b128 v[194:197], v157 offset:18432
	ds_read_b128 v[198:201], v157 offset:19456
	ds_read_b128 v[202:205], v157 offset:20480
	ds_read_b128 v[206:209], v157 offset:21504
	ds_read_b128 v[210:213], v157 offset:22528
	ds_read_b128 v[214:217], v157 offset:23552
	global_load_lds_dwordx4 v140, s[24:25]
	s_add_i32 m0, s68, 0x2000
	s_add_u32 s68, s24, 0x4000
	s_addc_u32 s69, s25, 0
	s_add_i32 s77, s77, s29
	global_load_lds_dwordx4 v136, s[24:25]
	s_mov_b32 m0, s77
	s_nop 0
	global_load_lds_dwordx4 v140, s[68:69]
	s_add_i32 m0, s77, 0x2000
	s_nop 0
	global_load_lds_dwordx4 v136, s[68:69]
	s_mov_b32 m0, s31
	s_nop 0
	global_load_lds_dwordx4 v142, s[26:27]
	s_mov_b32 m0, s34
	s_nop 0
	global_load_lds_dwordx4 v138, s[26:27]
	s_waitcnt vmcnt(8)
	s_waitcnt lgkmcnt(0)
	s_barrier
; #define PG8_STAGE(bufoff, gbase, voff) do { _Pragma("unroll") for (int _i = 0; _i < 2; ++_i) \
;         __builtin_amdgcn_global_load_lds((const unsigned*)((const char*)(gbase) + (voff)[_i]), (PG8_LAS unsigned*)(lds + (bufoff) + ldsw + _i * 8192), 16, 0, 0); } while (0)
; #define PG8_LDA(dst, b, h) do { _Pragma("unroll") for (int m = 0; m < 4; ++m) _Pragma("unroll") for (int k = 0; k < 2; ++k) dst[m][k] = *(const PG8_LAS bf16x8*)(lds + PG8_SA(b, h) + aoff + m * 2048 + k * 1024); } while (0)
; #define PG8_LDB(dst, b, h) do { _Pragma("unroll") for (int n = 0; n < 2; ++n) _Pragma("unroll") for (int k = 0; k < 2; ++k) dst[n][k] = *(const PG8_LAS bf16x8*)(lds + PG8_SB(b, h) + boff + n * 2048 + k * 1024); } while (0)
; #define PG8_MMA(ai, bj, At, Bt) do { __builtin_amdgcn_s_setprio(1); _Pragma("unroll") for (int m = 0; m < 4; ++m) _Pragma("unroll") for (int n = 0; n < 2; ++n) _Pragma("unroll") for (int k = 0; k < 2; ++k) \
;         acc[ai][bj][m][n] = __builtin_amdgcn_mfma_f32_16x16x32_bf16(Bt[n][k], At[m][k], acc[ai][bj][m][n], 0, 0, 0); __builtin_amdgcn_s_setprio(0); } while (0)
; #define PG8_WAIT_V(n) asm volatile("s_waitcnt vmcnt(" #n ")" ::: "memory")
; #define PG8_WAIT_L(n) asm volatile("s_waitcnt lgkmcnt(" #n ")" ::: "memory")
; #define PG8_BAR __builtin_amdgcn_s_barrier()
; #define PG8_SCHED __builtin_amdgcn_sched_barrier(0)
; template <class Epi, class Sched, bool ALIGN_EPI = false, bool SP2 = false, bool ABLK = false, bool BBLK = false>
; __device__ __forceinline__ void gemm_phase(PG8_LAS unsigned char* lds, const Gemm g, const Sched& S, const Epi& E) {
;     ...
;             PG8_WAIT_V(8); PG8_WAIT_L(0); PG8_BAR; PG8_MMA(0, 0, At, B0); PG8_MMA(0, 1, At, B1); PG8_BAR; PG8_SCHED;
;             PG8_LDA(At, 0, 1); PG8_STAGE(PG8_SB(0, 0), b2, voffB); PG8_STAGE(PG8_SB(0, 1), b2 + hstepB, voffB); PG8_STAGE(PG8_SA(0, 0), a2, voffA);
;             PG8_WAIT_V(8); PG8_WAIT_L(0); PG8_BAR; PG8_MMA(1, 0, At, B0); PG8_MMA(1, 1, At, B1); PG8_BAR; PG8_SCHED;
;             PG8_LDB(B0, 1, 0); PG8_LDB(B1, 1, 1); PG8_SCHED; PG8_LDA(At, 1, 0); PG8_STAGE(PG8_SA(0, 1), a2 + hstepA, voffA);
	s_setprio 2
	s_waitcnt lgkmcnt(0)
	v_mfma_f32_16x16x32_bf16 v[68:71], v[150:153], v[186:189], v[68:71]
	v_mfma_f32_16x16x32_bf16 v[64:67], v[162:165], v[186:189], v[64:67]
	v_mfma_f32_16x16x32_bf16 v[60:63], v[150:153], v[194:197], v[60:63]
	v_mfma_f32_16x16x32_bf16 v[52:55], v[162:165], v[194:197], v[52:55]
	v_mfma_f32_16x16x32_bf16 v[44:47], v[150:153], v[202:205], v[44:47]
	v_mfma_f32_16x16x32_bf16 v[32:35], v[162:165], v[202:205], v[32:35]
	v_mfma_f32_16x16x32_bf16 v[24:27], v[150:153], v[210:213], v[24:27]
	v_mfma_f32_16x16x32_bf16 v[16:19], v[162:165], v[210:213], v[16:19]
	v_mfma_f32_16x16x32_bf16 v[68:71], v[158:161], v[190:193], v[68:71]
	v_mfma_f32_16x16x32_bf16 v[64:67], v[166:169], v[190:193], v[64:67]
	v_mfma_f32_16x16x32_bf16 v[60:63], v[158:161], v[198:201], v[60:63]
	v_mfma_f32_16x16x32_bf16 v[52:55], v[166:169], v[198:201], v[52:55]
	v_mfma_f32_16x16x32_bf16 v[44:47], v[158:161], v[206:209], v[44:47]
	v_mfma_f32_16x16x32_bf16 v[32:35], v[166:169], v[206:209], v[32:35]
	v_mfma_f32_16x16x32_bf16 v[24:27], v[158:161], v[214:217], v[24:27]
	v_mfma_f32_16x16x32_bf16 v[16:19], v[166:169], v[214:217], v[16:19]
	v_mfma_f32_16x16x32_bf16 v[56:59], v[170:173], v[186:189], v[56:59]
	v_mfma_f32_16x16x32_bf16 v[48:51], v[178:181], v[186:189], v[48:51]
	v_mfma_f32_16x16x32_bf16 v[40:43], v[170:173], v[194:197], v[40:43]
	v_mfma_f32_16x16x32_bf16 v[28:31], v[178:181], v[194:197], v[28:31]
	v_mfma_f32_16x16x32_bf16 v[20:23], v[170:173], v[202:205], v[20:23]
	v_mfma_f32_16x16x32_bf16 v[12:15], v[178:181], v[202:205], v[12:15]
	v_mfma_f32_16x16x32_bf16 v[8:11], v[170:173], v[210:213], v[8:11]
	v_mfma_f32_16x16x32_bf16 v[4:7], v[178:181], v[210:213], v[4:7]
	v_mfma_f32_16x16x32_bf16 v[56:59], v[174:177], v[190:193], v[56:59]
	v_mfma_f32_16x16x32_bf16 v[48:51], v[182:185], v[190:193], v[48:51]
	v_mfma_f32_16x16x32_bf16 v[40:43], v[174:177], v[198:201], v[40:43]
	v_mfma_f32_16x16x32_bf16 v[28:31], v[182:185], v[198:201], v[28:31]
	v_mfma_f32_16x16x32_bf16 v[20:23], v[174:177], v[206:209], v[20:23]
	v_mfma_f32_16x16x32_bf16 v[12:15], v[182:185], v[206:209], v[12:15]
	v_mfma_f32_16x16x32_bf16 v[8:11], v[174:177], v[214:217], v[8:11]
	v_mfma_f32_16x16x32_bf16 v[4:7], v[182:185], v[214:217], v[4:7]
	s_setprio 0
	s_add_i32 s68, 0, 0x18000
	v_add_u32_e32 v36, s68, v155
	s_add_i32 s69, 0, 0x1c000
	ds_read_b128 v[150:153], v36
	ds_read_b128 v[158:161], v36 offset:1024
	ds_read_b128 v[162:165], v36 offset:2048
	ds_read_b128 v[166:169], v36 offset:3072
	v_add_u32_e32 v36, s69, v155
	ds_read_b128 v[170:173], v36
	ds_read_b128 v[174:177], v36 offset:1024
	ds_read_b128 v[178:181], v36 offset:2048
	ds_read_b128 v[182:185], v36 offset:3072
	s_add_u32 s26, s26, 0x4000
	s_addc_u32 s27, s27, 0
	s_mov_b32 m0, s35
	ds_read_b128 v[186:189], v157 offset:32768
	ds_read_b128 v[190:193], v157 offset:33792
	ds_read_b128 v[194:197], v157 offset:34816
	ds_read_b128 v[198:201], v157 offset:35840
	ds_read_b128 v[202:205], v157 offset:36864
	ds_read_b128 v[206:209], v157 offset:37888
	ds_read_b128 v[210:213], v157 offset:38912
	ds_read_b128 v[214:217], v157 offset:39936
	global_load_lds_dwordx4 v142, s[26:27]
	s_mov_b32 m0, s36
	s_nop 0
	global_load_lds_dwordx4 v138, s[26:27]
	s_waitcnt vmcnt(8)
	s_waitcnt lgkmcnt(0)
	s_barrier
; #define PG8_STAGE(bufoff, gbase, voff) do { _Pragma("unroll") for (int _i = 0; _i < 2; ++_i) \
;         __builtin_amdgcn_global_load_lds((const unsigned*)((const char*)(gbase) + (voff)[_i]), (PG8_LAS unsigned*)(lds + (bufoff) + ldsw + _i * 8192), 16, 0, 0); } while (0)
; #define PG8_LDA(dst, b, h) do { _Pragma("unroll") for (int m = 0; m < 4; ++m) _Pragma("unroll") for (int k = 0; k < 2; ++k) dst[m][k] = *(const PG8_LAS bf16x8*)(lds + PG8_SA(b, h) + aoff + m * 2048 + k * 1024); } while (0)
; #define PG8_LDB(dst, b, h) do { _Pragma("unroll") for (int n = 0; n < 2; ++n) _Pragma("unroll") for (int k = 0; k < 2; ++k) dst[n][k] = *(const PG8_LAS bf16x8*)(lds + PG8_SB(b, h) + boff + n * 2048 + k * 1024); } while (0)
; #define PG8_MMA(ai, bj, At, Bt) do { __builtin_amdgcn_s_setprio(1); _Pragma("unroll") for (int m = 0; m < 4; ++m) _Pragma("unroll") for (int n = 0; n < 2; ++n) _Pragma("unroll") for (int k = 0; k < 2; ++k) \
;         acc[ai][bj][m][n] = __builtin_amdgcn_mfma_f32_16x16x32_bf16(Bt[n][k], At[m][k], acc[ai][bj][m][n], 0, 0, 0); __builtin_amdgcn_s_setprio(0); } while (0)
; #define PG8_WAIT_V(n) asm volatile("s_waitcnt vmcnt(" #n ")" ::: "memory")
; #define PG8_WAIT_L(n) asm volatile("s_waitcnt lgkmcnt(" #n ")" ::: "memory")
; #define PG8_BAR __builtin_amdgcn_s_barrier()
; #define PG8_SCHED __builtin_amdgcn_sched_barrier(0)
; template <class Epi, class Sched, bool ALIGN_EPI = false, bool SP2 = false, bool ABLK = false, bool BBLK = false>
; __device__ __forceinline__ void gemm_phase(PG8_LAS unsigned char* lds, const Gemm g, const Sched& S, const Epi& E) {
;     ...
;             PG8_LDB(B0, 1, 0); PG8_LDB(B1, 1, 1); PG8_SCHED; PG8_LDA(At, 1, 0); PG8_STAGE(PG8_SA(0, 1), a2 + hstepA, voffA);
;             PG8_WAIT_V(8); PG8_WAIT_L(0); PG8_BAR; PG8_MMA(0, 0, At, B0); PG8_MMA(0, 1, At, B1); PG8_BAR; PG8_SCHED;
;             PG8_LDA(At, 1, 1); PG8_STAGE(PG8_SB(1, 0), b3, voffB); PG8_STAGE(PG8_SB(1, 1), b3 + hstepB, voffB); PG8_STAGE(PG8_SA(1, 0), a3, voffA);
;             PG8_WAIT_V(8); PG8_WAIT_L(0); PG8_BAR; PG8_MMA(1, 0, At, B0); PG8_MMA(1, 1, At, B1); PG8_BAR; PG8_SCHED;
	s_setprio 2
	s_waitcnt lgkmcnt(0)
	v_mfma_f32_16x16x32_bf16 v[132:135], v[150:153], v[186:189], v[132:135]
	v_mfma_f32_16x16x32_bf16 v[128:131], v[162:165], v[186:189], v[128:131]
	v_mfma_f32_16x16x32_bf16 v[124:127], v[150:153], v[194:197], v[124:127]
	v_mfma_f32_16x16x32_bf16 v[116:119], v[162:165], v[194:197], v[116:119]
	v_mfma_f32_16x16x32_bf16 v[108:111], v[150:153], v[202:205], v[108:111]
	v_mfma_f32_16x16x32_bf16 v[100:103], v[162:165], v[202:205], v[100:103]
	v_mfma_f32_16x16x32_bf16 v[92:95], v[150:153], v[210:213], v[92:95]
	v_mfma_f32_16x16x32_bf16 v[84:87], v[162:165], v[210:213], v[84:87]
	v_mfma_f32_16x16x32_bf16 v[132:135], v[158:161], v[190:193], v[132:135]
	v_mfma_f32_16x16x32_bf16 v[128:131], v[166:169], v[190:193], v[128:131]
	v_mfma_f32_16x16x32_bf16 v[124:127], v[158:161], v[198:201], v[124:127]
	v_mfma_f32_16x16x32_bf16 v[116:119], v[166:169], v[198:201], v[116:119]
	v_mfma_f32_16x16x32_bf16 v[108:111], v[158:161], v[206:209], v[108:111]
	v_mfma_f32_16x16x32_bf16 v[100:103], v[166:169], v[206:209], v[100:103]
	v_mfma_f32_16x16x32_bf16 v[92:95], v[158:161], v[214:217], v[92:95]
	v_mfma_f32_16x16x32_bf16 v[84:87], v[166:169], v[214:217], v[84:87]
	v_mfma_f32_16x16x32_bf16 v[120:123], v[170:173], v[186:189], v[120:123]
	v_mfma_f32_16x16x32_bf16 v[112:115], v[178:181], v[186:189], v[112:115]
	v_mfma_f32_16x16x32_bf16 v[104:107], v[170:173], v[194:197], v[104:107]
	v_mfma_f32_16x16x32_bf16 v[96:99], v[178:181], v[194:197], v[96:99]
	v_mfma_f32_16x16x32_bf16 v[88:91], v[170:173], v[202:205], v[88:91]
	v_mfma_f32_16x16x32_bf16 v[80:83], v[178:181], v[202:205], v[80:83]
	v_mfma_f32_16x16x32_bf16 v[76:79], v[170:173], v[210:213], v[76:79]
	v_mfma_f32_16x16x32_bf16 v[72:75], v[178:181], v[210:213], v[72:75]
	v_mfma_f32_16x16x32_bf16 v[120:123], v[174:177], v[190:193], v[120:123]
	v_mfma_f32_16x16x32_bf16 v[112:115], v[182:185], v[190:193], v[112:115]
	v_mfma_f32_16x16x32_bf16 v[104:107], v[174:177], v[198:201], v[104:107]
	v_mfma_f32_16x16x32_bf16 v[96:99], v[182:185], v[198:201], v[96:99]
	v_mfma_f32_16x16x32_bf16 v[88:91], v[174:177], v[206:209], v[88:91]
	v_mfma_f32_16x16x32_bf16 v[80:83], v[182:185], v[206:209], v[80:83]
	v_mfma_f32_16x16x32_bf16 v[76:79], v[174:177], v[214:217], v[76:79]
	v_mfma_f32_16x16x32_bf16 v[72:75], v[182:185], v[214:217], v[72:75]
	s_setprio 0
	s_add_u32 s26, s24, 0x8000
	s_addc_u32 s27, s25, 0
	s_add_i32 s68, s68, s29
	s_mov_b32 m0, s68
	ds_read_b128 v[186:189], v157 offset:49152
	ds_read_b128 v[190:193], v157 offset:50176
	ds_read_b128 v[194:197], v157 offset:51200
	ds_read_b128 v[198:201], v157 offset:52224
	ds_read_b128 v[202:205], v157 offset:53248
	ds_read_b128 v[206:209], v157 offset:54272
	ds_read_b128 v[210:213], v157 offset:55296
	ds_read_b128 v[214:217], v157 offset:56320
	global_load_lds_dwordx4 v140, s[26:27]
	s_add_i32 m0, s68, 0x2000
	s_add_u32 s24, s24, 0xc000
	s_addc_u32 s25, s25, 0
	global_load_lds_dwordx4 v136, s[26:27]
	s_add_i32 s26, s69, s29
	s_mov_b32 m0, s26
	s_nop 0
	global_load_lds_dwordx4 v140, s[24:25]
	s_add_i32 m0, s26, 0x2000
	s_nop 0
	global_load_lds_dwordx4 v136, s[24:25]
	s_mov_b32 m0, s37
	s_nop 0
	global_load_lds_dwordx4 v142, s[22:23]
	s_mov_b32 m0, s62
	s_nop 0
	global_load_lds_dwordx4 v138, s[22:23]
	s_waitcnt vmcnt(8)
	s_waitcnt lgkmcnt(0)
	s_barrier
	s_setprio 2
	s_waitcnt lgkmcnt(0)
	v_mfma_f32_16x16x32_bf16 v[68:71], v[150:153], v[186:189], v[68:71]
	v_mfma_f32_16x16x32_bf16 v[64:67], v[162:165], v[186:189], v[64:67]
	v_mfma_f32_16x16x32_bf16 v[60:63], v[150:153], v[194:197], v[60:63]
	v_mfma_f32_16x16x32_bf16 v[52:55], v[162:165], v[194:197], v[52:55]
	v_mfma_f32_16x16x32_bf16 v[44:47], v[150:153], v[202:205], v[44:47]
	v_mfma_f32_16x16x32_bf16 v[32:35], v[162:165], v[202:205], v[32:35]
	v_mfma_f32_16x16x32_bf16 v[24:27], v[150:153], v[210:213], v[24:27]
	v_mfma_f32_16x16x32_bf16 v[16:19], v[162:165], v[210:213], v[16:19]
	v_mfma_f32_16x16x32_bf16 v[68:71], v[158:161], v[190:193], v[68:71]
	v_mfma_f32_16x16x32_bf16 v[64:67], v[166:169], v[190:193], v[64:67]
	v_mfma_f32_16x16x32_bf16 v[60:63], v[158:161], v[198:201], v[60:63]
	v_mfma_f32_16x16x32_bf16 v[52:55], v[166:169], v[198:201], v[52:55]
	v_mfma_f32_16x16x32_bf16 v[44:47], v[158:161], v[206:209], v[44:47]
	v_mfma_f32_16x16x32_bf16 v[32:35], v[166:169], v[206:209], v[32:35]
	v_mfma_f32_16x16x32_bf16 v[24:27], v[158:161], v[214:217], v[24:27]
	v_mfma_f32_16x16x32_bf16 v[16:19], v[166:169], v[214:217], v[16:19]
	v_mfma_f32_16x16x32_bf16 v[56:59], v[170:173], v[186:189], v[56:59]
	v_mfma_f32_16x16x32_bf16 v[48:51], v[178:181], v[186:189], v[48:51]
	v_mfma_f32_16x16x32_bf16 v[40:43], v[170:173], v[194:197], v[40:43]
	v_mfma_f32_16x16x32_bf16 v[28:31], v[178:181], v[194:197], v[28:31]
	v_mfma_f32_16x16x32_bf16 v[20:23], v[170:173], v[202:205], v[20:23]
	v_mfma_f32_16x16x32_bf16 v[12:15], v[178:181], v[202:205], v[12:15]
	v_mfma_f32_16x16x32_bf16 v[8:11], v[170:173], v[210:213], v[8:11]
	v_mfma_f32_16x16x32_bf16 v[4:7], v[178:181], v[210:213], v[4:7]
	v_mfma_f32_16x16x32_bf16 v[56:59], v[174:177], v[190:193], v[56:59]
	v_mfma_f32_16x16x32_bf16 v[48:51], v[182:185], v[190:193], v[48:51]
	v_mfma_f32_16x16x32_bf16 v[40:43], v[174:177], v[198:201], v[40:43]
	v_mfma_f32_16x16x32_bf16 v[28:31], v[182:185], v[198:201], v[28:31]
	v_mfma_f32_16x16x32_bf16 v[20:23], v[174:177], v[206:209], v[20:23]
	v_mfma_f32_16x16x32_bf16 v[12:15], v[182:185], v[206:209], v[12:15]
	v_mfma_f32_16x16x32_bf16 v[8:11], v[174:177], v[214:217], v[8:11]
	v_mfma_f32_16x16x32_bf16 v[4:7], v[182:185], v[214:217], v[4:7]
	s_setprio 0
	s_add_i32 s13, s13, 2
	s_add_u32 s20, s20, 0x10000
	s_addc_u32 s21, s21, 0
	s_add_u32 s70, s70, 0x10000
	s_addc_u32 s71, s71, 0
	s_cmp_gt_u32 s13, 29
	s_cbranch_scc0 .Lk1_MIN

; #define PG8_LAS __attribute__((address_space(3)))
; __device__ __forceinline__ unsigned cvt_pk_bf16(float lo, float hi) { const hwf2_t v = {lo, hi}; return __builtin_bit_cast(unsigned, __builtin_convertvector(v, hwbf2_t)); }
; #define PG8_BAR __builtin_amdgcn_s_barrier()
;     __device__ __forceinline__ void operator()(const f32x4 (&acc)[2][2][4][2], const Unit& u, int wr, int wc, int fr, int fq, const PG8_LAS unsigned char* area) const {
;         const int row0 = u.pm * BM + wr * 64 + fr, col0 = u.pn * BM + wc * 32 + 8 * fq;
;         float rsv[2][4];
; #pragma unroll
;         for (int ai = 0; ai < 2; ++ai)
; #pragma unroll
;             for (int m = 0; m < 4; ++m) rsv[ai][m] = rs ? *(const PG8_LAS float*)(area + ai * 256 + (m * 16 + fr) * 4) : 1.0f;
; #pragma unroll
;         for (int ai = 0; ai < 2; ++ai)
; #pragma unroll
;             for (int m = 0; m < 4; ++m) { bf16_t* rowp = O + (size_t)(row0 + ai * HALF + m * 16) * ldc + col0; const float r_ = rsv[ai][m];
; #pragma unroll
;                 for (int bj = 0; bj < 2; ++bj) { const f32x4 v0 = acc[ai][bj][m][0] * r_, v1 = acc[ai][bj][m][1] * r_;
;                     u32x4 w; w.x = cvt_pk_bf16(v0[0], v0[1]); w.y = cvt_pk_bf16(v0[2], v0[3]); w.z = cvt_pk_bf16(v1[0], v1[1]); w.w = cvt_pk_bf16(v1[2], v1[3]);
;                     *(u32x4*)(rowp + bj * HALF) = w; } }
; template <class Epi, class Sched, bool ALIGN_EPI = false, bool SP2 = false, bool ABLK = false, bool BBLK = false>
; __device__ __forceinline__ void gemm_phase(PG8_LAS unsigned char* lds, const Gemm g, const Sched& S, const Epi& E) {
;     ...
;         if constexpr (ALIGN_EPI) { if (wr == 0) PG8_BAR; }
.LBB0_919:
	v_add_u32_e32 v150, s63, v154
	ds_read2_b32 v[36:37], v150 offset1:16
	ds_read2_b32 v[38:39], v150 offset0:32 offset1:48
	ds_read2_b32 v[158:159], v150 offset0:64 offset1:80
	ds_read2_b32 v[150:151], v150 offset0:96 offset1:112
	v_add_u32_e32 v164, s18, v3
	v_lshl_or_b32 v152, s12, 8, v156
	v_ashrrev_i32_e32 v153, 31, v152
	v_mad_i64_i32 v[160:161], s[12:13], v164, s57, 0
	v_lshl_add_u64 v[160:161], v[160:161], 1, s[96:97]
	v_lshlrev_b64 v[152:153], 1, v[152:153]
	s_waitcnt lgkmcnt(0)
	v_pk_mul_f32 v[134:135], v[134:135], v[36:37] op_sel_hi:[1,0]
	v_pk_mul_f32 v[132:133], v[132:133], v[36:37] op_sel_hi:[1,0]
	v_pk_mul_f32 v[162:163], v[130:131], v[36:37] op_sel_hi:[1,0]
	v_pk_mul_f32 v[130:131], v[128:129], v[36:37] op_sel_hi:[1,0]
	v_lshl_add_u64 v[160:161], v[160:161], 0, v[152:153]
	v_cvt_pk_bf16_f32 v128, v132, v133
	v_cvt_pk_bf16_f32 v129, v134, v135
	v_cvt_pk_bf16_f32 v130, v130, v131
	v_cvt_pk_bf16_f32 v131, v162, v163
	global_store_dwordx4 v[160:161], v[128:131], off
	v_pk_mul_f32 v[122:123], v[122:123], v[36:37] op_sel_hi:[1,0]
	v_pk_mul_f32 v[120:121], v[120:121], v[36:37] op_sel_hi:[1,0]
	v_pk_mul_f32 v[128:129], v[114:115], v[36:37] op_sel_hi:[1,0]
	v_pk_mul_f32 v[114:115], v[112:113], v[36:37] op_sel_hi:[1,0]
	v_cvt_pk_bf16_f32 v112, v120, v121
	v_cvt_pk_bf16_f32 v113, v122, v123
	v_cvt_pk_bf16_f32 v114, v114, v115
	v_cvt_pk_bf16_f32 v115, v128, v129
	v_or_b32_e32 v36, 16, v164
	global_store_dwordx4 v[160:161], v[112:115], off offset:256
	v_pk_mul_f32 v[102:103], v[102:103], v[38:39] op_sel_hi:[1,0]
	v_pk_mul_f32 v[100:101], v[100:101], v[38:39] op_sel_hi:[1,0]
	v_mad_i64_i32 v[112:113], s[12:13], v36, s57, 0
	v_lshl_add_u64 v[112:113], v[112:113], 1, s[96:97]
	v_mov_b32_e32 v36, v37
	v_lshl_add_u64 v[120:121], v[112:113], 0, v[152:153]
	v_pk_mul_f32 v[114:115], v[126:127], v[36:37] op_sel_hi:[1,0]
	v_pk_mul_f32 v[112:113], v[124:125], v[36:37] op_sel_hi:[1,0]
	v_pk_mul_f32 v[118:119], v[118:119], v[36:37] op_sel_hi:[1,0]
	v_pk_mul_f32 v[116:117], v[116:117], v[36:37] op_sel_hi:[1,0]
	v_cvt_pk_bf16_f32 v112, v112, v113
	v_cvt_pk_bf16_f32 v113, v114, v115
	v_cvt_pk_bf16_f32 v114, v116, v117
	v_cvt_pk_bf16_f32 v115, v118, v119
	global_store_dwordx4 v[120:121], v[112:115], off
	v_pk_mul_f32 v[106:107], v[106:107], v[36:37] op_sel_hi:[1,0]
	v_pk_mul_f32 v[104:105], v[104:105], v[36:37] op_sel_hi:[1,0]
	v_pk_mul_f32 v[112:113], v[98:99], v[36:37] op_sel_hi:[1,0]
	v_pk_mul_f32 v[36:37], v[96:97], v[36:37] op_sel_hi:[1,0]
	v_cvt_pk_bf16_f32 v96, v104, v105
	v_cvt_pk_bf16_f32 v98, v36, v37
	v_or_b32_e32 v36, 32, v164
	v_cvt_pk_bf16_f32 v97, v106, v107
	v_cvt_pk_bf16_f32 v99, v112, v113
	v_mad_i64_i32 v[36:37], s[12:13], v36, s57, 0
	global_store_dwordx4 v[120:121], v[96:99], off offset:256
	v_lshl_add_u64 v[36:37], v[36:37], 1, s[96:97]
	v_lshl_add_u64 v[36:37], v[36:37], 0, v[152:153]
	v_pk_mul_f32 v[98:99], v[110:111], v[38:39] op_sel_hi:[1,0]
	v_pk_mul_f32 v[96:97], v[108:109], v[38:39] op_sel_hi:[1,0]
	v_pk_mul_f32 v[90:91], v[90:91], v[38:39] op_sel_hi:[1,0]
	v_cvt_pk_bf16_f32 v96, v96, v97
	v_cvt_pk_bf16_f32 v97, v98, v99
	v_cvt_pk_bf16_f32 v98, v100, v101
	v_cvt_pk_bf16_f32 v99, v102, v103
	global_store_dwordx4 v[36:37], v[96:99], off
	v_pk_mul_f32 v[88:89], v[88:89], v[38:39] op_sel_hi:[1,0]
	v_pk_mul_f32 v[68:69], v[68:69], v[158:159] op_sel_hi:[1,0]
	v_pk_mul_f32 v[96:97], v[82:83], v[38:39] op_sel_hi:[1,0]
	v_pk_mul_f32 v[82:83], v[80:81], v[38:39] op_sel_hi:[1,0]
	v_cvt_pk_bf16_f32 v80, v88, v89
	v_cvt_pk_bf16_f32 v81, v90, v91
	v_cvt_pk_bf16_f32 v82, v82, v83
	v_cvt_pk_bf16_f32 v83, v96, v97
	global_store_dwordx4 v[36:37], v[80:83], off offset:256
	v_or_b32_e32 v36, 48, v164
	v_mad_i64_i32 v[36:37], s[12:13], v36, s57, 0
	v_mov_b32_e32 v38, v39
	v_lshl_add_u64 v[36:37], v[36:37], 1, s[96:97]
	v_pk_mul_f32 v[82:83], v[94:95], v[38:39] op_sel_hi:[1,0]
	v_pk_mul_f32 v[80:81], v[92:93], v[38:39] op_sel_hi:[1,0]
	v_pk_mul_f32 v[86:87], v[86:87], v[38:39] op_sel_hi:[1,0]
	v_pk_mul_f32 v[84:85], v[84:85], v[38:39] op_sel_hi:[1,0]
	v_lshl_add_u64 v[36:37], v[36:37], 0, v[152:153]
	v_cvt_pk_bf16_f32 v80, v80, v81
	v_cvt_pk_bf16_f32 v81, v82, v83
	v_cvt_pk_bf16_f32 v82, v84, v85
	v_cvt_pk_bf16_f32 v83, v86, v87
	global_store_dwordx4 v[36:37], v[80:83], off
	v_pk_mul_f32 v[78:79], v[78:79], v[38:39] op_sel_hi:[1,0]
	v_pk_mul_f32 v[76:77], v[76:77], v[38:39] op_sel_hi:[1,0]
	v_pk_mul_f32 v[80:81], v[74:75], v[38:39] op_sel_hi:[1,0]
; __device__ __forceinline__ unsigned cvt_pk_bf16(float lo, float hi) { const hwf2_t v = {lo, hi}; return __builtin_bit_cast(unsigned, __builtin_convertvector(v, hwbf2_t)); }
; #define PG8_BAR __builtin_amdgcn_s_barrier()
;     __device__ __forceinline__ void operator()(const f32x4 (&acc)[2][2][4][2], const Unit& u, int wr, int wc, int fr, int fq, const PG8_LAS unsigned char* area) const {
;     ...
;         for (int ai = 0; ai < 2; ++ai)
; #pragma unroll
;             for (int m = 0; m < 4; ++m) { bf16_t* rowp = O + (size_t)(row0 + ai * HALF + m * 16) * ldc + col0; const float r_ = rsv[ai][m];
; #pragma unroll
;                 for (int bj = 0; bj < 2; ++bj) { const f32x4 v0 = acc[ai][bj][m][0] * r_, v1 = acc[ai][bj][m][1] * r_;
;                     u32x4 w; w.x = cvt_pk_bf16(v0[0], v0[1]); w.y = cvt_pk_bf16(v0[2], v0[3]); w.z = cvt_pk_bf16(v1[0], v1[1]); w.w = cvt_pk_bf16(v1[2], v1[3]);
;                     *(u32x4*)(rowp + bj * HALF) = w; } }
; template <class Epi, class Sched, bool ALIGN_EPI = false, bool SP2 = false, bool ABLK = false, bool BBLK = false>
; __device__ __forceinline__ void gemm_phase(PG8_LAS unsigned char* lds, const Gemm g, const Sched& S, const Epi& E) {
;     ...
;         if constexpr (!Epi::AFTER_DRAIN) { E(acc, cur, wr, wc, fr, fq, rs_area); S.done(cur); }
;         if (!has_next) break;
; #pragma unroll
;         for (int a = 0; a < 2; ++a)
; #pragma unroll
;             for (int b = 0; b < 2; ++b)
; #pragma unroll
;                 for (int m = 0; m < 4; ++m)
; #pragma unroll
;                     for (int n = 0; n < 2; ++n) acc[a][b][m][n] = (f32x4){0.f, 0.f, 0.f, 0.f};
;         cur = nxt; cA = nA; cB = nB; ++ui;
;         if constexpr (ALIGN_EPI) { if (wr == 1) PG8_BAR; }
	v_pk_mul_f32 v[38:39], v[72:73], v[38:39] op_sel_hi:[1,0]
	v_cvt_pk_bf16_f32 v72, v76, v77
	v_cvt_pk_bf16_f32 v73, v78, v79
	v_cvt_pk_bf16_f32 v74, v38, v39
	v_cvt_pk_bf16_f32 v75, v80, v81
	global_store_dwordx4 v[36:37], v[72:75], off offset:256
	v_add_u32_e32 v36, 0x80, v164
	v_mad_i64_i32 v[36:37], s[12:13], v36, s57, 0
	v_pk_mul_f32 v[38:39], v[70:71], v[158:159] op_sel_hi:[1,0]
	v_lshl_add_u64 v[36:37], v[36:37], 1, s[96:97]
	v_pk_mul_f32 v[70:71], v[66:67], v[158:159] op_sel_hi:[1,0]
	v_pk_mul_f32 v[66:67], v[64:65], v[158:159] op_sel_hi:[1,0]
	v_cvt_pk_bf16_f32 v65, v38, v39
	v_pk_mul_f32 v[38:39], v[58:59], v[158:159] op_sel_hi:[1,0]
	v_pk_mul_f32 v[56:57], v[56:57], v[158:159] op_sel_hi:[1,0]
	v_pk_mul_f32 v[58:59], v[50:51], v[158:159] op_sel_hi:[1,0]
	v_pk_mul_f32 v[50:51], v[48:49], v[158:159] op_sel_hi:[1,0]
	v_lshl_add_u64 v[36:37], v[36:37], 0, v[152:153]
	v_cvt_pk_bf16_f32 v64, v68, v69
	v_cvt_pk_bf16_f32 v66, v66, v67
	v_cvt_pk_bf16_f32 v67, v70, v71
	v_cvt_pk_bf16_f32 v48, v56, v57
	v_cvt_pk_bf16_f32 v49, v38, v39
	v_cvt_pk_bf16_f32 v50, v50, v51
	v_cvt_pk_bf16_f32 v51, v58, v59
	global_store_dwordx4 v[36:37], v[64:67], off
	global_store_dwordx4 v[36:37], v[48:51], off offset:256
	v_add_u32_e32 v36, 0x90, v164
	v_mad_i64_i32 v[36:37], s[12:13], v36, s57, 0
	v_mov_b32_e32 v38, v159
	v_lshl_add_u64 v[36:37], v[36:37], 1, s[96:97]
	v_pk_mul_f32 v[50:51], v[62:63], v[38:39] op_sel_hi:[1,0]
	v_pk_mul_f32 v[48:49], v[60:61], v[38:39] op_sel_hi:[1,0]
	v_pk_mul_f32 v[54:55], v[54:55], v[38:39] op_sel_hi:[1,0]
	v_pk_mul_f32 v[52:53], v[52:53], v[38:39] op_sel_hi:[1,0]
	v_lshl_add_u64 v[36:37], v[36:37], 0, v[152:153]
	v_cvt_pk_bf16_f32 v48, v48, v49
	v_cvt_pk_bf16_f32 v49, v50, v51
	v_cvt_pk_bf16_f32 v50, v52, v53
	v_cvt_pk_bf16_f32 v51, v54, v55
	global_store_dwordx4 v[36:37], v[48:51], off
	v_pk_mul_f32 v[42:43], v[42:43], v[38:39] op_sel_hi:[1,0]
	v_pk_mul_f32 v[40:41], v[40:41], v[38:39] op_sel_hi:[1,0]
	v_pk_mul_f32 v[48:49], v[30:31], v[38:39] op_sel_hi:[1,0]
	v_pk_mul_f32 v[30:31], v[28:29], v[38:39] op_sel_hi:[1,0]
	v_cvt_pk_bf16_f32 v28, v40, v41
	v_cvt_pk_bf16_f32 v29, v42, v43
	v_cvt_pk_bf16_f32 v30, v30, v31
	v_cvt_pk_bf16_f32 v31, v48, v49
	global_store_dwordx4 v[36:37], v[28:31], off offset:256
	v_pk_mul_f32 v[34:35], v[34:35], v[150:151] op_sel_hi:[1,0]
	v_pk_mul_f32 v[32:33], v[32:33], v[150:151] op_sel_hi:[1,0]
	v_add_u32_e32 v28, 0xa0, v164
	v_mad_i64_i32 v[28:29], s[12:13], v28, s57, 0
	v_lshl_add_u64 v[28:29], v[28:29], 1, s[96:97]
	v_lshl_add_u64 v[36:37], v[28:29], 0, v[152:153]
	v_pk_mul_f32 v[30:31], v[46:47], v[150:151] op_sel_hi:[1,0]
	v_pk_mul_f32 v[28:29], v[44:45], v[150:151] op_sel_hi:[1,0]
	v_pk_mul_f32 v[22:23], v[22:23], v[150:151] op_sel_hi:[1,0]
	v_cvt_pk_bf16_f32 v28, v28, v29
	v_cvt_pk_bf16_f32 v29, v30, v31
	v_cvt_pk_bf16_f32 v30, v32, v33
	v_cvt_pk_bf16_f32 v31, v34, v35
	global_store_dwordx4 v[36:37], v[28:31], off
	v_pk_mul_f32 v[20:21], v[20:21], v[150:151] op_sel_hi:[1,0]
	s_andn2_b64 vcc, exec, s[2:3]
	v_pk_mul_f32 v[28:29], v[14:15], v[150:151] op_sel_hi:[1,0]
	v_pk_mul_f32 v[14:15], v[12:13], v[150:151] op_sel_hi:[1,0]
	v_cvt_pk_bf16_f32 v12, v20, v21
	v_cvt_pk_bf16_f32 v13, v22, v23
	v_cvt_pk_bf16_f32 v14, v14, v15
	v_cvt_pk_bf16_f32 v15, v28, v29
	global_store_dwordx4 v[36:37], v[12:15], off offset:256
	v_mov_b32_e32 v22, v151
	v_pk_mul_f32 v[18:19], v[18:19], v[22:23] op_sel_hi:[1,0]
	v_add_u32_e32 v12, 0xb0, v164
	v_mad_i64_i32 v[12:13], s[12:13], v12, s57, 0
	v_lshl_add_u64 v[12:13], v[12:13], 1, s[96:97]
	v_lshl_add_u64 v[20:21], v[12:13], 0, v[152:153]
	v_pk_mul_f32 v[14:15], v[26:27], v[22:23] op_sel_hi:[1,0]
	v_pk_mul_f32 v[12:13], v[24:25], v[22:23] op_sel_hi:[1,0]
	v_pk_mul_f32 v[16:17], v[16:17], v[22:23] op_sel_hi:[1,0]
	v_cvt_pk_bf16_f32 v12, v12, v13
	v_cvt_pk_bf16_f32 v13, v14, v15
	v_cvt_pk_bf16_f32 v14, v16, v17
	v_cvt_pk_bf16_f32 v15, v18, v19
	global_store_dwordx4 v[20:21], v[12:15], off
	v_pk_mul_f32 v[10:11], v[10:11], v[22:23] op_sel_hi:[1,0]
	v_pk_mul_f32 v[8:9], v[8:9], v[22:23] op_sel_hi:[1,0]
	v_pk_mul_f32 v[12:13], v[6:7], v[22:23] op_sel_hi:[1,0]
	v_pk_mul_f32 v[6:7], v[4:5], v[22:23] op_sel_hi:[1,0]
	v_cvt_pk_bf16_f32 v4, v8, v9
	v_cvt_pk_bf16_f32 v5, v10, v11
	v_cvt_pk_bf16_f32 v6, v6, v7
	v_cvt_pk_bf16_f32 v7, v12, v13
	s_mov_b64 s[2:3], -1
	global_store_dwordx4 v[20:21], v[4:7], off offset:256
	s_cbranch_vccnz .LBB0_912
	s_andn2_b64 vcc, exec, s[4:5]
	s_cbranch_vccnz .LBB0_911
	s_branch .LBB0_911

; #define PG8_BAR __builtin_amdgcn_s_barrier()
;     __host__ __device__ bool next(int i, Unit& u) const {
;         const long L = (long)i * G + c; if (L >= nwg) return false;
;         int wgid = (int)L; { const int q = nwg / NXCD, r = nwg % NXCD, xcd = wgid % NXCD, off = wgid / NXCD; wgid = (xcd < r ? xcd * (q + 1) : r * (q + 1) + (xcd - r) * q) + off; }
; template <class Epi, class Sched, bool ALIGN_EPI = false, bool SP2 = false, bool ABLK = false, bool BBLK = false>
; __device__ __forceinline__ void gemm_phase(PG8_LAS unsigned char* lds, const Gemm g, const Sched& S, const Epi& E) {
;     ...
;     for (int i = 0; i < 2; ++i) { int R, C; stage_rc(tid * 16 + i * 8192, R, C); const int Rb = Epi::PERM ? ((R & ~31) + perm32(R & 31)) : R;
;         voffA[i] = ABLK ? (unsigned)(R * BK + C) * 2u : (unsigned)(R * K + C) * 2u; voffB[i] = BBLK ? (unsigned)(Rb * BK + C) * 2u : (unsigned)(Rb * K + C) * 2u; }
;     const size_t kstepB = BBLK ? (size_t)BM * BK * 2 : (size_t)(BK * 2), kstepA = ABLK ? (size_t)BM * BK * 2 : (size_t)(BK * 2);
;     const size_t hstepB = BBLK ? (size_t)HALF * BK * 2 : (size_t)HALF * K * 2, hstepA = ABLK ? (size_t)HALF * BK * 2 : (size_t)HALF * K * 2;
;     const size_t tstep = (size_t)BM * K * 2;
;     const unsigned ldsw = (unsigned)wid * 1024u;
;     const int aoff = lds_byte(wr * 64 + fr, fq * 8), boff = lds_byte(wc * 32 + fr, fq * 8);
;     ...
;     Unit cur, nxt; int ui = 0;
;     if (!S.next(0, cur)) return;
;     f32x4 acc[2][2][4][2];
; #pragma unroll
;     for (int a = 0; a < 2; ++a)
; #pragma unroll
;         for (int b = 0; b < 2; ++b)
; #pragma unroll
;             for (int m = 0; m < 4; ++m)
; #pragma unroll
;                 for (int n = 0; n < 2; ++n) acc[a][b][m][n] = (f32x4){0.f, 0.f, 0.f, 0.f};
;     bf16x8 At[4][2], B0[2][2], B1[2][2];
;     const char* cA = (const char*)g.A + (size_t)cur.pm * tstep; const char* cB = (const char*)g.Bt + (size_t)cur.pn * tstep;
;     S.a_ready(cur);
;     if constexpr (SP2) {
;         PG8_STAGE(PG8_SB(0, 0), cB, voffB); PG8_STAGE(PG8_SB(0, 1), cB + hstepB, voffB); PG8_STAGE(PG8_SA(0, 0), cA, voffA); PG8_STAGE(PG8_SA(0, 1), cA + hstepA, voffA);
;         if (wr == 1) PG8_BAR;
;         PG8_WAIT_V(2); PG8_BAR;
;         PG8_STAGE(PG8_SB(1, 0), cB + kstepB, voffB); PG8_STAGE(PG8_SA(1, 0), cA + kstepA, voffA); PG8_STAGE(PG8_SB(1, 1), cB + hstepB + kstepB, voffB);
;         PG8_WAIT_V(6); PG8_BAR;
.LBB0_2099:
	v_bfe_i32 v5, v10, 27, 1
	v_lshlrev_b32_e32 v3, 4, v10
	v_lshrrev_b32_e32 v5, 22, v5
	v_add_u32_e32 v5, v3, v5
	v_and_b32_e32 v5, 0xfffffc00, v5
	v_sub_u32_e32 v5, v3, v5
	v_lshrrev_b32_e32 v6, 4, v5
	v_bitop3_b32 v6, v6, v5, 32 bitop3:0x6c
	v_ashrrev_i32_e32 v5, 31, v5
	v_lshrrev_b32_e32 v5, 26, v5
	v_ashrrev_i32_e32 v4, 31, v10
	v_add_u32_e32 v5, v6, v5
	v_lshrrev_b32_e32 v4, 26, v4
	v_ashrrev_i32_e32 v5, 6, v5
	v_add_u32_e32 v4, v10, v4
	v_mul_i32_i24_e32 v9, 64, v5
	v_ashrrev_i32_e32 v4, 6, v4
	v_sub_u32_e32 v6, v6, v9
	v_lshlrev_b32_e32 v7, 3, v4
	v_lshlrev_b32_e32 v8, 5, v4
	v_ashrrev_i16_sdwa v6, v1, sext(v6) dst_sel:DWORD dst_unused:UNUSED_PAD src0_sel:DWORD src1_sel:BYTE_0
	v_and_b32_e32 v7, -16, v7
	v_and_b32_e32 v8, 32, v8
	v_bfe_i32 v6, v6, 0, 16
	v_add_u32_e32 v7, v5, v7
	v_and_b32_e32 v12, 3, v5
	s_mov_b32 s1, 0x1ffffe0
	v_add_lshl_u32 v8, v8, v6, 1
	v_add_u32_e32 v3, 0x2000, v3
	v_lshlrev_b32_e32 v9, 1, v7
	v_lshrrev_b32_e32 v11, 2, v7
	v_and_or_b32 v12, v7, s1, v12
	v_lshl_add_u32 v136, v7, 7, v8
	v_ashrrev_i32_e32 v7, 31, v3
	v_lshrrev_b32_e32 v7, 22, v7
	v_and_b32_e32 v9, 24, v9
	v_and_b32_e32 v11, 4, v11
	v_add_u32_e32 v7, v3, v7
	v_or3_b32 v9, v12, v11, v9
	v_ashrrev_i32_e32 v7, 10, v7
	v_lshl_add_u32 v138, v9, 7, v8
	v_mul_i32_i24_e32 v8, 0x400, v7
	v_sub_u32_e32 v3, v3, v8
	v_lshrrev_b32_e32 v8, 4, v3
	v_bitop3_b32 v3, v8, v3, 32 bitop3:0x6c
	v_lshlrev_b32_e32 v8, 3, v7
	v_and_b32_e32 v9, -16, v8
	v_ashrrev_i32_e32 v8, 31, v3
	v_lshrrev_b32_e32 v8, 26, v8
	v_add_u32_e32 v11, v3, v8
	v_ashrrev_i32_e32 v8, 6, v11
	v_add_u32_e32 v12, v8, v9
	v_and_b32_e32 v14, 3, v8
	s_add_i32 s0, s4, s0
	v_and_or_b32 v14, v12, s1, v14
	s_ashr_i32 s1, s0, 31
	s_lshr_b32 s1, s1, 27
	s_add_i32 s1, s0, s1
	s_ashr_i32 s4, s1, 5
	s_and_b32 s1, s1, 0xffe0
	s_sub_i32 s0, s0, s1
	s_bfe_i32 s1, s0, 0x80000
	s_bfe_u32 s1, s1, 0x2000d
	s_add_i32 s1, s0, s1
	s_lshl_b32 s8, s4, 2
	s_bfe_i32 s4, s1, 0x80000
	s_and_b32 s1, s1, 0xfc
	s_sub_i32 s0, s0, s1
	s_sext_i32_i16 s4, s4
	s_sext_i32_i8 s0, s0
	v_lshlrev_b32_e32 v9, 5, v7
	s_lshr_b32 s4, s4, 2
	s_add_i32 s8, s8, s0
	v_and_b32_e32 v13, 32, v9
	v_and_b32_e32 v9, 0xc0, v11
	s_ashr_i32 s6, s5, 6
	s_ashr_i32 s9, s8, 31
	s_bfe_i64 s[10:11], s[4:5], 0x100000
	v_sub_u32_e32 v3, v3, v9
	s_ashr_i32 s7, s5, 8
	s_lshl_b32 s34, s6, 10
	s_lshl_b64 s[0:1], s[8:9], 20
	s_lshl_b64 s[10:11], s[10:11], 20
	v_readlane_b32 s12, v254, 3
	v_ashrrev_i16_sdwa v3, v1, sext(v3) dst_sel:DWORD dst_unused:UNUSED_PAD src0_sel:DWORD src1_sel:BYTE_0
	v_readlane_b32 s13, v254, 4
	s_add_u32 s24, s12, s10
	v_bfe_i32 v9, v3, 0, 16
	v_lshlrev_b32_e32 v3, 1, v12
	v_lshrrev_b32_e32 v11, 2, v12
	s_addc_u32 s25, s13, s11
	s_add_i32 s9, s34, 0
	v_and_b32_e32 v3, 24, v3
	v_and_b32_e32 v11, 4, v11
	s_add_i32 m0, s9, 0x10000
	v_or3_b32 v3, v14, v11, v3
	v_add_lshl_u32 v11, v13, v9, 1
	global_load_lds_dwordx4 v138, s[24:25]
	s_add_i32 m0, s9, 0x12000
	v_lshl_add_u32 v142, v3, 7, v11
	s_add_u32 s10, s24, 0x4000
	global_load_lds_dwordx4 v142, s[24:25]
	s_addc_u32 s11, s25, 0
	s_add_i32 m0, s9, 0x14000
	v_lshl_add_u32 v140, v12, 7, v11
	global_load_lds_dwordx4 v138, s[10:11]
	s_add_i32 m0, s9, 0x16000
	s_add_u32 s22, s72, s0
	s_addc_u32 s23, s73, s1
	s_add_i32 s35, s9, 0x2000
	global_load_lds_dwordx4 v142, s[10:11]
	s_mov_b32 m0, s9
	s_add_u32 s0, s22, 0x4000
	global_load_lds_dwordx4 v136, s[22:23]
	s_mov_b32 m0, s35
	s_addc_u32 s1, s23, 0
	s_add_i32 s36, s9, 0x4000
	global_load_lds_dwordx4 v140, s[22:23]
	s_mov_b32 m0, s36
	s_add_i32 s37, s9, 0x6000
	global_load_lds_dwordx4 v136, s[0:1]
	s_mov_b32 m0, s37
	s_cmp_eq_u32 s7, 1
	global_load_lds_dwordx4 v140, s[0:1]
	v_readlane_b32 s0, v252, 21
	v_readlane_b32 s1, v252, 22
	s_load_dword s62, s[0:1], 0x0
	s_cselect_b64 s[0:1], -1, 0
	s_cmp_lg_u32 s7, 1
	s_cbranch_scc1 .LBB0_2101
.LBB0_2101:
	v_lshrrev_b32_e32 v12, 1, v10
	v_and_b32_e32 v12, 24, v12
	v_and_b32_e32 v11, 15, v10
	v_lshlrev_b32_e32 v13, 1, v12
	v_lshlrev_b32_e32 v10, 2, v10
	s_sext_i32_i8 s71, s4
	v_lshl_or_b32 v3, s7, 6, v11
	v_lshl_or_b32 v11, v11, 6, v13
	s_lshl_b32 s4, s7, 13
	v_and_b32_e32 v10, 32, v10
	v_bitop3_b32 v13, v11, s4, v10 bitop3:0xde
	s_lshl_b32 s4, s6, 5
	s_and_b32 s4, s4, 0x60
	s_waitcnt lgkmcnt(0)
	s_ashr_i32 s63, s62, 31
	s_lshl_b32 s6, s4, 7
	v_bitop3_b32 v148, v11, s6, v10 bitop3:0xde
	s_add_u32 s6, s24, 0x8000
	v_mov_b32_e32 v139, v2
	s_addc_u32 s7, s25, 0
	s_add_i32 m0, s9, 0x18000
	v_lshl_add_u64 v[10:11], s[6:7], 0, v[138:139]
	v_mov_b32_e32 v143, v2
	s_waitcnt vmcnt(2)
	s_barrier
	global_load_lds_dwordx4 v[10:11], off
	s_add_i32 m0, s9, 0x1a000
	v_lshl_add_u64 v[10:11], s[6:7], 0, v[142:143]
	s_add_u32 s6, s22, 0x8000
	v_mov_b32_e32 v137, v2
	s_addc_u32 s7, s23, 0
	s_add_i32 s64, s9, 0x8000
	v_mov_b32_e32 v141, v2
	global_load_lds_dwordx4 v[10:11], off
	v_lshl_add_u64 v[10:11], s[6:7], 0, v[136:137]
	s_mov_b32 m0, s64
	s_add_i32 s65, s9, 0xa000
	global_load_lds_dwordx4 v[10:11], off
	v_lshl_add_u64 v[10:11], s[6:7], 0, v[140:141]
	s_add_u32 s6, s24, 0xc000
	s_mov_b32 m0, s65
	s_addc_u32 s7, s25, 0
	global_load_lds_dwordx4 v[10:11], off
	s_add_i32 m0, s9, 0x1c000
	v_lshl_add_u64 v[10:11], s[6:7], 0, v[138:139]
	global_load_lds_dwordx4 v[10:11], off
	v_lshl_add_u64 v[10:11], s[6:7], 0, v[142:143]
	s_add_i32 m0, s9, 0x1e000
	s_cmpk_lt_u32 s5, 0x100
	global_load_lds_dwordx4 v[10:11], off
	v_lshlrev_b32_e32 v10, 10, v4
	v_and_b32_e32 v10, 0xfffff800, v10
	v_lshl_add_u32 v5, v5, 7, v10
	v_and_b32_e32 v4, 1, v4
	v_lshl_or_b32 v4, v4, 6, v5
	v_lshl_add_u32 v144, v6, 1, v4
	v_lshlrev_b32_e32 v4, 10, v7
	v_and_b32_e32 v4, 0xfffff800, v4
	s_waitcnt vmcnt(6)
	v_lshl_add_u32 v4, v8, 7, v4
	v_and_b32_e32 v5, 1, v7
	v_lshl_or_b32 v4, v5, 6, v4
	s_cselect_b64 s[6:7], -1, 0
	v_or_b32_e32 v149, s4, v12
	v_mov_b32_e32 v145, v2
	v_lshl_add_u32 v146, v9, 1, v4
	v_mov_b32_e32 v147, v2
	s_mov_b32 s70, 0
	v_add_u32_e32 v150, 0, v13
	s_barrier
	s_branch .LBB0_2104

; #define PG8_LAS __attribute__((address_space(3)))
; #define PG8_STAGE(bufoff, gbase, voff) do { _Pragma("unroll") for (int _i = 0; _i < 2; ++_i) \
;         __builtin_amdgcn_global_load_lds((const unsigned*)((const char*)(gbase) + (voff)[_i]), (PG8_LAS unsigned*)(lds + (bufoff) + ldsw + _i * 8192), 16, 0, 0); } while (0)
; #define PG8_LDA(dst, b, h) do { _Pragma("unroll") for (int m = 0; m < 4; ++m) _Pragma("unroll") for (int k = 0; k < 2; ++k) dst[m][k] = *(const PG8_LAS bf16x8*)(lds + PG8_SA(b, h) + aoff + m * 2048 + k * 1024); } while (0)
; #define PG8_LDB(dst, b, h) do { _Pragma("unroll") for (int n = 0; n < 2; ++n) _Pragma("unroll") for (int k = 0; k < 2; ++k) dst[n][k] = *(const PG8_LAS bf16x8*)(lds + PG8_SB(b, h) + boff + n * 2048 + k * 1024); } while (0)
; template <class Epi, class Sched, bool ALIGN_EPI = false, bool SP2 = false, bool ABLK = false, bool BBLK = false>
; __device__ __forceinline__ void gemm_phase(PG8_LAS unsigned char* lds, const Gemm g, const Sched& S, const Epi& E) {
;     ...
;         const bool has_next = S.next(ui + 1, nxt);
;         PG8_LAS unsigned char* const rs_area = lds + STAGE_BYTES + wid * 512;
;         E.stage(cur, rs_area, wr, lane);
;         const char* nA = has_next ? (const char*)g.A + (size_t)nxt.pm * tstep : cA; const char* nB = has_next ? (const char*)g.Bt + (size_t)nxt.pn * tstep : cB;
;         for (int t = 0; t < nt; t += 2) {
;             const bool last = (t == nt - 2);
;             const char* a1 = cA + (size_t)(t + 1) * kstepA;
;             const char* a2 = last ? nA : cA + (size_t)(t + 2) * kstepA; const char* b2 = last ? nB : cB + (size_t)(t + 2) * kstepB;
;             const char* a3 = a2 + kstepA; const char* b3 = b2 + kstepB;
;             if (last && has_next) S.a_ready(nxt);
;             if constexpr (SP2) {
;             PG8_LDB(B0, 0, 0); PG8_LDB(B1, 0, 1); PG8_SCHED; PG8_LDA(At, 0, 0); PG8_STAGE(PG8_SA(1, 1), a1 + hstepA, voffA);
;             PG8_WAIT_V(8); PG8_WAIT_L(0); PG8_BAR; PG8_MMA(0, 0, At, B0); PG8_MMA(0, 1, At, B1); PG8_BAR; PG8_SCHED;
;     ...
; #pragma unroll
;         for (int a = 0; a < 2; ++a)
; #pragma unroll
;             for (int b = 0; b < 2; ++b)
; #pragma unroll
;                 for (int m = 0; m < 4; ++m)
; #pragma unroll
;                     for (int n = 0; n < 2; ++n) acc[a][b][m][n] = (f32x4){0.f, 0.f, 0.f, 0.f};
;         cur = nxt; cA = nA; cB = nB; ++ui;
.LBB0_2110:
	s_ashr_i32 s17, s16, 31
	s_lshl_b64 s[12:13], s[16:17], 20
	s_add_u32 s18, s72, s12
	s_addc_u32 s19, s73, s13
	s_and_b64 s[12:13], s[4:5], exec
	s_cselect_b32 s12, s19, s23
	s_cselect_b32 s17, s18, s22
	s_ashr_i32 s11, s10, 31
	s_lshl_b64 s[20:21], s[10:11], 20
	v_readlane_b32 s26, v254, 3
	v_readlane_b32 s27, v254, 4
	s_add_u32 s20, s26, s20
	s_addc_u32 s21, s27, s21
	s_and_b64 s[26:27], s[4:5], exec
	s_cselect_b32 s11, s21, s25
	s_cselect_b32 s77, s20, s24
	s_add_u32 s22, s22, 0xc000
	s_addc_u32 s23, s23, 0
	s_add_u32 s82, s24, 0x10000
	v_mov_b32_e32 v4, 0
	s_addc_u32 vcc_lo, s25, 0
	s_mov_b32 s13, -2
	v_mov_b32_e32 v5, v4
	v_mov_b32_e32 v6, v4
	v_mov_b32_e32 v7, v4
	v_mov_b32_e32 v8, v4
	v_mov_b32_e32 v9, v4
	v_mov_b32_e32 v10, v4
	v_mov_b32_e32 v11, v4
	v_mov_b32_e32 v12, v4
	v_mov_b32_e32 v13, v4
	v_mov_b32_e32 v14, v4
	v_mov_b32_e32 v15, v4
	v_mov_b32_e32 v16, v4
	v_mov_b32_e32 v17, v4
	v_mov_b32_e32 v18, v4
	v_mov_b32_e32 v19, v4
	v_mov_b32_e32 v28, v4
	v_mov_b32_e32 v29, v4
	v_mov_b32_e32 v30, v4
	v_mov_b32_e32 v31, v4
	v_mov_b32_e32 v32, v4
	v_mov_b32_e32 v33, v4
	v_mov_b32_e32 v34, v4
	v_mov_b32_e32 v35, v4
	v_mov_b32_e32 v48, v4
	v_mov_b32_e32 v49, v4
	v_mov_b32_e32 v50, v4
	v_mov_b32_e32 v51, v4
	v_mov_b32_e32 v52, v4
	v_mov_b32_e32 v53, v4
	v_mov_b32_e32 v54, v4
	v_mov_b32_e32 v55, v4
	v_mov_b32_e32 v20, v4
	v_mov_b32_e32 v21, v4
	v_mov_b32_e32 v22, v4
	v_mov_b32_e32 v23, v4
	v_mov_b32_e32 v24, v4
	v_mov_b32_e32 v25, v4
	v_mov_b32_e32 v26, v4
	v_mov_b32_e32 v27, v4
	v_mov_b32_e32 v40, v4
	v_mov_b32_e32 v41, v4
	v_mov_b32_e32 v42, v4
	v_mov_b32_e32 v43, v4
	v_mov_b32_e32 v44, v4
	v_mov_b32_e32 v45, v4
	v_mov_b32_e32 v46, v4
	v_mov_b32_e32 v47, v4
	v_mov_b32_e32 v56, v4
	v_mov_b32_e32 v57, v4
	v_mov_b32_e32 v58, v4
	v_mov_b32_e32 v59, v4
	v_mov_b32_e32 v60, v4
	v_mov_b32_e32 v61, v4
	v_mov_b32_e32 v62, v4
	v_mov_b32_e32 v63, v4
	v_mov_b32_e32 v64, v4
	v_mov_b32_e32 v65, v4
	v_mov_b32_e32 v66, v4
	v_mov_b32_e32 v67, v4
	v_mov_b32_e32 v68, v4
	v_mov_b32_e32 v69, v4
	v_mov_b32_e32 v70, v4
	v_mov_b32_e32 v71, v4
	v_mov_b32_e32 v72, v4
	v_mov_b32_e32 v73, v4
	v_mov_b32_e32 v74, v4
	v_mov_b32_e32 v75, v4
	v_mov_b32_e32 v76, v4
	v_mov_b32_e32 v77, v4
	v_mov_b32_e32 v78, v4
	v_mov_b32_e32 v79, v4
	v_mov_b32_e32 v80, v4
	v_mov_b32_e32 v81, v4
	v_mov_b32_e32 v82, v4
	v_mov_b32_e32 v83, v4
	v_mov_b32_e32 v84, v4
	v_mov_b32_e32 v85, v4
	v_mov_b32_e32 v86, v4
	v_mov_b32_e32 v87, v4
	v_mov_b32_e32 v96, v4
	v_mov_b32_e32 v97, v4
	v_mov_b32_e32 v98, v4
	v_mov_b32_e32 v99, v4
	v_mov_b32_e32 v100, v4
	v_mov_b32_e32 v101, v4
	v_mov_b32_e32 v102, v4
	v_mov_b32_e32 v103, v4
	v_mov_b32_e32 v112, v4
	v_mov_b32_e32 v113, v4
	v_mov_b32_e32 v114, v4
	v_mov_b32_e32 v115, v4
	v_mov_b32_e32 v116, v4
	v_mov_b32_e32 v117, v4
	v_mov_b32_e32 v118, v4
	v_mov_b32_e32 v119, v4
	v_mov_b32_e32 v88, v4
	v_mov_b32_e32 v89, v4
	v_mov_b32_e32 v90, v4
	v_mov_b32_e32 v91, v4
	v_mov_b32_e32 v92, v4
	v_mov_b32_e32 v93, v4
	v_mov_b32_e32 v94, v4
	v_mov_b32_e32 v95, v4
	v_mov_b32_e32 v104, v4
	v_mov_b32_e32 v105, v4
	v_mov_b32_e32 v106, v4
	v_mov_b32_e32 v107, v4
	v_mov_b32_e32 v108, v4
	v_mov_b32_e32 v109, v4
	v_mov_b32_e32 v110, v4
	v_mov_b32_e32 v111, v4
	v_mov_b32_e32 v120, v4
	v_mov_b32_e32 v121, v4
	v_mov_b32_e32 v122, v4
	v_mov_b32_e32 v123, v4
	v_mov_b32_e32 v124, v4
	v_mov_b32_e32 v125, v4
	v_mov_b32_e32 v126, v4
	v_mov_b32_e32 v127, v4
	v_mov_b32_e32 v128, v4
	v_mov_b32_e32 v129, v4
	v_mov_b32_e32 v130, v4
	v_mov_b32_e32 v131, v4
	v_mov_b32_e32 v132, v4
	v_mov_b32_e32 v133, v4
	v_mov_b32_e32 v134, v4
	v_mov_b32_e32 v135, v4
	s_cmp_eq_u32 s100, 0
	s_cbranch_scc0 .Lk1_MOUT
.LBB0_2111:
	s_add_u32 s24, s22, 0x4000
	s_addc_u32 s25, s23, 0
	s_cmp_eq_u32 s13, 28
	s_cselect_b32 s28, s17, s24
	s_cselect_b32 s29, s12, s25
	s_cselect_b32 s26, s77, s82
	s_cselect_b32 s27, s11, vcc_lo
	s_add_u32 s24, s28, 0x8000
	s_addc_u32 s25, s29, 0
	s_add_i32 s68, 0, 0x10000
	v_add_u32_e32 v151, s68, v148
	s_add_i32 s88, 0, 0x14000
	ds_read_b128 v[36:39], v151
	ds_read_b128 v[152:155], v151 offset:1024
	ds_read_b128 v[156:159], v151 offset:2048
	ds_read_b128 v[160:163], v151 offset:3072
	v_add_u32_e32 v151, s88, v148
	ds_read_b128 v[164:167], v151
	ds_read_b128 v[168:171], v151 offset:1024
	ds_read_b128 v[172:175], v151 offset:2048
	ds_read_b128 v[176:179], v151 offset:3072
	s_add_i32 m0, s9, 0xc000
	ds_read_b128 v[180:183], v150
	ds_read_b128 v[184:187], v150 offset:1024
	ds_read_b128 v[188:191], v150 offset:2048
	ds_read_b128 v[192:195], v150 offset:3072
	ds_read_b128 v[196:199], v150 offset:4096
	ds_read_b128 v[200:203], v150 offset:5120
	ds_read_b128 v[204:207], v150 offset:6144
	ds_read_b128 v[208:211], v150 offset:7168
	global_load_lds_dwordx4 v144, s[22:23]
	s_add_i32 m0, s9, 0xe000
	s_nop 0
	global_load_lds_dwordx4 v146, s[22:23]
	s_waitcnt vmcnt(8)
	s_waitcnt lgkmcnt(0)
	s_setprio 1
	s_waitcnt lgkmcnt(0)
; #define PG8_STAGE(bufoff, gbase, voff) do { _Pragma("unroll") for (int _i = 0; _i < 2; ++_i) \
;         __builtin_amdgcn_global_load_lds((const unsigned*)((const char*)(gbase) + (voff)[_i]), (PG8_LAS unsigned*)(lds + (bufoff) + ldsw + _i * 8192), 16, 0, 0); } while (0)
; #define PG8_LDA(dst, b, h) do { _Pragma("unroll") for (int m = 0; m < 4; ++m) _Pragma("unroll") for (int k = 0; k < 2; ++k) dst[m][k] = *(const PG8_LAS bf16x8*)(lds + PG8_SA(b, h) + aoff + m * 2048 + k * 1024); } while (0)
; #define PG8_MMA(ai, bj, At, Bt) do { __builtin_amdgcn_s_setprio(1); _Pragma("unroll") for (int m = 0; m < 4; ++m) _Pragma("unroll") for (int n = 0; n < 2; ++n) _Pragma("unroll") for (int k = 0; k < 2; ++k) \
;         acc[ai][bj][m][n] = __builtin_amdgcn_mfma_f32_16x16x32_bf16(Bt[n][k], At[m][k], acc[ai][bj][m][n], 0, 0, 0); __builtin_amdgcn_s_setprio(0); } while (0)
; #define PG8_WAIT_V(n) asm volatile("s_waitcnt vmcnt(" #n ")" ::: "memory")
; #define PG8_WAIT_L(n) asm volatile("s_waitcnt lgkmcnt(" #n ")" ::: "memory")
; #define PG8_BAR __builtin_amdgcn_s_barrier()
; #define PG8_SCHED __builtin_amdgcn_sched_barrier(0)
; template <class Epi, class Sched, bool ALIGN_EPI = false, bool SP2 = false, bool ABLK = false, bool BBLK = false>
; __device__ __forceinline__ void gemm_phase(PG8_LAS unsigned char* lds, const Gemm g, const Sched& S, const Epi& E) {
;     ...
;             PG8_WAIT_V(8); PG8_WAIT_L(0); PG8_BAR; PG8_MMA(0, 0, At, B0); PG8_MMA(0, 1, At, B1); PG8_BAR; PG8_SCHED;
;             PG8_LDA(At, 0, 1); PG8_STAGE(PG8_SB(0, 0), b2, voffB); PG8_STAGE(PG8_SB(0, 1), b2 + hstepB, voffB); PG8_STAGE(PG8_SA(0, 0), a2, voffA);
;             PG8_WAIT_V(8); PG8_WAIT_L(0); PG8_BAR; PG8_MMA(1, 0, At, B0); PG8_MMA(1, 1, At, B1); PG8_BAR; PG8_SCHED;
	v_mfma_f32_16x16x32_bf16 v[132:135], v[36:39], v[180:183], v[132:135]
	v_mfma_f32_16x16x32_bf16 v[128:131], v[156:159], v[180:183], v[128:131]
	v_mfma_f32_16x16x32_bf16 v[124:127], v[36:39], v[188:191], v[124:127]
	v_mfma_f32_16x16x32_bf16 v[120:123], v[156:159], v[188:191], v[120:123]
	v_mfma_f32_16x16x32_bf16 v[108:111], v[36:39], v[196:199], v[108:111]
	v_mfma_f32_16x16x32_bf16 v[104:107], v[156:159], v[196:199], v[104:107]
	v_mfma_f32_16x16x32_bf16 v[92:95], v[36:39], v[204:207], v[92:95]
	v_mfma_f32_16x16x32_bf16 v[88:91], v[156:159], v[204:207], v[88:91]
	v_mfma_f32_16x16x32_bf16 v[132:135], v[152:155], v[184:187], v[132:135]
	v_mfma_f32_16x16x32_bf16 v[128:131], v[160:163], v[184:187], v[128:131]
	v_mfma_f32_16x16x32_bf16 v[124:127], v[152:155], v[192:195], v[124:127]
	v_mfma_f32_16x16x32_bf16 v[120:123], v[160:163], v[192:195], v[120:123]
	v_mfma_f32_16x16x32_bf16 v[108:111], v[152:155], v[200:203], v[108:111]
	v_mfma_f32_16x16x32_bf16 v[104:107], v[160:163], v[200:203], v[104:107]
	v_mfma_f32_16x16x32_bf16 v[92:95], v[152:155], v[208:211], v[92:95]
	v_mfma_f32_16x16x32_bf16 v[88:91], v[160:163], v[208:211], v[88:91]
	s_setprio 0
	s_setprio 1
	v_mfma_f32_16x16x32_bf16 v[116:119], v[164:167], v[180:183], v[116:119]
	v_mfma_f32_16x16x32_bf16 v[112:115], v[172:175], v[180:183], v[112:115]
	v_mfma_f32_16x16x32_bf16 v[100:103], v[164:167], v[188:191], v[100:103]
	v_mfma_f32_16x16x32_bf16 v[96:99], v[172:175], v[188:191], v[96:99]
	v_mfma_f32_16x16x32_bf16 v[84:87], v[164:167], v[196:199], v[84:87]
	v_mfma_f32_16x16x32_bf16 v[80:83], v[172:175], v[196:199], v[80:83]
	v_mfma_f32_16x16x32_bf16 v[76:79], v[164:167], v[204:207], v[76:79]
	v_mfma_f32_16x16x32_bf16 v[72:75], v[172:175], v[204:207], v[72:75]
	v_mfma_f32_16x16x32_bf16 v[116:119], v[168:171], v[184:187], v[116:119]
	v_mfma_f32_16x16x32_bf16 v[112:115], v[176:179], v[184:187], v[112:115]
	v_mfma_f32_16x16x32_bf16 v[100:103], v[168:171], v[192:195], v[100:103]
	v_mfma_f32_16x16x32_bf16 v[96:99], v[176:179], v[192:195], v[96:99]
	v_mfma_f32_16x16x32_bf16 v[84:87], v[168:171], v[200:203], v[84:87]
	v_mfma_f32_16x16x32_bf16 v[80:83], v[176:179], v[200:203], v[80:83]
	v_mfma_f32_16x16x32_bf16 v[76:79], v[168:171], v[208:211], v[76:79]
	v_mfma_f32_16x16x32_bf16 v[72:75], v[176:179], v[208:211], v[72:75]
	s_setprio 0
	s_barrier
	s_add_i32 s68, s68, s34
	s_mov_b32 m0, s68
	ds_read_b128 v[180:183], v150 offset:16384
	ds_read_b128 v[184:187], v150 offset:17408
	ds_read_b128 v[188:191], v150 offset:18432
	ds_read_b128 v[192:195], v150 offset:19456
	ds_read_b128 v[196:199], v150 offset:20480
	ds_read_b128 v[200:203], v150 offset:21504
	ds_read_b128 v[204:207], v150 offset:22528
	ds_read_b128 v[208:211], v150 offset:23552
	global_load_lds_dwordx4 v138, s[26:27]
	s_add_i32 m0, s68, 0x2000
	s_add_u32 s68, s26, 0x4000
	s_addc_u32 s69, s27, 0
	s_add_i32 s88, s88, s34
	global_load_lds_dwordx4 v142, s[26:27]
	s_mov_b32 m0, s88
	s_nop 0
	global_load_lds_dwordx4 v138, s[68:69]
	s_add_i32 m0, s88, 0x2000
	s_nop 0
	global_load_lds_dwordx4 v142, s[68:69]
	s_mov_b32 m0, s9
	s_nop 0
	global_load_lds_dwordx4 v136, s[28:29]
	s_mov_b32 m0, s35
	s_nop 0
	global_load_lds_dwordx4 v140, s[28:29]
	s_waitcnt vmcnt(8)
	s_waitcnt lgkmcnt(0)
	s_setprio 1
	s_waitcnt lgkmcnt(0)
	v_mfma_f32_16x16x32_bf16 v[68:71], v[36:39], v[180:183], v[68:71]
	v_mfma_f32_16x16x32_bf16 v[64:67], v[156:159], v[180:183], v[64:67]
	v_mfma_f32_16x16x32_bf16 v[60:63], v[36:39], v[188:191], v[60:63]
	v_mfma_f32_16x16x32_bf16 v[56:59], v[156:159], v[188:191], v[56:59]
	v_mfma_f32_16x16x32_bf16 v[44:47], v[36:39], v[196:199], v[44:47]
	v_mfma_f32_16x16x32_bf16 v[40:43], v[156:159], v[196:199], v[40:43]
	v_mfma_f32_16x16x32_bf16 v[24:27], v[36:39], v[204:207], v[24:27]
	v_mfma_f32_16x16x32_bf16 v[20:23], v[156:159], v[204:207], v[20:23]
	v_mfma_f32_16x16x32_bf16 v[68:71], v[152:155], v[184:187], v[68:71]
	v_mfma_f32_16x16x32_bf16 v[64:67], v[160:163], v[184:187], v[64:67]
	v_mfma_f32_16x16x32_bf16 v[60:63], v[152:155], v[192:195], v[60:63]
	v_mfma_f32_16x16x32_bf16 v[56:59], v[160:163], v[192:195], v[56:59]
	v_mfma_f32_16x16x32_bf16 v[44:47], v[152:155], v[200:203], v[44:47]
	v_mfma_f32_16x16x32_bf16 v[40:43], v[160:163], v[200:203], v[40:43]
	v_mfma_f32_16x16x32_bf16 v[24:27], v[152:155], v[208:211], v[24:27]
	v_mfma_f32_16x16x32_bf16 v[20:23], v[160:163], v[208:211], v[20:23]
	s_setprio 0
	s_setprio 1
	v_mfma_f32_16x16x32_bf16 v[48:51], v[172:175], v[180:183], v[48:51]
	v_mfma_f32_16x16x32_bf16 v[32:35], v[164:167], v[188:191], v[32:35]
	v_mfma_f32_16x16x32_bf16 v[28:31], v[172:175], v[188:191], v[28:31]
	v_mfma_f32_16x16x32_bf16 v[16:19], v[164:167], v[196:199], v[16:19]
	v_mfma_f32_16x16x32_bf16 v[12:15], v[172:175], v[196:199], v[12:15]
	v_mfma_f32_16x16x32_bf16 v[8:11], v[164:167], v[204:207], v[8:11]
	v_mfma_f32_16x16x32_bf16 v[4:7], v[172:175], v[204:207], v[4:7]
	v_mfma_f32_16x16x32_bf16 v[36:39], v[164:167], v[180:183], v[52:55]
	v_mfma_f32_16x16x32_bf16 v[48:51], v[176:179], v[184:187], v[48:51]
	v_mfma_f32_16x16x32_bf16 v[32:35], v[168:171], v[192:195], v[32:35]
	v_mfma_f32_16x16x32_bf16 v[28:31], v[176:179], v[192:195], v[28:31]
	v_mfma_f32_16x16x32_bf16 v[16:19], v[168:171], v[200:203], v[16:19]
	v_mfma_f32_16x16x32_bf16 v[12:15], v[176:179], v[200:203], v[12:15]
	v_mfma_f32_16x16x32_bf16 v[8:11], v[168:171], v[208:211], v[8:11]
	v_mfma_f32_16x16x32_bf16 v[4:7], v[176:179], v[208:211], v[4:7]
	v_mfma_f32_16x16x32_bf16 v[36:39], v[168:171], v[184:187], v[36:39]
	s_setprio 0
	s_barrier
; #define PG8_STAGE(bufoff, gbase, voff) do { _Pragma("unroll") for (int _i = 0; _i < 2; ++_i) \
;         __builtin_amdgcn_global_load_lds((const unsigned*)((const char*)(gbase) + (voff)[_i]), (PG8_LAS unsigned*)(lds + (bufoff) + ldsw + _i * 8192), 16, 0, 0); } while (0)
; #define PG8_LDA(dst, b, h) do { _Pragma("unroll") for (int m = 0; m < 4; ++m) _Pragma("unroll") for (int k = 0; k < 2; ++k) dst[m][k] = *(const PG8_LAS bf16x8*)(lds + PG8_SA(b, h) + aoff + m * 2048 + k * 1024); } while (0)
; #define PG8_LDB(dst, b, h) do { _Pragma("unroll") for (int n = 0; n < 2; ++n) _Pragma("unroll") for (int k = 0; k < 2; ++k) dst[n][k] = *(const PG8_LAS bf16x8*)(lds + PG8_SB(b, h) + boff + n * 2048 + k * 1024); } while (0)
; #define PG8_MMA(ai, bj, At, Bt) do { __builtin_amdgcn_s_setprio(1); _Pragma("unroll") for (int m = 0; m < 4; ++m) _Pragma("unroll") for (int n = 0; n < 2; ++n) _Pragma("unroll") for (int k = 0; k < 2; ++k) \
;         acc[ai][bj][m][n] = __builtin_amdgcn_mfma_f32_16x16x32_bf16(Bt[n][k], At[m][k], acc[ai][bj][m][n], 0, 0, 0); __builtin_amdgcn_s_setprio(0); } while (0)
; #define PG8_WAIT_V(n) asm volatile("s_waitcnt vmcnt(" #n ")" ::: "memory")
; #define PG8_WAIT_L(n) asm volatile("s_waitcnt lgkmcnt(" #n ")" ::: "memory")
; #define PG8_BAR __builtin_amdgcn_s_barrier()
; #define PG8_SCHED __builtin_amdgcn_sched_barrier(0)
; template <class Epi, class Sched, bool ALIGN_EPI = false, bool SP2 = false, bool ABLK = false, bool BBLK = false>
; __device__ __forceinline__ void gemm_phase(PG8_LAS unsigned char* lds, const Gemm g, const Sched& S, const Epi& E) {
;     ...
;             PG8_LDB(B0, 1, 0); PG8_LDB(B1, 1, 1); PG8_SCHED; PG8_LDA(At, 1, 0); PG8_STAGE(PG8_SA(0, 1), a2 + hstepA, voffA);
;             PG8_WAIT_V(8); PG8_WAIT_L(0); PG8_BAR; PG8_MMA(0, 0, At, B0); PG8_MMA(0, 1, At, B1); PG8_BAR; PG8_SCHED;
;             PG8_LDA(At, 1, 1); PG8_STAGE(PG8_SB(1, 0), b3, voffB); PG8_STAGE(PG8_SB(1, 1), b3 + hstepB, voffB); PG8_STAGE(PG8_SA(1, 0), a3, voffA);
;             PG8_WAIT_V(8); PG8_WAIT_L(0); PG8_BAR; PG8_MMA(1, 0, At, B0); PG8_MMA(1, 1, At, B1); PG8_BAR; PG8_SCHED;
	s_add_i32 s68, 0, 0x18000
	v_add_u32_e32 v151, s68, v148
	s_add_i32 s69, 0, 0x1c000
	ds_read_b128 v[52:55], v151
	ds_read_b128 v[152:155], v151 offset:1024
	ds_read_b128 v[156:159], v151 offset:2048
	ds_read_b128 v[160:163], v151 offset:3072
	v_add_u32_e32 v151, s69, v148
	ds_read_b128 v[164:167], v151
	ds_read_b128 v[168:171], v151 offset:1024
	ds_read_b128 v[172:175], v151 offset:2048
	ds_read_b128 v[176:179], v151 offset:3072
	s_add_u32 s28, s28, 0x4000
	s_addc_u32 s29, s29, 0
	s_mov_b32 m0, s36
	ds_read_b128 v[180:183], v150 offset:32768
	ds_read_b128 v[184:187], v150 offset:33792
	ds_read_b128 v[188:191], v150 offset:34816
	ds_read_b128 v[192:195], v150 offset:35840
	ds_read_b128 v[196:199], v150 offset:36864
	ds_read_b128 v[200:203], v150 offset:37888
	ds_read_b128 v[204:207], v150 offset:38912
	ds_read_b128 v[208:211], v150 offset:39936
	global_load_lds_dwordx4 v136, s[28:29]
	s_mov_b32 m0, s37
	s_nop 0
	global_load_lds_dwordx4 v140, s[28:29]
	s_waitcnt vmcnt(8)
	s_waitcnt lgkmcnt(0)
	s_setprio 1
	s_waitcnt lgkmcnt(0)
	v_mfma_f32_16x16x32_bf16 v[132:135], v[52:55], v[180:183], v[132:135]
	v_mfma_f32_16x16x32_bf16 v[128:131], v[156:159], v[180:183], v[128:131]
	v_mfma_f32_16x16x32_bf16 v[124:127], v[52:55], v[188:191], v[124:127]
	v_mfma_f32_16x16x32_bf16 v[120:123], v[156:159], v[188:191], v[120:123]
	v_mfma_f32_16x16x32_bf16 v[108:111], v[52:55], v[196:199], v[108:111]
	v_mfma_f32_16x16x32_bf16 v[104:107], v[156:159], v[196:199], v[104:107]
	v_mfma_f32_16x16x32_bf16 v[92:95], v[52:55], v[204:207], v[92:95]
	v_mfma_f32_16x16x32_bf16 v[88:91], v[156:159], v[204:207], v[88:91]
	v_mfma_f32_16x16x32_bf16 v[132:135], v[152:155], v[184:187], v[132:135]
	v_mfma_f32_16x16x32_bf16 v[128:131], v[160:163], v[184:187], v[128:131]
	v_mfma_f32_16x16x32_bf16 v[124:127], v[152:155], v[192:195], v[124:127]
	v_mfma_f32_16x16x32_bf16 v[120:123], v[160:163], v[192:195], v[120:123]
	v_mfma_f32_16x16x32_bf16 v[108:111], v[152:155], v[200:203], v[108:111]
	v_mfma_f32_16x16x32_bf16 v[104:107], v[160:163], v[200:203], v[104:107]
	v_mfma_f32_16x16x32_bf16 v[92:95], v[152:155], v[208:211], v[92:95]
	v_mfma_f32_16x16x32_bf16 v[88:91], v[160:163], v[208:211], v[88:91]
	s_setprio 0
	s_setprio 1
	v_mfma_f32_16x16x32_bf16 v[116:119], v[164:167], v[180:183], v[116:119]
	v_mfma_f32_16x16x32_bf16 v[112:115], v[172:175], v[180:183], v[112:115]
	v_mfma_f32_16x16x32_bf16 v[100:103], v[164:167], v[188:191], v[100:103]
	v_mfma_f32_16x16x32_bf16 v[96:99], v[172:175], v[188:191], v[96:99]
	v_mfma_f32_16x16x32_bf16 v[84:87], v[164:167], v[196:199], v[84:87]
	v_mfma_f32_16x16x32_bf16 v[80:83], v[172:175], v[196:199], v[80:83]
	v_mfma_f32_16x16x32_bf16 v[76:79], v[164:167], v[204:207], v[76:79]
	v_mfma_f32_16x16x32_bf16 v[72:75], v[172:175], v[204:207], v[72:75]
	v_mfma_f32_16x16x32_bf16 v[116:119], v[168:171], v[184:187], v[116:119]
	v_mfma_f32_16x16x32_bf16 v[112:115], v[176:179], v[184:187], v[112:115]
	v_mfma_f32_16x16x32_bf16 v[100:103], v[168:171], v[192:195], v[100:103]
	v_mfma_f32_16x16x32_bf16 v[96:99], v[176:179], v[192:195], v[96:99]
	v_mfma_f32_16x16x32_bf16 v[84:87], v[168:171], v[200:203], v[84:87]
	v_mfma_f32_16x16x32_bf16 v[80:83], v[176:179], v[200:203], v[80:83]
	v_mfma_f32_16x16x32_bf16 v[76:79], v[168:171], v[208:211], v[76:79]
	v_mfma_f32_16x16x32_bf16 v[72:75], v[176:179], v[208:211], v[72:75]
	s_setprio 0
	s_barrier
	s_add_u32 s28, s26, 0x8000
	s_addc_u32 s29, s27, 0
	s_add_i32 s68, s68, s34
	s_mov_b32 m0, s68
	ds_read_b128 v[180:183], v150 offset:49152
	ds_read_b128 v[184:187], v150 offset:50176
	ds_read_b128 v[188:191], v150 offset:51200
	ds_read_b128 v[192:195], v150 offset:52224
	ds_read_b128 v[196:199], v150 offset:53248
	ds_read_b128 v[200:203], v150 offset:54272
	ds_read_b128 v[204:207], v150 offset:55296
	ds_read_b128 v[208:211], v150 offset:56320
	global_load_lds_dwordx4 v138, s[28:29]
	s_add_i32 m0, s68, 0x2000
	s_add_u32 s26, s26, 0xc000
	s_addc_u32 s27, s27, 0
	global_load_lds_dwordx4 v142, s[28:29]
	s_add_i32 s28, s69, s34
	s_mov_b32 m0, s28
	s_nop 0
	global_load_lds_dwordx4 v138, s[26:27]
	s_add_i32 m0, s28, 0x2000
	s_nop 0
	global_load_lds_dwordx4 v142, s[26:27]
	s_mov_b32 m0, s64
	s_nop 0
	global_load_lds_dwordx4 v136, s[24:25]
	s_mov_b32 m0, s65
	s_nop 0
	global_load_lds_dwordx4 v140, s[24:25]
	s_waitcnt vmcnt(8)
	s_waitcnt lgkmcnt(0)
	s_setprio 1
	s_waitcnt lgkmcnt(0)
	v_mfma_f32_16x16x32_bf16 v[68:71], v[52:55], v[180:183], v[68:71]
	v_mfma_f32_16x16x32_bf16 v[64:67], v[156:159], v[180:183], v[64:67]
	v_mfma_f32_16x16x32_bf16 v[60:63], v[52:55], v[188:191], v[60:63]
	v_mfma_f32_16x16x32_bf16 v[56:59], v[156:159], v[188:191], v[56:59]
	v_mfma_f32_16x16x32_bf16 v[44:47], v[52:55], v[196:199], v[44:47]
	v_mfma_f32_16x16x32_bf16 v[40:43], v[156:159], v[196:199], v[40:43]
	v_mfma_f32_16x16x32_bf16 v[24:27], v[52:55], v[204:207], v[24:27]
	v_mfma_f32_16x16x32_bf16 v[20:23], v[156:159], v[204:207], v[20:23]
	v_mfma_f32_16x16x32_bf16 v[68:71], v[152:155], v[184:187], v[68:71]
	v_mfma_f32_16x16x32_bf16 v[64:67], v[160:163], v[184:187], v[64:67]
	v_mfma_f32_16x16x32_bf16 v[60:63], v[152:155], v[192:195], v[60:63]
	v_mfma_f32_16x16x32_bf16 v[56:59], v[160:163], v[192:195], v[56:59]
	v_mfma_f32_16x16x32_bf16 v[44:47], v[152:155], v[200:203], v[44:47]
	v_mfma_f32_16x16x32_bf16 v[40:43], v[160:163], v[200:203], v[40:43]
	v_mfma_f32_16x16x32_bf16 v[24:27], v[152:155], v[208:211], v[24:27]
	v_mfma_f32_16x16x32_bf16 v[20:23], v[160:163], v[208:211], v[20:23]
	s_setprio 0
	s_setprio 1
	v_mfma_f32_16x16x32_bf16 v[36:39], v[164:167], v[180:183], v[36:39]
	v_mfma_f32_16x16x32_bf16 v[52:55], v[168:171], v[184:187], v[36:39]
	v_mfma_f32_16x16x32_bf16 v[36:39], v[172:175], v[180:183], v[48:51]
	v_mfma_f32_16x16x32_bf16 v[32:35], v[164:167], v[188:191], v[32:35]
	v_mfma_f32_16x16x32_bf16 v[28:31], v[172:175], v[188:191], v[28:31]
	v_mfma_f32_16x16x32_bf16 v[16:19], v[164:167], v[196:199], v[16:19]
	v_mfma_f32_16x16x32_bf16 v[12:15], v[172:175], v[196:199], v[12:15]
	v_mfma_f32_16x16x32_bf16 v[8:11], v[164:167], v[204:207], v[8:11]
	v_mfma_f32_16x16x32_bf16 v[4:7], v[172:175], v[204:207], v[4:7]
	v_mfma_f32_16x16x32_bf16 v[48:51], v[176:179], v[184:187], v[36:39]
	v_mfma_f32_16x16x32_bf16 v[32:35], v[168:171], v[192:195], v[32:35]
	v_mfma_f32_16x16x32_bf16 v[28:31], v[176:179], v[192:195], v[28:31]
	v_mfma_f32_16x16x32_bf16 v[16:19], v[168:171], v[200:203], v[16:19]
	v_mfma_f32_16x16x32_bf16 v[12:15], v[176:179], v[200:203], v[12:15]
	v_mfma_f32_16x16x32_bf16 v[8:11], v[168:171], v[208:211], v[8:11]
	v_mfma_f32_16x16x32_bf16 v[4:7], v[176:179], v[208:211], v[4:7]
	s_setprio 0
	s_barrier
	s_add_i32 s13, s13, 2
	s_add_u32 s22, s22, 0x10000
	s_addc_u32 s23, s23, 0
	s_add_u32 s82, s82, 0x10000
	s_addc_u32 vcc_lo, vcc_lo, 0
	s_cmp_gt_u32 s13, 29
	s_cbranch_scc0 .LBB0_2111
	s_branch .Lkx_MOUT
; #define PG8_STAGE(bufoff, gbase, voff) do { _Pragma("unroll") for (int _i = 0; _i < 2; ++_i) \
;         __builtin_amdgcn_global_load_lds((const unsigned*)((const char*)(gbase) + (voff)[_i]), (PG8_LAS unsigned*)(lds + (bufoff) + ldsw + _i * 8192), 16, 0, 0); } while (0)
; #define PG8_LDA(dst, b, h) do { _Pragma("unroll") for (int m = 0; m < 4; ++m) _Pragma("unroll") for (int k = 0; k < 2; ++k) dst[m][k] = *(const PG8_LAS bf16x8*)(lds + PG8_SA(b, h) + aoff + m * 2048 + k * 1024); } while (0)
; #define PG8_LDB(dst, b, h) do { _Pragma("unroll") for (int n = 0; n < 2; ++n) _Pragma("unroll") for (int k = 0; k < 2; ++k) dst[n][k] = *(const PG8_LAS bf16x8*)(lds + PG8_SB(b, h) + boff + n * 2048 + k * 1024); } while (0)
; #define PG8_MMA(ai, bj, At, Bt) do { __builtin_amdgcn_s_setprio(1); _Pragma("unroll") for (int m = 0; m < 4; ++m) _Pragma("unroll") for (int n = 0; n < 2; ++n) _Pragma("unroll") for (int k = 0; k < 2; ++k) \
;         acc[ai][bj][m][n] = __builtin_amdgcn_mfma_f32_16x16x32_bf16(Bt[n][k], At[m][k], acc[ai][bj][m][n], 0, 0, 0); __builtin_amdgcn_s_setprio(0); } while (0)
; #define PG8_WAIT_V(n) asm volatile("s_waitcnt vmcnt(" #n ")" ::: "memory")
; #define PG8_WAIT_L(n) asm volatile("s_waitcnt lgkmcnt(" #n ")" ::: "memory")
; #define PG8_BAR __builtin_amdgcn_s_barrier()
; #define PG8_SCHED __builtin_amdgcn_sched_barrier(0)
; template <class Epi, class Sched, bool ALIGN_EPI = false, bool SP2 = false, bool ABLK = false, bool BBLK = false>
; __device__ __forceinline__ void gemm_phase(PG8_LAS unsigned char* lds, const Gemm g, const Sched& S, const Epi& E) {
;     ...
;             PG8_LDB(B0, 0, 0); PG8_LDB(B1, 0, 1); PG8_SCHED; PG8_LDA(At, 0, 0); PG8_STAGE(PG8_SA(1, 1), a1 + hstepA, voffA);
;             PG8_WAIT_V(8); PG8_WAIT_L(0); PG8_BAR; PG8_MMA(0, 0, At, B0); PG8_MMA(0, 1, At, B1); PG8_BAR; PG8_SCHED;
;             PG8_LDA(At, 0, 1); PG8_STAGE(PG8_SB(0, 0), b2, voffB); PG8_STAGE(PG8_SB(0, 1), b2 + hstepB, voffB); PG8_STAGE(PG8_SA(0, 0), a2, voffA);
.Lk1_MOUT:
	s_add_u32 s24, s22, 0x4000
	s_addc_u32 s25, s23, 0
	s_cmp_eq_u32 s13, 28
	s_cselect_b32 s28, s17, s24
	s_cselect_b32 s29, s12, s25
	s_cselect_b32 s26, s77, s82
	s_cselect_b32 s27, s11, vcc_lo
	s_add_u32 s24, s28, 0x8000
	s_addc_u32 s25, s29, 0
	s_add_i32 s68, 0, 0x10000
	v_add_u32_e32 v151, s68, v148
	s_add_i32 s88, 0, 0x14000
	ds_read_b128 v[36:39], v151
	ds_read_b128 v[152:155], v151 offset:1024
	ds_read_b128 v[156:159], v151 offset:2048
	ds_read_b128 v[160:163], v151 offset:3072
	v_add_u32_e32 v151, s88, v148
	ds_read_b128 v[164:167], v151
	ds_read_b128 v[168:171], v151 offset:1024
	ds_read_b128 v[172:175], v151 offset:2048
	ds_read_b128 v[176:179], v151 offset:3072
	s_add_i32 m0, s9, 0xc000
	ds_read_b128 v[180:183], v150
	ds_read_b128 v[184:187], v150 offset:1024
	ds_read_b128 v[188:191], v150 offset:2048
	ds_read_b128 v[192:195], v150 offset:3072
	ds_read_b128 v[196:199], v150 offset:4096
	ds_read_b128 v[200:203], v150 offset:5120
	ds_read_b128 v[204:207], v150 offset:6144
	ds_read_b128 v[208:211], v150 offset:7168
	global_load_lds_dwordx4 v144, s[22:23]
	s_add_i32 m0, s9, 0xe000
	s_nop 0
	global_load_lds_dwordx4 v146, s[22:23]
	s_waitcnt vmcnt(8)
	s_waitcnt lgkmcnt(0)
	s_barrier
	s_setprio 2
	s_waitcnt lgkmcnt(0)
	v_mfma_f32_16x16x32_bf16 v[132:135], v[36:39], v[180:183], v[132:135]
	v_mfma_f32_16x16x32_bf16 v[128:131], v[156:159], v[180:183], v[128:131]
	v_mfma_f32_16x16x32_bf16 v[124:127], v[36:39], v[188:191], v[124:127]
	v_mfma_f32_16x16x32_bf16 v[120:123], v[156:159], v[188:191], v[120:123]
	v_mfma_f32_16x16x32_bf16 v[108:111], v[36:39], v[196:199], v[108:111]
	v_mfma_f32_16x16x32_bf16 v[104:107], v[156:159], v[196:199], v[104:107]
	v_mfma_f32_16x16x32_bf16 v[92:95], v[36:39], v[204:207], v[92:95]
	v_mfma_f32_16x16x32_bf16 v[88:91], v[156:159], v[204:207], v[88:91]
	v_mfma_f32_16x16x32_bf16 v[132:135], v[152:155], v[184:187], v[132:135]
	v_mfma_f32_16x16x32_bf16 v[128:131], v[160:163], v[184:187], v[128:131]
	v_mfma_f32_16x16x32_bf16 v[124:127], v[152:155], v[192:195], v[124:127]
	v_mfma_f32_16x16x32_bf16 v[120:123], v[160:163], v[192:195], v[120:123]
	v_mfma_f32_16x16x32_bf16 v[108:111], v[152:155], v[200:203], v[108:111]
	v_mfma_f32_16x16x32_bf16 v[104:107], v[160:163], v[200:203], v[104:107]
	v_mfma_f32_16x16x32_bf16 v[92:95], v[152:155], v[208:211], v[92:95]
	v_mfma_f32_16x16x32_bf16 v[88:91], v[160:163], v[208:211], v[88:91]
	v_mfma_f32_16x16x32_bf16 v[116:119], v[164:167], v[180:183], v[116:119]
	v_mfma_f32_16x16x32_bf16 v[112:115], v[172:175], v[180:183], v[112:115]
	v_mfma_f32_16x16x32_bf16 v[100:103], v[164:167], v[188:191], v[100:103]
	v_mfma_f32_16x16x32_bf16 v[96:99], v[172:175], v[188:191], v[96:99]
	v_mfma_f32_16x16x32_bf16 v[84:87], v[164:167], v[196:199], v[84:87]
	v_mfma_f32_16x16x32_bf16 v[80:83], v[172:175], v[196:199], v[80:83]
	v_mfma_f32_16x16x32_bf16 v[76:79], v[164:167], v[204:207], v[76:79]
	v_mfma_f32_16x16x32_bf16 v[72:75], v[172:175], v[204:207], v[72:75]
	v_mfma_f32_16x16x32_bf16 v[116:119], v[168:171], v[184:187], v[116:119]
	v_mfma_f32_16x16x32_bf16 v[112:115], v[176:179], v[184:187], v[112:115]
	v_mfma_f32_16x16x32_bf16 v[100:103], v[168:171], v[192:195], v[100:103]
	v_mfma_f32_16x16x32_bf16 v[96:99], v[176:179], v[192:195], v[96:99]
	v_mfma_f32_16x16x32_bf16 v[84:87], v[168:171], v[200:203], v[84:87]
	v_mfma_f32_16x16x32_bf16 v[80:83], v[176:179], v[200:203], v[80:83]
	v_mfma_f32_16x16x32_bf16 v[76:79], v[168:171], v[208:211], v[76:79]
	v_mfma_f32_16x16x32_bf16 v[72:75], v[176:179], v[208:211], v[72:75]
	s_setprio 0
	s_add_i32 s68, s68, s34
	s_mov_b32 m0, s68
	ds_read_b128 v[180:183], v150 offset:16384
	ds_read_b128 v[184:187], v150 offset:17408
	ds_read_b128 v[188:191], v150 offset:18432
	ds_read_b128 v[192:195], v150 offset:19456
	ds_read_b128 v[196:199], v150 offset:20480
	ds_read_b128 v[200:203], v150 offset:21504
	ds_read_b128 v[204:207], v150 offset:22528
	ds_read_b128 v[208:211], v150 offset:23552
	global_load_lds_dwordx4 v138, s[26:27]
	s_add_i32 m0, s68, 0x2000
	s_add_u32 s68, s26, 0x4000
	s_addc_u32 s69, s27, 0
	s_add_i32 s88, s88, s34
	global_load_lds_dwordx4 v142, s[26:27]
	s_mov_b32 m0, s88
	s_nop 0
	global_load_lds_dwordx4 v138, s[68:69]
	s_add_i32 m0, s88, 0x2000
	s_nop 0
	global_load_lds_dwordx4 v142, s[68:69]
	s_mov_b32 m0, s9
	s_nop 0
	global_load_lds_dwordx4 v136, s[28:29]
	s_mov_b32 m0, s35
	s_nop 0
	global_load_lds_dwordx4 v140, s[28:29]
	s_waitcnt vmcnt(8)
	s_waitcnt lgkmcnt(0)
	s_barrier
; #define PG8_STAGE(bufoff, gbase, voff) do { _Pragma("unroll") for (int _i = 0; _i < 2; ++_i) \
;         __builtin_amdgcn_global_load_lds((const unsigned*)((const char*)(gbase) + (voff)[_i]), (PG8_LAS unsigned*)(lds + (bufoff) + ldsw + _i * 8192), 16, 0, 0); } while (0)
; #define PG8_LDA(dst, b, h) do { _Pragma("unroll") for (int m = 0; m < 4; ++m) _Pragma("unroll") for (int k = 0; k < 2; ++k) dst[m][k] = *(const PG8_LAS bf16x8*)(lds + PG8_SA(b, h) + aoff + m * 2048 + k * 1024); } while (0)
; #define PG8_LDB(dst, b, h) do { _Pragma("unroll") for (int n = 0; n < 2; ++n) _Pragma("unroll") for (int k = 0; k < 2; ++k) dst[n][k] = *(const PG8_LAS bf16x8*)(lds + PG8_SB(b, h) + boff + n * 2048 + k * 1024); } while (0)
; #define PG8_MMA(ai, bj, At, Bt) do { __builtin_amdgcn_s_setprio(1); _Pragma("unroll") for (int m = 0; m < 4; ++m) _Pragma("unroll") for (int n = 0; n < 2; ++n) _Pragma("unroll") for (int k = 0; k < 2; ++k) \
;         acc[ai][bj][m][n] = __builtin_amdgcn_mfma_f32_16x16x32_bf16(Bt[n][k], At[m][k], acc[ai][bj][m][n], 0, 0, 0); __builtin_amdgcn_s_setprio(0); } while (0)
; #define PG8_WAIT_V(n) asm volatile("s_waitcnt vmcnt(" #n ")" ::: "memory")
; #define PG8_WAIT_L(n) asm volatile("s_waitcnt lgkmcnt(" #n ")" ::: "memory")
; #define PG8_BAR __builtin_amdgcn_s_barrier()
; #define PG8_SCHED __builtin_amdgcn_sched_barrier(0)
; template <class Epi, class Sched, bool ALIGN_EPI = false, bool SP2 = false, bool ABLK = false, bool BBLK = false>
; __device__ __forceinline__ void gemm_phase(PG8_LAS unsigned char* lds, const Gemm g, const Sched& S, const Epi& E) {
;     ...
;             PG8_WAIT_V(8); PG8_WAIT_L(0); PG8_BAR; PG8_MMA(1, 0, At, B0); PG8_MMA(1, 1, At, B1); PG8_BAR; PG8_SCHED;
;             PG8_LDB(B0, 1, 0); PG8_LDB(B1, 1, 1); PG8_SCHED; PG8_LDA(At, 1, 0); PG8_STAGE(PG8_SA(0, 1), a2 + hstepA, voffA);
;             PG8_WAIT_V(8); PG8_WAIT_L(0); PG8_BAR; PG8_MMA(0, 0, At, B0); PG8_MMA(0, 1, At, B1); PG8_BAR; PG8_SCHED;
	s_setprio 2
	s_waitcnt lgkmcnt(0)
	v_mfma_f32_16x16x32_bf16 v[68:71], v[36:39], v[180:183], v[68:71]
	v_mfma_f32_16x16x32_bf16 v[64:67], v[156:159], v[180:183], v[64:67]
	v_mfma_f32_16x16x32_bf16 v[60:63], v[36:39], v[188:191], v[60:63]
	v_mfma_f32_16x16x32_bf16 v[56:59], v[156:159], v[188:191], v[56:59]
	v_mfma_f32_16x16x32_bf16 v[44:47], v[36:39], v[196:199], v[44:47]
	v_mfma_f32_16x16x32_bf16 v[40:43], v[156:159], v[196:199], v[40:43]
	v_mfma_f32_16x16x32_bf16 v[24:27], v[36:39], v[204:207], v[24:27]
	v_mfma_f32_16x16x32_bf16 v[20:23], v[156:159], v[204:207], v[20:23]
	v_mfma_f32_16x16x32_bf16 v[68:71], v[152:155], v[184:187], v[68:71]
	v_mfma_f32_16x16x32_bf16 v[64:67], v[160:163], v[184:187], v[64:67]
	v_mfma_f32_16x16x32_bf16 v[60:63], v[152:155], v[192:195], v[60:63]
	v_mfma_f32_16x16x32_bf16 v[56:59], v[160:163], v[192:195], v[56:59]
	v_mfma_f32_16x16x32_bf16 v[44:47], v[152:155], v[200:203], v[44:47]
	v_mfma_f32_16x16x32_bf16 v[40:43], v[160:163], v[200:203], v[40:43]
	v_mfma_f32_16x16x32_bf16 v[24:27], v[152:155], v[208:211], v[24:27]
	v_mfma_f32_16x16x32_bf16 v[20:23], v[160:163], v[208:211], v[20:23]
	v_mfma_f32_16x16x32_bf16 v[48:51], v[172:175], v[180:183], v[48:51]
	v_mfma_f32_16x16x32_bf16 v[32:35], v[164:167], v[188:191], v[32:35]
	v_mfma_f32_16x16x32_bf16 v[28:31], v[172:175], v[188:191], v[28:31]
	v_mfma_f32_16x16x32_bf16 v[16:19], v[164:167], v[196:199], v[16:19]
	v_mfma_f32_16x16x32_bf16 v[12:15], v[172:175], v[196:199], v[12:15]
	v_mfma_f32_16x16x32_bf16 v[8:11], v[164:167], v[204:207], v[8:11]
	v_mfma_f32_16x16x32_bf16 v[4:7], v[172:175], v[204:207], v[4:7]
	v_mfma_f32_16x16x32_bf16 v[36:39], v[164:167], v[180:183], v[52:55]
	v_mfma_f32_16x16x32_bf16 v[48:51], v[176:179], v[184:187], v[48:51]
	v_mfma_f32_16x16x32_bf16 v[32:35], v[168:171], v[192:195], v[32:35]
	v_mfma_f32_16x16x32_bf16 v[28:31], v[176:179], v[192:195], v[28:31]
	v_mfma_f32_16x16x32_bf16 v[16:19], v[168:171], v[200:203], v[16:19]
	v_mfma_f32_16x16x32_bf16 v[12:15], v[176:179], v[200:203], v[12:15]
	v_mfma_f32_16x16x32_bf16 v[8:11], v[168:171], v[208:211], v[8:11]
	v_mfma_f32_16x16x32_bf16 v[4:7], v[176:179], v[208:211], v[4:7]
	v_mfma_f32_16x16x32_bf16 v[36:39], v[168:171], v[184:187], v[36:39]
	s_setprio 0
	s_add_i32 s68, 0, 0x18000
	v_add_u32_e32 v151, s68, v148
	s_add_i32 s69, 0, 0x1c000
	ds_read_b128 v[52:55], v151
	ds_read_b128 v[152:155], v151 offset:1024
	ds_read_b128 v[156:159], v151 offset:2048
	ds_read_b128 v[160:163], v151 offset:3072
	v_add_u32_e32 v151, s69, v148
	ds_read_b128 v[164:167], v151
	ds_read_b128 v[168:171], v151 offset:1024
	ds_read_b128 v[172:175], v151 offset:2048
	ds_read_b128 v[176:179], v151 offset:3072
	s_add_u32 s28, s28, 0x4000
	s_addc_u32 s29, s29, 0
	s_mov_b32 m0, s36
	ds_read_b128 v[180:183], v150 offset:32768
	ds_read_b128 v[184:187], v150 offset:33792
	ds_read_b128 v[188:191], v150 offset:34816
	ds_read_b128 v[192:195], v150 offset:35840
	ds_read_b128 v[196:199], v150 offset:36864
	ds_read_b128 v[200:203], v150 offset:37888
	ds_read_b128 v[204:207], v150 offset:38912
	ds_read_b128 v[208:211], v150 offset:39936
	global_load_lds_dwordx4 v136, s[28:29]
	s_mov_b32 m0, s37
	s_nop 0
	global_load_lds_dwordx4 v140, s[28:29]
	s_waitcnt vmcnt(8)
	s_waitcnt lgkmcnt(0)
	s_barrier
	s_setprio 2
	s_waitcnt lgkmcnt(0)
	v_mfma_f32_16x16x32_bf16 v[132:135], v[52:55], v[180:183], v[132:135]
	v_mfma_f32_16x16x32_bf16 v[128:131], v[156:159], v[180:183], v[128:131]
	v_mfma_f32_16x16x32_bf16 v[124:127], v[52:55], v[188:191], v[124:127]
	v_mfma_f32_16x16x32_bf16 v[120:123], v[156:159], v[188:191], v[120:123]
	v_mfma_f32_16x16x32_bf16 v[108:111], v[52:55], v[196:199], v[108:111]
	v_mfma_f32_16x16x32_bf16 v[104:107], v[156:159], v[196:199], v[104:107]
	v_mfma_f32_16x16x32_bf16 v[92:95], v[52:55], v[204:207], v[92:95]
	v_mfma_f32_16x16x32_bf16 v[88:91], v[156:159], v[204:207], v[88:91]
	v_mfma_f32_16x16x32_bf16 v[132:135], v[152:155], v[184:187], v[132:135]
	v_mfma_f32_16x16x32_bf16 v[128:131], v[160:163], v[184:187], v[128:131]
	v_mfma_f32_16x16x32_bf16 v[124:127], v[152:155], v[192:195], v[124:127]
	v_mfma_f32_16x16x32_bf16 v[120:123], v[160:163], v[192:195], v[120:123]
	v_mfma_f32_16x16x32_bf16 v[108:111], v[152:155], v[200:203], v[108:111]
	v_mfma_f32_16x16x32_bf16 v[104:107], v[160:163], v[200:203], v[104:107]
	v_mfma_f32_16x16x32_bf16 v[92:95], v[152:155], v[208:211], v[92:95]
	v_mfma_f32_16x16x32_bf16 v[88:91], v[160:163], v[208:211], v[88:91]
	v_mfma_f32_16x16x32_bf16 v[116:119], v[164:167], v[180:183], v[116:119]
	v_mfma_f32_16x16x32_bf16 v[112:115], v[172:175], v[180:183], v[112:115]
	v_mfma_f32_16x16x32_bf16 v[100:103], v[164:167], v[188:191], v[100:103]
	v_mfma_f32_16x16x32_bf16 v[96:99], v[172:175], v[188:191], v[96:99]
	v_mfma_f32_16x16x32_bf16 v[84:87], v[164:167], v[196:199], v[84:87]
	v_mfma_f32_16x16x32_bf16 v[80:83], v[172:175], v[196:199], v[80:83]
	v_mfma_f32_16x16x32_bf16 v[76:79], v[164:167], v[204:207], v[76:79]
	v_mfma_f32_16x16x32_bf16 v[72:75], v[172:175], v[204:207], v[72:75]
	v_mfma_f32_16x16x32_bf16 v[116:119], v[168:171], v[184:187], v[116:119]
	v_mfma_f32_16x16x32_bf16 v[112:115], v[176:179], v[184:187], v[112:115]
	v_mfma_f32_16x16x32_bf16 v[100:103], v[168:171], v[192:195], v[100:103]
	v_mfma_f32_16x16x32_bf16 v[96:99], v[176:179], v[192:195], v[96:99]
	v_mfma_f32_16x16x32_bf16 v[84:87], v[168:171], v[200:203], v[84:87]
	v_mfma_f32_16x16x32_bf16 v[80:83], v[176:179], v[200:203], v[80:83]
	v_mfma_f32_16x16x32_bf16 v[76:79], v[168:171], v[208:211], v[76:79]
	v_mfma_f32_16x16x32_bf16 v[72:75], v[176:179], v[208:211], v[72:75]
	s_setprio 0
	s_add_u32 s28, s26, 0x8000
	s_addc_u32 s29, s27, 0
	s_add_i32 s68, s68, s34
	s_mov_b32 m0, s68
	ds_read_b128 v[180:183], v150 offset:49152
	ds_read_b128 v[184:187], v150 offset:50176
	ds_read_b128 v[188:191], v150 offset:51200
	ds_read_b128 v[192:195], v150 offset:52224
	ds_read_b128 v[196:199], v150 offset:53248
	ds_read_b128 v[200:203], v150 offset:54272
	ds_read_b128 v[204:207], v150 offset:55296
	ds_read_b128 v[208:211], v150 offset:56320
	global_load_lds_dwordx4 v138, s[28:29]
	s_add_i32 m0, s68, 0x2000
	s_add_u32 s26, s26, 0xc000
	s_addc_u32 s27, s27, 0
	global_load_lds_dwordx4 v142, s[28:29]
	s_add_i32 s28, s69, s34
	s_mov_b32 m0, s28
	s_nop 0
	global_load_lds_dwordx4 v138, s[26:27]
	s_add_i32 m0, s28, 0x2000
	s_nop 0
	global_load_lds_dwordx4 v142, s[26:27]
	s_mov_b32 m0, s64
	s_nop 0
	global_load_lds_dwordx4 v136, s[24:25]
	s_mov_b32 m0, s65
	s_nop 0
	global_load_lds_dwordx4 v140, s[24:25]
	s_waitcnt vmcnt(8)
	s_waitcnt lgkmcnt(0)
	s_barrier
; #define PG8_STAGE(bufoff, gbase, voff) do { _Pragma("unroll") for (int _i = 0; _i < 2; ++_i) \
;         __builtin_amdgcn_global_load_lds((const unsigned*)((const char*)(gbase) + (voff)[_i]), (PG8_LAS unsigned*)(lds + (bufoff) + ldsw + _i * 8192), 16, 0, 0); } while (0)
; #define PG8_LDA(dst, b, h) do { _Pragma("unroll") for (int m = 0; m < 4; ++m) _Pragma("unroll") for (int k = 0; k < 2; ++k) dst[m][k] = *(const PG8_LAS bf16x8*)(lds + PG8_SA(b, h) + aoff + m * 2048 + k * 1024); } while (0)
; #define PG8_MMA(ai, bj, At, Bt) do { __builtin_amdgcn_s_setprio(1); _Pragma("unroll") for (int m = 0; m < 4; ++m) _Pragma("unroll") for (int n = 0; n < 2; ++n) _Pragma("unroll") for (int k = 0; k < 2; ++k) \
;         acc[ai][bj][m][n] = __builtin_amdgcn_mfma_f32_16x16x32_bf16(Bt[n][k], At[m][k], acc[ai][bj][m][n], 0, 0, 0); __builtin_amdgcn_s_setprio(0); } while (0)
; #define PG8_WAIT_V(n) asm volatile("s_waitcnt vmcnt(" #n ")" ::: "memory")
; #define PG8_WAIT_L(n) asm volatile("s_waitcnt lgkmcnt(" #n ")" ::: "memory")
; #define PG8_BAR __builtin_amdgcn_s_barrier()
; #define PG8_SCHED __builtin_amdgcn_sched_barrier(0)
; template <class Epi, class Sched, bool ALIGN_EPI = false, bool SP2 = false, bool ABLK = false, bool BBLK = false>
; __device__ __forceinline__ void gemm_phase(PG8_LAS unsigned char* lds, const Gemm g, const Sched& S, const Epi& E) {
;     ...
;             PG8_LDA(At, 1, 1); PG8_STAGE(PG8_SB(1, 0), b3, voffB); PG8_STAGE(PG8_SB(1, 1), b3 + hstepB, voffB); PG8_STAGE(PG8_SA(1, 0), a3, voffA);
;             PG8_WAIT_V(8); PG8_WAIT_L(0); PG8_BAR; PG8_MMA(1, 0, At, B0); PG8_MMA(1, 1, At, B1); PG8_BAR; PG8_SCHED;
	s_setprio 2
	s_waitcnt lgkmcnt(0)
	v_mfma_f32_16x16x32_bf16 v[68:71], v[52:55], v[180:183], v[68:71]
	v_mfma_f32_16x16x32_bf16 v[64:67], v[156:159], v[180:183], v[64:67]
	v_mfma_f32_16x16x32_bf16 v[60:63], v[52:55], v[188:191], v[60:63]
	v_mfma_f32_16x16x32_bf16 v[56:59], v[156:159], v[188:191], v[56:59]
	v_mfma_f32_16x16x32_bf16 v[44:47], v[52:55], v[196:199], v[44:47]
	v_mfma_f32_16x16x32_bf16 v[40:43], v[156:159], v[196:199], v[40:43]
	v_mfma_f32_16x16x32_bf16 v[24:27], v[52:55], v[204:207], v[24:27]
	v_mfma_f32_16x16x32_bf16 v[20:23], v[156:159], v[204:207], v[20:23]
	v_mfma_f32_16x16x32_bf16 v[68:71], v[152:155], v[184:187], v[68:71]
	v_mfma_f32_16x16x32_bf16 v[64:67], v[160:163], v[184:187], v[64:67]
	v_mfma_f32_16x16x32_bf16 v[60:63], v[152:155], v[192:195], v[60:63]
	v_mfma_f32_16x16x32_bf16 v[56:59], v[160:163], v[192:195], v[56:59]
	v_mfma_f32_16x16x32_bf16 v[44:47], v[152:155], v[200:203], v[44:47]
	v_mfma_f32_16x16x32_bf16 v[40:43], v[160:163], v[200:203], v[40:43]
	v_mfma_f32_16x16x32_bf16 v[24:27], v[152:155], v[208:211], v[24:27]
	v_mfma_f32_16x16x32_bf16 v[20:23], v[160:163], v[208:211], v[20:23]
	v_mfma_f32_16x16x32_bf16 v[36:39], v[164:167], v[180:183], v[36:39]
	v_mfma_f32_16x16x32_bf16 v[52:55], v[168:171], v[184:187], v[36:39]
	v_mfma_f32_16x16x32_bf16 v[36:39], v[172:175], v[180:183], v[48:51]
	v_mfma_f32_16x16x32_bf16 v[32:35], v[164:167], v[188:191], v[32:35]
	v_mfma_f32_16x16x32_bf16 v[28:31], v[172:175], v[188:191], v[28:31]
	v_mfma_f32_16x16x32_bf16 v[16:19], v[164:167], v[196:199], v[16:19]
	v_mfma_f32_16x16x32_bf16 v[12:15], v[172:175], v[196:199], v[12:15]
	v_mfma_f32_16x16x32_bf16 v[8:11], v[164:167], v[204:207], v[8:11]
	v_mfma_f32_16x16x32_bf16 v[4:7], v[172:175], v[204:207], v[4:7]
	v_mfma_f32_16x16x32_bf16 v[48:51], v[176:179], v[184:187], v[36:39]
	v_mfma_f32_16x16x32_bf16 v[32:35], v[168:171], v[192:195], v[32:35]
	v_mfma_f32_16x16x32_bf16 v[28:31], v[176:179], v[192:195], v[28:31]
	v_mfma_f32_16x16x32_bf16 v[16:19], v[168:171], v[200:203], v[16:19]
	v_mfma_f32_16x16x32_bf16 v[12:15], v[176:179], v[200:203], v[12:15]
	v_mfma_f32_16x16x32_bf16 v[8:11], v[168:171], v[208:211], v[8:11]
	v_mfma_f32_16x16x32_bf16 v[4:7], v[176:179], v[208:211], v[4:7]
	s_setprio 0
	s_add_i32 s13, s13, 2
	s_add_u32 s22, s22, 0x10000
	s_addc_u32 s23, s23, 0
	s_add_u32 s82, s82, 0x10000
	s_addc_u32 vcc_lo, vcc_lo, 0
	s_cmp_gt_u32 s13, 29
	s_cbranch_scc0 .Lk1_MOUT
.Lkx_MOUT:
	s_and_b64 vcc, exec, s[6:7]
	s_movk_i32 s77, 0x1000
	s_cbranch_vccz .LBB0_2114
; __device__ __forceinline__ unsigned cvt_pk_bf16(float lo, float hi) { const hwf2_t v = {lo, hi}; return __builtin_bit_cast(unsigned, __builtin_convertvector(v, hwbf2_t)); }
; #define PG8_BAR __builtin_amdgcn_s_barrier()
;     __device__ __forceinline__ void operator()(const f32x4 (&acc)[2][2][4][2], const Unit& u, int wr, int wc, int fr, int fq, const PG8_LAS unsigned char* area) const {
;     ...
;         for (int ai = 0; ai < 2; ++ai)
; #pragma unroll
;             for (int m = 0; m < 4; ++m) { bf16_t* rowp = O + (size_t)(row0 + ai * HALF + m * 16) * ldc + col0; const float r_ = rsv[ai][m];
; #pragma unroll
;                 for (int bj = 0; bj < 2; ++bj) { const f32x4 v0 = acc[ai][bj][m][0] * r_, v1 = acc[ai][bj][m][1] * r_;
;                     u32x4 w; w.x = cvt_pk_bf16(v0[0], v0[1]); w.y = cvt_pk_bf16(v0[2], v0[3]); w.z = cvt_pk_bf16(v1[0], v1[1]); w.w = cvt_pk_bf16(v1[2], v1[3]);
;                     *(u32x4*)(rowp + bj * HALF) = w; } }
; template <class Epi, class Sched, bool ALIGN_EPI = false, bool SP2 = false, bool ABLK = false, bool BBLK = false>
; __device__ __forceinline__ void gemm_phase(PG8_LAS unsigned char* lds, const Gemm g, const Sched& S, const Epi& E) {
;     ...
;         if constexpr (ALIGN_EPI) { if (wr == 0) PG8_BAR; }
;         if constexpr (!Epi::AFTER_DRAIN) { E(acc, cur, wr, wc, fr, fq, rs_area); S.done(cur); }
;         if (!has_next) break;
; #pragma unroll
;         for (int a = 0; a < 2; ++a)
; #pragma unroll
;             for (int b = 0; b < 2; ++b)
; #pragma unroll
;                 for (int m = 0; m < 4; ++m)
; #pragma unroll
;                     for (int n = 0; n < 2; ++n) acc[a][b][m][n] = (f32x4){0.f, 0.f, 0.f, 0.f};
;         cur = nxt; cA = nA; cB = nB; ++ui;
;         if constexpr (ALIGN_EPI) { if (wr == 1) PG8_BAR; }
.LBB0_2114:
	v_lshl_add_u32 v152, s8, 8, v3
	v_lshl_or_b32 v36, s71, 8, v149
	v_ashrrev_i32_e32 v153, 31, v152
	v_ashrrev_i32_e32 v37, 31, v36
	v_lshlrev_b64 v[38:39], 12, v[152:153]
	v_lshl_add_u64 v[38:39], s[92:93], 0, v[38:39]
	v_lshlrev_b64 v[154:155], 1, v[36:37]
	v_lshl_add_u64 v[156:157], v[38:39], 0, v[154:155]
	v_cvt_pk_bf16_f32 v36, v132, v133
	v_cvt_pk_bf16_f32 v37, v134, v135
	v_cvt_pk_bf16_f32 v38, v128, v129
	v_cvt_pk_bf16_f32 v39, v130, v131
	global_store_dwordx4 v[156:157], v[36:39], off
	s_mov_b32 s8, 0x80000
	s_mov_b64 s[12:13], 0x80000
	v_cvt_pk_bf16_f32 v36, v116, v117
	v_cvt_pk_bf16_f32 v37, v118, v119
	v_cvt_pk_bf16_f32 v38, v112, v113
	v_cvt_pk_bf16_f32 v39, v114, v115
	global_store_dwordx4 v[156:157], v[36:39], off offset:256
	v_cvt_pk_bf16_f32 v32, v32, v33
	v_cvt_pk_bf16_f32 v33, v34, v35
	v_or_b32_e32 v36, 16, v152
	v_ashrrev_i32_e32 v37, 31, v36
	v_lshlrev_b64 v[36:37], 12, v[36:37]
	v_lshl_add_u64 v[36:37], s[92:93], 0, v[36:37]
	v_lshl_add_u64 v[112:113], v[36:37], 0, v[154:155]
	v_cvt_pk_bf16_f32 v36, v124, v125
	v_cvt_pk_bf16_f32 v37, v126, v127
	v_cvt_pk_bf16_f32 v38, v120, v121
	v_cvt_pk_bf16_f32 v39, v122, v123
	global_store_dwordx4 v[112:113], v[36:39], off
	v_cvt_pk_bf16_f32 v34, v28, v29
	v_cvt_pk_bf16_f32 v35, v30, v31
	v_cvt_pk_bf16_f32 v36, v100, v101
	v_cvt_pk_bf16_f32 v37, v102, v103
	v_cvt_pk_bf16_f32 v38, v96, v97
	v_cvt_pk_bf16_f32 v39, v98, v99
	global_store_dwordx4 v[112:113], v[36:39], off offset:256
	v_cvt_pk_bf16_f32 v16, v16, v17
	v_cvt_pk_bf16_f32 v17, v18, v19
	v_or_b32_e32 v36, 32, v152
	v_ashrrev_i32_e32 v37, 31, v36
	v_lshlrev_b64 v[36:37], 12, v[36:37]
	v_lshl_add_u64 v[36:37], s[92:93], 0, v[36:37]
	v_lshl_add_u64 v[96:97], v[36:37], 0, v[154:155]
	v_cvt_pk_bf16_f32 v36, v108, v109
	v_cvt_pk_bf16_f32 v37, v110, v111
	v_cvt_pk_bf16_f32 v38, v104, v105
	v_cvt_pk_bf16_f32 v39, v106, v107
	global_store_dwordx4 v[96:97], v[36:39], off
	v_cvt_pk_bf16_f32 v18, v12, v13
	v_cvt_pk_bf16_f32 v19, v14, v15
	v_cvt_pk_bf16_f32 v36, v84, v85
	v_cvt_pk_bf16_f32 v37, v86, v87
	v_cvt_pk_bf16_f32 v38, v80, v81
	v_cvt_pk_bf16_f32 v39, v82, v83
	global_store_dwordx4 v[96:97], v[36:39], off offset:256
	v_cvt_pk_bf16_f32 v28, v44, v45
	v_cvt_pk_bf16_f32 v29, v46, v47
	v_or_b32_e32 v36, 48, v152
	v_ashrrev_i32_e32 v37, 31, v36
	v_lshlrev_b64 v[36:37], 12, v[36:37]
	v_lshl_add_u64 v[36:37], s[92:93], 0, v[36:37]
	v_lshl_add_u64 v[80:81], v[36:37], 0, v[154:155]
	v_cvt_pk_bf16_f32 v36, v92, v93
	v_cvt_pk_bf16_f32 v37, v94, v95
	v_cvt_pk_bf16_f32 v38, v88, v89
	v_cvt_pk_bf16_f32 v39, v90, v91
	global_store_dwordx4 v[80:81], v[36:39], off
	v_cvt_pk_bf16_f32 v30, v40, v41
	v_cvt_pk_bf16_f32 v31, v42, v43
	v_cvt_pk_bf16_f32 v36, v76, v77
	v_cvt_pk_bf16_f32 v37, v78, v79
	v_cvt_pk_bf16_f32 v38, v72, v73
	v_cvt_pk_bf16_f32 v39, v74, v75
	global_store_dwordx4 v[80:81], v[36:39], off offset:256
	v_lshl_add_u64 v[72:73], v[156:157], 0, s[12:13]
	s_mov_b64 s[12:13], 0x90000
	v_cvt_pk_bf16_f32 v38, v64, v65
	v_add_co_u32_e32 v64, vcc, s8, v156
	v_cvt_pk_bf16_f32 v36, v68, v69
	v_cvt_pk_bf16_f32 v37, v70, v71
	v_cvt_pk_bf16_f32 v39, v66, v67
	v_addc_co_u32_e32 v65, vcc, 0, v157, vcc
	s_mov_b32 s8, 0x90000
	global_store_dwordx4 v[64:65], v[36:39], off
	v_cvt_pk_bf16_f32 v12, v24, v25
	v_cvt_pk_bf16_f32 v13, v26, v27
	v_cvt_pk_bf16_f32 v39, v50, v51
	v_add_co_u32_e32 v50, vcc, s8, v156
	v_cvt_pk_bf16_f32 v38, v48, v49
	v_lshl_add_u64 v[48:49], v[156:157], 0, s[12:13]
	v_addc_co_u32_e32 v51, vcc, 0, v157, vcc
	s_mov_b32 s8, 0xa0000
	global_store_dwordx4 v[48:49], v[32:35], off offset:256
	s_mov_b64 s[12:13], 0xa0000
	v_cvt_pk_bf16_f32 v36, v52, v53
	v_add_co_u32_e32 v34, vcc, s8, v156
	v_lshl_add_u64 v[32:33], v[156:157], 0, s[12:13]
	s_nop 0
	v_addc_co_u32_e32 v35, vcc, 0, v157, vcc
	s_mov_b32 s8, 0xb0000
	global_store_dwordx4 v[32:33], v[16:19], off offset:256
	v_cvt_pk_bf16_f32 v37, v54, v55
	s_mov_b64 s[12:13], 0xb0000
	v_add_co_u32_e32 v18, vcc, s8, v156
	global_store_dwordx4 v[72:73], v[36:39], off offset:256
	s_nop 0
	v_addc_co_u32_e32 v19, vcc, 0, v157, vcc
	v_cvt_pk_bf16_f32 v36, v60, v61
	v_cvt_pk_bf16_f32 v37, v62, v63
	v_cvt_pk_bf16_f32 v38, v56, v57
	v_cvt_pk_bf16_f32 v39, v58, v59
	v_lshl_add_u64 v[16:17], v[156:157], 0, s[12:13]
	v_cvt_pk_bf16_f32 v14, v20, v21
	v_cvt_pk_bf16_f32 v15, v22, v23
	v_cvt_pk_bf16_f32 v8, v8, v9
	v_cvt_pk_bf16_f32 v9, v10, v11
	v_cvt_pk_bf16_f32 v10, v4, v5
	v_cvt_pk_bf16_f32 v11, v6, v7
	s_andn2_b64 vcc, exec, s[4:5]
	s_mov_b64 s[4:5], -1
	v_readlane_b32 s85, v253, 33
	global_store_dwordx4 v[50:51], v[36:39], off
	global_store_dwordx4 v[34:35], v[28:31], off
	global_store_dwordx4 v[18:19], v[12:15], off
	global_store_dwordx4 v[16:17], v[8:11], off offset:256
	s_cbranch_vccnz .LBB0_2103
	s_andn2_b64 vcc, exec, s[0:1]
	s_cbranch_vccnz .LBB0_2102
	s_branch .LBB0_2102

; #define LAS __attribute__((address_space(3)))
; __global__ void __launch_bounds__(NTHREADS, 2) k_mega(KP p) {
;     extern __shared__ __attribute__((aligned(16))) unsigned char smem[];
;     LAS unsigned char* lds = (LAS unsigned char*)smem;
;     volatile LAS unsigned* xbw = (volatile LAS unsigned*)(lds + LDS_BYTES - 16);
;     if (threadIdx.x < 4) xbw[threadIdx.x] = 0u;
;     __syncthreads();
;     const XcdBarrier bar = xcd_barrier_post((unsigned*)(p.ws + WS_CTL) + CW_BAR, xbw);
	.amdhsa_kernel _Z6k_mega2KP
		.amdhsa_group_segment_fixed_size 0
		.amdhsa_private_segment_fixed_size 0
		.amdhsa_kernarg_size 512
		.amdhsa_user_sgpr_count 2
		.amdhsa_user_sgpr_dispatch_ptr 0
		.amdhsa_user_sgpr_queue_ptr 0
		.amdhsa_user_sgpr_kernarg_segment_ptr 1
		.amdhsa_user_sgpr_dispatch_id 0
		.amdhsa_user_sgpr_kernarg_preload_length 0
		.amdhsa_user_sgpr_kernarg_preload_offset 0
		.amdhsa_user_sgpr_private_segment_size 0
		.amdhsa_uses_dynamic_stack 0
		.amdhsa_enable_private_segment 0
		.amdhsa_system_sgpr_workgroup_id_x 1
		.amdhsa_system_sgpr_workgroup_id_y 0
		.amdhsa_system_sgpr_workgroup_id_z 0
		.amdhsa_system_sgpr_workgroup_info 0
		.amdhsa_system_vgpr_workitem_id 0
		.amdhsa_next_free_vgpr 256
		.amdhsa_next_free_sgpr 102
		.amdhsa_accum_offset 256
		.amdhsa_reserve_vcc 1
		.amdhsa_float_round_mode_32 0
		.amdhsa_float_round_mode_16_64 0
		.amdhsa_float_denorm_mode_32 3
		.amdhsa_float_denorm_mode_16_64 3
		.amdhsa_dx10_clamp 1
		.amdhsa_ieee_mode 1
		.amdhsa_fp16_overflow 0
		.amdhsa_tg_split 0
		.amdhsa_exception_fp_ieee_invalid_op 0
		.amdhsa_exception_fp_denorm_src 0
		.amdhsa_exception_fp_ieee_div_zero 0
		.amdhsa_exception_fp_ieee_overflow 0
		.amdhsa_exception_fp_ieee_underflow 0
		.amdhsa_exception_fp_ieee_inexact 0
		.amdhsa_exception_int_div_zero 0
	.end_amdhsa_kernel

; __global__ void __launch_bounds__(NTHREADS, 2) k_mega(KP p) {
;     extern __shared__ __attribute__((aligned(16))) unsigned char smem[];
amdhsa.kernels:
  - .agpr_count:     0
    .args:
      - .offset:         0
        .size:           256
        .value_kind:     by_value
      - .offset:         256
        .size:           4
        .value_kind:     hidden_block_count_x
      - .offset:         260
        .size:           4
        .value_kind:     hidden_block_count_y
      - .offset:         264
        .size:           4
        .value_kind:     hidden_block_count_z
      - .offset:         268
        .size:           2
        .value_kind:     hidden_group_size_x
      - .offset:         270
        .size:           2
        .value_kind:     hidden_group_size_y
      - .offset:         272
        .size:           2
        .value_kind:     hidden_group_size_z
      - .offset:         274
        .size:           2
        .value_kind:     hidden_remainder_x
      - .offset:         276
        .size:           2
        .value_kind:     hidden_remainder_y
      - .offset:         278
        .size:           2
        .value_kind:     hidden_remainder_z
      - .offset:         296
        .size:           8
        .value_kind:     hidden_global_offset_x
      - .offset:         304
        .size:           8
        .value_kind:     hidden_global_offset_y
      - .offset:         312
        .size:           8
        .value_kind:     hidden_global_offset_z
      - .offset:         320
        .size:           2
        .value_kind:     hidden_grid_dims
      - .offset:         376
        .size:           4
        .value_kind:     hidden_dynamic_lds_size
    .group_segment_fixed_size: 0
    .kernarg_segment_align: 8
    .kernarg_segment_size: 512
    .language:       OpenCL C
    .language_version:
      - 2
      - 0
    .max_flat_workgroup_size: 512
    .name:           _Z6k_mega2KP
    .private_segment_fixed_size: 0
    .sgpr_count:     108
    .sgpr_spill_count: 255
    .symbol:         _Z6k_mega2KP.kd
    .uniform_work_group_size: 1
    .uses_dynamic_stack: false
    .vgpr_count:     256
    .vgpr_spill_count: 0
    .wavefront_size: 64
